# P1/FF1 epilogues: 16 partial sums of squares per row added with a packed-add tree (8 VALU) instead of the compiled shuffle/add sequence
# baseline (speedup 1.0000x reference)
; #define PG8_STAGE(bufoff, gbase, voff) do { _Pragma("unroll") for (int _i = 0; _i < 2; ++_i) \
;         __builtin_amdgcn_global_load_lds((const unsigned*)((const char*)(gbase) + (voff)[_i]), (LAS unsigned*)(lds + (bufoff) + ldsw + _i * 8192), 16, 0, 0); } while (0)
; #define PG8_LDA(dst, b, h) do { _Pragma("unroll") for (int m = 0; m < 4; ++m) _Pragma("unroll") for (int k = 0; k < 2; ++k) dst[m][k] = *(const LAS bf16x8*)(lds + PG8_SA(b, h) + aoff + m * 2048 + k * 1024); } while (0)
; #define PG8_LDB(dst, b, h) do { _Pragma("unroll") for (int n = 0; n < 2; ++n) _Pragma("unroll") for (int k = 0; k < 2; ++k) dst[n][k] = *(const LAS bf16x8*)(lds + PG8_SB(b, h) + boff + n * 2048 + k * 1024); } while (0)
; #define PG8_MMA(ai, bj, At, Bt) do { __builtin_amdgcn_s_setprio(1); _Pragma("unroll") for (int m = 0; m < 4; ++m) _Pragma("unroll") for (int n = 0; n < 2; ++n) _Pragma("unroll") for (int k = 0; k < 2; ++k) \
;         acc[ai][bj][m][n] = __builtin_amdgcn_mfma_f32_16x16x32_bf16(Bt[n][k], At[m][k], acc[ai][bj][m][n], 0, 0, 0); __builtin_amdgcn_s_setprio(0); } while (0)
; #define PG8_WAIT_L(n) asm volatile("s_waitcnt lgkmcnt(" #n ")" ::: "memory")
; #define PG8_BAR __builtin_amdgcn_s_barrier()
; #define PG8_SCHED __builtin_amdgcn_sched_barrier(0)
;     ...
;             PG8_LDB(B0, 0, 0); PG8_SCHED; PG8_LDA(At, 0, 0); PG8_STAGE(PG8_SA(1, 1), a1 + hA, voffA);
;             PG8_WAIT_L(8); PG8_BAR; PG8_WAIT_L(0); PG8_MMA(0, 0, At, B0); PG8_BAR; PG8_SCHED;
;             PG8_LDB(B1, 0, 1); PG8_STAGE(PG8_SB(0, 0), b2, voffB);
;             PG8_BAR; PG8_WAIT_L(0); PG8_MMA(0, 1, At, B1); PG8_BAR;
;             PG8_LDA(At, 0, 1); PG8_STAGE(PG8_SA(0, 0), a2, voffA);
;             PG8_BAR; PG8_WAIT_L(0); PG8_MMA(1, 0, At, B0); PG8_BAR; PG8_SCHED;
.LBB0_125:
	ds_read_b128 v[146:149], v155
	ds_read_b128 v[160:163], v155 offset:1024
	ds_read_b128 v[170:173], v155 offset:2048
	ds_read_b128 v[174:177], v155 offset:3072
	s_add_u32 s34, s30, 0xfffc0080
	s_addc_u32 s35, s31, -1
	s_cmp_eq_u32 s44, 12
	s_cselect_b32 s37, s7, s35
	s_cselect_b32 s36, s23, s34
	s_cselect_b32 s35, s21, s43
	s_cselect_b32 s34, s33, s42
	v_lshl_add_u64 v[150:151], s[30:31], 0, v[138:139]
	s_add_i32 m0, s29, 0xc000
	ds_read_b128 v[178:181], v156
	ds_read_b128 v[182:185], v156 offset:1024
	ds_read_b128 v[186:189], v156 offset:2048
	ds_read_b128 v[190:193], v156 offset:3072
	ds_read_b128 v[194:197], v156 offset:4096
	ds_read_b128 v[198:201], v156 offset:5120
	ds_read_b128 v[202:205], v156 offset:6144
	ds_read_b128 v[206:209], v156 offset:7168
	global_load_lds_dwordx4 v[150:151], off
	v_lshl_add_u64 v[150:151], s[30:31], 0, v[136:137]
	s_add_i32 m0, s29, 0xe000
	s_nop 0
	global_load_lds_dwordx4 v[150:151], off
	s_waitcnt lgkmcnt(8)
	s_barrier
	s_waitcnt lgkmcnt(0)
	s_setprio 1
	s_waitcnt lgkmcnt(0)
	v_mfma_f32_16x16x32_bf16 v[124:127], v[146:149], v[178:181], v[124:127]
	v_mfma_f32_16x16x32_bf16 v[120:123], v[170:173], v[178:181], v[120:123]
	v_mfma_f32_16x16x32_bf16 v[108:111], v[146:149], v[186:189], v[108:111]
	v_mfma_f32_16x16x32_bf16 v[104:107], v[170:173], v[186:189], v[104:107]
	v_mfma_f32_16x16x32_bf16 v[92:95], v[146:149], v[194:197], v[92:95]
	v_mfma_f32_16x16x32_bf16 v[88:91], v[170:173], v[194:197], v[88:91]
	v_mfma_f32_16x16x32_bf16 v[76:79], v[146:149], v[202:205], v[76:79]
	v_mfma_f32_16x16x32_bf16 v[72:75], v[170:173], v[202:205], v[72:75]
	v_mfma_f32_16x16x32_bf16 v[124:127], v[160:163], v[182:185], v[124:127]
	v_mfma_f32_16x16x32_bf16 v[120:123], v[174:177], v[182:185], v[120:123]
	v_mfma_f32_16x16x32_bf16 v[108:111], v[160:163], v[190:193], v[108:111]
	v_mfma_f32_16x16x32_bf16 v[104:107], v[174:177], v[190:193], v[104:107]
	v_mfma_f32_16x16x32_bf16 v[92:95], v[160:163], v[198:201], v[92:95]
	v_mfma_f32_16x16x32_bf16 v[88:91], v[174:177], v[198:201], v[88:91]
	v_mfma_f32_16x16x32_bf16 v[76:79], v[160:163], v[206:209], v[76:79]
	v_mfma_f32_16x16x32_bf16 v[72:75], v[174:177], v[206:209], v[72:75]
	s_setprio 0
	s_barrier
	s_add_i32 s45, s59, s51
	v_lshl_add_u64 v[150:151], s[34:35], 0, v[130:131]
	s_mov_b32 m0, s45
	ds_read_b128 v[210:213], v157
	ds_read_b128 v[214:217], v157 offset:1024
	ds_read_b128 v[218:221], v157 offset:2048
	ds_read_b128 v[222:225], v157 offset:3072
	global_load_lds_dwordx4 v[150:151], off
	v_lshl_add_u64 v[164:165], s[34:35], 0, v[134:135]
	s_add_i32 m0, s45, 0x2000
	s_nop 0
	global_load_lds_dwordx4 v[164:165], off
	s_barrier
	s_waitcnt lgkmcnt(0)
	s_setprio 1
	s_waitcnt lgkmcnt(0)
	v_mfma_f32_16x16x32_bf16 v[116:119], v[210:213], v[178:181], v[116:119]
	v_mfma_f32_16x16x32_bf16 v[112:115], v[218:221], v[178:181], v[112:115]
	v_mfma_f32_16x16x32_bf16 v[100:103], v[210:213], v[186:189], v[100:103]
	v_mfma_f32_16x16x32_bf16 v[96:99], v[218:221], v[186:189], v[96:99]
	v_mfma_f32_16x16x32_bf16 v[84:87], v[210:213], v[194:197], v[84:87]
	v_mfma_f32_16x16x32_bf16 v[80:83], v[218:221], v[194:197], v[80:83]
	v_mfma_f32_16x16x32_bf16 v[68:71], v[210:213], v[202:205], v[68:71]
	v_mfma_f32_16x16x32_bf16 v[64:67], v[218:221], v[202:205], v[64:67]
	v_mfma_f32_16x16x32_bf16 v[116:119], v[214:217], v[182:185], v[116:119]
	v_mfma_f32_16x16x32_bf16 v[112:115], v[222:225], v[182:185], v[112:115]
	v_mfma_f32_16x16x32_bf16 v[100:103], v[214:217], v[190:193], v[100:103]
	v_mfma_f32_16x16x32_bf16 v[96:99], v[222:225], v[190:193], v[96:99]
	v_mfma_f32_16x16x32_bf16 v[84:87], v[214:217], v[198:201], v[84:87]
	v_mfma_f32_16x16x32_bf16 v[80:83], v[222:225], v[198:201], v[80:83]
	v_mfma_f32_16x16x32_bf16 v[68:71], v[214:217], v[206:209], v[68:71]
	v_mfma_f32_16x16x32_bf16 v[64:67], v[222:225], v[206:209], v[64:67]
	s_setprio 0
	s_mov_b32 m0, s29
	v_lshl_add_u64 v[226:227], s[36:37], 0, v[128:129]
	s_barrier
	ds_read_b128 v[178:181], v156 offset:16384
	ds_read_b128 v[182:185], v156 offset:17408
	ds_read_b128 v[186:189], v156 offset:18432
	ds_read_b128 v[190:193], v156 offset:19456
	ds_read_b128 v[194:197], v156 offset:20480
	ds_read_b128 v[198:201], v156 offset:21504
	ds_read_b128 v[202:205], v156 offset:22528
	ds_read_b128 v[206:209], v156 offset:23552
	global_load_lds_dwordx4 v[226:227], off
	v_lshl_add_u64 v[228:229], s[36:37], 0, v[132:133]
	s_mov_b32 m0, s52
	s_nop 0
	global_load_lds_dwordx4 v[228:229], off
	s_barrier
	s_waitcnt lgkmcnt(0)
	s_setprio 1
	s_waitcnt lgkmcnt(0)
	v_mfma_f32_16x16x32_bf16 v[60:63], v[146:149], v[178:181], v[60:63]
	v_mfma_f32_16x16x32_bf16 v[56:59], v[170:173], v[178:181], v[56:59]
	v_mfma_f32_16x16x32_bf16 v[44:47], v[146:149], v[186:189], v[44:47]
	v_mfma_f32_16x16x32_bf16 v[40:43], v[170:173], v[186:189], v[40:43]
	v_mfma_f32_16x16x32_bf16 v[28:31], v[146:149], v[194:197], v[28:31]
	v_mfma_f32_16x16x32_bf16 v[24:27], v[170:173], v[194:197], v[24:27]
	v_mfma_f32_16x16x32_bf16 v[12:15], v[146:149], v[202:205], v[12:15]
	v_mfma_f32_16x16x32_bf16 v[8:11], v[170:173], v[202:205], v[8:11]
	v_mfma_f32_16x16x32_bf16 v[60:63], v[160:163], v[182:185], v[60:63]
	v_mfma_f32_16x16x32_bf16 v[56:59], v[174:177], v[182:185], v[56:59]
	v_mfma_f32_16x16x32_bf16 v[44:47], v[160:163], v[190:193], v[44:47]
	v_mfma_f32_16x16x32_bf16 v[40:43], v[174:177], v[190:193], v[40:43]
	v_mfma_f32_16x16x32_bf16 v[28:31], v[160:163], v[198:201], v[28:31]
	v_mfma_f32_16x16x32_bf16 v[24:27], v[174:177], v[198:201], v[24:27]
	v_mfma_f32_16x16x32_bf16 v[12:15], v[160:163], v[206:209], v[12:15]
	v_mfma_f32_16x16x32_bf16 v[8:11], v[174:177], v[206:209], v[8:11]
	s_setprio 0
	s_barrier
; #define PG8_STAGE(bufoff, gbase, voff) do { _Pragma("unroll") for (int _i = 0; _i < 2; ++_i) \
;         __builtin_amdgcn_global_load_lds((const unsigned*)((const char*)(gbase) + (voff)[_i]), (LAS unsigned*)(lds + (bufoff) + ldsw + _i * 8192), 16, 0, 0); } while (0)
; #define PG8_LDA(dst, b, h) do { _Pragma("unroll") for (int m = 0; m < 4; ++m) _Pragma("unroll") for (int k = 0; k < 2; ++k) dst[m][k] = *(const LAS bf16x8*)(lds + PG8_SA(b, h) + aoff + m * 2048 + k * 1024); } while (0)
; #define PG8_LDB(dst, b, h) do { _Pragma("unroll") for (int n = 0; n < 2; ++n) _Pragma("unroll") for (int k = 0; k < 2; ++k) dst[n][k] = *(const LAS bf16x8*)(lds + PG8_SB(b, h) + boff + n * 2048 + k * 1024); } while (0)
; #define PG8_MMA(ai, bj, At, Bt) do { __builtin_amdgcn_s_setprio(1); _Pragma("unroll") for (int m = 0; m < 4; ++m) _Pragma("unroll") for (int n = 0; n < 2; ++n) _Pragma("unroll") for (int k = 0; k < 2; ++k) \
;         acc[ai][bj][m][n] = __builtin_amdgcn_mfma_f32_16x16x32_bf16(Bt[n][k], At[m][k], acc[ai][bj][m][n], 0, 0, 0); __builtin_amdgcn_s_setprio(0); } while (0)
; #define PG8_WAIT_V(n) asm volatile("s_waitcnt vmcnt(" #n ")" ::: "memory")
; #define PG8_WAIT_L(n) asm volatile("s_waitcnt lgkmcnt(" #n ")" ::: "memory")
; #define PG8_BAR __builtin_amdgcn_s_barrier()
; #define PG8_SCHED __builtin_amdgcn_sched_barrier(0)
;     ...
;             PG8_STAGE(PG8_SB(0, 1), b2 + hB, voffB);
;             PG8_WAIT_V(6); PG8_BAR; PG8_MMA(1, 1, At, B1); PG8_BAR;
;             PG8_LDB(B0, 1, 0); PG8_SCHED; PG8_LDA(At, 1, 0); PG8_STAGE(PG8_SA(0, 1), a2 + hA, voffA);
;             PG8_WAIT_L(8); PG8_BAR; PG8_WAIT_L(0); PG8_MMA(0, 0, At, B0); PG8_BAR; PG8_SCHED;
;             PG8_LDB(B1, 1, 1); PG8_STAGE(PG8_SB(1, 0), b3, voffB);
;             PG8_BAR; PG8_WAIT_L(0); PG8_MMA(0, 1, At, B1); PG8_BAR;
;             PG8_LDA(At, 1, 1); PG8_STAGE(PG8_SA(1, 0), a3, voffA);
;             PG8_BAR; PG8_WAIT_L(0); PG8_MMA(1, 0, At, B0); PG8_BAR; PG8_SCHED;
	s_add_u32 s64, s34, 0x40000
	s_addc_u32 s65, s35, 0
	s_add_i32 s45, s60, s51
	v_lshl_add_u64 v[146:147], s[64:65], 0, v[130:131]
	s_mov_b32 m0, s45
	s_nop 0
	global_load_lds_dwordx4 v[146:147], off
	v_lshl_add_u64 v[146:147], s[64:65], 0, v[134:135]
	s_add_i32 m0, s45, 0x2000
	s_nop 0
	global_load_lds_dwordx4 v[146:147], off
	s_waitcnt vmcnt(6)
	s_barrier
	s_setprio 1
	v_mfma_f32_16x16x32_bf16 v[52:55], v[210:213], v[178:181], v[52:55]
	v_mfma_f32_16x16x32_bf16 v[48:51], v[218:221], v[178:181], v[48:51]
	v_mfma_f32_16x16x32_bf16 v[36:39], v[210:213], v[186:189], v[36:39]
	v_mfma_f32_16x16x32_bf16 v[32:35], v[218:221], v[186:189], v[32:35]
	v_mfma_f32_16x16x32_bf16 v[20:23], v[210:213], v[194:197], v[20:23]
	v_mfma_f32_16x16x32_bf16 v[16:19], v[218:221], v[194:197], v[16:19]
	v_mfma_f32_16x16x32_bf16 v[4:7], v[210:213], v[202:205], v[4:7]
	v_mfma_f32_16x16x32_bf16 v[0:3], v[218:221], v[202:205], v[0:3]
	v_mfma_f32_16x16x32_bf16 v[52:55], v[214:217], v[182:185], v[52:55]
	v_mfma_f32_16x16x32_bf16 v[48:51], v[222:225], v[182:185], v[48:51]
	v_mfma_f32_16x16x32_bf16 v[36:39], v[214:217], v[190:193], v[36:39]
	v_mfma_f32_16x16x32_bf16 v[32:35], v[222:225], v[190:193], v[32:35]
	v_mfma_f32_16x16x32_bf16 v[20:23], v[214:217], v[198:201], v[20:23]
	v_mfma_f32_16x16x32_bf16 v[16:19], v[222:225], v[198:201], v[16:19]
	v_mfma_f32_16x16x32_bf16 v[4:7], v[214:217], v[206:209], v[4:7]
	v_mfma_f32_16x16x32_bf16 v[0:3], v[222:225], v[206:209], v[0:3]
	s_setprio 0
	s_add_i32 s45, 0, 0x18000
	v_add_u32_e32 v159, s45, v153
	s_barrier
	ds_read_b128 v[146:149], v159
	ds_read_b128 v[160:163], v159 offset:1024
	ds_read_b128 v[170:173], v159 offset:2048
	ds_read_b128 v[174:177], v159 offset:3072
	s_add_u32 s36, s36, 0x40000
	s_addc_u32 s37, s37, 0
	s_mov_b32 m0, s53
	v_lshl_add_u64 v[210:211], s[36:37], 0, v[128:129]
	ds_read_b128 v[178:181], v156 offset:32768
	ds_read_b128 v[182:185], v156 offset:33792
	ds_read_b128 v[186:189], v156 offset:34816
	ds_read_b128 v[190:193], v156 offset:35840
	ds_read_b128 v[194:197], v156 offset:36864
	ds_read_b128 v[198:201], v156 offset:37888
	ds_read_b128 v[202:205], v156 offset:38912
	ds_read_b128 v[206:209], v156 offset:39936
	global_load_lds_dwordx4 v[210:211], off
	v_lshl_add_u64 v[210:211], s[36:37], 0, v[132:133]
	s_mov_b32 m0, s54
	s_nop 0
	global_load_lds_dwordx4 v[210:211], off
	s_waitcnt lgkmcnt(8)
	s_barrier
	s_waitcnt lgkmcnt(0)
	s_setprio 1
	s_waitcnt lgkmcnt(0)
	v_mfma_f32_16x16x32_bf16 v[124:127], v[146:149], v[178:181], v[124:127]
	v_mfma_f32_16x16x32_bf16 v[120:123], v[170:173], v[178:181], v[120:123]
	v_mfma_f32_16x16x32_bf16 v[108:111], v[146:149], v[186:189], v[108:111]
	v_mfma_f32_16x16x32_bf16 v[104:107], v[170:173], v[186:189], v[104:107]
	v_mfma_f32_16x16x32_bf16 v[92:95], v[146:149], v[194:197], v[92:95]
	v_mfma_f32_16x16x32_bf16 v[88:91], v[170:173], v[194:197], v[88:91]
	v_mfma_f32_16x16x32_bf16 v[76:79], v[146:149], v[202:205], v[76:79]
	v_mfma_f32_16x16x32_bf16 v[72:75], v[170:173], v[202:205], v[72:75]
	v_mfma_f32_16x16x32_bf16 v[124:127], v[160:163], v[182:185], v[124:127]
	v_mfma_f32_16x16x32_bf16 v[120:123], v[174:177], v[182:185], v[120:123]
	v_mfma_f32_16x16x32_bf16 v[108:111], v[160:163], v[190:193], v[108:111]
	v_mfma_f32_16x16x32_bf16 v[104:107], v[174:177], v[190:193], v[104:107]
	v_mfma_f32_16x16x32_bf16 v[92:95], v[160:163], v[198:201], v[92:95]
	v_mfma_f32_16x16x32_bf16 v[88:91], v[174:177], v[198:201], v[88:91]
	v_mfma_f32_16x16x32_bf16 v[76:79], v[160:163], v[206:209], v[76:79]
	v_mfma_f32_16x16x32_bf16 v[72:75], v[174:177], v[206:209], v[72:75]
	s_setprio 0
	s_barrier
	s_add_i32 s36, 0, 0x1c000
	s_add_i32 s37, s45, s51
	v_add_u32_e32 v159, s36, v153
	v_lshl_add_u64 v[150:151], v[150:151], 0, s[18:19]
	s_mov_b32 m0, s37
	ds_read_b128 v[210:213], v159
	ds_read_b128 v[214:217], v159 offset:1024
	ds_read_b128 v[218:221], v159 offset:2048
	ds_read_b128 v[222:225], v159 offset:3072
	global_load_lds_dwordx4 v[150:151], off
	v_lshl_add_u64 v[150:151], v[164:165], 0, s[18:19]
	s_add_i32 m0, s37, 0x2000
	s_nop 0
	global_load_lds_dwordx4 v[150:151], off
	s_barrier
	s_waitcnt lgkmcnt(0)
	s_setprio 1
	s_waitcnt lgkmcnt(0)
	v_mfma_f32_16x16x32_bf16 v[116:119], v[210:213], v[178:181], v[116:119]
	v_mfma_f32_16x16x32_bf16 v[112:115], v[218:221], v[178:181], v[112:115]
	v_mfma_f32_16x16x32_bf16 v[100:103], v[210:213], v[186:189], v[100:103]
	v_mfma_f32_16x16x32_bf16 v[96:99], v[218:221], v[186:189], v[96:99]
	v_mfma_f32_16x16x32_bf16 v[84:87], v[210:213], v[194:197], v[84:87]
	v_mfma_f32_16x16x32_bf16 v[80:83], v[218:221], v[194:197], v[80:83]
	v_mfma_f32_16x16x32_bf16 v[68:71], v[210:213], v[202:205], v[68:71]
	v_mfma_f32_16x16x32_bf16 v[64:67], v[218:221], v[202:205], v[64:67]
	v_mfma_f32_16x16x32_bf16 v[116:119], v[214:217], v[182:185], v[116:119]
	v_mfma_f32_16x16x32_bf16 v[112:115], v[222:225], v[182:185], v[112:115]
	v_mfma_f32_16x16x32_bf16 v[100:103], v[214:217], v[190:193], v[100:103]
	v_mfma_f32_16x16x32_bf16 v[96:99], v[222:225], v[190:193], v[96:99]
	v_mfma_f32_16x16x32_bf16 v[84:87], v[214:217], v[198:201], v[84:87]
	v_mfma_f32_16x16x32_bf16 v[80:83], v[222:225], v[198:201], v[80:83]
	v_mfma_f32_16x16x32_bf16 v[68:71], v[214:217], v[206:209], v[68:71]
	v_mfma_f32_16x16x32_bf16 v[64:67], v[222:225], v[206:209], v[64:67]
	s_setprio 0
	s_mov_b32 m0, s56
	v_lshl_add_u64 v[150:151], v[226:227], 0, s[18:19]
	s_barrier
	ds_read_b128 v[178:181], v156 offset:49152
	ds_read_b128 v[182:185], v156 offset:50176
	ds_read_b128 v[186:189], v156 offset:51200
	ds_read_b128 v[190:193], v156 offset:52224
	ds_read_b128 v[194:197], v156 offset:53248
	ds_read_b128 v[198:201], v156 offset:54272
	ds_read_b128 v[202:205], v156 offset:55296
	ds_read_b128 v[206:209], v156 offset:56320
	global_load_lds_dwordx4 v[150:151], off
	v_lshl_add_u64 v[150:151], v[228:229], 0, s[18:19]
	s_mov_b32 m0, s57
	s_nop 0
	global_load_lds_dwordx4 v[150:151], off
	s_barrier
; __device__ __forceinline__ float bflo(unsigned w) { return __uint_as_float(w << 16); }
; __device__ __forceinline__ float bfhi(unsigned w) { return __uint_as_float(w & 0xffff0000u); }
; __device__ __forceinline__ unsigned pk2(float lo, float hi) { unsigned r; asm volatile("v_cvt_pk_bf16_f32 %0, %1, %2" : "=v"(r) : "v"(lo), "v"(hi)); return r; }
; #define PG8_WAIT_V(n) asm volatile("s_waitcnt vmcnt(" #n ")" ::: "memory")
;     ...
;             PG8_BAR; PG8_WAIT_L(0); PG8_MMA(1, 0, At, B0); PG8_BAR; PG8_SCHED;
;             PG8_STAGE(PG8_SB(1, 1), b3 + hB, voffB);
;             PG8_WAIT_V(6); PG8_BAR; PG8_MMA(1, 1, At, B1); PG8_BAR;
;         }
; __device__ __forceinline__ float row_rstd(const float* ssq, int row) {
;     const f32x4* p = (const f32x4*)(ssq + (size_t)row * 16);
;     const f32x4 a = p[0], b = p[1], c = p[2], d = p[3];
;     const float s = ((a[0] + a[1]) + (a[2] + a[3])) + ((b[0] + b[1]) + (b[2] + b[3])) + ((c[0] + c[1]) + (c[2] + c[3])) + ((d[0] + d[1]) + (d[2] + d[3]));
;     return rsqrtf(s * (1.0f / 1024.0f) + 1e-6f);
; }
; __device__ __forceinline__ u32x4 pack8(const f32x4 v0, const f32x4 v1) { u32x4 w; w.x = pk2(v0[0], v0[1]); w.y = pk2(v0[2], v0[3]); w.z = pk2(v1[0], v1[1]); w.w = pk2(v1[2], v1[3]); return w; }
; __device__ __forceinline__ void unpack8(const u32x4 w, f32x4& v0, f32x4& v1) { v0 = (f32x4){bflo(w.x), bfhi(w.x), bflo(w.y), bfhi(w.y)}; v1 = (f32x4){bflo(w.z), bfhi(w.z), bflo(w.w), bfhi(w.w)}; }
;     __device__ __forceinline__ void operator()(const f32x4 (&acc)[2][2][4][2], const Unit& u, int wr, int wc, int fr, int fq) const {
;         const int row0 = u.pm * 256 + wr * 64 + fr, col0 = u.pn * 256 + wc * 32 + 8 * fq;
; #pragma unroll
;         for (int ai = 0; ai < 2; ++ai)
; #pragma unroll
;             for (int m = 0; m < 4; ++m) {
;                 const int row = row0 + ai * 128 + m * 16; const float rs = row_rstd(ssq, row);
;                 bf16_t* rowp = O + (size_t)row * ldc + col0;
; #pragma unroll
;                 for (int bj = 0; bj < 2; ++bj) { f32x4 v0 = acc[ai][bj][m][0] * rs, v1 = acc[ai][bj][m][1] * rs;
;                     if (ACT == 1) {
; #pragma unroll
;                         for (int j = 0; j < 4; ++j) { const float a = fmaxf(v0[j], 0.f), b = fmaxf(v1[j], 0.f); v0[j] = a * a; v1[j] = b * b; } }
;                     *(u32x4*)(rowp + bj * 128) = pack8(v0, v1); }
	s_waitcnt lgkmcnt(0)
	s_setprio 1
	s_waitcnt lgkmcnt(0)
	v_mfma_f32_16x16x32_bf16 v[60:63], v[146:149], v[178:181], v[60:63]
	v_mfma_f32_16x16x32_bf16 v[56:59], v[170:173], v[178:181], v[56:59]
	v_mfma_f32_16x16x32_bf16 v[44:47], v[146:149], v[186:189], v[44:47]
	v_mfma_f32_16x16x32_bf16 v[40:43], v[170:173], v[186:189], v[40:43]
	v_mfma_f32_16x16x32_bf16 v[28:31], v[146:149], v[194:197], v[28:31]
	v_mfma_f32_16x16x32_bf16 v[24:27], v[170:173], v[194:197], v[24:27]
	v_mfma_f32_16x16x32_bf16 v[12:15], v[146:149], v[202:205], v[12:15]
	v_mfma_f32_16x16x32_bf16 v[8:11], v[170:173], v[202:205], v[8:11]
	v_mfma_f32_16x16x32_bf16 v[60:63], v[160:163], v[182:185], v[60:63]
	v_mfma_f32_16x16x32_bf16 v[56:59], v[174:177], v[182:185], v[56:59]
	v_mfma_f32_16x16x32_bf16 v[44:47], v[160:163], v[190:193], v[44:47]
	v_mfma_f32_16x16x32_bf16 v[40:43], v[174:177], v[190:193], v[40:43]
	v_mfma_f32_16x16x32_bf16 v[28:31], v[160:163], v[198:201], v[28:31]
	v_mfma_f32_16x16x32_bf16 v[24:27], v[174:177], v[198:201], v[24:27]
	v_mfma_f32_16x16x32_bf16 v[12:15], v[160:163], v[206:209], v[12:15]
	v_mfma_f32_16x16x32_bf16 v[8:11], v[174:177], v[206:209], v[8:11]
	s_setprio 0
	s_barrier
	s_add_u32 s34, s34, 0x40080
	s_addc_u32 s35, s35, 0
	s_add_i32 s36, s36, s51
	v_lshl_add_u64 v[146:147], s[34:35], 0, v[130:131]
	s_mov_b32 m0, s36
	s_nop 0
	global_load_lds_dwordx4 v[146:147], off
	v_lshl_add_u64 v[146:147], s[34:35], 0, v[134:135]
	s_add_i32 m0, s36, 0x2000
	s_nop 0
	global_load_lds_dwordx4 v[146:147], off
	s_waitcnt vmcnt(6)
	s_barrier
	s_setprio 1
	v_mfma_f32_16x16x32_bf16 v[52:55], v[210:213], v[178:181], v[52:55]
	v_mfma_f32_16x16x32_bf16 v[48:51], v[218:221], v[178:181], v[48:51]
	v_mfma_f32_16x16x32_bf16 v[36:39], v[210:213], v[186:189], v[36:39]
	v_mfma_f32_16x16x32_bf16 v[32:35], v[218:221], v[186:189], v[32:35]
	v_mfma_f32_16x16x32_bf16 v[20:23], v[210:213], v[194:197], v[20:23]
	v_mfma_f32_16x16x32_bf16 v[16:19], v[218:221], v[194:197], v[16:19]
	v_mfma_f32_16x16x32_bf16 v[4:7], v[210:213], v[202:205], v[4:7]
	v_mfma_f32_16x16x32_bf16 v[0:3], v[218:221], v[202:205], v[0:3]
	v_mfma_f32_16x16x32_bf16 v[52:55], v[214:217], v[182:185], v[52:55]
	v_mfma_f32_16x16x32_bf16 v[48:51], v[222:225], v[182:185], v[48:51]
	v_mfma_f32_16x16x32_bf16 v[36:39], v[214:217], v[190:193], v[36:39]
	v_mfma_f32_16x16x32_bf16 v[32:35], v[222:225], v[190:193], v[32:35]
	v_mfma_f32_16x16x32_bf16 v[20:23], v[214:217], v[198:201], v[20:23]
	v_mfma_f32_16x16x32_bf16 v[16:19], v[222:225], v[198:201], v[16:19]
	v_mfma_f32_16x16x32_bf16 v[4:7], v[214:217], v[206:209], v[4:7]
	v_mfma_f32_16x16x32_bf16 v[0:3], v[222:225], v[206:209], v[0:3]
	s_setprio 0
	s_add_i32 s44, s44, 2
	s_add_u32 s42, s42, 0x100
	s_addc_u32 s43, s43, 0
	s_add_u32 s30, s30, 0x100
	s_addc_u32 s31, s31, 0
	s_cmp_gt_u32 s44, 13
	s_barrier
	s_cbranch_scc0 .LBB0_125
	v_lshl_add_u32 v150, s28, 8, v152
	v_ashrrev_i32_e32 v151, 31, v150
	v_lshlrev_b64 v[146:147], 6, v[150:151]
	v_lshl_add_u64 v[146:147], s[16:17], 0, v[146:147]
	v_subrev_u32_e32 v186, s16, v146
	v_add_u32_e32 v187, 0x0, v186
	global_load_dwordx4 v[188:191], v187, s[16:17]
	v_add_u32_e32 v187, 0x20, v186
	global_load_dwordx4 v[192:195], v187, s[16:17]
	v_add_u32_e32 v187, 0x10, v186
	global_load_dwordx4 v[196:199], v187, s[16:17]
	v_add_u32_e32 v187, 0x30, v186
	global_load_dwordx4 v[200:203], v187, s[16:17]
	v_add_u32_e32 v187, 0x400, v186
	global_load_dwordx4 v[204:207], v187, s[16:17]
	v_add_u32_e32 v187, 0x410, v186
	global_load_dwordx4 v[208:211], v187, s[16:17]
	v_add_u32_e32 v187, 0x420, v186
	global_load_dwordx4 v[212:215], v187, s[16:17]
	v_add_u32_e32 v187, 0x430, v186
	global_load_dwordx4 v[216:219], v187, s[16:17]
	v_add_u32_e32 v187, 0x800, v186
	global_load_dwordx4 v[220:223], v187, s[16:17]
	v_add_u32_e32 v187, 0x810, v186
	global_load_dwordx4 v[232:235], v187, s[16:17]
	v_add_u32_e32 v187, 0x820, v186
	global_load_dwordx4 v[236:239], v187, s[16:17]
	v_add_u32_e32 v187, 0x830, v186
	global_load_dwordx4 v[240:243], v187, s[16:17]
	v_lshl_or_b32 v148, s6, 8, v154
	v_mov_b64_e32 v[146:147], s[14:15]
	v_ashrrev_i32_e32 v149, 31, v148
	v_mad_i64_i32 v[164:165], s[6:7], v150, s62, v[146:147]
	v_or_b32_e32 v182, 16, v150
	v_lshlrev_b64 v[148:149], 1, v[148:149]
	v_ashrrev_i32_e32 v183, 31, v182
	s_mov_b64 s[34:35], s[24:25]
	s_mov_b32 s28, s22
	s_mov_b64 s[30:31], s[26:27]
	s_waitcnt vmcnt(8)
	s_nop 0
	v_lshlrev_b64 v[162:163], 6, v[182:183]
	v_pk_add_f32 v[160:161], v[188:189], v[190:191]
	v_pk_add_f32 v[170:171], v[192:193], v[194:195]
	v_pk_add_f32 v[172:173], v[196:197], v[198:199]
	v_pk_add_f32 v[174:175], v[200:201], v[202:203]
	v_pk_add_f32 v[160:161], v[160:161], v[170:171]
	v_pk_add_f32 v[172:173], v[172:173], v[174:175]
	v_pk_add_f32 v[160:161], v[160:161], v[172:173]
	v_add_f32_e32 v151, v160, v161
	v_fmamk_f32 v151, v151, 0x3a800000, v158
	v_mul_f32_e32 v159, 0x4b800000, v151
	v_cmp_gt_f32_e32 vcc, s61, v151
	v_lshl_add_u64 v[160:161], v[164:165], 0, v[148:149]
	v_lshl_add_u64 v[162:163], s[16:17], 0, v[162:163]
	v_cndmask_b32_e32 v151, v151, v159, vcc
	v_rsq_f32_e32 v151, v151
	s_nop 0
	v_mul_f32_e32 v159, 0x45800000, v151
	v_cndmask_b32_e32 v164, v151, v159, vcc
	v_pk_mul_f32 v[126:127], v[126:127], v[164:165] op_sel_hi:[1,0]
	v_pk_mul_f32 v[124:125], v[124:125], v[164:165] op_sel_hi:[1,0]
	v_pk_mul_f32 v[122:123], v[122:123], v[164:165] op_sel_hi:[1,0]
	v_pk_mul_f32 v[120:121], v[120:121], v[164:165] op_sel_hi:[1,0]
	v_pk_mul_f32 v[118:119], v[118:119], v[164:165] op_sel_hi:[1,0]
	v_pk_mul_f32 v[116:117], v[116:117], v[164:165] op_sel_hi:[1,0]
	v_pk_mul_f32 v[170:171], v[114:115], v[164:165] op_sel_hi:[1,0]
	v_pk_mul_f32 v[164:165], v[112:113], v[164:165] op_sel_hi:[1,0]
	v_cvt_pk_bf16_f32 v112, v124, v125
	v_cvt_pk_bf16_f32 v113, v126, v127
	v_cvt_pk_bf16_f32 v114, v120, v121
	v_cvt_pk_bf16_f32 v115, v122, v123
	global_store_dwordx4 v[160:161], v[112:115], off sc1
	s_nop 1
	v_cvt_pk_bf16_f32 v112, v116, v117
	v_cvt_pk_bf16_f32 v113, v118, v119
	v_cvt_pk_bf16_f32 v114, v164, v165
	v_cvt_pk_bf16_f32 v115, v170, v171
	global_store_dwordx4 v[160:161], v[112:115], off offset:256 sc1
	s_nop 0
	v_or_b32_e32 v160, 32, v150
	v_mad_i64_i32 v[162:163], s[6:7], v182, s62, v[146:147]
	v_ashrrev_i32_e32 v161, 31, v160
	v_add_u32_e32 v187, 0xc00, v186
	global_load_dwordx4 v[188:191], v187, s[16:17]
	v_add_u32_e32 v187, 0xc10, v186
	global_load_dwordx4 v[192:195], v187, s[16:17]
	v_add_u32_e32 v187, 0xc20, v186
	global_load_dwordx4 v[196:199], v187, s[16:17]
	v_add_u32_e32 v187, 0xc30, v186
	global_load_dwordx4 v[200:203], v187, s[16:17]
	s_waitcnt vmcnt(10)
; __device__ __forceinline__ u32x4 pack8(const f32x4 v0, const f32x4 v1) { u32x4 w; w.x = pk2(v0[0], v0[1]); w.y = pk2(v0[2], v0[3]); w.z = pk2(v1[0], v1[1]); w.w = pk2(v1[2], v1[3]); return w; }
; __device__ __forceinline__ float row_rstd(const float* ssq, int row) {
;     const f32x4* p = (const f32x4*)(ssq + (size_t)row * 16);
;     const f32x4 a = p[0], b = p[1], c = p[2], d = p[3];
;     const float s = ((a[0] + a[1]) + (a[2] + a[3])) + ((b[0] + b[1]) + (b[2] + b[3])) + ((c[0] + c[1]) + (c[2] + c[3])) + ((d[0] + d[1]) + (d[2] + d[3]));
;     return rsqrtf(s * (1.0f / 1024.0f) + 1e-6f);
; }
;     __device__ __forceinline__ void operator()(const f32x4 (&acc)[2][2][4][2], const Unit& u, int wr, int wc, int fr, int fq) const {
;         const int row0 = u.pm * 256 + wr * 64 + fr, col0 = u.pn * 256 + wc * 32 + 8 * fq;
; #pragma unroll
;         for (int ai = 0; ai < 2; ++ai)
; #pragma unroll
;             for (int m = 0; m < 4; ++m) {
;                 const int row = row0 + ai * 128 + m * 16; const float rs = row_rstd(ssq, row);
;                 bf16_t* rowp = O + (size_t)row * ldc + col0;
; #pragma unroll
;                 for (int bj = 0; bj < 2; ++bj) { f32x4 v0 = acc[ai][bj][m][0] * rs, v1 = acc[ai][bj][m][1] * rs;
;                     if (ACT == 1) {
; #pragma unroll
;                         for (int j = 0; j < 4; ++j) { const float a = fmaxf(v0[j], 0.f), b = fmaxf(v1[j], 0.f); v0[j] = a * a; v1[j] = b * b; } }
;                     *(u32x4*)(rowp + bj * 128) = pack8(v0, v1); }
	v_lshlrev_b64 v[114:115], 6, v[160:161]
	v_lshl_add_u64 v[114:115], s[16:17], 0, v[114:115]
	v_pk_add_f32 v[112:113], v[204:205], v[206:207]
	v_pk_add_f32 v[116:117], v[208:209], v[210:211]
	v_pk_add_f32 v[118:119], v[212:213], v[214:215]
	v_pk_add_f32 v[120:121], v[216:217], v[218:219]
	v_pk_add_f32 v[112:113], v[112:113], v[116:117]
	v_pk_add_f32 v[118:119], v[118:119], v[120:121]
	v_pk_add_f32 v[112:113], v[112:113], v[118:119]
	v_add_f32_e32 v112, v112, v113
	v_fmamk_f32 v112, v112, 0x3a800000, v158
	v_mul_f32_e32 v113, 0x4b800000, v112
	v_cmp_gt_f32_e32 vcc, s61, v112
	s_nop 1
	v_cndmask_b32_e32 v112, v112, v113, vcc
	v_rsq_f32_e32 v116, v112
	v_lshl_add_u64 v[112:113], v[162:163], 0, v[148:149]
	v_mul_f32_e32 v117, 0x45800000, v116
	v_cndmask_b32_e32 v116, v116, v117, vcc
	v_pk_mul_f32 v[110:111], v[110:111], v[116:117] op_sel_hi:[1,0]
	v_pk_mul_f32 v[108:109], v[108:109], v[116:117] op_sel_hi:[1,0]
	v_pk_mul_f32 v[106:107], v[106:107], v[116:117] op_sel_hi:[1,0]
	v_pk_mul_f32 v[104:105], v[104:105], v[116:117] op_sel_hi:[1,0]
	v_pk_mul_f32 v[102:103], v[102:103], v[116:117] op_sel_hi:[1,0]
	v_pk_mul_f32 v[100:101], v[100:101], v[116:117] op_sel_hi:[1,0]
	v_pk_mul_f32 v[118:119], v[98:99], v[116:117] op_sel_hi:[1,0]
	v_pk_mul_f32 v[116:117], v[96:97], v[116:117] op_sel_hi:[1,0]
	v_cvt_pk_bf16_f32 v96, v108, v109
	v_cvt_pk_bf16_f32 v97, v110, v111
	v_cvt_pk_bf16_f32 v98, v104, v105
	v_cvt_pk_bf16_f32 v99, v106, v107
	global_store_dwordx4 v[112:113], v[96:99], off sc1
	s_nop 1
	v_cvt_pk_bf16_f32 v96, v100, v101
	v_cvt_pk_bf16_f32 v97, v102, v103
	v_cvt_pk_bf16_f32 v98, v116, v117
	v_cvt_pk_bf16_f32 v99, v118, v119
	global_store_dwordx4 v[112:113], v[96:99], off offset:256 sc1
	s_nop 0
	v_or_b32_e32 v112, 48, v150
	v_mad_i64_i32 v[114:115], s[6:7], v160, s62, v[146:147]
	v_ashrrev_i32_e32 v113, 31, v112
	v_add_u32_e32 v187, 0x2000, v186
	global_load_dwordx4 v[204:207], v187, s[16:17]
	v_add_u32_e32 v187, 0x2010, v186
	global_load_dwordx4 v[208:211], v187, s[16:17]
	v_add_u32_e32 v187, 0x2020, v186
	global_load_dwordx4 v[212:215], v187, s[16:17]
	v_add_u32_e32 v187, 0x2030, v186
	global_load_dwordx4 v[216:219], v187, s[16:17]
	s_waitcnt vmcnt(12)
	v_lshlrev_b64 v[98:99], 6, v[112:113]
	v_lshl_add_u64 v[98:99], s[16:17], 0, v[98:99]
	v_pk_add_f32 v[96:97], v[220:221], v[222:223]
	v_pk_add_f32 v[100:101], v[232:233], v[234:235]
	v_pk_add_f32 v[102:103], v[236:237], v[238:239]
	v_pk_add_f32 v[104:105], v[240:241], v[242:243]
	v_pk_add_f32 v[96:97], v[96:97], v[100:101]
	v_pk_add_f32 v[102:103], v[102:103], v[104:105]
	v_pk_add_f32 v[96:97], v[96:97], v[102:103]
	v_add_f32_e32 v96, v96, v97
	v_fmamk_f32 v96, v96, 0x3a800000, v158
	v_mul_f32_e32 v97, 0x4b800000, v96
	v_cmp_gt_f32_e32 vcc, s61, v96
	s_nop 1
	v_cndmask_b32_e32 v96, v96, v97, vcc
	v_rsq_f32_e32 v100, v96
	v_lshl_add_u64 v[96:97], v[114:115], 0, v[148:149]
	v_mul_f32_e32 v101, 0x45800000, v100
	v_cndmask_b32_e32 v100, v100, v101, vcc
	v_pk_mul_f32 v[94:95], v[94:95], v[100:101] op_sel_hi:[1,0]
	v_pk_mul_f32 v[92:93], v[92:93], v[100:101] op_sel_hi:[1,0]
	v_pk_mul_f32 v[90:91], v[90:91], v[100:101] op_sel_hi:[1,0]
	v_pk_mul_f32 v[88:89], v[88:89], v[100:101] op_sel_hi:[1,0]
	v_pk_mul_f32 v[86:87], v[86:87], v[100:101] op_sel_hi:[1,0]
	v_pk_mul_f32 v[84:85], v[84:85], v[100:101] op_sel_hi:[1,0]
	v_pk_mul_f32 v[102:103], v[82:83], v[100:101] op_sel_hi:[1,0]
	v_pk_mul_f32 v[100:101], v[80:81], v[100:101] op_sel_hi:[1,0]
	v_cvt_pk_bf16_f32 v80, v92, v93
	v_cvt_pk_bf16_f32 v81, v94, v95
	v_cvt_pk_bf16_f32 v82, v88, v89
	v_cvt_pk_bf16_f32 v83, v90, v91
	global_store_dwordx4 v[96:97], v[80:83], off sc1
	s_nop 1
	v_cvt_pk_bf16_f32 v80, v84, v85
	v_cvt_pk_bf16_f32 v81, v86, v87
	v_cvt_pk_bf16_f32 v82, v100, v101
	v_cvt_pk_bf16_f32 v83, v102, v103
	global_store_dwordx4 v[96:97], v[80:83], off offset:256 sc1
	s_nop 0
	v_add_u32_e32 v96, 0x80, v150
	v_mad_i64_i32 v[98:99], s[6:7], v112, s62, v[146:147]
	v_ashrrev_i32_e32 v97, 31, v96
	v_add_u32_e32 v187, 0x2400, v186
	global_load_dwordx4 v[220:223], v187, s[16:17]
	v_add_u32_e32 v187, 0x2410, v186
	global_load_dwordx4 v[232:235], v187, s[16:17]
	v_add_u32_e32 v187, 0x2420, v186
	global_load_dwordx4 v[236:239], v187, s[16:17]
	v_add_u32_e32 v187, 0x2430, v186
	global_load_dwordx4 v[240:243], v187, s[16:17]
	s_waitcnt vmcnt(12)
	v_lshlrev_b64 v[82:83], 6, v[96:97]
	v_lshl_add_u64 v[82:83], s[16:17], 0, v[82:83]
	v_pk_add_f32 v[80:81], v[188:189], v[190:191]
	v_pk_add_f32 v[84:85], v[192:193], v[194:195]
	v_pk_add_f32 v[86:87], v[196:197], v[198:199]
	v_pk_add_f32 v[88:89], v[200:201], v[202:203]
	v_pk_add_f32 v[80:81], v[80:81], v[84:85]
	v_pk_add_f32 v[86:87], v[86:87], v[88:89]
	v_pk_add_f32 v[80:81], v[80:81], v[86:87]
	v_add_f32_e32 v80, v80, v81
	v_fmamk_f32 v80, v80, 0x3a800000, v158
	v_mul_f32_e32 v81, 0x4b800000, v80
	v_cmp_gt_f32_e32 vcc, s61, v80
	s_nop 1
	v_cndmask_b32_e32 v80, v80, v81, vcc
	v_rsq_f32_e32 v84, v80
	v_lshl_add_u64 v[80:81], v[98:99], 0, v[148:149]
	v_mul_f32_e32 v85, 0x45800000, v84
	v_cndmask_b32_e32 v84, v84, v85, vcc
	v_pk_mul_f32 v[78:79], v[78:79], v[84:85] op_sel_hi:[1,0]
	v_pk_mul_f32 v[76:77], v[76:77], v[84:85] op_sel_hi:[1,0]
	v_pk_mul_f32 v[74:75], v[74:75], v[84:85] op_sel_hi:[1,0]
	v_pk_mul_f32 v[72:73], v[72:73], v[84:85] op_sel_hi:[1,0]
	v_pk_mul_f32 v[70:71], v[70:71], v[84:85] op_sel_hi:[1,0]
	v_pk_mul_f32 v[68:69], v[68:69], v[84:85] op_sel_hi:[1,0]
	v_pk_mul_f32 v[86:87], v[66:67], v[84:85] op_sel_hi:[1,0]
	v_pk_mul_f32 v[84:85], v[64:65], v[84:85] op_sel_hi:[1,0]
	v_cvt_pk_bf16_f32 v64, v76, v77
	v_cvt_pk_bf16_f32 v65, v78, v79
	v_cvt_pk_bf16_f32 v66, v72, v73
	v_cvt_pk_bf16_f32 v67, v74, v75
	global_store_dwordx4 v[80:81], v[64:67], off sc1
	s_nop 1
	v_cvt_pk_bf16_f32 v64, v68, v69
	v_cvt_pk_bf16_f32 v65, v70, v71
	v_cvt_pk_bf16_f32 v66, v84, v85
	v_cvt_pk_bf16_f32 v67, v86, v87
	global_store_dwordx4 v[80:81], v[64:67], off offset:256 sc1
	s_nop 0
	v_add_u32_e32 v80, 0x90, v150
	v_mad_i64_i32 v[82:83], s[6:7], v96, s62, v[146:147]
	v_ashrrev_i32_e32 v81, 31, v80
	v_add_u32_e32 v187, 0x2800, v186
	global_load_dwordx4 v[188:191], v187, s[16:17]
	v_add_u32_e32 v187, 0x2810, v186
	global_load_dwordx4 v[192:195], v187, s[16:17]
	v_add_u32_e32 v187, 0x2820, v186
	global_load_dwordx4 v[196:199], v187, s[16:17]
	v_add_u32_e32 v187, 0x2830, v186
	global_load_dwordx4 v[200:203], v187, s[16:17]
	s_waitcnt vmcnt(12)
; __device__ __forceinline__ u32x4 pack8(const f32x4 v0, const f32x4 v1) { u32x4 w; w.x = pk2(v0[0], v0[1]); w.y = pk2(v0[2], v0[3]); w.z = pk2(v1[0], v1[1]); w.w = pk2(v1[2], v1[3]); return w; }
; __device__ __forceinline__ float row_rstd(const float* ssq, int row) {
;     const f32x4* p = (const f32x4*)(ssq + (size_t)row * 16);
;     const f32x4 a = p[0], b = p[1], c = p[2], d = p[3];
;     const float s = ((a[0] + a[1]) + (a[2] + a[3])) + ((b[0] + b[1]) + (b[2] + b[3])) + ((c[0] + c[1]) + (c[2] + c[3])) + ((d[0] + d[1]) + (d[2] + d[3]));
;     return rsqrtf(s * (1.0f / 1024.0f) + 1e-6f);
; }
;     __device__ __forceinline__ void operator()(const f32x4 (&acc)[2][2][4][2], const Unit& u, int wr, int wc, int fr, int fq) const {
;         const int row0 = u.pm * 256 + wr * 64 + fr, col0 = u.pn * 256 + wc * 32 + 8 * fq;
; #pragma unroll
;         for (int ai = 0; ai < 2; ++ai)
; #pragma unroll
;             for (int m = 0; m < 4; ++m) {
;                 const int row = row0 + ai * 128 + m * 16; const float rs = row_rstd(ssq, row);
;                 bf16_t* rowp = O + (size_t)row * ldc + col0;
; #pragma unroll
;                 for (int bj = 0; bj < 2; ++bj) { f32x4 v0 = acc[ai][bj][m][0] * rs, v1 = acc[ai][bj][m][1] * rs;
;                     if (ACT == 1) {
; #pragma unroll
;                         for (int j = 0; j < 4; ++j) { const float a = fmaxf(v0[j], 0.f), b = fmaxf(v1[j], 0.f); v0[j] = a * a; v1[j] = b * b; } }
;                     *(u32x4*)(rowp + bj * 128) = pack8(v0, v1); }
	v_lshlrev_b64 v[66:67], 6, v[80:81]
	v_lshl_add_u64 v[66:67], s[16:17], 0, v[66:67]
	v_pk_add_f32 v[64:65], v[204:205], v[206:207]
	v_pk_add_f32 v[68:69], v[208:209], v[210:211]
	v_pk_add_f32 v[70:71], v[212:213], v[214:215]
	v_pk_add_f32 v[72:73], v[216:217], v[218:219]
	v_pk_add_f32 v[64:65], v[64:65], v[68:69]
	v_pk_add_f32 v[70:71], v[70:71], v[72:73]
	v_pk_add_f32 v[64:65], v[64:65], v[70:71]
	v_add_f32_e32 v64, v64, v65
	v_fmamk_f32 v64, v64, 0x3a800000, v158
	v_mul_f32_e32 v65, 0x4b800000, v64
	v_cmp_gt_f32_e32 vcc, s61, v64
	s_nop 1
	v_cndmask_b32_e32 v64, v64, v65, vcc
	v_rsq_f32_e32 v68, v64
	v_lshl_add_u64 v[64:65], v[82:83], 0, v[148:149]
	v_mul_f32_e32 v69, 0x45800000, v68
	v_cndmask_b32_e32 v68, v68, v69, vcc
	v_pk_mul_f32 v[62:63], v[62:63], v[68:69] op_sel_hi:[1,0]
	v_pk_mul_f32 v[60:61], v[60:61], v[68:69] op_sel_hi:[1,0]
	v_pk_mul_f32 v[58:59], v[58:59], v[68:69] op_sel_hi:[1,0]
	v_pk_mul_f32 v[56:57], v[56:57], v[68:69] op_sel_hi:[1,0]
	v_pk_mul_f32 v[54:55], v[54:55], v[68:69] op_sel_hi:[1,0]
	v_pk_mul_f32 v[52:53], v[52:53], v[68:69] op_sel_hi:[1,0]
	v_pk_mul_f32 v[70:71], v[50:51], v[68:69] op_sel_hi:[1,0]
	v_pk_mul_f32 v[68:69], v[48:49], v[68:69] op_sel_hi:[1,0]
	v_cvt_pk_bf16_f32 v48, v60, v61
	v_cvt_pk_bf16_f32 v49, v62, v63
	v_cvt_pk_bf16_f32 v50, v56, v57
	v_cvt_pk_bf16_f32 v51, v58, v59
	global_store_dwordx4 v[64:65], v[48:51], off sc1
	s_nop 1
	v_cvt_pk_bf16_f32 v48, v52, v53
	v_cvt_pk_bf16_f32 v49, v54, v55
	v_cvt_pk_bf16_f32 v50, v68, v69
	v_cvt_pk_bf16_f32 v51, v70, v71
	global_store_dwordx4 v[64:65], v[48:51], off offset:256 sc1
	s_nop 0
	v_add_u32_e32 v64, 0xa0, v150
	v_mad_i64_i32 v[66:67], s[6:7], v80, s62, v[146:147]
	v_ashrrev_i32_e32 v65, 31, v64
	v_add_u32_e32 v187, 0x2c00, v186
	global_load_dwordx4 v[204:207], v187, s[16:17]
	v_add_u32_e32 v187, 0x2c10, v186
	global_load_dwordx4 v[208:211], v187, s[16:17]
	v_add_u32_e32 v187, 0x2c20, v186
	global_load_dwordx4 v[212:215], v187, s[16:17]
	v_add_u32_e32 v187, 0x2c30, v186
	global_load_dwordx4 v[216:219], v187, s[16:17]
	s_waitcnt vmcnt(12)
	v_lshlrev_b64 v[50:51], 6, v[64:65]
	v_lshl_add_u64 v[50:51], s[16:17], 0, v[50:51]
	v_pk_add_f32 v[48:49], v[220:221], v[222:223]
	v_pk_add_f32 v[52:53], v[232:233], v[234:235]
	v_pk_add_f32 v[54:55], v[236:237], v[238:239]
	v_pk_add_f32 v[56:57], v[240:241], v[242:243]
	v_pk_add_f32 v[48:49], v[48:49], v[52:53]
	v_pk_add_f32 v[54:55], v[54:55], v[56:57]
	v_pk_add_f32 v[48:49], v[48:49], v[54:55]
	v_add_f32_e32 v48, v48, v49
	v_fmamk_f32 v48, v48, 0x3a800000, v158
	v_mul_f32_e32 v49, 0x4b800000, v48
	v_cmp_gt_f32_e32 vcc, s61, v48
	s_nop 1
	v_cndmask_b32_e32 v48, v48, v49, vcc
	v_rsq_f32_e32 v52, v48
	v_lshl_add_u64 v[48:49], v[66:67], 0, v[148:149]
	v_mul_f32_e32 v53, 0x45800000, v52
	v_cndmask_b32_e32 v52, v52, v53, vcc
	v_pk_mul_f32 v[46:47], v[46:47], v[52:53] op_sel_hi:[1,0]
	v_pk_mul_f32 v[44:45], v[44:45], v[52:53] op_sel_hi:[1,0]
	v_pk_mul_f32 v[42:43], v[42:43], v[52:53] op_sel_hi:[1,0]
	v_pk_mul_f32 v[40:41], v[40:41], v[52:53] op_sel_hi:[1,0]
	v_pk_mul_f32 v[38:39], v[38:39], v[52:53] op_sel_hi:[1,0]
	v_pk_mul_f32 v[36:37], v[36:37], v[52:53] op_sel_hi:[1,0]
	v_pk_mul_f32 v[54:55], v[34:35], v[52:53] op_sel_hi:[1,0]
	v_pk_mul_f32 v[52:53], v[32:33], v[52:53] op_sel_hi:[1,0]
	v_cvt_pk_bf16_f32 v32, v44, v45
	v_cvt_pk_bf16_f32 v33, v46, v47
	v_cvt_pk_bf16_f32 v34, v40, v41
	v_cvt_pk_bf16_f32 v35, v42, v43
	global_store_dwordx4 v[48:49], v[32:35], off sc1
	s_nop 1
	v_cvt_pk_bf16_f32 v32, v36, v37
	v_cvt_pk_bf16_f32 v33, v38, v39
	v_cvt_pk_bf16_f32 v34, v52, v53
	v_cvt_pk_bf16_f32 v35, v54, v55
	global_store_dwordx4 v[48:49], v[32:35], off offset:256 sc1
	s_nop 0
	v_add_u32_e32 v48, 0xb0, v150
	v_mad_i64_i32 v[50:51], s[6:7], v64, s62, v[146:147]
	v_ashrrev_i32_e32 v49, 31, v48
	s_mov_b32 s6, s20
	s_waitcnt vmcnt(8)
	v_lshlrev_b64 v[34:35], 6, v[48:49]
	v_lshl_add_u64 v[34:35], s[16:17], 0, v[34:35]
	v_pk_add_f32 v[32:33], v[188:189], v[190:191]
	v_pk_add_f32 v[36:37], v[192:193], v[194:195]
	v_pk_add_f32 v[38:39], v[196:197], v[198:199]
	v_pk_add_f32 v[40:41], v[200:201], v[202:203]
	v_pk_add_f32 v[32:33], v[32:33], v[36:37]
	v_pk_add_f32 v[38:39], v[38:39], v[40:41]
	v_pk_add_f32 v[32:33], v[32:33], v[38:39]
	v_add_f32_e32 v32, v32, v33
	v_fmamk_f32 v32, v32, 0x3a800000, v158
	v_mul_f32_e32 v33, 0x4b800000, v32
	v_cmp_gt_f32_e32 vcc, s61, v32
	s_nop 1
	v_cndmask_b32_e32 v32, v32, v33, vcc
	v_rsq_f32_e32 v36, v32
	v_lshl_add_u64 v[32:33], v[50:51], 0, v[148:149]
	v_mul_f32_e32 v37, 0x45800000, v36
	v_cndmask_b32_e32 v36, v36, v37, vcc
	v_pk_mul_f32 v[30:31], v[30:31], v[36:37] op_sel_hi:[1,0]
	v_pk_mul_f32 v[28:29], v[28:29], v[36:37] op_sel_hi:[1,0]
	v_pk_mul_f32 v[26:27], v[26:27], v[36:37] op_sel_hi:[1,0]
	v_pk_mul_f32 v[24:25], v[24:25], v[36:37] op_sel_hi:[1,0]
	v_pk_mul_f32 v[22:23], v[22:23], v[36:37] op_sel_hi:[1,0]
	v_pk_mul_f32 v[20:21], v[20:21], v[36:37] op_sel_hi:[1,0]
	v_pk_mul_f32 v[38:39], v[18:19], v[36:37] op_sel_hi:[1,0]
	v_pk_mul_f32 v[36:37], v[16:17], v[36:37] op_sel_hi:[1,0]
	v_cvt_pk_bf16_f32 v16, v28, v29
	v_cvt_pk_bf16_f32 v17, v30, v31
	v_cvt_pk_bf16_f32 v18, v24, v25
	v_cvt_pk_bf16_f32 v19, v26, v27
	global_store_dwordx4 v[32:33], v[16:19], off sc1
	s_and_b64 vcc, exec, s[8:9]
	s_nop 0
	v_cvt_pk_bf16_f32 v16, v20, v21
	v_cvt_pk_bf16_f32 v17, v22, v23
	v_cvt_pk_bf16_f32 v18, v36, v37
	v_cvt_pk_bf16_f32 v19, v38, v39
	global_store_dwordx4 v[32:33], v[16:19], off offset:256 sc1
	s_nop 0
	s_waitcnt vmcnt(4)
	s_nop 0
	s_nop 0
	v_pk_add_f32 v[16:17], v[204:205], v[206:207]
	v_pk_add_f32 v[18:19], v[208:209], v[210:211]
	v_pk_add_f32 v[20:21], v[212:213], v[214:215]
	v_pk_add_f32 v[22:23], v[216:217], v[218:219]
	v_pk_add_f32 v[16:17], v[16:17], v[18:19]
	v_pk_add_f32 v[20:21], v[20:21], v[22:23]
	v_pk_add_f32 v[16:17], v[16:17], v[20:21]
	v_add_f32_e32 v16, v16, v17
	v_fmamk_f32 v16, v16, 0x3a800000, v158
	v_mul_f32_e32 v17, 0x4b800000, v16
	v_cmp_gt_f32_e64 s[8:9], s61, v16
	s_nop 1
	v_cndmask_b32_e64 v16, v16, v17, s[8:9]
	v_rsq_f32_e32 v18, v16
	v_mad_i64_i32 v[16:17], s[24:25], v48, s62, v[146:147]
	v_lshl_add_u64 v[16:17], v[16:17], 0, v[148:149]
	v_mul_f32_e32 v19, 0x45800000, v18
	v_cndmask_b32_e64 v18, v18, v19, s[8:9]
	v_pk_mul_f32 v[14:15], v[14:15], v[18:19] op_sel_hi:[1,0]
	v_pk_mul_f32 v[12:13], v[12:13], v[18:19] op_sel_hi:[1,0]
	v_pk_mul_f32 v[10:11], v[10:11], v[18:19] op_sel_hi:[1,0]
	v_pk_mul_f32 v[8:9], v[8:9], v[18:19] op_sel_hi:[1,0]
	v_pk_mul_f32 v[6:7], v[6:7], v[18:19] op_sel_hi:[1,0]
	v_pk_mul_f32 v[4:5], v[4:5], v[18:19] op_sel_hi:[1,0]
	v_pk_mul_f32 v[20:21], v[2:3], v[18:19] op_sel_hi:[1,0]
	v_pk_mul_f32 v[18:19], v[0:1], v[18:19] op_sel_hi:[1,0]
	v_cvt_pk_bf16_f32 v0, v12, v13
	v_cvt_pk_bf16_f32 v1, v14, v15
	v_cvt_pk_bf16_f32 v2, v8, v9
	v_cvt_pk_bf16_f32 v3, v10, v11
	global_store_dwordx4 v[16:17], v[0:3], off sc1
	s_nop 1
	v_cvt_pk_bf16_f32 v0, v4, v5
	v_cvt_pk_bf16_f32 v1, v6, v7
	v_cvt_pk_bf16_f32 v2, v18, v19
	v_cvt_pk_bf16_f32 v3, v20, v21
	global_store_dwordx4 v[16:17], v[0:3], off offset:256 sc1
	s_cbranch_vccz .LBB0_118
; #define PG8_WAIT_V(n) asm volatile("s_waitcnt vmcnt(" #n ")" ::: "memory")
; #define PG8_BAR __builtin_amdgcn_s_barrier()
;     ...
;     PG8_WAIT_V(0);
;     if (wr == 0) PG8_BAR;
;     PG8_BAR;
	s_waitcnt vmcnt(0)
	s_cmpk_gt_u32 s40, 0xff
	s_cbranch_scc1 .LBB0_129
	s_barrier

; #define PG8_STAGE(bufoff, gbase, voff) do { _Pragma("unroll") for (int _i = 0; _i < 2; ++_i) \
;         __builtin_amdgcn_global_load_lds((const unsigned*)((const char*)(gbase) + (voff)[_i]), (LAS unsigned*)(lds + (bufoff) + ldsw + _i * 8192), 16, 0, 0); } while (0)
; #define PG8_LDA(dst, b, h) do { _Pragma("unroll") for (int m = 0; m < 4; ++m) _Pragma("unroll") for (int k = 0; k < 2; ++k) dst[m][k] = *(const LAS bf16x8*)(lds + PG8_SA(b, h) + aoff + m * 2048 + k * 1024); } while (0)
; #define PG8_LDB(dst, b, h) do { _Pragma("unroll") for (int n = 0; n < 2; ++n) _Pragma("unroll") for (int k = 0; k < 2; ++k) dst[n][k] = *(const LAS bf16x8*)(lds + PG8_SB(b, h) + boff + n * 2048 + k * 1024); } while (0)
; #define PG8_MMA(ai, bj, At, Bt) do { __builtin_amdgcn_s_setprio(1); _Pragma("unroll") for (int m = 0; m < 4; ++m) _Pragma("unroll") for (int n = 0; n < 2; ++n) _Pragma("unroll") for (int k = 0; k < 2; ++k) \
;         acc[ai][bj][m][n] = __builtin_amdgcn_mfma_f32_16x16x32_bf16(Bt[n][k], At[m][k], acc[ai][bj][m][n], 0, 0, 0); __builtin_amdgcn_s_setprio(0); } while (0)
; #define PG8_WAIT_L(n) asm volatile("s_waitcnt lgkmcnt(" #n ")" ::: "memory")
; #define PG8_BAR __builtin_amdgcn_s_barrier()
; #define PG8_SCHED __builtin_amdgcn_sched_barrier(0)
;     ...
;             PG8_LDB(B0, 0, 0); PG8_SCHED; PG8_LDA(At, 0, 0); PG8_STAGE(PG8_SA(1, 1), a1 + hA, voffA);
;             PG8_WAIT_L(8); PG8_BAR; PG8_WAIT_L(0); PG8_MMA(0, 0, At, B0); PG8_BAR; PG8_SCHED;
;             PG8_LDB(B1, 0, 1); PG8_STAGE(PG8_SB(0, 0), b2, voffB);
;             PG8_BAR; PG8_WAIT_L(0); PG8_MMA(0, 1, At, B1); PG8_BAR;
;             PG8_LDA(At, 0, 1); PG8_STAGE(PG8_SA(0, 0), a2, voffA);
;             PG8_BAR; PG8_WAIT_L(0); PG8_MMA(1, 0, At, B0); PG8_BAR; PG8_SCHED;
.LBB0_958:
	ds_read_b128 v[156:159], v151
	ds_read_b128 v[160:163], v151 offset:1024
	ds_read_b128 v[170:173], v151 offset:2048
	ds_read_b128 v[174:177], v151 offset:3072
	s_add_u32 s43, s40, 0xfffc0080
	s_addc_u32 s44, s41, -1
	s_cmp_eq_u32 s42, 12
	s_cselect_b32 s57, s7, s44
	s_cselect_b32 s56, s8, s43
	s_cselect_b32 s55, s9, s39
	s_cselect_b32 s54, s29, s33
	v_lshl_add_u64 v[146:147], s[40:41], 0, v[138:139]
	s_add_i32 m0, s61, 0xc000
	ds_read_b128 v[178:181], v152
	ds_read_b128 v[182:185], v152 offset:1024
	ds_read_b128 v[186:189], v152 offset:2048
	ds_read_b128 v[190:193], v152 offset:3072
	ds_read_b128 v[194:197], v152 offset:4096
	ds_read_b128 v[198:201], v152 offset:5120
	ds_read_b128 v[202:205], v152 offset:6144
	ds_read_b128 v[206:209], v152 offset:7168
	global_load_lds_dwordx4 v[146:147], off
	v_lshl_add_u64 v[146:147], s[40:41], 0, v[136:137]
	s_add_i32 m0, s61, 0xe000
	s_nop 0
	global_load_lds_dwordx4 v[146:147], off
	s_waitcnt lgkmcnt(8)
	s_barrier
	s_waitcnt lgkmcnt(0)
	s_setprio 1
	s_waitcnt lgkmcnt(0)
	v_mfma_f32_16x16x32_bf16 v[124:127], v[156:159], v[178:181], v[124:127]
	v_mfma_f32_16x16x32_bf16 v[120:123], v[170:173], v[178:181], v[120:123]
	v_mfma_f32_16x16x32_bf16 v[108:111], v[156:159], v[186:189], v[108:111]
	v_mfma_f32_16x16x32_bf16 v[104:107], v[170:173], v[186:189], v[104:107]
	v_mfma_f32_16x16x32_bf16 v[92:95], v[156:159], v[194:197], v[92:95]
	v_mfma_f32_16x16x32_bf16 v[88:91], v[170:173], v[194:197], v[88:91]
	v_mfma_f32_16x16x32_bf16 v[76:79], v[156:159], v[202:205], v[76:79]
	v_mfma_f32_16x16x32_bf16 v[72:75], v[170:173], v[202:205], v[72:75]
	v_mfma_f32_16x16x32_bf16 v[124:127], v[160:163], v[182:185], v[124:127]
	v_mfma_f32_16x16x32_bf16 v[120:123], v[174:177], v[182:185], v[120:123]
	v_mfma_f32_16x16x32_bf16 v[108:111], v[160:163], v[190:193], v[108:111]
	v_mfma_f32_16x16x32_bf16 v[104:107], v[174:177], v[190:193], v[104:107]
	v_mfma_f32_16x16x32_bf16 v[92:95], v[160:163], v[198:201], v[92:95]
	v_mfma_f32_16x16x32_bf16 v[88:91], v[174:177], v[198:201], v[88:91]
	v_mfma_f32_16x16x32_bf16 v[76:79], v[160:163], v[206:209], v[76:79]
	v_mfma_f32_16x16x32_bf16 v[72:75], v[174:177], v[206:209], v[72:75]
	s_setprio 0
	s_barrier
	s_add_i32 s43, s69, s60
	v_lshl_add_u64 v[146:147], s[54:55], 0, v[130:131]
	s_mov_b32 m0, s43
	ds_read_b128 v[210:213], v153
	ds_read_b128 v[214:217], v153 offset:1024
	ds_read_b128 v[218:221], v153 offset:2048
	ds_read_b128 v[222:225], v153 offset:3072
	global_load_lds_dwordx4 v[146:147], off
	v_lshl_add_u64 v[164:165], s[54:55], 0, v[134:135]
	s_add_i32 m0, s43, 0x2000
	s_nop 0
	global_load_lds_dwordx4 v[164:165], off
	s_barrier
	s_waitcnt lgkmcnt(0)
	s_setprio 1
	s_waitcnt lgkmcnt(0)
	v_mfma_f32_16x16x32_bf16 v[116:119], v[210:213], v[178:181], v[116:119]
	v_mfma_f32_16x16x32_bf16 v[112:115], v[218:221], v[178:181], v[112:115]
	v_mfma_f32_16x16x32_bf16 v[100:103], v[210:213], v[186:189], v[100:103]
	v_mfma_f32_16x16x32_bf16 v[96:99], v[218:221], v[186:189], v[96:99]
	v_mfma_f32_16x16x32_bf16 v[84:87], v[210:213], v[194:197], v[84:87]
	v_mfma_f32_16x16x32_bf16 v[80:83], v[218:221], v[194:197], v[80:83]
	v_mfma_f32_16x16x32_bf16 v[68:71], v[210:213], v[202:205], v[68:71]
	v_mfma_f32_16x16x32_bf16 v[64:67], v[218:221], v[202:205], v[64:67]
	v_mfma_f32_16x16x32_bf16 v[116:119], v[214:217], v[182:185], v[116:119]
	v_mfma_f32_16x16x32_bf16 v[112:115], v[222:225], v[182:185], v[112:115]
	v_mfma_f32_16x16x32_bf16 v[100:103], v[214:217], v[190:193], v[100:103]
	v_mfma_f32_16x16x32_bf16 v[96:99], v[222:225], v[190:193], v[96:99]
	v_mfma_f32_16x16x32_bf16 v[84:87], v[214:217], v[198:201], v[84:87]
	v_mfma_f32_16x16x32_bf16 v[80:83], v[222:225], v[198:201], v[80:83]
	v_mfma_f32_16x16x32_bf16 v[68:71], v[214:217], v[206:209], v[68:71]
	v_mfma_f32_16x16x32_bf16 v[64:67], v[222:225], v[206:209], v[64:67]
	s_setprio 0
	s_mov_b32 m0, s61
	v_lshl_add_u64 v[226:227], s[56:57], 0, v[128:129]
	s_barrier
	ds_read_b128 v[178:181], v152 offset:16384
	ds_read_b128 v[182:185], v152 offset:17408
	ds_read_b128 v[186:189], v152 offset:18432
	ds_read_b128 v[190:193], v152 offset:19456
	ds_read_b128 v[194:197], v152 offset:20480
	ds_read_b128 v[198:201], v152 offset:21504
	ds_read_b128 v[202:205], v152 offset:22528
	ds_read_b128 v[206:209], v152 offset:23552
	global_load_lds_dwordx4 v[226:227], off
	v_lshl_add_u64 v[228:229], s[56:57], 0, v[132:133]
	s_mov_b32 m0, s62
	s_nop 0
	global_load_lds_dwordx4 v[228:229], off
	s_barrier
	s_waitcnt lgkmcnt(0)
	s_setprio 1
	s_waitcnt lgkmcnt(0)
	v_mfma_f32_16x16x32_bf16 v[60:63], v[156:159], v[178:181], v[60:63]
	v_mfma_f32_16x16x32_bf16 v[56:59], v[170:173], v[178:181], v[56:59]
	v_mfma_f32_16x16x32_bf16 v[44:47], v[156:159], v[186:189], v[44:47]
	v_mfma_f32_16x16x32_bf16 v[40:43], v[170:173], v[186:189], v[40:43]
	v_mfma_f32_16x16x32_bf16 v[28:31], v[156:159], v[194:197], v[28:31]
	v_mfma_f32_16x16x32_bf16 v[24:27], v[170:173], v[194:197], v[24:27]
	v_mfma_f32_16x16x32_bf16 v[12:15], v[156:159], v[202:205], v[12:15]
	v_mfma_f32_16x16x32_bf16 v[8:11], v[170:173], v[202:205], v[8:11]
	v_mfma_f32_16x16x32_bf16 v[60:63], v[160:163], v[182:185], v[60:63]
	v_mfma_f32_16x16x32_bf16 v[56:59], v[174:177], v[182:185], v[56:59]
	v_mfma_f32_16x16x32_bf16 v[44:47], v[160:163], v[190:193], v[44:47]
	v_mfma_f32_16x16x32_bf16 v[40:43], v[174:177], v[190:193], v[40:43]
	v_mfma_f32_16x16x32_bf16 v[28:31], v[160:163], v[198:201], v[28:31]
	v_mfma_f32_16x16x32_bf16 v[24:27], v[174:177], v[198:201], v[24:27]
	v_mfma_f32_16x16x32_bf16 v[12:15], v[160:163], v[206:209], v[12:15]
	v_mfma_f32_16x16x32_bf16 v[8:11], v[174:177], v[206:209], v[8:11]
	s_setprio 0
	s_barrier
; #define PG8_STAGE(bufoff, gbase, voff) do { _Pragma("unroll") for (int _i = 0; _i < 2; ++_i) \
;         __builtin_amdgcn_global_load_lds((const unsigned*)((const char*)(gbase) + (voff)[_i]), (LAS unsigned*)(lds + (bufoff) + ldsw + _i * 8192), 16, 0, 0); } while (0)
; #define PG8_LDA(dst, b, h) do { _Pragma("unroll") for (int m = 0; m < 4; ++m) _Pragma("unroll") for (int k = 0; k < 2; ++k) dst[m][k] = *(const LAS bf16x8*)(lds + PG8_SA(b, h) + aoff + m * 2048 + k * 1024); } while (0)
; #define PG8_LDB(dst, b, h) do { _Pragma("unroll") for (int n = 0; n < 2; ++n) _Pragma("unroll") for (int k = 0; k < 2; ++k) dst[n][k] = *(const LAS bf16x8*)(lds + PG8_SB(b, h) + boff + n * 2048 + k * 1024); } while (0)
; #define PG8_MMA(ai, bj, At, Bt) do { __builtin_amdgcn_s_setprio(1); _Pragma("unroll") for (int m = 0; m < 4; ++m) _Pragma("unroll") for (int n = 0; n < 2; ++n) _Pragma("unroll") for (int k = 0; k < 2; ++k) \
;         acc[ai][bj][m][n] = __builtin_amdgcn_mfma_f32_16x16x32_bf16(Bt[n][k], At[m][k], acc[ai][bj][m][n], 0, 0, 0); __builtin_amdgcn_s_setprio(0); } while (0)
; #define PG8_WAIT_V(n) asm volatile("s_waitcnt vmcnt(" #n ")" ::: "memory")
; #define PG8_WAIT_L(n) asm volatile("s_waitcnt lgkmcnt(" #n ")" ::: "memory")
; #define PG8_BAR __builtin_amdgcn_s_barrier()
; #define PG8_SCHED __builtin_amdgcn_sched_barrier(0)
;     ...
;             PG8_BAR; PG8_WAIT_L(0); PG8_MMA(1, 0, At, B0); PG8_BAR; PG8_SCHED;
;             PG8_STAGE(PG8_SB(0, 1), b2 + hB, voffB);
;             PG8_WAIT_V(6); PG8_BAR; PG8_MMA(1, 1, At, B1); PG8_BAR;
;             PG8_LDB(B0, 1, 0); PG8_SCHED; PG8_LDA(At, 1, 0); PG8_STAGE(PG8_SA(0, 1), a2 + hA, voffA);
;             PG8_WAIT_L(8); PG8_BAR; PG8_WAIT_L(0); PG8_MMA(0, 0, At, B0); PG8_BAR; PG8_SCHED;
;             PG8_LDB(B1, 1, 1); PG8_STAGE(PG8_SB(1, 0), b3, voffB);
;             PG8_BAR; PG8_WAIT_L(0); PG8_MMA(0, 1, At, B1); PG8_BAR;
;             PG8_LDA(At, 1, 1); PG8_STAGE(PG8_SA(1, 0), a3, voffA);
	s_add_u32 s44, s54, 0x40000
	s_addc_u32 s45, s55, 0
	s_add_i32 s43, s70, s60
	v_lshl_add_u64 v[156:157], s[44:45], 0, v[130:131]
	s_mov_b32 m0, s43
	s_nop 0
	global_load_lds_dwordx4 v[156:157], off
	v_lshl_add_u64 v[156:157], s[44:45], 0, v[134:135]
	s_add_i32 m0, s43, 0x2000
	s_nop 0
	global_load_lds_dwordx4 v[156:157], off
	s_waitcnt vmcnt(6)
	s_barrier
	s_setprio 1
	v_mfma_f32_16x16x32_bf16 v[52:55], v[210:213], v[178:181], v[52:55]
	v_mfma_f32_16x16x32_bf16 v[48:51], v[218:221], v[178:181], v[48:51]
	v_mfma_f32_16x16x32_bf16 v[36:39], v[210:213], v[186:189], v[36:39]
	v_mfma_f32_16x16x32_bf16 v[32:35], v[218:221], v[186:189], v[32:35]
	v_mfma_f32_16x16x32_bf16 v[20:23], v[210:213], v[194:197], v[20:23]
	v_mfma_f32_16x16x32_bf16 v[16:19], v[218:221], v[194:197], v[16:19]
	v_mfma_f32_16x16x32_bf16 v[4:7], v[210:213], v[202:205], v[4:7]
	v_mfma_f32_16x16x32_bf16 v[0:3], v[218:221], v[202:205], v[0:3]
	v_mfma_f32_16x16x32_bf16 v[52:55], v[214:217], v[182:185], v[52:55]
	v_mfma_f32_16x16x32_bf16 v[48:51], v[222:225], v[182:185], v[48:51]
	v_mfma_f32_16x16x32_bf16 v[36:39], v[214:217], v[190:193], v[36:39]
	v_mfma_f32_16x16x32_bf16 v[32:35], v[222:225], v[190:193], v[32:35]
	v_mfma_f32_16x16x32_bf16 v[20:23], v[214:217], v[198:201], v[20:23]
	v_mfma_f32_16x16x32_bf16 v[16:19], v[222:225], v[198:201], v[16:19]
	v_mfma_f32_16x16x32_bf16 v[4:7], v[214:217], v[206:209], v[4:7]
	v_mfma_f32_16x16x32_bf16 v[0:3], v[222:225], v[206:209], v[0:3]
	s_setprio 0
	s_add_i32 s43, 0, 0x18000
	v_add_u32_e32 v155, s43, v149
	s_barrier
	ds_read_b128 v[156:159], v155
	ds_read_b128 v[160:163], v155 offset:1024
	ds_read_b128 v[170:173], v155 offset:2048
	ds_read_b128 v[174:177], v155 offset:3072
	s_add_u32 s44, s56, 0x40000
	s_addc_u32 s45, s57, 0
	s_mov_b32 m0, s63
	v_lshl_add_u64 v[210:211], s[44:45], 0, v[128:129]
	ds_read_b128 v[178:181], v152 offset:32768
	ds_read_b128 v[182:185], v152 offset:33792
	ds_read_b128 v[186:189], v152 offset:34816
	ds_read_b128 v[190:193], v152 offset:35840
	ds_read_b128 v[194:197], v152 offset:36864
	ds_read_b128 v[198:201], v152 offset:37888
	ds_read_b128 v[202:205], v152 offset:38912
	ds_read_b128 v[206:209], v152 offset:39936
	global_load_lds_dwordx4 v[210:211], off
	v_lshl_add_u64 v[210:211], s[44:45], 0, v[132:133]
	s_mov_b32 m0, s64
	s_nop 0
	global_load_lds_dwordx4 v[210:211], off
	s_waitcnt lgkmcnt(8)
	s_barrier
	s_waitcnt lgkmcnt(0)
	s_setprio 1
	s_waitcnt lgkmcnt(0)
	v_mfma_f32_16x16x32_bf16 v[124:127], v[156:159], v[178:181], v[124:127]
	v_mfma_f32_16x16x32_bf16 v[120:123], v[170:173], v[178:181], v[120:123]
	v_mfma_f32_16x16x32_bf16 v[108:111], v[156:159], v[186:189], v[108:111]
	v_mfma_f32_16x16x32_bf16 v[104:107], v[170:173], v[186:189], v[104:107]
	v_mfma_f32_16x16x32_bf16 v[92:95], v[156:159], v[194:197], v[92:95]
	v_mfma_f32_16x16x32_bf16 v[88:91], v[170:173], v[194:197], v[88:91]
	v_mfma_f32_16x16x32_bf16 v[76:79], v[156:159], v[202:205], v[76:79]
	v_mfma_f32_16x16x32_bf16 v[72:75], v[170:173], v[202:205], v[72:75]
	v_mfma_f32_16x16x32_bf16 v[124:127], v[160:163], v[182:185], v[124:127]
	v_mfma_f32_16x16x32_bf16 v[120:123], v[174:177], v[182:185], v[120:123]
	v_mfma_f32_16x16x32_bf16 v[108:111], v[160:163], v[190:193], v[108:111]
	v_mfma_f32_16x16x32_bf16 v[104:107], v[174:177], v[190:193], v[104:107]
	v_mfma_f32_16x16x32_bf16 v[92:95], v[160:163], v[198:201], v[92:95]
	v_mfma_f32_16x16x32_bf16 v[88:91], v[174:177], v[198:201], v[88:91]
	v_mfma_f32_16x16x32_bf16 v[76:79], v[160:163], v[206:209], v[76:79]
	v_mfma_f32_16x16x32_bf16 v[72:75], v[174:177], v[206:209], v[72:75]
	s_setprio 0
	s_barrier
	s_add_i32 s56, 0, 0x1c000
	s_add_i32 s43, s43, s60
	v_add_u32_e32 v155, s56, v149
	v_lshl_add_u64 v[146:147], v[146:147], 0, s[30:31]
	s_mov_b32 m0, s43
	ds_read_b128 v[210:213], v155
	ds_read_b128 v[214:217], v155 offset:1024
	ds_read_b128 v[218:221], v155 offset:2048
	ds_read_b128 v[222:225], v155 offset:3072
	global_load_lds_dwordx4 v[146:147], off
	v_lshl_add_u64 v[146:147], v[164:165], 0, s[30:31]
	s_add_i32 m0, s43, 0x2000
	s_nop 0
	global_load_lds_dwordx4 v[146:147], off
	s_barrier
	s_waitcnt lgkmcnt(0)
	s_setprio 1
	s_waitcnt lgkmcnt(0)
	v_mfma_f32_16x16x32_bf16 v[116:119], v[210:213], v[178:181], v[116:119]
	v_mfma_f32_16x16x32_bf16 v[112:115], v[218:221], v[178:181], v[112:115]
	v_mfma_f32_16x16x32_bf16 v[100:103], v[210:213], v[186:189], v[100:103]
	v_mfma_f32_16x16x32_bf16 v[96:99], v[218:221], v[186:189], v[96:99]
	v_mfma_f32_16x16x32_bf16 v[84:87], v[210:213], v[194:197], v[84:87]
	v_mfma_f32_16x16x32_bf16 v[80:83], v[218:221], v[194:197], v[80:83]
	v_mfma_f32_16x16x32_bf16 v[68:71], v[210:213], v[202:205], v[68:71]
	v_mfma_f32_16x16x32_bf16 v[64:67], v[218:221], v[202:205], v[64:67]
	v_mfma_f32_16x16x32_bf16 v[116:119], v[214:217], v[182:185], v[116:119]
	v_mfma_f32_16x16x32_bf16 v[112:115], v[222:225], v[182:185], v[112:115]
	v_mfma_f32_16x16x32_bf16 v[100:103], v[214:217], v[190:193], v[100:103]
	v_mfma_f32_16x16x32_bf16 v[96:99], v[222:225], v[190:193], v[96:99]
	v_mfma_f32_16x16x32_bf16 v[84:87], v[214:217], v[198:201], v[84:87]
	v_mfma_f32_16x16x32_bf16 v[80:83], v[222:225], v[198:201], v[80:83]
	v_mfma_f32_16x16x32_bf16 v[68:71], v[214:217], v[206:209], v[68:71]
	v_mfma_f32_16x16x32_bf16 v[64:67], v[222:225], v[206:209], v[64:67]
	s_setprio 0
	s_mov_b32 m0, s66
	v_lshl_add_u64 v[146:147], v[226:227], 0, s[30:31]
	s_barrier
	ds_read_b128 v[178:181], v152 offset:49152
	ds_read_b128 v[182:185], v152 offset:50176
	ds_read_b128 v[186:189], v152 offset:51200
	ds_read_b128 v[190:193], v152 offset:52224
	ds_read_b128 v[194:197], v152 offset:53248
	ds_read_b128 v[198:201], v152 offset:54272
	ds_read_b128 v[202:205], v152 offset:55296
	ds_read_b128 v[206:209], v152 offset:56320
	global_load_lds_dwordx4 v[146:147], off
	v_lshl_add_u64 v[146:147], v[228:229], 0, s[30:31]
	s_mov_b32 m0, s67
	s_nop 0
	global_load_lds_dwordx4 v[146:147], off
	s_barrier
; #define PG8_STAGE(bufoff, gbase, voff) do { _Pragma("unroll") for (int _i = 0; _i < 2; ++_i) \
;         __builtin_amdgcn_global_load_lds((const unsigned*)((const char*)(gbase) + (voff)[_i]), (LAS unsigned*)(lds + (bufoff) + ldsw + _i * 8192), 16, 0, 0); } while (0)
; #define PG8_LDA(dst, b, h) do { _Pragma("unroll") for (int m = 0; m < 4; ++m) _Pragma("unroll") for (int k = 0; k < 2; ++k) dst[m][k] = *(const LAS bf16x8*)(lds + PG8_SA(b, h) + aoff + m * 2048 + k * 1024); } while (0)
; #define PG8_MMA(ai, bj, At, Bt) do { __builtin_amdgcn_s_setprio(1); _Pragma("unroll") for (int m = 0; m < 4; ++m) _Pragma("unroll") for (int n = 0; n < 2; ++n) _Pragma("unroll") for (int k = 0; k < 2; ++k) \
;         acc[ai][bj][m][n] = __builtin_amdgcn_mfma_f32_16x16x32_bf16(Bt[n][k], At[m][k], acc[ai][bj][m][n], 0, 0, 0); __builtin_amdgcn_s_setprio(0); } while (0)
; #define PG8_WAIT_V(n) asm volatile("s_waitcnt vmcnt(" #n ")" ::: "memory")
; #define PG8_WAIT_L(n) asm volatile("s_waitcnt lgkmcnt(" #n ")" ::: "memory")
; #define PG8_BAR __builtin_amdgcn_s_barrier()
; #define PG8_SCHED __builtin_amdgcn_sched_barrier(0)
;     ...
;             PG8_BAR; PG8_WAIT_L(0); PG8_MMA(0, 1, At, B1); PG8_BAR;
;             PG8_LDA(At, 1, 1); PG8_STAGE(PG8_SA(1, 0), a3, voffA);
;             PG8_BAR; PG8_WAIT_L(0); PG8_MMA(1, 0, At, B0); PG8_BAR; PG8_SCHED;
;             PG8_STAGE(PG8_SB(1, 1), b3 + hB, voffB);
;             PG8_WAIT_V(6); PG8_BAR; PG8_MMA(1, 1, At, B1); PG8_BAR;
;         }
;         E(acc, cur, wr, wc, fr, fq);
; __device__ __forceinline__ float row_rstd(const float* ssq, int row) {
;     const f32x4* p = (const f32x4*)(ssq + (size_t)row * 16);
;     const f32x4 a = p[0], b = p[1], c = p[2], d = p[3];
	s_waitcnt lgkmcnt(0)
	s_setprio 1
	s_waitcnt lgkmcnt(0)
	v_mfma_f32_16x16x32_bf16 v[60:63], v[156:159], v[178:181], v[60:63]
	v_mfma_f32_16x16x32_bf16 v[56:59], v[170:173], v[178:181], v[56:59]
	v_mfma_f32_16x16x32_bf16 v[44:47], v[156:159], v[186:189], v[44:47]
	v_mfma_f32_16x16x32_bf16 v[40:43], v[170:173], v[186:189], v[40:43]
	v_mfma_f32_16x16x32_bf16 v[28:31], v[156:159], v[194:197], v[28:31]
	v_mfma_f32_16x16x32_bf16 v[24:27], v[170:173], v[194:197], v[24:27]
	v_mfma_f32_16x16x32_bf16 v[12:15], v[156:159], v[202:205], v[12:15]
	v_mfma_f32_16x16x32_bf16 v[8:11], v[170:173], v[202:205], v[8:11]
	v_mfma_f32_16x16x32_bf16 v[60:63], v[160:163], v[182:185], v[60:63]
	v_mfma_f32_16x16x32_bf16 v[56:59], v[174:177], v[182:185], v[56:59]
	v_mfma_f32_16x16x32_bf16 v[44:47], v[160:163], v[190:193], v[44:47]
	v_mfma_f32_16x16x32_bf16 v[40:43], v[174:177], v[190:193], v[40:43]
	v_mfma_f32_16x16x32_bf16 v[28:31], v[160:163], v[198:201], v[28:31]
	v_mfma_f32_16x16x32_bf16 v[24:27], v[174:177], v[198:201], v[24:27]
	v_mfma_f32_16x16x32_bf16 v[12:15], v[160:163], v[206:209], v[12:15]
	v_mfma_f32_16x16x32_bf16 v[8:11], v[174:177], v[206:209], v[8:11]
	s_setprio 0
	s_barrier
	s_add_u32 s44, s54, 0x40080
	s_addc_u32 s45, s55, 0
	s_add_i32 s43, s56, s60
	v_lshl_add_u64 v[146:147], s[44:45], 0, v[130:131]
	s_mov_b32 m0, s43
	s_nop 0
	global_load_lds_dwordx4 v[146:147], off
	v_lshl_add_u64 v[146:147], s[44:45], 0, v[134:135]
	s_add_i32 m0, s43, 0x2000
	s_nop 0
	global_load_lds_dwordx4 v[146:147], off
	s_waitcnt vmcnt(6)
	s_barrier
	s_setprio 1
	v_mfma_f32_16x16x32_bf16 v[52:55], v[210:213], v[178:181], v[52:55]
	v_mfma_f32_16x16x32_bf16 v[48:51], v[218:221], v[178:181], v[48:51]
	v_mfma_f32_16x16x32_bf16 v[36:39], v[210:213], v[186:189], v[36:39]
	v_mfma_f32_16x16x32_bf16 v[32:35], v[218:221], v[186:189], v[32:35]
	v_mfma_f32_16x16x32_bf16 v[20:23], v[210:213], v[194:197], v[20:23]
	v_mfma_f32_16x16x32_bf16 v[16:19], v[218:221], v[194:197], v[16:19]
	v_mfma_f32_16x16x32_bf16 v[4:7], v[210:213], v[202:205], v[4:7]
	v_mfma_f32_16x16x32_bf16 v[0:3], v[218:221], v[202:205], v[0:3]
	v_mfma_f32_16x16x32_bf16 v[52:55], v[214:217], v[182:185], v[52:55]
	v_mfma_f32_16x16x32_bf16 v[48:51], v[222:225], v[182:185], v[48:51]
	v_mfma_f32_16x16x32_bf16 v[36:39], v[214:217], v[190:193], v[36:39]
	v_mfma_f32_16x16x32_bf16 v[32:35], v[222:225], v[190:193], v[32:35]
	v_mfma_f32_16x16x32_bf16 v[20:23], v[214:217], v[198:201], v[20:23]
	v_mfma_f32_16x16x32_bf16 v[16:19], v[222:225], v[198:201], v[16:19]
	v_mfma_f32_16x16x32_bf16 v[4:7], v[214:217], v[206:209], v[4:7]
	v_mfma_f32_16x16x32_bf16 v[0:3], v[222:225], v[206:209], v[0:3]
	s_setprio 0
	s_add_i32 s42, s42, 2
	s_add_u32 s33, s33, 0x100
	s_addc_u32 s39, s39, 0
	s_add_u32 s40, s40, 0x100
	s_addc_u32 s41, s41, 0
	s_cmp_gt_u32 s42, 13
	s_barrier
	s_cbranch_scc0 .LBB0_958
	v_lshl_add_u32 v146, s75, 8, v148
	v_ashrrev_i32_e32 v147, 31, v146
	v_lshlrev_b64 v[156:157], 6, v[146:147]
	v_lshl_add_u64 v[164:165], s[26:27], 0, v[156:157]
	v_subrev_u32_e32 v180, s26, v164
	v_add_u32_e32 v181, 0x0, v180
	global_load_dwordx4 v[182:185], v181, s[26:27]
	v_add_u32_e32 v181, 0x10, v180
	global_load_dwordx4 v[186:189], v181, s[26:27]
	v_add_u32_e32 v181, 0x20, v180
	global_load_dwordx4 v[190:193], v181, s[26:27]
	v_add_u32_e32 v181, 0x30, v180
	global_load_dwordx4 v[194:197], v181, s[26:27]
	v_add_u32_e32 v181, 0x400, v180
	global_load_dwordx4 v[198:201], v181, s[26:27]
	v_add_u32_e32 v181, 0x410, v180
	global_load_dwordx4 v[202:205], v181, s[26:27]
	v_add_u32_e32 v181, 0x420, v180
	global_load_dwordx4 v[206:209], v181, s[26:27]
	v_add_u32_e32 v181, 0x430, v180
	global_load_dwordx4 v[210:213], v181, s[26:27]
	v_add_u32_e32 v181, 0x800, v180
	global_load_dwordx4 v[214:217], v181, s[26:27]
	v_add_u32_e32 v181, 0x810, v180
	global_load_dwordx4 v[218:221], v181, s[26:27]
	v_add_u32_e32 v181, 0x820, v180
	global_load_dwordx4 v[222:225], v181, s[26:27]
	v_add_u32_e32 v181, 0x830, v180
	global_load_dwordx4 v[232:235], v181, s[26:27]
	v_add_u32_e32 v181, 0xc00, v180
	global_load_dwordx4 v[236:239], v181, s[26:27]
	v_add_u32_e32 v181, 0xc10, v180
	global_load_dwordx4 v[240:243], v181, s[26:27]
	v_add_u32_e32 v181, 0xc20, v180
	global_load_dwordx4 v[244:247], v181, s[26:27]
	v_add_u32_e32 v181, 0xc30, v180
	global_load_dwordx4 v[248:251], v181, s[26:27]
	v_or_b32_e32 v164, 16, v146
	v_lshl_or_b32 v147, s6, 9, v150
	v_ashrrev_i32_e32 v165, 31, v164
	v_lshl_add_u32 v155, v146, 13, v147
	s_waitcnt vmcnt(12)
; __device__ __forceinline__ u32x4 pack8(const f32x4 v0, const f32x4 v1) { u32x4 w; w.x = pk2(v0[0], v0[1]); w.y = pk2(v0[2], v0[3]); w.z = pk2(v1[0], v1[1]); w.w = pk2(v1[2], v1[3]); return w; }
; __device__ __forceinline__ float row_rstd(const float* ssq, int row) {
;     const f32x4* p = (const f32x4*)(ssq + (size_t)row * 16);
;     const f32x4 a = p[0], b = p[1], c = p[2], d = p[3];
;     const float s = ((a[0] + a[1]) + (a[2] + a[3])) + ((b[0] + b[1]) + (b[2] + b[3])) + ((c[0] + c[1]) + (c[2] + c[3])) + ((d[0] + d[1]) + (d[2] + d[3]));
;     return rsqrtf(s * (1.0f / 1024.0f) + 1e-6f);
; }
;     __device__ __forceinline__ void operator()(const f32x4 (&acc)[2][2][4][2], const Unit& u, int wr, int wc, int fr, int fq) const {
;     ...
;                 const int row = row0 + ai * 128 + m * 16; const float rs = row_rstd(ssq, row);
; #pragma unroll
;                 for (int bj = 0; bj < 2; ++bj) { f32x4 v0 = acc[ai][bj][m][0] * rs, v1 = acc[ai][bj][m][1] * rs;
; #pragma unroll
;                     for (int j = 0; j < 4; ++j) { const float a = fmaxf(v0[j], 0.f), b = fmaxf(v1[j], 0.f); v0[j] = a * a; v1[j] = b * b; }
;                     __builtin_amdgcn_raw_buffer_store_b128(pack8(v0, v1), rsrc, (unsigned)(((size_t)row * DFF + col0 + bj * 128) * 2), 0, 16  ); }
	s_nop 0
	s_nop 0
	v_pk_add_f32 v[156:157], v[182:183], v[184:185]
	v_pk_add_f32 v[158:159], v[186:187], v[188:189]
	v_pk_add_f32 v[160:161], v[190:191], v[192:193]
	v_pk_add_f32 v[162:163], v[194:195], v[196:197]
	v_pk_add_f32 v[156:157], v[156:157], v[158:159]
	v_pk_add_f32 v[160:161], v[160:161], v[162:163]
	v_pk_add_f32 v[156:157], v[156:157], v[160:161]
	v_add_f32_e32 v156, v156, v157
	v_fmamk_f32 v156, v156, 0x3a800000, v154
	v_mul_f32_e32 v157, 0x4b800000, v156
	v_cmp_gt_f32_e32 vcc, s71, v156
	s_nop 1
	v_cndmask_b32_e32 v156, v156, v157, vcc
	v_rsq_f32_e32 v158, v156
	v_lshlrev_b64 v[156:157], 6, v[164:165]
	v_lshl_add_u64 v[156:157], s[26:27], 0, v[156:157]
	v_mul_f32_e32 v159, 0x45800000, v158
	v_cndmask_b32_e32 v158, v158, v159, vcc
	v_pk_mul_f32 v[126:127], v[126:127], v[158:159] op_sel_hi:[1,0]
	v_pk_mul_f32 v[124:125], v[124:125], v[158:159] op_sel_hi:[1,0]
	v_pk_mul_f32 v[122:123], v[122:123], v[158:159] op_sel_hi:[1,0]
	v_pk_mul_f32 v[120:121], v[120:121], v[158:159] op_sel_hi:[1,0]
	v_pk_mul_f32 v[114:115], v[114:115], v[158:159] op_sel_hi:[1,0]
	v_pk_mul_f32 v[112:113], v[112:113], v[158:159] op_sel_hi:[1,0]
	v_pk_mul_f32 v[118:119], v[118:119], v[158:159] op_sel_hi:[1,0]
	v_pk_mul_f32 v[116:117], v[116:117], v[158:159] op_sel_hi:[1,0]
	v_max_f32_e32 v124, 0, v124
	v_max_f32_e32 v120, 0, v120
	v_max_f32_e32 v125, 0, v125
	v_max_f32_e32 v121, 0, v121
	v_max_f32_e32 v126, 0, v126
	v_max_f32_e32 v122, 0, v122
	v_max_f32_e32 v127, 0, v127
	v_max_f32_e32 v123, 0, v123
	v_max_f32_e32 v112, 0, v112
	v_max_f32_e32 v113, 0, v113
	v_max_f32_e32 v114, 0, v114
	v_max_f32_e32 v115, 0, v115
	v_max_f32_e32 v116, 0, v116
	v_max_f32_e32 v117, 0, v117
	v_max_f32_e32 v118, 0, v118
	v_max_f32_e32 v119, 0, v119
	v_pk_mul_f32 v[124:125], v[124:125], v[124:125]
	v_pk_mul_f32 v[120:121], v[120:121], v[120:121]
	v_pk_mul_f32 v[126:127], v[126:127], v[126:127]
	v_pk_mul_f32 v[122:123], v[122:123], v[122:123]
	v_pk_mul_f32 v[158:159], v[112:113], v[112:113]
	v_pk_mul_f32 v[160:161], v[114:115], v[114:115]
	v_cvt_pk_bf16_f32 v112, v124, v125
	v_cvt_pk_bf16_f32 v113, v126, v127
	v_cvt_pk_bf16_f32 v114, v120, v121
	v_cvt_pk_bf16_f32 v115, v122, v123
	v_pk_mul_f32 v[116:117], v[116:117], v[116:117]
	v_pk_mul_f32 v[118:119], v[118:119], v[118:119]
	buffer_store_dwordx4 v[112:115], v155, s[16:19], 0 offen sc1
	s_nop 1
	v_cvt_pk_bf16_f32 v112, v116, v117
	v_cvt_pk_bf16_f32 v113, v118, v119
	v_cvt_pk_bf16_f32 v114, v158, v159
	v_cvt_pk_bf16_f32 v115, v160, v161
	buffer_store_dwordx4 v[112:115], v155, s[16:19], 0 offen offset:256 sc1
	s_nop 0
	v_or_b32_e32 v156, 32, v146
	v_ashrrev_i32_e32 v157, 31, v156
	v_lshl_add_u32 v155, v164, 13, v147
	v_add_u32_e32 v181, 0x2000, v180
	global_load_dwordx4 v[182:185], v181, s[26:27]
	v_add_u32_e32 v181, 0x2010, v180
	global_load_dwordx4 v[186:189], v181, s[26:27]
	v_add_u32_e32 v181, 0x2020, v180
	global_load_dwordx4 v[190:193], v181, s[26:27]
	v_add_u32_e32 v181, 0x2030, v180
	global_load_dwordx4 v[194:197], v181, s[26:27]
	s_waitcnt vmcnt(14)
	s_nop 0
	s_nop 0
	v_pk_add_f32 v[112:113], v[198:199], v[200:201]
	v_pk_add_f32 v[114:115], v[202:203], v[204:205]
	v_pk_add_f32 v[116:117], v[206:207], v[208:209]
	v_pk_add_f32 v[118:119], v[210:211], v[212:213]
	v_pk_add_f32 v[112:113], v[112:113], v[114:115]
	v_pk_add_f32 v[116:117], v[116:117], v[118:119]
	v_pk_add_f32 v[112:113], v[112:113], v[116:117]
	v_add_f32_e32 v112, v112, v113
	v_fmamk_f32 v112, v112, 0x3a800000, v154
	v_mul_f32_e32 v113, 0x4b800000, v112
	v_cmp_gt_f32_e32 vcc, s71, v112
	s_nop 1
	v_cndmask_b32_e32 v112, v112, v113, vcc
	v_rsq_f32_e32 v114, v112
	v_lshlrev_b64 v[112:113], 6, v[156:157]
	v_lshl_add_u64 v[112:113], s[26:27], 0, v[112:113]
	v_mul_f32_e32 v115, 0x45800000, v114
	v_cndmask_b32_e32 v114, v114, v115, vcc
	v_pk_mul_f32 v[110:111], v[110:111], v[114:115] op_sel_hi:[1,0]
	v_pk_mul_f32 v[108:109], v[108:109], v[114:115] op_sel_hi:[1,0]
	v_pk_mul_f32 v[106:107], v[106:107], v[114:115] op_sel_hi:[1,0]
	v_pk_mul_f32 v[104:105], v[104:105], v[114:115] op_sel_hi:[1,0]
	v_pk_mul_f32 v[98:99], v[98:99], v[114:115] op_sel_hi:[1,0]
	v_pk_mul_f32 v[96:97], v[96:97], v[114:115] op_sel_hi:[1,0]
	v_pk_mul_f32 v[102:103], v[102:103], v[114:115] op_sel_hi:[1,0]
	v_pk_mul_f32 v[100:101], v[100:101], v[114:115] op_sel_hi:[1,0]
	v_max_f32_e32 v108, 0, v108
	v_max_f32_e32 v104, 0, v104
	v_max_f32_e32 v109, 0, v109
	v_max_f32_e32 v105, 0, v105
	v_max_f32_e32 v110, 0, v110
	v_max_f32_e32 v106, 0, v106
	v_max_f32_e32 v111, 0, v111
	v_max_f32_e32 v107, 0, v107
	v_max_f32_e32 v96, 0, v96
	v_max_f32_e32 v97, 0, v97
	v_max_f32_e32 v98, 0, v98
	v_max_f32_e32 v99, 0, v99
	v_max_f32_e32 v100, 0, v100
	v_max_f32_e32 v101, 0, v101
	v_max_f32_e32 v102, 0, v102
	v_max_f32_e32 v103, 0, v103
	v_pk_mul_f32 v[108:109], v[108:109], v[108:109]
	v_pk_mul_f32 v[104:105], v[104:105], v[104:105]
	v_pk_mul_f32 v[110:111], v[110:111], v[110:111]
	v_pk_mul_f32 v[106:107], v[106:107], v[106:107]
	v_pk_mul_f32 v[114:115], v[96:97], v[96:97]
	v_pk_mul_f32 v[116:117], v[98:99], v[98:99]
	v_cvt_pk_bf16_f32 v96, v108, v109
	v_cvt_pk_bf16_f32 v97, v110, v111
	v_cvt_pk_bf16_f32 v98, v104, v105
	v_cvt_pk_bf16_f32 v99, v106, v107
	v_pk_mul_f32 v[100:101], v[100:101], v[100:101]
	v_pk_mul_f32 v[102:103], v[102:103], v[102:103]
	buffer_store_dwordx4 v[96:99], v155, s[16:19], 0 offen sc1
	s_nop 1
	v_cvt_pk_bf16_f32 v96, v100, v101
	v_cvt_pk_bf16_f32 v97, v102, v103
	v_cvt_pk_bf16_f32 v98, v114, v115
	v_cvt_pk_bf16_f32 v99, v116, v117
	buffer_store_dwordx4 v[96:99], v155, s[16:19], 0 offen offset:256 sc1
	s_nop 0
	v_or_b32_e32 v112, 48, v146
	v_ashrrev_i32_e32 v113, 31, v112
	v_lshl_add_u32 v116, v156, 13, v147
	v_add_u32_e32 v181, 0x2400, v180
	global_load_dwordx4 v[198:201], v181, s[26:27]
	v_add_u32_e32 v181, 0x2410, v180
	global_load_dwordx4 v[202:205], v181, s[26:27]
	v_add_u32_e32 v181, 0x2420, v180
	global_load_dwordx4 v[206:209], v181, s[26:27]
	v_add_u32_e32 v181, 0x2430, v180
	global_load_dwordx4 v[210:213], v181, s[26:27]
	s_waitcnt vmcnt(16)
; __device__ __forceinline__ u32x4 pack8(const f32x4 v0, const f32x4 v1) { u32x4 w; w.x = pk2(v0[0], v0[1]); w.y = pk2(v0[2], v0[3]); w.z = pk2(v1[0], v1[1]); w.w = pk2(v1[2], v1[3]); return w; }
; __device__ __forceinline__ float row_rstd(const float* ssq, int row) {
;     const f32x4* p = (const f32x4*)(ssq + (size_t)row * 16);
;     const f32x4 a = p[0], b = p[1], c = p[2], d = p[3];
;     const float s = ((a[0] + a[1]) + (a[2] + a[3])) + ((b[0] + b[1]) + (b[2] + b[3])) + ((c[0] + c[1]) + (c[2] + c[3])) + ((d[0] + d[1]) + (d[2] + d[3]));
;     return rsqrtf(s * (1.0f / 1024.0f) + 1e-6f);
; }
;     __device__ __forceinline__ void operator()(const f32x4 (&acc)[2][2][4][2], const Unit& u, int wr, int wc, int fr, int fq) const {
;     ...
;                 const int row = row0 + ai * 128 + m * 16; const float rs = row_rstd(ssq, row);
; #pragma unroll
;                 for (int bj = 0; bj < 2; ++bj) { f32x4 v0 = acc[ai][bj][m][0] * rs, v1 = acc[ai][bj][m][1] * rs;
; #pragma unroll
;                     for (int j = 0; j < 4; ++j) { const float a = fmaxf(v0[j], 0.f), b = fmaxf(v1[j], 0.f); v0[j] = a * a; v1[j] = b * b; }
;                     __builtin_amdgcn_raw_buffer_store_b128(pack8(v0, v1), rsrc, (unsigned)(((size_t)row * DFF + col0 + bj * 128) * 2), 0, 16  ); }
	s_nop 0
	s_nop 0
	v_pk_add_f32 v[96:97], v[214:215], v[216:217]
	v_pk_add_f32 v[98:99], v[218:219], v[220:221]
	v_pk_add_f32 v[100:101], v[222:223], v[224:225]
	v_pk_add_f32 v[102:103], v[232:233], v[234:235]
	v_pk_add_f32 v[96:97], v[96:97], v[98:99]
	v_pk_add_f32 v[100:101], v[100:101], v[102:103]
	v_pk_add_f32 v[96:97], v[96:97], v[100:101]
	v_add_f32_e32 v96, v96, v97
	v_fmamk_f32 v96, v96, 0x3a800000, v154
	v_mul_f32_e32 v97, 0x4b800000, v96
	v_cmp_gt_f32_e32 vcc, s71, v96
	s_nop 1
	v_cndmask_b32_e32 v96, v96, v97, vcc
	v_rsq_f32_e32 v98, v96
	v_lshlrev_b64 v[96:97], 6, v[112:113]
	v_lshl_add_u64 v[96:97], s[26:27], 0, v[96:97]
	v_mul_f32_e32 v99, 0x45800000, v98
	v_cndmask_b32_e32 v98, v98, v99, vcc
	v_pk_mul_f32 v[94:95], v[94:95], v[98:99] op_sel_hi:[1,0]
	v_pk_mul_f32 v[92:93], v[92:93], v[98:99] op_sel_hi:[1,0]
	v_pk_mul_f32 v[90:91], v[90:91], v[98:99] op_sel_hi:[1,0]
	v_pk_mul_f32 v[88:89], v[88:89], v[98:99] op_sel_hi:[1,0]
	v_pk_mul_f32 v[82:83], v[82:83], v[98:99] op_sel_hi:[1,0]
	v_pk_mul_f32 v[80:81], v[80:81], v[98:99] op_sel_hi:[1,0]
	v_pk_mul_f32 v[86:87], v[86:87], v[98:99] op_sel_hi:[1,0]
	v_pk_mul_f32 v[84:85], v[84:85], v[98:99] op_sel_hi:[1,0]
	v_max_f32_e32 v92, 0, v92
	v_max_f32_e32 v88, 0, v88
	v_max_f32_e32 v93, 0, v93
	v_max_f32_e32 v89, 0, v89
	v_max_f32_e32 v94, 0, v94
	v_max_f32_e32 v90, 0, v90
	v_max_f32_e32 v95, 0, v95
	v_max_f32_e32 v91, 0, v91
	v_max_f32_e32 v80, 0, v80
	v_max_f32_e32 v81, 0, v81
	v_max_f32_e32 v82, 0, v82
	v_max_f32_e32 v83, 0, v83
	v_max_f32_e32 v84, 0, v84
	v_max_f32_e32 v85, 0, v85
	v_max_f32_e32 v86, 0, v86
	v_max_f32_e32 v87, 0, v87
	v_pk_mul_f32 v[92:93], v[92:93], v[92:93]
	v_pk_mul_f32 v[88:89], v[88:89], v[88:89]
	v_pk_mul_f32 v[94:95], v[94:95], v[94:95]
	v_pk_mul_f32 v[90:91], v[90:91], v[90:91]
	v_pk_mul_f32 v[98:99], v[80:81], v[80:81]
	v_pk_mul_f32 v[100:101], v[82:83], v[82:83]
	v_cvt_pk_bf16_f32 v80, v92, v93
	v_cvt_pk_bf16_f32 v81, v94, v95
	v_cvt_pk_bf16_f32 v82, v88, v89
	v_cvt_pk_bf16_f32 v83, v90, v91
	v_pk_mul_f32 v[84:85], v[84:85], v[84:85]
	v_pk_mul_f32 v[86:87], v[86:87], v[86:87]
	buffer_store_dwordx4 v[80:83], v116, s[16:19], 0 offen sc1
	s_nop 1
	v_cvt_pk_bf16_f32 v80, v84, v85
	v_cvt_pk_bf16_f32 v81, v86, v87
	v_cvt_pk_bf16_f32 v82, v98, v99
	v_cvt_pk_bf16_f32 v83, v100, v101
	buffer_store_dwordx4 v[80:83], v116, s[16:19], 0 offen offset:256 sc1
	s_nop 0
	v_add_u32_e32 v96, 0x80, v146
	v_ashrrev_i32_e32 v97, 31, v96
	v_lshl_add_u32 v100, v112, 13, v147
	v_add_u32_e32 v181, 0x2800, v180
	global_load_dwordx4 v[214:217], v181, s[26:27]
	v_add_u32_e32 v181, 0x2810, v180
	global_load_dwordx4 v[218:221], v181, s[26:27]
	v_add_u32_e32 v181, 0x2820, v180
	global_load_dwordx4 v[222:225], v181, s[26:27]
	v_add_u32_e32 v181, 0x2830, v180
	global_load_dwordx4 v[232:235], v181, s[26:27]
	s_waitcnt vmcnt(18)
	s_nop 0
	s_nop 0
	v_pk_add_f32 v[80:81], v[236:237], v[238:239]
	v_pk_add_f32 v[82:83], v[240:241], v[242:243]
	v_pk_add_f32 v[84:85], v[244:245], v[246:247]
	v_pk_add_f32 v[86:87], v[248:249], v[250:251]
	v_pk_add_f32 v[80:81], v[80:81], v[82:83]
	v_pk_add_f32 v[84:85], v[84:85], v[86:87]
	v_pk_add_f32 v[80:81], v[80:81], v[84:85]
	v_add_f32_e32 v80, v80, v81
	v_fmamk_f32 v80, v80, 0x3a800000, v154
	v_mul_f32_e32 v81, 0x4b800000, v80
	v_cmp_gt_f32_e32 vcc, s71, v80
	s_nop 1
	v_cndmask_b32_e32 v80, v80, v81, vcc
	v_rsq_f32_e32 v82, v80
	v_lshlrev_b64 v[80:81], 6, v[96:97]
	v_lshl_add_u64 v[80:81], s[26:27], 0, v[80:81]
	v_mul_f32_e32 v83, 0x45800000, v82
	v_cndmask_b32_e32 v82, v82, v83, vcc
	v_pk_mul_f32 v[78:79], v[78:79], v[82:83] op_sel_hi:[1,0]
	v_pk_mul_f32 v[76:77], v[76:77], v[82:83] op_sel_hi:[1,0]
	v_pk_mul_f32 v[74:75], v[74:75], v[82:83] op_sel_hi:[1,0]
	v_pk_mul_f32 v[72:73], v[72:73], v[82:83] op_sel_hi:[1,0]
	v_pk_mul_f32 v[66:67], v[66:67], v[82:83] op_sel_hi:[1,0]
	v_pk_mul_f32 v[64:65], v[64:65], v[82:83] op_sel_hi:[1,0]
	v_pk_mul_f32 v[70:71], v[70:71], v[82:83] op_sel_hi:[1,0]
	v_pk_mul_f32 v[68:69], v[68:69], v[82:83] op_sel_hi:[1,0]
	v_max_f32_e32 v76, 0, v76
	v_max_f32_e32 v72, 0, v72
	v_max_f32_e32 v77, 0, v77
	v_max_f32_e32 v73, 0, v73
	v_max_f32_e32 v78, 0, v78
	v_max_f32_e32 v74, 0, v74
	v_max_f32_e32 v79, 0, v79
	v_max_f32_e32 v75, 0, v75
	v_max_f32_e32 v64, 0, v64
	v_max_f32_e32 v65, 0, v65
	v_max_f32_e32 v66, 0, v66
	v_max_f32_e32 v67, 0, v67
	v_max_f32_e32 v68, 0, v68
	v_max_f32_e32 v69, 0, v69
	v_max_f32_e32 v70, 0, v70
	v_max_f32_e32 v71, 0, v71
	v_pk_mul_f32 v[76:77], v[76:77], v[76:77]
	v_pk_mul_f32 v[72:73], v[72:73], v[72:73]
	v_pk_mul_f32 v[78:79], v[78:79], v[78:79]
	v_pk_mul_f32 v[74:75], v[74:75], v[74:75]
	v_pk_mul_f32 v[82:83], v[64:65], v[64:65]
	v_pk_mul_f32 v[84:85], v[66:67], v[66:67]
	v_cvt_pk_bf16_f32 v64, v76, v77
	v_cvt_pk_bf16_f32 v65, v78, v79
	v_cvt_pk_bf16_f32 v66, v72, v73
	v_cvt_pk_bf16_f32 v67, v74, v75
	v_pk_mul_f32 v[68:69], v[68:69], v[68:69]
	v_pk_mul_f32 v[70:71], v[70:71], v[70:71]
	buffer_store_dwordx4 v[64:67], v100, s[16:19], 0 offen sc1
	s_nop 1
	v_cvt_pk_bf16_f32 v64, v68, v69
	v_cvt_pk_bf16_f32 v65, v70, v71
	v_cvt_pk_bf16_f32 v66, v82, v83
	v_cvt_pk_bf16_f32 v67, v84, v85
	buffer_store_dwordx4 v[64:67], v100, s[16:19], 0 offen offset:256 sc1
	s_nop 0
	v_add_u32_e32 v80, 0x90, v146
	v_ashrrev_i32_e32 v81, 31, v80
	v_lshl_add_u32 v84, v96, 13, v147
	v_add_u32_e32 v181, 0x2c00, v180
	global_load_dwordx4 v[236:239], v181, s[26:27]
	v_add_u32_e32 v181, 0x2c10, v180
	global_load_dwordx4 v[240:243], v181, s[26:27]
	v_add_u32_e32 v181, 0x2c20, v180
	global_load_dwordx4 v[244:247], v181, s[26:27]
	v_add_u32_e32 v181, 0x2c30, v180
	global_load_dwordx4 v[248:251], v181, s[26:27]
	s_waitcnt vmcnt(18)
; __device__ __forceinline__ u32x4 pack8(const f32x4 v0, const f32x4 v1) { u32x4 w; w.x = pk2(v0[0], v0[1]); w.y = pk2(v0[2], v0[3]); w.z = pk2(v1[0], v1[1]); w.w = pk2(v1[2], v1[3]); return w; }
; __device__ __forceinline__ float row_rstd(const float* ssq, int row) {
;     const f32x4* p = (const f32x4*)(ssq + (size_t)row * 16);
;     const f32x4 a = p[0], b = p[1], c = p[2], d = p[3];
;     const float s = ((a[0] + a[1]) + (a[2] + a[3])) + ((b[0] + b[1]) + (b[2] + b[3])) + ((c[0] + c[1]) + (c[2] + c[3])) + ((d[0] + d[1]) + (d[2] + d[3]));
;     return rsqrtf(s * (1.0f / 1024.0f) + 1e-6f);
; }
;     __device__ __forceinline__ void operator()(const f32x4 (&acc)[2][2][4][2], const Unit& u, int wr, int wc, int fr, int fq) const {
;     ...
;                 const int row = row0 + ai * 128 + m * 16; const float rs = row_rstd(ssq, row);
; #pragma unroll
;                 for (int bj = 0; bj < 2; ++bj) { f32x4 v0 = acc[ai][bj][m][0] * rs, v1 = acc[ai][bj][m][1] * rs;
; #pragma unroll
;                     for (int j = 0; j < 4; ++j) { const float a = fmaxf(v0[j], 0.f), b = fmaxf(v1[j], 0.f); v0[j] = a * a; v1[j] = b * b; }
;                     __builtin_amdgcn_raw_buffer_store_b128(pack8(v0, v1), rsrc, (unsigned)(((size_t)row * DFF + col0 + bj * 128) * 2), 0, 16  ); }
	s_nop 0
	s_nop 0
	v_pk_add_f32 v[64:65], v[182:183], v[184:185]
	v_pk_add_f32 v[66:67], v[186:187], v[188:189]
	v_pk_add_f32 v[68:69], v[190:191], v[192:193]
	v_pk_add_f32 v[70:71], v[194:195], v[196:197]
	v_pk_add_f32 v[64:65], v[64:65], v[66:67]
	v_pk_add_f32 v[68:69], v[68:69], v[70:71]
	v_pk_add_f32 v[64:65], v[64:65], v[68:69]
	v_add_f32_e32 v64, v64, v65
	v_fmamk_f32 v64, v64, 0x3a800000, v154
	v_mul_f32_e32 v65, 0x4b800000, v64
	v_cmp_gt_f32_e32 vcc, s71, v64
	s_nop 1
	v_cndmask_b32_e32 v64, v64, v65, vcc
	v_rsq_f32_e32 v66, v64
	v_lshlrev_b64 v[64:65], 6, v[80:81]
	v_lshl_add_u64 v[64:65], s[26:27], 0, v[64:65]
	v_mul_f32_e32 v67, 0x45800000, v66
	v_cndmask_b32_e32 v66, v66, v67, vcc
	v_pk_mul_f32 v[62:63], v[62:63], v[66:67] op_sel_hi:[1,0]
	v_pk_mul_f32 v[60:61], v[60:61], v[66:67] op_sel_hi:[1,0]
	v_pk_mul_f32 v[58:59], v[58:59], v[66:67] op_sel_hi:[1,0]
	v_pk_mul_f32 v[56:57], v[56:57], v[66:67] op_sel_hi:[1,0]
	v_pk_mul_f32 v[50:51], v[50:51], v[66:67] op_sel_hi:[1,0]
	v_pk_mul_f32 v[48:49], v[48:49], v[66:67] op_sel_hi:[1,0]
	v_pk_mul_f32 v[54:55], v[54:55], v[66:67] op_sel_hi:[1,0]
	v_pk_mul_f32 v[52:53], v[52:53], v[66:67] op_sel_hi:[1,0]
	v_max_f32_e32 v60, 0, v60
	v_max_f32_e32 v56, 0, v56
	v_max_f32_e32 v61, 0, v61
	v_max_f32_e32 v57, 0, v57
	v_max_f32_e32 v62, 0, v62
	v_max_f32_e32 v58, 0, v58
	v_max_f32_e32 v63, 0, v63
	v_max_f32_e32 v59, 0, v59
	v_max_f32_e32 v48, 0, v48
	v_max_f32_e32 v49, 0, v49
	v_max_f32_e32 v50, 0, v50
	v_max_f32_e32 v51, 0, v51
	v_max_f32_e32 v52, 0, v52
	v_max_f32_e32 v53, 0, v53
	v_max_f32_e32 v54, 0, v54
	v_max_f32_e32 v55, 0, v55
	v_pk_mul_f32 v[60:61], v[60:61], v[60:61]
	v_pk_mul_f32 v[56:57], v[56:57], v[56:57]
	v_pk_mul_f32 v[62:63], v[62:63], v[62:63]
	v_pk_mul_f32 v[58:59], v[58:59], v[58:59]
	v_pk_mul_f32 v[66:67], v[48:49], v[48:49]
	v_pk_mul_f32 v[68:69], v[50:51], v[50:51]
	v_cvt_pk_bf16_f32 v48, v60, v61
	v_cvt_pk_bf16_f32 v49, v62, v63
	v_cvt_pk_bf16_f32 v50, v56, v57
	v_cvt_pk_bf16_f32 v51, v58, v59
	v_pk_mul_f32 v[52:53], v[52:53], v[52:53]
	v_pk_mul_f32 v[54:55], v[54:55], v[54:55]
	buffer_store_dwordx4 v[48:51], v84, s[16:19], 0 offen sc1
	s_nop 1
	v_cvt_pk_bf16_f32 v48, v52, v53
	v_cvt_pk_bf16_f32 v49, v54, v55
	v_cvt_pk_bf16_f32 v50, v66, v67
	v_cvt_pk_bf16_f32 v51, v68, v69
	buffer_store_dwordx4 v[48:51], v84, s[16:19], 0 offen offset:256 sc1
	s_nop 0
	v_add_u32_e32 v64, 0xa0, v146
	v_ashrrev_i32_e32 v65, 31, v64
	v_lshl_add_u32 v68, v80, 13, v147
	s_waitcnt vmcnt(14)
	s_nop 0
	s_nop 0
	v_pk_add_f32 v[48:49], v[198:199], v[200:201]
	v_pk_add_f32 v[50:51], v[202:203], v[204:205]
	v_pk_add_f32 v[52:53], v[206:207], v[208:209]
	v_pk_add_f32 v[54:55], v[210:211], v[212:213]
	v_pk_add_f32 v[48:49], v[48:49], v[50:51]
	v_pk_add_f32 v[52:53], v[52:53], v[54:55]
	v_pk_add_f32 v[48:49], v[48:49], v[52:53]
	v_add_f32_e32 v48, v48, v49
	v_fmamk_f32 v48, v48, 0x3a800000, v154
	v_mul_f32_e32 v49, 0x4b800000, v48
	v_cmp_gt_f32_e32 vcc, s71, v48
	s_nop 1
	v_cndmask_b32_e32 v48, v48, v49, vcc
	v_rsq_f32_e32 v50, v48
	v_lshlrev_b64 v[48:49], 6, v[64:65]
	v_lshl_add_u64 v[48:49], s[26:27], 0, v[48:49]
	v_mul_f32_e32 v51, 0x45800000, v50
	v_cndmask_b32_e32 v50, v50, v51, vcc
	v_pk_mul_f32 v[46:47], v[46:47], v[50:51] op_sel_hi:[1,0]
	v_pk_mul_f32 v[44:45], v[44:45], v[50:51] op_sel_hi:[1,0]
	v_pk_mul_f32 v[42:43], v[42:43], v[50:51] op_sel_hi:[1,0]
	v_pk_mul_f32 v[40:41], v[40:41], v[50:51] op_sel_hi:[1,0]
	v_pk_mul_f32 v[34:35], v[34:35], v[50:51] op_sel_hi:[1,0]
	v_pk_mul_f32 v[32:33], v[32:33], v[50:51] op_sel_hi:[1,0]
	v_pk_mul_f32 v[38:39], v[38:39], v[50:51] op_sel_hi:[1,0]
	v_pk_mul_f32 v[36:37], v[36:37], v[50:51] op_sel_hi:[1,0]
	v_max_f32_e32 v44, 0, v44
	v_max_f32_e32 v40, 0, v40
	v_max_f32_e32 v45, 0, v45
	v_max_f32_e32 v41, 0, v41
	v_max_f32_e32 v46, 0, v46
	v_max_f32_e32 v42, 0, v42
	v_max_f32_e32 v47, 0, v47
	v_max_f32_e32 v43, 0, v43
	v_max_f32_e32 v32, 0, v32
	v_max_f32_e32 v33, 0, v33
	v_max_f32_e32 v34, 0, v34
	v_max_f32_e32 v35, 0, v35
	v_max_f32_e32 v36, 0, v36
	v_max_f32_e32 v37, 0, v37
	v_max_f32_e32 v38, 0, v38
	v_max_f32_e32 v39, 0, v39
	v_pk_mul_f32 v[44:45], v[44:45], v[44:45]
	v_pk_mul_f32 v[40:41], v[40:41], v[40:41]
	v_pk_mul_f32 v[46:47], v[46:47], v[46:47]
	v_pk_mul_f32 v[42:43], v[42:43], v[42:43]
	v_pk_mul_f32 v[50:51], v[32:33], v[32:33]
	v_pk_mul_f32 v[52:53], v[34:35], v[34:35]
	v_cvt_pk_bf16_f32 v32, v44, v45
	v_cvt_pk_bf16_f32 v33, v46, v47
	v_cvt_pk_bf16_f32 v34, v40, v41
	v_cvt_pk_bf16_f32 v35, v42, v43
	v_pk_mul_f32 v[36:37], v[36:37], v[36:37]
	v_pk_mul_f32 v[38:39], v[38:39], v[38:39]
	buffer_store_dwordx4 v[32:35], v68, s[16:19], 0 offen sc1
	s_nop 1
	v_cvt_pk_bf16_f32 v32, v36, v37
	v_cvt_pk_bf16_f32 v33, v38, v39
	v_cvt_pk_bf16_f32 v34, v50, v51
	v_cvt_pk_bf16_f32 v35, v52, v53
	buffer_store_dwordx4 v[32:35], v68, s[16:19], 0 offen offset:256 sc1
	s_nop 0
	v_add_u32_e32 v48, 0xb0, v146
	v_ashrrev_i32_e32 v49, 31, v48
	v_lshl_add_u32 v52, v64, 13, v147
	s_waitcnt vmcnt(10)
; __device__ __forceinline__ u32x4 pack8(const f32x4 v0, const f32x4 v1) { u32x4 w; w.x = pk2(v0[0], v0[1]); w.y = pk2(v0[2], v0[3]); w.z = pk2(v1[0], v1[1]); w.w = pk2(v1[2], v1[3]); return w; }
; __device__ __forceinline__ float row_rstd(const float* ssq, int row) {
;     const f32x4* p = (const f32x4*)(ssq + (size_t)row * 16);
;     const f32x4 a = p[0], b = p[1], c = p[2], d = p[3];
;     const float s = ((a[0] + a[1]) + (a[2] + a[3])) + ((b[0] + b[1]) + (b[2] + b[3])) + ((c[0] + c[1]) + (c[2] + c[3])) + ((d[0] + d[1]) + (d[2] + d[3]));
;     return rsqrtf(s * (1.0f / 1024.0f) + 1e-6f);
; }
;     __device__ __forceinline__ void operator()(const f32x4 (&acc)[2][2][4][2], const Unit& u, int wr, int wc, int fr, int fq) const {
;     ...
;                 const int row = row0 + ai * 128 + m * 16; const float rs = row_rstd(ssq, row);
; #pragma unroll
;                 for (int bj = 0; bj < 2; ++bj) { f32x4 v0 = acc[ai][bj][m][0] * rs, v1 = acc[ai][bj][m][1] * rs;
; #pragma unroll
;                     for (int j = 0; j < 4; ++j) { const float a = fmaxf(v0[j], 0.f), b = fmaxf(v1[j], 0.f); v0[j] = a * a; v1[j] = b * b; }
;                     __builtin_amdgcn_raw_buffer_store_b128(pack8(v0, v1), rsrc, (unsigned)(((size_t)row * DFF + col0 + bj * 128) * 2), 0, 16  ); }
;             }
;         asm volatile("s_waitcnt vmcnt(0)" ::: "memory");
;         if (fr == 0 && fq == 0) (void)__hip_atomic_fetch_add(ready + 64 * (pm_off + u.pm), 1u, __ATOMIC_RELAXED, __HIP_MEMORY_SCOPE_AGENT);
	s_nop 0
	s_nop 0
	v_pk_add_f32 v[32:33], v[214:215], v[216:217]
	v_pk_add_f32 v[34:35], v[218:219], v[220:221]
	v_pk_add_f32 v[36:37], v[222:223], v[224:225]
	v_pk_add_f32 v[38:39], v[232:233], v[234:235]
	v_pk_add_f32 v[32:33], v[32:33], v[34:35]
	v_pk_add_f32 v[36:37], v[36:37], v[38:39]
	v_pk_add_f32 v[32:33], v[32:33], v[36:37]
	v_add_f32_e32 v32, v32, v33
	v_fmamk_f32 v32, v32, 0x3a800000, v154
	v_mul_f32_e32 v33, 0x4b800000, v32
	v_cmp_gt_f32_e32 vcc, s71, v32
	s_nop 1
	v_cndmask_b32_e32 v32, v32, v33, vcc
	v_rsq_f32_e32 v34, v32
	v_lshlrev_b64 v[32:33], 6, v[48:49]
	v_lshl_add_u64 v[32:33], s[26:27], 0, v[32:33]
	v_mul_f32_e32 v35, 0x45800000, v34
	v_cndmask_b32_e32 v34, v34, v35, vcc
	v_pk_mul_f32 v[30:31], v[30:31], v[34:35] op_sel_hi:[1,0]
	v_pk_mul_f32 v[28:29], v[28:29], v[34:35] op_sel_hi:[1,0]
	v_pk_mul_f32 v[26:27], v[26:27], v[34:35] op_sel_hi:[1,0]
	v_pk_mul_f32 v[24:25], v[24:25], v[34:35] op_sel_hi:[1,0]
	v_pk_mul_f32 v[18:19], v[18:19], v[34:35] op_sel_hi:[1,0]
	v_pk_mul_f32 v[16:17], v[16:17], v[34:35] op_sel_hi:[1,0]
	v_pk_mul_f32 v[22:23], v[22:23], v[34:35] op_sel_hi:[1,0]
	v_pk_mul_f32 v[20:21], v[20:21], v[34:35] op_sel_hi:[1,0]
	v_max_f32_e32 v28, 0, v28
	v_max_f32_e32 v24, 0, v24
	v_max_f32_e32 v29, 0, v29
	v_max_f32_e32 v25, 0, v25
	v_max_f32_e32 v30, 0, v30
	v_max_f32_e32 v26, 0, v26
	v_max_f32_e32 v31, 0, v31
	v_max_f32_e32 v27, 0, v27
	v_max_f32_e32 v16, 0, v16
	v_max_f32_e32 v17, 0, v17
	v_max_f32_e32 v18, 0, v18
	v_max_f32_e32 v19, 0, v19
	v_max_f32_e32 v20, 0, v20
	v_max_f32_e32 v21, 0, v21
	v_max_f32_e32 v22, 0, v22
	v_max_f32_e32 v23, 0, v23
	v_pk_mul_f32 v[28:29], v[28:29], v[28:29]
	v_pk_mul_f32 v[24:25], v[24:25], v[24:25]
	v_pk_mul_f32 v[30:31], v[30:31], v[30:31]
	v_pk_mul_f32 v[26:27], v[26:27], v[26:27]
	v_pk_mul_f32 v[34:35], v[16:17], v[16:17]
	v_pk_mul_f32 v[36:37], v[18:19], v[18:19]
	v_cvt_pk_bf16_f32 v16, v28, v29
	v_cvt_pk_bf16_f32 v17, v30, v31
	v_cvt_pk_bf16_f32 v18, v24, v25
	v_cvt_pk_bf16_f32 v19, v26, v27
	v_pk_mul_f32 v[20:21], v[20:21], v[20:21]
	v_pk_mul_f32 v[22:23], v[22:23], v[22:23]
	buffer_store_dwordx4 v[16:19], v52, s[16:19], 0 offen sc1
	s_nop 1
	v_cvt_pk_bf16_f32 v16, v20, v21
	v_cvt_pk_bf16_f32 v17, v22, v23
	v_cvt_pk_bf16_f32 v18, v34, v35
	v_cvt_pk_bf16_f32 v19, v36, v37
	buffer_store_dwordx4 v[16:19], v52, s[16:19], 0 offen offset:256 sc1
	s_nop 0
	s_waitcnt vmcnt(6)
	s_nop 0
	s_nop 0
	v_pk_add_f32 v[16:17], v[236:237], v[238:239]
	v_pk_add_f32 v[18:19], v[240:241], v[242:243]
	v_pk_add_f32 v[20:21], v[244:245], v[246:247]
	v_pk_add_f32 v[22:23], v[248:249], v[250:251]
	v_pk_add_f32 v[16:17], v[16:17], v[18:19]
	v_pk_add_f32 v[20:21], v[20:21], v[22:23]
	v_pk_add_f32 v[16:17], v[16:17], v[20:21]
	v_add_f32_e32 v16, v16, v17
	v_fmamk_f32 v16, v16, 0x3a800000, v154
	v_mul_f32_e32 v17, 0x4b800000, v16
	v_cmp_gt_f32_e32 vcc, s71, v16
	s_nop 1
	v_cndmask_b32_e32 v16, v16, v17, vcc
	v_rsq_f32_e32 v16, v16
	v_lshl_add_u32 v17, v48, 13, v147
	v_mul_f32_e32 v18, 0x45800000, v16
	v_cndmask_b32_e32 v16, v16, v18, vcc
	v_pk_mul_f32 v[14:15], v[14:15], v[16:17] op_sel_hi:[1,0]
	v_pk_mul_f32 v[12:13], v[12:13], v[16:17] op_sel_hi:[1,0]
	v_pk_mul_f32 v[10:11], v[10:11], v[16:17] op_sel_hi:[1,0]
	v_pk_mul_f32 v[8:9], v[8:9], v[16:17] op_sel_hi:[1,0]
	v_pk_mul_f32 v[2:3], v[2:3], v[16:17] op_sel_hi:[1,0]
	v_pk_mul_f32 v[0:1], v[0:1], v[16:17] op_sel_hi:[1,0]
	v_pk_mul_f32 v[6:7], v[6:7], v[16:17] op_sel_hi:[1,0]
	v_pk_mul_f32 v[4:5], v[4:5], v[16:17] op_sel_hi:[1,0]
	v_max_f32_e32 v12, 0, v12
	v_max_f32_e32 v8, 0, v8
	v_max_f32_e32 v13, 0, v13
	v_max_f32_e32 v9, 0, v9
	v_max_f32_e32 v14, 0, v14
	v_max_f32_e32 v10, 0, v10
	v_max_f32_e32 v15, 0, v15
	v_max_f32_e32 v11, 0, v11
	v_max_f32_e32 v0, 0, v0
	v_max_f32_e32 v1, 0, v1
	v_max_f32_e32 v2, 0, v2
	v_max_f32_e32 v3, 0, v3
	v_max_f32_e32 v4, 0, v4
	v_max_f32_e32 v5, 0, v5
	v_max_f32_e32 v6, 0, v6
	v_max_f32_e32 v7, 0, v7
	v_pk_mul_f32 v[12:13], v[12:13], v[12:13]
	v_pk_mul_f32 v[8:9], v[8:9], v[8:9]
	v_pk_mul_f32 v[14:15], v[14:15], v[14:15]
	v_pk_mul_f32 v[10:11], v[10:11], v[10:11]
	v_mul_f32_e32 v16, v0, v0
	v_mul_f32_e32 v18, v1, v1
	v_mul_f32_e32 v19, v2, v2
	v_mul_f32_e32 v20, v3, v3
	v_cvt_pk_bf16_f32 v0, v12, v13
	v_cvt_pk_bf16_f32 v1, v14, v15
	v_cvt_pk_bf16_f32 v2, v8, v9
	v_cvt_pk_bf16_f32 v3, v10, v11
	v_pk_mul_f32 v[4:5], v[4:5], v[4:5]
	v_pk_mul_f32 v[6:7], v[6:7], v[6:7]
	buffer_store_dwordx4 v[0:3], v17, s[16:19], 0 offen sc1
	s_nop 1
	v_cvt_pk_bf16_f32 v0, v4, v5
	v_cvt_pk_bf16_f32 v1, v6, v7
	v_cvt_pk_bf16_f32 v2, v16, v18
	v_cvt_pk_bf16_f32 v3, v19, v20
	buffer_store_dwordx4 v[0:3], v17, s[16:19], 0 offen offset:256 sc1
	s_waitcnt vmcnt(0)
	s_and_saveexec_b64 s[40:41], s[10:11]
	s_cbranch_execz .LBB0_950
	s_mov_b64 s[54:55], exec
	v_mbcnt_lo_u32_b32 v0, s54, 0
	v_mbcnt_hi_u32_b32 v0, s55, v0
	v_cmp_eq_u32_e32 vcc, 0, v0
	s_and_b64 s[6:7], exec, vcc
	s_mov_b64 exec, s[6:7]
	s_cbranch_execz .LBB0_950
	s_lshl_b32 s6, s75, 6
	s_ashr_i32 s7, s6, 31
	s_lshl_b64 s[6:7], s[6:7], 2
	s_add_u32 s6, s73, s6
	s_addc_u32 s7, s74, s7
	s_bcnt1_i32_b64 s8, s[54:55]
	v_mov_b32_e32 v0, s8
	global_atomic_add v131, v0, s[6:7]
	s_branch .LBB0_950

; #define PG8_STAGE(bufoff, gbase, voff) do { _Pragma("unroll") for (int _i = 0; _i < 2; ++_i) \
;         __builtin_amdgcn_global_load_lds((const unsigned*)((const char*)(gbase) + (voff)[_i]), (LAS unsigned*)(lds + (bufoff) + ldsw + _i * 8192), 16, 0, 0); } while (0)
; #define PG8_LDA(dst, b, h) do { _Pragma("unroll") for (int m = 0; m < 4; ++m) _Pragma("unroll") for (int k = 0; k < 2; ++k) dst[m][k] = *(const LAS bf16x8*)(lds + PG8_SA(b, h) + aoff + m * 2048 + k * 1024); } while (0)
; #define PG8_LDB(dst, b, h) do { _Pragma("unroll") for (int n = 0; n < 2; ++n) _Pragma("unroll") for (int k = 0; k < 2; ++k) dst[n][k] = *(const LAS bf16x8*)(lds + PG8_SB(b, h) + boff + n * 2048 + k * 1024); } while (0)
; #define PG8_MMA(ai, bj, At, Bt) do { __builtin_amdgcn_s_setprio(1); _Pragma("unroll") for (int m = 0; m < 4; ++m) _Pragma("unroll") for (int n = 0; n < 2; ++n) _Pragma("unroll") for (int k = 0; k < 2; ++k) \
;         acc[ai][bj][m][n] = __builtin_amdgcn_mfma_f32_16x16x32_bf16(Bt[n][k], At[m][k], acc[ai][bj][m][n], 0, 0, 0); __builtin_amdgcn_s_setprio(0); } while (0)
; #define PG8_WAIT_L(n) asm volatile("s_waitcnt lgkmcnt(" #n ")" ::: "memory")
; #define PG8_BAR __builtin_amdgcn_s_barrier()
; #define PG8_SCHED __builtin_amdgcn_sched_barrier(0)
;     ...
;             PG8_LDB(B0, 0, 0); PG8_SCHED; PG8_LDA(At, 0, 0); PG8_STAGE(PG8_SA(1, 1), a1 + hA, voffA);
;             PG8_WAIT_L(8); PG8_BAR; PG8_WAIT_L(0); PG8_MMA(0, 0, At, B0); PG8_BAR; PG8_SCHED;
;             PG8_LDB(B1, 0, 1); PG8_STAGE(PG8_SB(0, 0), b2, voffB);
;             PG8_BAR; PG8_WAIT_L(0); PG8_MMA(0, 1, At, B1); PG8_BAR;
;             PG8_LDA(At, 0, 1); PG8_STAGE(PG8_SA(0, 0), a2, voffA);
;             PG8_BAR; PG8_WAIT_L(0); PG8_MMA(1, 0, At, B0); PG8_BAR; PG8_SCHED;
.LBB0_981:
	ds_read_b128 v[150:153], v143
	ds_read_b128 v[154:157], v143 offset:1024
	ds_read_b128 v[158:161], v143 offset:2048
	ds_read_b128 v[162:165], v143 offset:3072
	s_add_u32 s40, s38, 0xfffc0080
	s_addc_u32 s41, s39, -1
	s_cmp_eq_u32 s42, 12
	s_cselect_b32 s55, s7, s41
	s_cselect_b32 s54, s8, s40
	s_cselect_b32 s41, s9, s35
	s_cselect_b32 s40, s25, s33
	v_lshl_add_u64 v[202:203], s[38:39], 0, v[138:139]
	s_add_i32 m0, s61, 0xc000
	ds_read_b128 v[170:173], v146
	ds_read_b128 v[174:177], v146 offset:1024
	ds_read_b128 v[178:181], v146 offset:2048
	ds_read_b128 v[182:185], v146 offset:3072
	ds_read_b128 v[186:189], v146 offset:4096
	ds_read_b128 v[190:193], v146 offset:5120
	ds_read_b128 v[194:197], v146 offset:6144
	ds_read_b128 v[198:201], v146 offset:7168
	global_load_lds_dwordx4 v[202:203], off
	v_lshl_add_u64 v[202:203], s[38:39], 0, v[136:137]
	s_add_i32 m0, s61, 0xe000
	s_nop 0
	global_load_lds_dwordx4 v[202:203], off
	s_waitcnt lgkmcnt(8)
	s_barrier
	s_waitcnt lgkmcnt(0)
	s_setprio 1
	s_waitcnt lgkmcnt(0)
	v_mfma_f32_16x16x32_bf16 v[124:127], v[150:153], v[170:173], v[124:127]
	v_mfma_f32_16x16x32_bf16 v[120:123], v[158:161], v[170:173], v[120:123]
	v_mfma_f32_16x16x32_bf16 v[108:111], v[150:153], v[178:181], v[108:111]
	v_mfma_f32_16x16x32_bf16 v[104:107], v[158:161], v[178:181], v[104:107]
	v_mfma_f32_16x16x32_bf16 v[92:95], v[150:153], v[186:189], v[92:95]
	v_mfma_f32_16x16x32_bf16 v[88:91], v[158:161], v[186:189], v[88:91]
	v_mfma_f32_16x16x32_bf16 v[76:79], v[150:153], v[194:197], v[76:79]
	v_mfma_f32_16x16x32_bf16 v[72:75], v[158:161], v[194:197], v[72:75]
	v_mfma_f32_16x16x32_bf16 v[124:127], v[154:157], v[174:177], v[124:127]
	v_mfma_f32_16x16x32_bf16 v[120:123], v[162:165], v[174:177], v[120:123]
	v_mfma_f32_16x16x32_bf16 v[108:111], v[154:157], v[182:185], v[108:111]
	v_mfma_f32_16x16x32_bf16 v[104:107], v[162:165], v[182:185], v[104:107]
	v_mfma_f32_16x16x32_bf16 v[92:95], v[154:157], v[190:193], v[92:95]
	v_mfma_f32_16x16x32_bf16 v[88:91], v[162:165], v[190:193], v[88:91]
	v_mfma_f32_16x16x32_bf16 v[76:79], v[154:157], v[198:201], v[76:79]
	v_mfma_f32_16x16x32_bf16 v[72:75], v[162:165], v[198:201], v[72:75]
	s_setprio 0
	s_barrier
	s_add_i32 s43, s69, s60
	v_lshl_add_u64 v[218:219], s[40:41], 0, v[130:131]
	s_mov_b32 m0, s43
	ds_read_b128 v[202:205], v147
	ds_read_b128 v[206:209], v147 offset:1024
	ds_read_b128 v[210:213], v147 offset:2048
	ds_read_b128 v[214:217], v147 offset:3072
	global_load_lds_dwordx4 v[218:219], off
	v_lshl_add_u64 v[220:221], s[40:41], 0, v[134:135]
	s_add_i32 m0, s43, 0x2000
	s_nop 0
	global_load_lds_dwordx4 v[220:221], off
	s_barrier
	s_waitcnt lgkmcnt(0)
	s_setprio 1
	s_waitcnt lgkmcnt(0)
	v_mfma_f32_16x16x32_bf16 v[116:119], v[202:205], v[170:173], v[116:119]
	v_mfma_f32_16x16x32_bf16 v[112:115], v[210:213], v[170:173], v[112:115]
	v_mfma_f32_16x16x32_bf16 v[100:103], v[202:205], v[178:181], v[100:103]
	v_mfma_f32_16x16x32_bf16 v[96:99], v[210:213], v[178:181], v[96:99]
	v_mfma_f32_16x16x32_bf16 v[84:87], v[202:205], v[186:189], v[84:87]
	v_mfma_f32_16x16x32_bf16 v[80:83], v[210:213], v[186:189], v[80:83]
	v_mfma_f32_16x16x32_bf16 v[68:71], v[202:205], v[194:197], v[68:71]
	v_mfma_f32_16x16x32_bf16 v[64:67], v[210:213], v[194:197], v[64:67]
	v_mfma_f32_16x16x32_bf16 v[116:119], v[206:209], v[174:177], v[116:119]
	v_mfma_f32_16x16x32_bf16 v[112:115], v[214:217], v[174:177], v[112:115]
	v_mfma_f32_16x16x32_bf16 v[100:103], v[206:209], v[182:185], v[100:103]
	v_mfma_f32_16x16x32_bf16 v[96:99], v[214:217], v[182:185], v[96:99]
	v_mfma_f32_16x16x32_bf16 v[84:87], v[206:209], v[190:193], v[84:87]
	v_mfma_f32_16x16x32_bf16 v[80:83], v[214:217], v[190:193], v[80:83]
	v_mfma_f32_16x16x32_bf16 v[68:71], v[206:209], v[198:201], v[68:71]
	v_mfma_f32_16x16x32_bf16 v[64:67], v[214:217], v[198:201], v[64:67]
	s_setprio 0
	s_mov_b32 m0, s61
	v_lshl_add_u64 v[222:223], s[54:55], 0, v[128:129]
	s_barrier
	ds_read_b128 v[170:173], v146 offset:16384
	ds_read_b128 v[174:177], v146 offset:17408
	ds_read_b128 v[178:181], v146 offset:18432
	ds_read_b128 v[182:185], v146 offset:19456
	ds_read_b128 v[186:189], v146 offset:20480
	ds_read_b128 v[190:193], v146 offset:21504
	ds_read_b128 v[194:197], v146 offset:22528
	ds_read_b128 v[198:201], v146 offset:23552
	global_load_lds_dwordx4 v[222:223], off
	v_lshl_add_u64 v[224:225], s[54:55], 0, v[132:133]
	s_mov_b32 m0, s62
	s_nop 0
	global_load_lds_dwordx4 v[224:225], off
	s_barrier
	s_waitcnt lgkmcnt(0)
	s_setprio 1
	s_waitcnt lgkmcnt(0)
	v_mfma_f32_16x16x32_bf16 v[60:63], v[150:153], v[170:173], v[60:63]
	v_mfma_f32_16x16x32_bf16 v[56:59], v[158:161], v[170:173], v[56:59]
	v_mfma_f32_16x16x32_bf16 v[44:47], v[150:153], v[178:181], v[44:47]
	v_mfma_f32_16x16x32_bf16 v[40:43], v[158:161], v[178:181], v[40:43]
	v_mfma_f32_16x16x32_bf16 v[28:31], v[150:153], v[186:189], v[28:31]
	v_mfma_f32_16x16x32_bf16 v[24:27], v[158:161], v[186:189], v[24:27]
	v_mfma_f32_16x16x32_bf16 v[12:15], v[150:153], v[194:197], v[12:15]
	v_mfma_f32_16x16x32_bf16 v[8:11], v[158:161], v[194:197], v[8:11]
	v_mfma_f32_16x16x32_bf16 v[60:63], v[154:157], v[174:177], v[60:63]
	v_mfma_f32_16x16x32_bf16 v[56:59], v[162:165], v[174:177], v[56:59]
	v_mfma_f32_16x16x32_bf16 v[44:47], v[154:157], v[182:185], v[44:47]
	v_mfma_f32_16x16x32_bf16 v[40:43], v[162:165], v[182:185], v[40:43]
	v_mfma_f32_16x16x32_bf16 v[28:31], v[154:157], v[190:193], v[28:31]
	v_mfma_f32_16x16x32_bf16 v[24:27], v[162:165], v[190:193], v[24:27]
	v_mfma_f32_16x16x32_bf16 v[12:15], v[154:157], v[198:201], v[12:15]
	v_mfma_f32_16x16x32_bf16 v[8:11], v[162:165], v[198:201], v[8:11]
	s_setprio 0
	s_barrier
; #define PG8_STAGE(bufoff, gbase, voff) do { _Pragma("unroll") for (int _i = 0; _i < 2; ++_i) \
;         __builtin_amdgcn_global_load_lds((const unsigned*)((const char*)(gbase) + (voff)[_i]), (LAS unsigned*)(lds + (bufoff) + ldsw + _i * 8192), 16, 0, 0); } while (0)
; #define PG8_LDA(dst, b, h) do { _Pragma("unroll") for (int m = 0; m < 4; ++m) _Pragma("unroll") for (int k = 0; k < 2; ++k) dst[m][k] = *(const LAS bf16x8*)(lds + PG8_SA(b, h) + aoff + m * 2048 + k * 1024); } while (0)
; #define PG8_LDB(dst, b, h) do { _Pragma("unroll") for (int n = 0; n < 2; ++n) _Pragma("unroll") for (int k = 0; k < 2; ++k) dst[n][k] = *(const LAS bf16x8*)(lds + PG8_SB(b, h) + boff + n * 2048 + k * 1024); } while (0)
; #define PG8_MMA(ai, bj, At, Bt) do { __builtin_amdgcn_s_setprio(1); _Pragma("unroll") for (int m = 0; m < 4; ++m) _Pragma("unroll") for (int n = 0; n < 2; ++n) _Pragma("unroll") for (int k = 0; k < 2; ++k) \
;         acc[ai][bj][m][n] = __builtin_amdgcn_mfma_f32_16x16x32_bf16(Bt[n][k], At[m][k], acc[ai][bj][m][n], 0, 0, 0); __builtin_amdgcn_s_setprio(0); } while (0)
; #define PG8_WAIT_V(n) asm volatile("s_waitcnt vmcnt(" #n ")" ::: "memory")
; #define PG8_WAIT_L(n) asm volatile("s_waitcnt lgkmcnt(" #n ")" ::: "memory")
; #define PG8_BAR __builtin_amdgcn_s_barrier()
; #define PG8_SCHED __builtin_amdgcn_sched_barrier(0)
;     ...
;             PG8_BAR; PG8_WAIT_L(0); PG8_MMA(1, 0, At, B0); PG8_BAR; PG8_SCHED;
;             PG8_STAGE(PG8_SB(0, 1), b2 + hB, voffB);
;             PG8_WAIT_V(6); PG8_BAR; PG8_MMA(1, 1, At, B1); PG8_BAR;
;             PG8_LDB(B0, 1, 0); PG8_SCHED; PG8_LDA(At, 1, 0); PG8_STAGE(PG8_SA(0, 1), a2 + hA, voffA);
;             PG8_WAIT_L(8); PG8_BAR; PG8_WAIT_L(0); PG8_MMA(0, 0, At, B0); PG8_BAR; PG8_SCHED;
;             PG8_LDB(B1, 1, 1); PG8_STAGE(PG8_SB(1, 0), b3, voffB);
;             PG8_BAR; PG8_WAIT_L(0); PG8_MMA(0, 1, At, B1); PG8_BAR;
;             PG8_LDA(At, 1, 1); PG8_STAGE(PG8_SA(1, 0), a3, voffA);
	s_add_u32 s44, s40, 0x40000
	s_addc_u32 s45, s41, 0
	s_add_i32 s43, s70, s60
	v_lshl_add_u64 v[150:151], s[44:45], 0, v[130:131]
	s_mov_b32 m0, s43
	s_nop 0
	global_load_lds_dwordx4 v[150:151], off
	v_lshl_add_u64 v[150:151], s[44:45], 0, v[134:135]
	s_add_i32 m0, s43, 0x2000
	s_nop 0
	global_load_lds_dwordx4 v[150:151], off
	s_waitcnt vmcnt(6)
	s_barrier
	s_setprio 1
	v_mfma_f32_16x16x32_bf16 v[52:55], v[202:205], v[170:173], v[52:55]
	v_mfma_f32_16x16x32_bf16 v[48:51], v[210:213], v[170:173], v[48:51]
	v_mfma_f32_16x16x32_bf16 v[36:39], v[202:205], v[178:181], v[36:39]
	v_mfma_f32_16x16x32_bf16 v[32:35], v[210:213], v[178:181], v[32:35]
	v_mfma_f32_16x16x32_bf16 v[20:23], v[202:205], v[186:189], v[20:23]
	v_mfma_f32_16x16x32_bf16 v[16:19], v[210:213], v[186:189], v[16:19]
	v_mfma_f32_16x16x32_bf16 v[4:7], v[202:205], v[194:197], v[4:7]
	v_mfma_f32_16x16x32_bf16 v[0:3], v[210:213], v[194:197], v[0:3]
	v_mfma_f32_16x16x32_bf16 v[52:55], v[206:209], v[174:177], v[52:55]
	v_mfma_f32_16x16x32_bf16 v[48:51], v[214:217], v[174:177], v[48:51]
	v_mfma_f32_16x16x32_bf16 v[36:39], v[206:209], v[182:185], v[36:39]
	v_mfma_f32_16x16x32_bf16 v[32:35], v[214:217], v[182:185], v[32:35]
	v_mfma_f32_16x16x32_bf16 v[20:23], v[206:209], v[190:193], v[20:23]
	v_mfma_f32_16x16x32_bf16 v[16:19], v[214:217], v[190:193], v[16:19]
	v_mfma_f32_16x16x32_bf16 v[4:7], v[206:209], v[198:201], v[4:7]
	v_mfma_f32_16x16x32_bf16 v[0:3], v[214:217], v[198:201], v[0:3]
	s_setprio 0
	s_add_i32 s43, 0, 0x18000
	v_add_u32_e32 v149, s43, v141
	s_barrier
	ds_read_b128 v[150:153], v149
	ds_read_b128 v[154:157], v149 offset:1024
	ds_read_b128 v[158:161], v149 offset:2048
	ds_read_b128 v[162:165], v149 offset:3072
	s_add_u32 s44, s54, 0x40000
	s_addc_u32 s45, s55, 0
	s_mov_b32 m0, s63
	v_lshl_add_u64 v[202:203], s[44:45], 0, v[128:129]
	ds_read_b128 v[170:173], v146 offset:32768
	ds_read_b128 v[174:177], v146 offset:33792
	ds_read_b128 v[178:181], v146 offset:34816
	ds_read_b128 v[182:185], v146 offset:35840
	ds_read_b128 v[186:189], v146 offset:36864
	ds_read_b128 v[190:193], v146 offset:37888
	ds_read_b128 v[194:197], v146 offset:38912
	ds_read_b128 v[198:201], v146 offset:39936
	global_load_lds_dwordx4 v[202:203], off
	v_lshl_add_u64 v[202:203], s[44:45], 0, v[132:133]
	s_mov_b32 m0, s64
	s_nop 0
	global_load_lds_dwordx4 v[202:203], off
	s_waitcnt lgkmcnt(8)
	s_barrier
	s_waitcnt lgkmcnt(0)
	s_setprio 1
	s_waitcnt lgkmcnt(0)
	v_mfma_f32_16x16x32_bf16 v[124:127], v[150:153], v[170:173], v[124:127]
	v_mfma_f32_16x16x32_bf16 v[120:123], v[158:161], v[170:173], v[120:123]
	v_mfma_f32_16x16x32_bf16 v[108:111], v[150:153], v[178:181], v[108:111]
	v_mfma_f32_16x16x32_bf16 v[104:107], v[158:161], v[178:181], v[104:107]
	v_mfma_f32_16x16x32_bf16 v[92:95], v[150:153], v[186:189], v[92:95]
	v_mfma_f32_16x16x32_bf16 v[88:91], v[158:161], v[186:189], v[88:91]
	v_mfma_f32_16x16x32_bf16 v[76:79], v[150:153], v[194:197], v[76:79]
	v_mfma_f32_16x16x32_bf16 v[72:75], v[158:161], v[194:197], v[72:75]
	v_mfma_f32_16x16x32_bf16 v[124:127], v[154:157], v[174:177], v[124:127]
	v_mfma_f32_16x16x32_bf16 v[120:123], v[162:165], v[174:177], v[120:123]
	v_mfma_f32_16x16x32_bf16 v[108:111], v[154:157], v[182:185], v[108:111]
	v_mfma_f32_16x16x32_bf16 v[104:107], v[162:165], v[182:185], v[104:107]
	v_mfma_f32_16x16x32_bf16 v[92:95], v[154:157], v[190:193], v[92:95]
	v_mfma_f32_16x16x32_bf16 v[88:91], v[162:165], v[190:193], v[88:91]
	v_mfma_f32_16x16x32_bf16 v[76:79], v[154:157], v[198:201], v[76:79]
	v_mfma_f32_16x16x32_bf16 v[72:75], v[162:165], v[198:201], v[72:75]
	s_setprio 0
	s_barrier
	s_add_i32 s44, 0, 0x1c000
	s_add_i32 s43, s43, s60
	v_add_u32_e32 v149, s44, v141
	v_lshl_add_u64 v[218:219], v[218:219], 0, s[26:27]
	s_mov_b32 m0, s43
	ds_read_b128 v[202:205], v149
	ds_read_b128 v[206:209], v149 offset:1024
	ds_read_b128 v[210:213], v149 offset:2048
	ds_read_b128 v[214:217], v149 offset:3072
	global_load_lds_dwordx4 v[218:219], off
	v_lshl_add_u64 v[218:219], v[220:221], 0, s[26:27]
	s_add_i32 m0, s43, 0x2000
	s_nop 0
	global_load_lds_dwordx4 v[218:219], off
	s_barrier
	s_waitcnt lgkmcnt(0)
	s_setprio 1
	s_waitcnt lgkmcnt(0)
	v_mfma_f32_16x16x32_bf16 v[116:119], v[202:205], v[170:173], v[116:119]
	v_mfma_f32_16x16x32_bf16 v[112:115], v[210:213], v[170:173], v[112:115]
	v_mfma_f32_16x16x32_bf16 v[100:103], v[202:205], v[178:181], v[100:103]
	v_mfma_f32_16x16x32_bf16 v[96:99], v[210:213], v[178:181], v[96:99]
	v_mfma_f32_16x16x32_bf16 v[84:87], v[202:205], v[186:189], v[84:87]
	v_mfma_f32_16x16x32_bf16 v[80:83], v[210:213], v[186:189], v[80:83]
	v_mfma_f32_16x16x32_bf16 v[68:71], v[202:205], v[194:197], v[68:71]
	v_mfma_f32_16x16x32_bf16 v[64:67], v[210:213], v[194:197], v[64:67]
	v_mfma_f32_16x16x32_bf16 v[116:119], v[206:209], v[174:177], v[116:119]
	v_mfma_f32_16x16x32_bf16 v[112:115], v[214:217], v[174:177], v[112:115]
	v_mfma_f32_16x16x32_bf16 v[100:103], v[206:209], v[182:185], v[100:103]
	v_mfma_f32_16x16x32_bf16 v[96:99], v[214:217], v[182:185], v[96:99]
	v_mfma_f32_16x16x32_bf16 v[84:87], v[206:209], v[190:193], v[84:87]
	v_mfma_f32_16x16x32_bf16 v[80:83], v[214:217], v[190:193], v[80:83]
	v_mfma_f32_16x16x32_bf16 v[68:71], v[206:209], v[198:201], v[68:71]
	v_mfma_f32_16x16x32_bf16 v[64:67], v[214:217], v[198:201], v[64:67]
	s_setprio 0
	s_mov_b32 m0, s66
	v_lshl_add_u64 v[218:219], v[222:223], 0, s[26:27]
	s_barrier
	ds_read_b128 v[170:173], v146 offset:49152
	ds_read_b128 v[174:177], v146 offset:50176
	ds_read_b128 v[178:181], v146 offset:51200
	ds_read_b128 v[182:185], v146 offset:52224
	ds_read_b128 v[186:189], v146 offset:53248
	ds_read_b128 v[190:193], v146 offset:54272
	ds_read_b128 v[194:197], v146 offset:55296
	ds_read_b128 v[198:201], v146 offset:56320
	global_load_lds_dwordx4 v[218:219], off
	v_lshl_add_u64 v[218:219], v[224:225], 0, s[26:27]
	s_mov_b32 m0, s67
	s_nop 0
	global_load_lds_dwordx4 v[218:219], off
	s_barrier
; #define PG8_STAGE(bufoff, gbase, voff) do { _Pragma("unroll") for (int _i = 0; _i < 2; ++_i) \
;         __builtin_amdgcn_global_load_lds((const unsigned*)((const char*)(gbase) + (voff)[_i]), (LAS unsigned*)(lds + (bufoff) + ldsw + _i * 8192), 16, 0, 0); } while (0)
; #define PG8_LDA(dst, b, h) do { _Pragma("unroll") for (int m = 0; m < 4; ++m) _Pragma("unroll") for (int k = 0; k < 2; ++k) dst[m][k] = *(const LAS bf16x8*)(lds + PG8_SA(b, h) + aoff + m * 2048 + k * 1024); } while (0)
; #define PG8_MMA(ai, bj, At, Bt) do { __builtin_amdgcn_s_setprio(1); _Pragma("unroll") for (int m = 0; m < 4; ++m) _Pragma("unroll") for (int n = 0; n < 2; ++n) _Pragma("unroll") for (int k = 0; k < 2; ++k) \
;         acc[ai][bj][m][n] = __builtin_amdgcn_mfma_f32_16x16x32_bf16(Bt[n][k], At[m][k], acc[ai][bj][m][n], 0, 0, 0); __builtin_amdgcn_s_setprio(0); } while (0)
; #define PG8_WAIT_V(n) asm volatile("s_waitcnt vmcnt(" #n ")" ::: "memory")
; #define PG8_WAIT_L(n) asm volatile("s_waitcnt lgkmcnt(" #n ")" ::: "memory")
; #define PG8_BAR __builtin_amdgcn_s_barrier()
; #define PG8_SCHED __builtin_amdgcn_sched_barrier(0)
;     ...
;             PG8_BAR; PG8_WAIT_L(0); PG8_MMA(0, 1, At, B1); PG8_BAR;
;             PG8_LDA(At, 1, 1); PG8_STAGE(PG8_SA(1, 0), a3, voffA);
;             PG8_BAR; PG8_WAIT_L(0); PG8_MMA(1, 0, At, B0); PG8_BAR; PG8_SCHED;
;             PG8_STAGE(PG8_SB(1, 1), b3 + hB, voffB);
;             PG8_WAIT_V(6); PG8_BAR; PG8_MMA(1, 1, At, B1); PG8_BAR;
;         }
;         E(acc, cur, wr, wc, fr, fq);
; __device__ __forceinline__ float row_rstd(const float* ssq, int row) {
;     const f32x4* p = (const f32x4*)(ssq + (size_t)row * 16);
;     const f32x4 a = p[0], b = p[1], c = p[2], d = p[3];
	s_waitcnt lgkmcnt(0)
	s_setprio 1
	s_waitcnt lgkmcnt(0)
	v_mfma_f32_16x16x32_bf16 v[60:63], v[150:153], v[170:173], v[60:63]
	v_mfma_f32_16x16x32_bf16 v[56:59], v[158:161], v[170:173], v[56:59]
	v_mfma_f32_16x16x32_bf16 v[44:47], v[150:153], v[178:181], v[44:47]
	v_mfma_f32_16x16x32_bf16 v[40:43], v[158:161], v[178:181], v[40:43]
	v_mfma_f32_16x16x32_bf16 v[28:31], v[150:153], v[186:189], v[28:31]
	v_mfma_f32_16x16x32_bf16 v[24:27], v[158:161], v[186:189], v[24:27]
	v_mfma_f32_16x16x32_bf16 v[12:15], v[150:153], v[194:197], v[12:15]
	v_mfma_f32_16x16x32_bf16 v[8:11], v[158:161], v[194:197], v[8:11]
	v_mfma_f32_16x16x32_bf16 v[60:63], v[154:157], v[174:177], v[60:63]
	v_mfma_f32_16x16x32_bf16 v[56:59], v[162:165], v[174:177], v[56:59]
	v_mfma_f32_16x16x32_bf16 v[44:47], v[154:157], v[182:185], v[44:47]
	v_mfma_f32_16x16x32_bf16 v[40:43], v[162:165], v[182:185], v[40:43]
	v_mfma_f32_16x16x32_bf16 v[28:31], v[154:157], v[190:193], v[28:31]
	v_mfma_f32_16x16x32_bf16 v[24:27], v[162:165], v[190:193], v[24:27]
	v_mfma_f32_16x16x32_bf16 v[12:15], v[154:157], v[198:201], v[12:15]
	v_mfma_f32_16x16x32_bf16 v[8:11], v[162:165], v[198:201], v[8:11]
	s_setprio 0
	s_barrier
	s_add_u32 s40, s40, 0x40080
	s_addc_u32 s41, s41, 0
	s_add_i32 s43, s44, s60
	v_lshl_add_u64 v[150:151], s[40:41], 0, v[130:131]
	s_mov_b32 m0, s43
	s_nop 0
	global_load_lds_dwordx4 v[150:151], off
	v_lshl_add_u64 v[150:151], s[40:41], 0, v[134:135]
	s_add_i32 m0, s43, 0x2000
	s_nop 0
	global_load_lds_dwordx4 v[150:151], off
	s_waitcnt vmcnt(6)
	s_barrier
	s_setprio 1
	v_mfma_f32_16x16x32_bf16 v[52:55], v[202:205], v[170:173], v[52:55]
	v_mfma_f32_16x16x32_bf16 v[48:51], v[210:213], v[170:173], v[48:51]
	v_mfma_f32_16x16x32_bf16 v[36:39], v[202:205], v[178:181], v[36:39]
	v_mfma_f32_16x16x32_bf16 v[32:35], v[210:213], v[178:181], v[32:35]
	v_mfma_f32_16x16x32_bf16 v[20:23], v[202:205], v[186:189], v[20:23]
	v_mfma_f32_16x16x32_bf16 v[16:19], v[210:213], v[186:189], v[16:19]
	v_mfma_f32_16x16x32_bf16 v[4:7], v[202:205], v[194:197], v[4:7]
	v_mfma_f32_16x16x32_bf16 v[0:3], v[210:213], v[194:197], v[0:3]
	v_mfma_f32_16x16x32_bf16 v[52:55], v[206:209], v[174:177], v[52:55]
	v_mfma_f32_16x16x32_bf16 v[48:51], v[214:217], v[174:177], v[48:51]
	v_mfma_f32_16x16x32_bf16 v[36:39], v[206:209], v[182:185], v[36:39]
	v_mfma_f32_16x16x32_bf16 v[32:35], v[214:217], v[182:185], v[32:35]
	v_mfma_f32_16x16x32_bf16 v[20:23], v[206:209], v[190:193], v[20:23]
	v_mfma_f32_16x16x32_bf16 v[16:19], v[214:217], v[190:193], v[16:19]
	v_mfma_f32_16x16x32_bf16 v[4:7], v[206:209], v[198:201], v[4:7]
	v_mfma_f32_16x16x32_bf16 v[0:3], v[214:217], v[198:201], v[0:3]
	s_setprio 0
	s_add_i32 s42, s42, 2
	s_add_u32 s33, s33, 0x100
	s_addc_u32 s35, s35, 0
	s_add_u32 s38, s38, 0x100
	s_addc_u32 s39, s39, 0
	s_cmp_gt_u32 s42, 13
	s_barrier
	s_cbranch_scc0 .LBB0_981
	v_lshl_add_u32 v150, s75, 8, v140
	v_add_u32_e32 v164, 0x4000, v150
	v_ashrrev_i32_e32 v165, 31, v164
	v_lshlrev_b64 v[152:153], 6, v[164:165]
	v_lshl_add_u64 v[170:171], s[18:19], 0, v[152:153]
	v_subrev_u32_e32 v176, s18, v170
	v_add_u32_e32 v177, 0x0, v176
	global_load_dwordx4 v[178:181], v177, s[18:19]
	v_add_u32_e32 v177, 0x10, v176
	global_load_dwordx4 v[182:185], v177, s[18:19]
	v_add_u32_e32 v177, 0x20, v176
	global_load_dwordx4 v[186:189], v177, s[18:19]
	v_add_u32_e32 v177, 0x30, v176
	global_load_dwordx4 v[190:193], v177, s[18:19]
	v_add_u32_e32 v177, 0x400, v176
	global_load_dwordx4 v[194:197], v177, s[18:19]
	v_add_u32_e32 v177, 0x410, v176
	global_load_dwordx4 v[198:201], v177, s[18:19]
	v_add_u32_e32 v177, 0x420, v176
	global_load_dwordx4 v[202:205], v177, s[18:19]
	v_add_u32_e32 v177, 0x430, v176
	global_load_dwordx4 v[206:209], v177, s[18:19]
	v_add_u32_e32 v177, 0x800, v176
	global_load_dwordx4 v[210:213], v177, s[18:19]
	v_add_u32_e32 v177, 0x810, v176
	global_load_dwordx4 v[214:217], v177, s[18:19]
	v_add_u32_e32 v177, 0x820, v176
	global_load_dwordx4 v[232:235], v177, s[18:19]
	v_add_u32_e32 v177, 0x830, v176
	global_load_dwordx4 v[236:239], v177, s[18:19]
	v_add_u32_e32 v177, 0xc00, v176
	global_load_dwordx4 v[240:243], v177, s[18:19]
	v_add_u32_e32 v177, 0xc10, v176
	global_load_dwordx4 v[244:247], v177, s[18:19]
	v_add_u32_e32 v177, 0xc20, v176
	global_load_dwordx4 v[248:251], v177, s[18:19]
	v_add_u32_e32 v177, 0xc30, v176
	global_load_dwordx4 v[252:255], v177, s[18:19]
	s_nop 0
	v_lshl_or_b32 v149, s6, 9, v142
	v_lshl_add_u32 v151, v164, 13, v149
	v_add_u32_e32 v174, 0x4010, v150
	v_ashrrev_i32_e32 v175, 31, v174
	s_waitcnt vmcnt(12)
; __device__ __forceinline__ u32x4 pack8(const f32x4 v0, const f32x4 v1) { u32x4 w; w.x = pk2(v0[0], v0[1]); w.y = pk2(v0[2], v0[3]); w.z = pk2(v1[0], v1[1]); w.w = pk2(v1[2], v1[3]); return w; }
; __device__ __forceinline__ float row_rstd(const float* ssq, int row) {
;     const f32x4* p = (const f32x4*)(ssq + (size_t)row * 16);
;     const f32x4 a = p[0], b = p[1], c = p[2], d = p[3];
;     const float s = ((a[0] + a[1]) + (a[2] + a[3])) + ((b[0] + b[1]) + (b[2] + b[3])) + ((c[0] + c[1]) + (c[2] + c[3])) + ((d[0] + d[1]) + (d[2] + d[3]));
;     return rsqrtf(s * (1.0f / 1024.0f) + 1e-6f);
; }
;     __device__ __forceinline__ void operator()(const f32x4 (&acc)[2][2][4][2], const Unit& u, int wr, int wc, int fr, int fq) const {
;     ...
;                 const int row = row0 + ai * 128 + m * 16; const float rs = row_rstd(ssq, row);
; #pragma unroll
;                 for (int bj = 0; bj < 2; ++bj) { f32x4 v0 = acc[ai][bj][m][0] * rs, v1 = acc[ai][bj][m][1] * rs;
; #pragma unroll
;                     for (int j = 0; j < 4; ++j) { const float a = fmaxf(v0[j], 0.f), b = fmaxf(v1[j], 0.f); v0[j] = a * a; v1[j] = b * b; }
;                     __builtin_amdgcn_raw_buffer_store_b128(pack8(v0, v1), rsrc, (unsigned)(((size_t)row * DFF + col0 + bj * 128) * 2), 0, 16  ); }
	s_nop 0
	s_nop 0
	v_pk_add_f32 v[152:153], v[178:179], v[180:181]
	v_pk_add_f32 v[154:155], v[182:183], v[184:185]
	v_pk_add_f32 v[156:157], v[186:187], v[188:189]
	v_pk_add_f32 v[158:159], v[190:191], v[192:193]
	v_pk_add_f32 v[152:153], v[152:153], v[154:155]
	v_pk_add_f32 v[156:157], v[156:157], v[158:159]
	v_pk_add_f32 v[152:153], v[152:153], v[156:157]
	v_add_f32_e32 v152, v152, v153
	v_fmamk_f32 v152, v152, 0x3a800000, v148
	v_mul_f32_e32 v153, 0x4b800000, v152
	v_cmp_gt_f32_e32 vcc, s71, v152
	s_nop 1
	v_cndmask_b32_e32 v152, v152, v153, vcc
	v_rsq_f32_e32 v154, v152
	v_lshlrev_b64 v[152:153], 6, v[174:175]
	v_lshl_add_u64 v[152:153], s[18:19], 0, v[152:153]
	v_mul_f32_e32 v155, 0x45800000, v154
	v_cndmask_b32_e32 v154, v154, v155, vcc
	v_pk_mul_f32 v[126:127], v[126:127], v[154:155] op_sel_hi:[1,0]
	v_pk_mul_f32 v[124:125], v[124:125], v[154:155] op_sel_hi:[1,0]
	v_pk_mul_f32 v[122:123], v[122:123], v[154:155] op_sel_hi:[1,0]
	v_pk_mul_f32 v[120:121], v[120:121], v[154:155] op_sel_hi:[1,0]
	v_pk_mul_f32 v[114:115], v[114:115], v[154:155] op_sel_hi:[1,0]
	v_pk_mul_f32 v[112:113], v[112:113], v[154:155] op_sel_hi:[1,0]
	v_pk_mul_f32 v[118:119], v[118:119], v[154:155] op_sel_hi:[1,0]
	v_pk_mul_f32 v[116:117], v[116:117], v[154:155] op_sel_hi:[1,0]
	v_max_f32_e32 v124, 0, v124
	v_max_f32_e32 v120, 0, v120
	v_max_f32_e32 v125, 0, v125
	v_max_f32_e32 v121, 0, v121
	v_max_f32_e32 v126, 0, v126
	v_max_f32_e32 v122, 0, v122
	v_max_f32_e32 v127, 0, v127
	v_max_f32_e32 v123, 0, v123
	v_max_f32_e32 v112, 0, v112
	v_max_f32_e32 v113, 0, v113
	v_max_f32_e32 v114, 0, v114
	v_max_f32_e32 v115, 0, v115
	v_max_f32_e32 v116, 0, v116
	v_max_f32_e32 v117, 0, v117
	v_max_f32_e32 v118, 0, v118
	v_max_f32_e32 v119, 0, v119
	v_pk_mul_f32 v[124:125], v[124:125], v[124:125]
	v_pk_mul_f32 v[120:121], v[120:121], v[120:121]
	v_pk_mul_f32 v[126:127], v[126:127], v[126:127]
	v_pk_mul_f32 v[122:123], v[122:123], v[122:123]
	v_pk_mul_f32 v[154:155], v[112:113], v[112:113]
	v_pk_mul_f32 v[156:157], v[114:115], v[114:115]
	v_cvt_pk_bf16_f32 v112, v124, v125
	v_cvt_pk_bf16_f32 v113, v126, v127
	v_cvt_pk_bf16_f32 v114, v120, v121
	v_cvt_pk_bf16_f32 v115, v122, v123
	v_pk_mul_f32 v[116:117], v[116:117], v[116:117]
	v_pk_mul_f32 v[118:119], v[118:119], v[118:119]
	buffer_store_dwordx4 v[112:115], v151, s[12:15], 0 offen sc1
	s_nop 1
	v_cvt_pk_bf16_f32 v112, v116, v117
	v_cvt_pk_bf16_f32 v113, v118, v119
	v_cvt_pk_bf16_f32 v114, v154, v155
	v_cvt_pk_bf16_f32 v115, v156, v157
	buffer_store_dwordx4 v[112:115], v151, s[12:15], 0 offen offset:256 sc1
	s_nop 0
	v_add_u32_e32 v152, 0x4020, v150
	v_ashrrev_i32_e32 v153, 31, v152
	v_lshl_add_u32 v151, v174, 13, v149
	v_add_u32_e32 v177, 0x2000, v176
	global_load_dwordx4 v[178:181], v177, s[18:19]
	v_add_u32_e32 v177, 0x2010, v176
	global_load_dwordx4 v[182:185], v177, s[18:19]
	v_add_u32_e32 v177, 0x2020, v176
	global_load_dwordx4 v[186:189], v177, s[18:19]
	v_add_u32_e32 v177, 0x2030, v176
	global_load_dwordx4 v[190:193], v177, s[18:19]
	s_waitcnt vmcnt(14)
	s_nop 0
	s_nop 0
	v_pk_add_f32 v[112:113], v[194:195], v[196:197]
	v_pk_add_f32 v[114:115], v[198:199], v[200:201]
	v_pk_add_f32 v[116:117], v[202:203], v[204:205]
	v_pk_add_f32 v[118:119], v[206:207], v[208:209]
	v_pk_add_f32 v[112:113], v[112:113], v[114:115]
	v_pk_add_f32 v[116:117], v[116:117], v[118:119]
	v_pk_add_f32 v[112:113], v[112:113], v[116:117]
	v_add_f32_e32 v112, v112, v113
	v_fmamk_f32 v112, v112, 0x3a800000, v148
	v_mul_f32_e32 v113, 0x4b800000, v112
	v_cmp_gt_f32_e32 vcc, s71, v112
	s_nop 1
	v_cndmask_b32_e32 v112, v112, v113, vcc
	v_rsq_f32_e32 v114, v112
	v_lshlrev_b64 v[112:113], 6, v[152:153]
	v_lshl_add_u64 v[112:113], s[18:19], 0, v[112:113]
	v_mul_f32_e32 v115, 0x45800000, v114
	v_cndmask_b32_e32 v114, v114, v115, vcc
	v_pk_mul_f32 v[110:111], v[110:111], v[114:115] op_sel_hi:[1,0]
	v_pk_mul_f32 v[108:109], v[108:109], v[114:115] op_sel_hi:[1,0]
	v_pk_mul_f32 v[106:107], v[106:107], v[114:115] op_sel_hi:[1,0]
	v_pk_mul_f32 v[104:105], v[104:105], v[114:115] op_sel_hi:[1,0]
	v_pk_mul_f32 v[98:99], v[98:99], v[114:115] op_sel_hi:[1,0]
	v_pk_mul_f32 v[96:97], v[96:97], v[114:115] op_sel_hi:[1,0]
	v_pk_mul_f32 v[102:103], v[102:103], v[114:115] op_sel_hi:[1,0]
	v_pk_mul_f32 v[100:101], v[100:101], v[114:115] op_sel_hi:[1,0]
	v_max_f32_e32 v108, 0, v108
	v_max_f32_e32 v104, 0, v104
	v_max_f32_e32 v109, 0, v109
	v_max_f32_e32 v105, 0, v105
	v_max_f32_e32 v110, 0, v110
	v_max_f32_e32 v106, 0, v106
	v_max_f32_e32 v111, 0, v111
	v_max_f32_e32 v107, 0, v107
	v_max_f32_e32 v96, 0, v96
	v_max_f32_e32 v97, 0, v97
	v_max_f32_e32 v98, 0, v98
	v_max_f32_e32 v99, 0, v99
	v_max_f32_e32 v100, 0, v100
	v_max_f32_e32 v101, 0, v101
	v_max_f32_e32 v102, 0, v102
	v_max_f32_e32 v103, 0, v103
	v_pk_mul_f32 v[108:109], v[108:109], v[108:109]
	v_pk_mul_f32 v[104:105], v[104:105], v[104:105]
	v_pk_mul_f32 v[110:111], v[110:111], v[110:111]
	v_pk_mul_f32 v[106:107], v[106:107], v[106:107]
	v_pk_mul_f32 v[114:115], v[96:97], v[96:97]
	v_pk_mul_f32 v[116:117], v[98:99], v[98:99]
	v_cvt_pk_bf16_f32 v96, v108, v109
	v_cvt_pk_bf16_f32 v97, v110, v111
	v_cvt_pk_bf16_f32 v98, v104, v105
	v_cvt_pk_bf16_f32 v99, v106, v107
	v_pk_mul_f32 v[100:101], v[100:101], v[100:101]
	v_pk_mul_f32 v[102:103], v[102:103], v[102:103]
	buffer_store_dwordx4 v[96:99], v151, s[12:15], 0 offen sc1
	s_nop 1
	v_cvt_pk_bf16_f32 v96, v100, v101
	v_cvt_pk_bf16_f32 v97, v102, v103
	v_cvt_pk_bf16_f32 v98, v114, v115
	v_cvt_pk_bf16_f32 v99, v116, v117
	buffer_store_dwordx4 v[96:99], v151, s[12:15], 0 offen offset:256 sc1
	s_nop 0
	v_add_u32_e32 v112, 0x4030, v150
	v_ashrrev_i32_e32 v113, 31, v112
	v_lshl_add_u32 v116, v152, 13, v149
	v_add_u32_e32 v177, 0x2400, v176
	global_load_dwordx4 v[194:197], v177, s[18:19]
	v_add_u32_e32 v177, 0x2410, v176
	global_load_dwordx4 v[198:201], v177, s[18:19]
	v_add_u32_e32 v177, 0x2420, v176
	global_load_dwordx4 v[202:205], v177, s[18:19]
	v_add_u32_e32 v177, 0x2430, v176
	global_load_dwordx4 v[206:209], v177, s[18:19]
	s_waitcnt vmcnt(16)
; __device__ __forceinline__ u32x4 pack8(const f32x4 v0, const f32x4 v1) { u32x4 w; w.x = pk2(v0[0], v0[1]); w.y = pk2(v0[2], v0[3]); w.z = pk2(v1[0], v1[1]); w.w = pk2(v1[2], v1[3]); return w; }
; __device__ __forceinline__ float row_rstd(const float* ssq, int row) {
;     const f32x4* p = (const f32x4*)(ssq + (size_t)row * 16);
;     const f32x4 a = p[0], b = p[1], c = p[2], d = p[3];
;     const float s = ((a[0] + a[1]) + (a[2] + a[3])) + ((b[0] + b[1]) + (b[2] + b[3])) + ((c[0] + c[1]) + (c[2] + c[3])) + ((d[0] + d[1]) + (d[2] + d[3]));
;     return rsqrtf(s * (1.0f / 1024.0f) + 1e-6f);
; }
;     __device__ __forceinline__ void operator()(const f32x4 (&acc)[2][2][4][2], const Unit& u, int wr, int wc, int fr, int fq) const {
;     ...
;                 const int row = row0 + ai * 128 + m * 16; const float rs = row_rstd(ssq, row);
; #pragma unroll
;                 for (int bj = 0; bj < 2; ++bj) { f32x4 v0 = acc[ai][bj][m][0] * rs, v1 = acc[ai][bj][m][1] * rs;
; #pragma unroll
;                     for (int j = 0; j < 4; ++j) { const float a = fmaxf(v0[j], 0.f), b = fmaxf(v1[j], 0.f); v0[j] = a * a; v1[j] = b * b; }
;                     __builtin_amdgcn_raw_buffer_store_b128(pack8(v0, v1), rsrc, (unsigned)(((size_t)row * DFF + col0 + bj * 128) * 2), 0, 16  ); }
	s_nop 0
	s_nop 0
	v_pk_add_f32 v[96:97], v[210:211], v[212:213]
	v_pk_add_f32 v[98:99], v[214:215], v[216:217]
	v_pk_add_f32 v[100:101], v[232:233], v[234:235]
	v_pk_add_f32 v[102:103], v[236:237], v[238:239]
	v_pk_add_f32 v[96:97], v[96:97], v[98:99]
	v_pk_add_f32 v[100:101], v[100:101], v[102:103]
	v_pk_add_f32 v[96:97], v[96:97], v[100:101]
	v_add_f32_e32 v96, v96, v97
	v_fmamk_f32 v96, v96, 0x3a800000, v148
	v_mul_f32_e32 v97, 0x4b800000, v96
	v_cmp_gt_f32_e32 vcc, s71, v96
	s_nop 1
	v_cndmask_b32_e32 v96, v96, v97, vcc
	v_rsq_f32_e32 v98, v96
	v_lshlrev_b64 v[96:97], 6, v[112:113]
	v_lshl_add_u64 v[96:97], s[18:19], 0, v[96:97]
	v_mul_f32_e32 v99, 0x45800000, v98
	v_cndmask_b32_e32 v98, v98, v99, vcc
	v_pk_mul_f32 v[94:95], v[94:95], v[98:99] op_sel_hi:[1,0]
	v_pk_mul_f32 v[92:93], v[92:93], v[98:99] op_sel_hi:[1,0]
	v_pk_mul_f32 v[90:91], v[90:91], v[98:99] op_sel_hi:[1,0]
	v_pk_mul_f32 v[88:89], v[88:89], v[98:99] op_sel_hi:[1,0]
	v_pk_mul_f32 v[82:83], v[82:83], v[98:99] op_sel_hi:[1,0]
	v_pk_mul_f32 v[80:81], v[80:81], v[98:99] op_sel_hi:[1,0]
	v_pk_mul_f32 v[86:87], v[86:87], v[98:99] op_sel_hi:[1,0]
	v_pk_mul_f32 v[84:85], v[84:85], v[98:99] op_sel_hi:[1,0]
	v_max_f32_e32 v92, 0, v92
	v_max_f32_e32 v88, 0, v88
	v_max_f32_e32 v93, 0, v93
	v_max_f32_e32 v89, 0, v89
	v_max_f32_e32 v94, 0, v94
	v_max_f32_e32 v90, 0, v90
	v_max_f32_e32 v95, 0, v95
	v_max_f32_e32 v91, 0, v91
	v_max_f32_e32 v80, 0, v80
	v_max_f32_e32 v81, 0, v81
	v_max_f32_e32 v82, 0, v82
	v_max_f32_e32 v83, 0, v83
	v_max_f32_e32 v84, 0, v84
	v_max_f32_e32 v85, 0, v85
	v_max_f32_e32 v86, 0, v86
	v_max_f32_e32 v87, 0, v87
	v_pk_mul_f32 v[92:93], v[92:93], v[92:93]
	v_pk_mul_f32 v[88:89], v[88:89], v[88:89]
	v_pk_mul_f32 v[94:95], v[94:95], v[94:95]
	v_pk_mul_f32 v[90:91], v[90:91], v[90:91]
	v_pk_mul_f32 v[98:99], v[80:81], v[80:81]
	v_pk_mul_f32 v[100:101], v[82:83], v[82:83]
	v_cvt_pk_bf16_f32 v80, v92, v93
	v_cvt_pk_bf16_f32 v81, v94, v95
	v_cvt_pk_bf16_f32 v82, v88, v89
	v_cvt_pk_bf16_f32 v83, v90, v91
	v_pk_mul_f32 v[84:85], v[84:85], v[84:85]
	v_pk_mul_f32 v[86:87], v[86:87], v[86:87]
	buffer_store_dwordx4 v[80:83], v116, s[12:15], 0 offen sc1
	s_nop 1
	v_cvt_pk_bf16_f32 v80, v84, v85
	v_cvt_pk_bf16_f32 v81, v86, v87
	v_cvt_pk_bf16_f32 v82, v98, v99
	v_cvt_pk_bf16_f32 v83, v100, v101
	buffer_store_dwordx4 v[80:83], v116, s[12:15], 0 offen offset:256 sc1
	s_nop 0
	v_add_u32_e32 v96, 0x4080, v150
	v_ashrrev_i32_e32 v97, 31, v96
	v_lshl_add_u32 v100, v112, 13, v149
	v_add_u32_e32 v177, 0x2800, v176
	global_load_dwordx4 v[210:213], v177, s[18:19]
	v_add_u32_e32 v177, 0x2810, v176
	global_load_dwordx4 v[214:217], v177, s[18:19]
	v_add_u32_e32 v177, 0x2820, v176
	global_load_dwordx4 v[232:235], v177, s[18:19]
	v_add_u32_e32 v177, 0x2830, v176
	global_load_dwordx4 v[236:239], v177, s[18:19]
	s_waitcnt vmcnt(18)
	s_nop 0
	s_nop 0
	v_pk_add_f32 v[80:81], v[240:241], v[242:243]
	v_pk_add_f32 v[82:83], v[244:245], v[246:247]
	v_pk_add_f32 v[84:85], v[248:249], v[250:251]
	v_pk_add_f32 v[86:87], v[252:253], v[254:255]
	v_pk_add_f32 v[80:81], v[80:81], v[82:83]
	v_pk_add_f32 v[84:85], v[84:85], v[86:87]
	v_pk_add_f32 v[80:81], v[80:81], v[84:85]
	v_add_f32_e32 v80, v80, v81
	v_fmamk_f32 v80, v80, 0x3a800000, v148
	v_mul_f32_e32 v81, 0x4b800000, v80
	v_cmp_gt_f32_e32 vcc, s71, v80
	s_nop 1
	v_cndmask_b32_e32 v80, v80, v81, vcc
	v_rsq_f32_e32 v82, v80
	v_lshlrev_b64 v[80:81], 6, v[96:97]
	v_lshl_add_u64 v[80:81], s[18:19], 0, v[80:81]
	v_mul_f32_e32 v83, 0x45800000, v82
	v_cndmask_b32_e32 v82, v82, v83, vcc
	v_pk_mul_f32 v[78:79], v[78:79], v[82:83] op_sel_hi:[1,0]
	v_pk_mul_f32 v[76:77], v[76:77], v[82:83] op_sel_hi:[1,0]
	v_pk_mul_f32 v[74:75], v[74:75], v[82:83] op_sel_hi:[1,0]
	v_pk_mul_f32 v[72:73], v[72:73], v[82:83] op_sel_hi:[1,0]
	v_pk_mul_f32 v[66:67], v[66:67], v[82:83] op_sel_hi:[1,0]
	v_pk_mul_f32 v[64:65], v[64:65], v[82:83] op_sel_hi:[1,0]
	v_pk_mul_f32 v[70:71], v[70:71], v[82:83] op_sel_hi:[1,0]
	v_pk_mul_f32 v[68:69], v[68:69], v[82:83] op_sel_hi:[1,0]
	v_max_f32_e32 v76, 0, v76
	v_max_f32_e32 v72, 0, v72
	v_max_f32_e32 v77, 0, v77
	v_max_f32_e32 v73, 0, v73
	v_max_f32_e32 v78, 0, v78
	v_max_f32_e32 v74, 0, v74
	v_max_f32_e32 v79, 0, v79
	v_max_f32_e32 v75, 0, v75
	v_max_f32_e32 v64, 0, v64
	v_max_f32_e32 v65, 0, v65
	v_max_f32_e32 v66, 0, v66
	v_max_f32_e32 v67, 0, v67
	v_max_f32_e32 v68, 0, v68
	v_max_f32_e32 v69, 0, v69
	v_max_f32_e32 v70, 0, v70
	v_max_f32_e32 v71, 0, v71
	v_pk_mul_f32 v[76:77], v[76:77], v[76:77]
	v_pk_mul_f32 v[72:73], v[72:73], v[72:73]
	v_pk_mul_f32 v[78:79], v[78:79], v[78:79]
	v_pk_mul_f32 v[74:75], v[74:75], v[74:75]
	v_pk_mul_f32 v[82:83], v[64:65], v[64:65]
	v_pk_mul_f32 v[84:85], v[66:67], v[66:67]
	v_cvt_pk_bf16_f32 v64, v76, v77
	v_cvt_pk_bf16_f32 v65, v78, v79
	v_cvt_pk_bf16_f32 v66, v72, v73
	v_cvt_pk_bf16_f32 v67, v74, v75
	v_pk_mul_f32 v[68:69], v[68:69], v[68:69]
	v_pk_mul_f32 v[70:71], v[70:71], v[70:71]
	buffer_store_dwordx4 v[64:67], v100, s[12:15], 0 offen sc1
	s_nop 1
	v_cvt_pk_bf16_f32 v64, v68, v69
	v_cvt_pk_bf16_f32 v65, v70, v71
	v_cvt_pk_bf16_f32 v66, v82, v83
	v_cvt_pk_bf16_f32 v67, v84, v85
	buffer_store_dwordx4 v[64:67], v100, s[12:15], 0 offen offset:256 sc1
	s_nop 0
	v_add_u32_e32 v80, 0x4090, v150
	v_ashrrev_i32_e32 v81, 31, v80
	v_lshl_add_u32 v84, v96, 13, v149
	v_add_u32_e32 v177, 0x2c00, v176
	global_load_dwordx4 v[240:243], v177, s[18:19]
	v_add_u32_e32 v177, 0x2c10, v176
	global_load_dwordx4 v[244:247], v177, s[18:19]
	v_add_u32_e32 v177, 0x2c20, v176
	global_load_dwordx4 v[248:251], v177, s[18:19]
	v_add_u32_e32 v177, 0x2c30, v176
	global_load_dwordx4 v[252:255], v177, s[18:19]
	s_waitcnt vmcnt(18)
; __device__ __forceinline__ u32x4 pack8(const f32x4 v0, const f32x4 v1) { u32x4 w; w.x = pk2(v0[0], v0[1]); w.y = pk2(v0[2], v0[3]); w.z = pk2(v1[0], v1[1]); w.w = pk2(v1[2], v1[3]); return w; }
; __device__ __forceinline__ float row_rstd(const float* ssq, int row) {
;     const f32x4* p = (const f32x4*)(ssq + (size_t)row * 16);
;     const f32x4 a = p[0], b = p[1], c = p[2], d = p[3];
;     const float s = ((a[0] + a[1]) + (a[2] + a[3])) + ((b[0] + b[1]) + (b[2] + b[3])) + ((c[0] + c[1]) + (c[2] + c[3])) + ((d[0] + d[1]) + (d[2] + d[3]));
;     return rsqrtf(s * (1.0f / 1024.0f) + 1e-6f);
; }
;     __device__ __forceinline__ void operator()(const f32x4 (&acc)[2][2][4][2], const Unit& u, int wr, int wc, int fr, int fq) const {
;     ...
;                 const int row = row0 + ai * 128 + m * 16; const float rs = row_rstd(ssq, row);
; #pragma unroll
;                 for (int bj = 0; bj < 2; ++bj) { f32x4 v0 = acc[ai][bj][m][0] * rs, v1 = acc[ai][bj][m][1] * rs;
; #pragma unroll
;                     for (int j = 0; j < 4; ++j) { const float a = fmaxf(v0[j], 0.f), b = fmaxf(v1[j], 0.f); v0[j] = a * a; v1[j] = b * b; }
;                     __builtin_amdgcn_raw_buffer_store_b128(pack8(v0, v1), rsrc, (unsigned)(((size_t)row * DFF + col0 + bj * 128) * 2), 0, 16  ); }
	s_nop 0
	s_nop 0
	v_pk_add_f32 v[64:65], v[178:179], v[180:181]
	v_pk_add_f32 v[66:67], v[182:183], v[184:185]
	v_pk_add_f32 v[68:69], v[186:187], v[188:189]
	v_pk_add_f32 v[70:71], v[190:191], v[192:193]
	v_pk_add_f32 v[64:65], v[64:65], v[66:67]
	v_pk_add_f32 v[68:69], v[68:69], v[70:71]
	v_pk_add_f32 v[64:65], v[64:65], v[68:69]
	v_add_f32_e32 v64, v64, v65
	v_fmamk_f32 v64, v64, 0x3a800000, v148
	v_mul_f32_e32 v65, 0x4b800000, v64
	v_cmp_gt_f32_e32 vcc, s71, v64
	s_nop 1
	v_cndmask_b32_e32 v64, v64, v65, vcc
	v_rsq_f32_e32 v66, v64
	v_lshlrev_b64 v[64:65], 6, v[80:81]
	v_lshl_add_u64 v[64:65], s[18:19], 0, v[64:65]
	v_mul_f32_e32 v67, 0x45800000, v66
	v_cndmask_b32_e32 v66, v66, v67, vcc
	v_pk_mul_f32 v[62:63], v[62:63], v[66:67] op_sel_hi:[1,0]
	v_pk_mul_f32 v[60:61], v[60:61], v[66:67] op_sel_hi:[1,0]
	v_pk_mul_f32 v[58:59], v[58:59], v[66:67] op_sel_hi:[1,0]
	v_pk_mul_f32 v[56:57], v[56:57], v[66:67] op_sel_hi:[1,0]
	v_pk_mul_f32 v[50:51], v[50:51], v[66:67] op_sel_hi:[1,0]
	v_pk_mul_f32 v[48:49], v[48:49], v[66:67] op_sel_hi:[1,0]
	v_pk_mul_f32 v[54:55], v[54:55], v[66:67] op_sel_hi:[1,0]
	v_pk_mul_f32 v[52:53], v[52:53], v[66:67] op_sel_hi:[1,0]
	v_max_f32_e32 v60, 0, v60
	v_max_f32_e32 v56, 0, v56
	v_max_f32_e32 v61, 0, v61
	v_max_f32_e32 v57, 0, v57
	v_max_f32_e32 v62, 0, v62
	v_max_f32_e32 v58, 0, v58
	v_max_f32_e32 v63, 0, v63
	v_max_f32_e32 v59, 0, v59
	v_max_f32_e32 v48, 0, v48
	v_max_f32_e32 v49, 0, v49
	v_max_f32_e32 v50, 0, v50
	v_max_f32_e32 v51, 0, v51
	v_max_f32_e32 v52, 0, v52
	v_max_f32_e32 v53, 0, v53
	v_max_f32_e32 v54, 0, v54
	v_max_f32_e32 v55, 0, v55
	v_pk_mul_f32 v[60:61], v[60:61], v[60:61]
	v_pk_mul_f32 v[56:57], v[56:57], v[56:57]
	v_pk_mul_f32 v[62:63], v[62:63], v[62:63]
	v_pk_mul_f32 v[58:59], v[58:59], v[58:59]
	v_pk_mul_f32 v[66:67], v[48:49], v[48:49]
	v_pk_mul_f32 v[68:69], v[50:51], v[50:51]
	v_cvt_pk_bf16_f32 v48, v60, v61
	v_cvt_pk_bf16_f32 v49, v62, v63
	v_cvt_pk_bf16_f32 v50, v56, v57
	v_cvt_pk_bf16_f32 v51, v58, v59
	v_pk_mul_f32 v[52:53], v[52:53], v[52:53]
	v_pk_mul_f32 v[54:55], v[54:55], v[54:55]
	buffer_store_dwordx4 v[48:51], v84, s[12:15], 0 offen sc1
	s_nop 1
	v_cvt_pk_bf16_f32 v48, v52, v53
	v_cvt_pk_bf16_f32 v49, v54, v55
	v_cvt_pk_bf16_f32 v50, v66, v67
	v_cvt_pk_bf16_f32 v51, v68, v69
	buffer_store_dwordx4 v[48:51], v84, s[12:15], 0 offen offset:256 sc1
	s_nop 0
	v_add_u32_e32 v64, 0x40a0, v150
	v_ashrrev_i32_e32 v65, 31, v64
	v_lshl_add_u32 v68, v80, 13, v149
	s_waitcnt vmcnt(14)
	s_nop 0
	s_nop 0
	v_pk_add_f32 v[48:49], v[194:195], v[196:197]
	v_pk_add_f32 v[50:51], v[198:199], v[200:201]
	v_pk_add_f32 v[52:53], v[202:203], v[204:205]
	v_pk_add_f32 v[54:55], v[206:207], v[208:209]
	v_pk_add_f32 v[48:49], v[48:49], v[50:51]
	v_pk_add_f32 v[52:53], v[52:53], v[54:55]
	v_pk_add_f32 v[48:49], v[48:49], v[52:53]
	v_add_f32_e32 v48, v48, v49
	v_fmamk_f32 v48, v48, 0x3a800000, v148
	v_mul_f32_e32 v49, 0x4b800000, v48
	v_cmp_gt_f32_e32 vcc, s71, v48
	s_nop 1
	v_cndmask_b32_e32 v48, v48, v49, vcc
	v_rsq_f32_e32 v50, v48
	v_lshlrev_b64 v[48:49], 6, v[64:65]
	v_lshl_add_u64 v[48:49], s[18:19], 0, v[48:49]
	v_mul_f32_e32 v51, 0x45800000, v50
	v_cndmask_b32_e32 v50, v50, v51, vcc
	v_pk_mul_f32 v[46:47], v[46:47], v[50:51] op_sel_hi:[1,0]
	v_pk_mul_f32 v[44:45], v[44:45], v[50:51] op_sel_hi:[1,0]
	v_pk_mul_f32 v[42:43], v[42:43], v[50:51] op_sel_hi:[1,0]
	v_pk_mul_f32 v[40:41], v[40:41], v[50:51] op_sel_hi:[1,0]
	v_pk_mul_f32 v[34:35], v[34:35], v[50:51] op_sel_hi:[1,0]
	v_pk_mul_f32 v[32:33], v[32:33], v[50:51] op_sel_hi:[1,0]
	v_pk_mul_f32 v[38:39], v[38:39], v[50:51] op_sel_hi:[1,0]
	v_pk_mul_f32 v[36:37], v[36:37], v[50:51] op_sel_hi:[1,0]
	v_max_f32_e32 v44, 0, v44
	v_max_f32_e32 v40, 0, v40
	v_max_f32_e32 v45, 0, v45
	v_max_f32_e32 v41, 0, v41
	v_max_f32_e32 v46, 0, v46
	v_max_f32_e32 v42, 0, v42
	v_max_f32_e32 v47, 0, v47
	v_max_f32_e32 v43, 0, v43
	v_max_f32_e32 v32, 0, v32
	v_max_f32_e32 v33, 0, v33
	v_max_f32_e32 v34, 0, v34
	v_max_f32_e32 v35, 0, v35
	v_max_f32_e32 v36, 0, v36
	v_max_f32_e32 v37, 0, v37
	v_max_f32_e32 v38, 0, v38
	v_max_f32_e32 v39, 0, v39
	v_pk_mul_f32 v[44:45], v[44:45], v[44:45]
	v_pk_mul_f32 v[40:41], v[40:41], v[40:41]
	v_pk_mul_f32 v[46:47], v[46:47], v[46:47]
	v_pk_mul_f32 v[42:43], v[42:43], v[42:43]
	v_pk_mul_f32 v[50:51], v[32:33], v[32:33]
	v_pk_mul_f32 v[52:53], v[34:35], v[34:35]
	v_cvt_pk_bf16_f32 v32, v44, v45
	v_cvt_pk_bf16_f32 v33, v46, v47
	v_cvt_pk_bf16_f32 v34, v40, v41
	v_cvt_pk_bf16_f32 v35, v42, v43
	v_pk_mul_f32 v[36:37], v[36:37], v[36:37]
	v_pk_mul_f32 v[38:39], v[38:39], v[38:39]
	buffer_store_dwordx4 v[32:35], v68, s[12:15], 0 offen sc1
	s_nop 1
	v_cvt_pk_bf16_f32 v32, v36, v37
	v_cvt_pk_bf16_f32 v33, v38, v39
	v_cvt_pk_bf16_f32 v34, v50, v51
	v_cvt_pk_bf16_f32 v35, v52, v53
	buffer_store_dwordx4 v[32:35], v68, s[12:15], 0 offen offset:256 sc1
	s_nop 0
	v_add_u32_e32 v48, 0x40b0, v150
	v_ashrrev_i32_e32 v49, 31, v48
	v_lshl_add_u32 v52, v64, 13, v149
	s_waitcnt vmcnt(10)
; __device__ __forceinline__ u32x4 pack8(const f32x4 v0, const f32x4 v1) { u32x4 w; w.x = pk2(v0[0], v0[1]); w.y = pk2(v0[2], v0[3]); w.z = pk2(v1[0], v1[1]); w.w = pk2(v1[2], v1[3]); return w; }
; __device__ __forceinline__ float row_rstd(const float* ssq, int row) {
;     const f32x4* p = (const f32x4*)(ssq + (size_t)row * 16);
;     const f32x4 a = p[0], b = p[1], c = p[2], d = p[3];
;     const float s = ((a[0] + a[1]) + (a[2] + a[3])) + ((b[0] + b[1]) + (b[2] + b[3])) + ((c[0] + c[1]) + (c[2] + c[3])) + ((d[0] + d[1]) + (d[2] + d[3]));
;     return rsqrtf(s * (1.0f / 1024.0f) + 1e-6f);
; }
;     __device__ __forceinline__ void operator()(const f32x4 (&acc)[2][2][4][2], const Unit& u, int wr, int wc, int fr, int fq) const {
;     ...
;                 const int row = row0 + ai * 128 + m * 16; const float rs = row_rstd(ssq, row);
; #pragma unroll
;                 for (int bj = 0; bj < 2; ++bj) { f32x4 v0 = acc[ai][bj][m][0] * rs, v1 = acc[ai][bj][m][1] * rs;
; #pragma unroll
;                     for (int j = 0; j < 4; ++j) { const float a = fmaxf(v0[j], 0.f), b = fmaxf(v1[j], 0.f); v0[j] = a * a; v1[j] = b * b; }
;                     __builtin_amdgcn_raw_buffer_store_b128(pack8(v0, v1), rsrc, (unsigned)(((size_t)row * DFF + col0 + bj * 128) * 2), 0, 16  ); }
;             }
;         asm volatile("s_waitcnt vmcnt(0)" ::: "memory");
;         if (fr == 0 && fq == 0) (void)__hip_atomic_fetch_add(ready + 64 * (pm_off + u.pm), 1u, __ATOMIC_RELAXED, __HIP_MEMORY_SCOPE_AGENT);
	s_nop 0
	s_nop 0
	v_pk_add_f32 v[32:33], v[210:211], v[212:213]
	v_pk_add_f32 v[34:35], v[214:215], v[216:217]
	v_pk_add_f32 v[36:37], v[232:233], v[234:235]
	v_pk_add_f32 v[38:39], v[236:237], v[238:239]
	v_pk_add_f32 v[32:33], v[32:33], v[34:35]
	v_pk_add_f32 v[36:37], v[36:37], v[38:39]
	v_pk_add_f32 v[32:33], v[32:33], v[36:37]
	v_add_f32_e32 v32, v32, v33
	v_fmamk_f32 v32, v32, 0x3a800000, v148
	v_mul_f32_e32 v33, 0x4b800000, v32
	v_cmp_gt_f32_e32 vcc, s71, v32
	s_nop 1
	v_cndmask_b32_e32 v32, v32, v33, vcc
	v_rsq_f32_e32 v34, v32
	v_lshlrev_b64 v[32:33], 6, v[48:49]
	v_lshl_add_u64 v[32:33], s[18:19], 0, v[32:33]
	v_mul_f32_e32 v35, 0x45800000, v34
	v_cndmask_b32_e32 v34, v34, v35, vcc
	v_pk_mul_f32 v[30:31], v[30:31], v[34:35] op_sel_hi:[1,0]
	v_pk_mul_f32 v[28:29], v[28:29], v[34:35] op_sel_hi:[1,0]
	v_pk_mul_f32 v[26:27], v[26:27], v[34:35] op_sel_hi:[1,0]
	v_pk_mul_f32 v[24:25], v[24:25], v[34:35] op_sel_hi:[1,0]
	v_pk_mul_f32 v[18:19], v[18:19], v[34:35] op_sel_hi:[1,0]
	v_pk_mul_f32 v[16:17], v[16:17], v[34:35] op_sel_hi:[1,0]
	v_pk_mul_f32 v[22:23], v[22:23], v[34:35] op_sel_hi:[1,0]
	v_pk_mul_f32 v[20:21], v[20:21], v[34:35] op_sel_hi:[1,0]
	v_max_f32_e32 v28, 0, v28
	v_max_f32_e32 v24, 0, v24
	v_max_f32_e32 v29, 0, v29
	v_max_f32_e32 v25, 0, v25
	v_max_f32_e32 v30, 0, v30
	v_max_f32_e32 v26, 0, v26
	v_max_f32_e32 v31, 0, v31
	v_max_f32_e32 v27, 0, v27
	v_max_f32_e32 v16, 0, v16
	v_max_f32_e32 v17, 0, v17
	v_max_f32_e32 v18, 0, v18
	v_max_f32_e32 v19, 0, v19
	v_max_f32_e32 v20, 0, v20
	v_max_f32_e32 v21, 0, v21
	v_max_f32_e32 v22, 0, v22
	v_max_f32_e32 v23, 0, v23
	v_pk_mul_f32 v[28:29], v[28:29], v[28:29]
	v_pk_mul_f32 v[24:25], v[24:25], v[24:25]
	v_pk_mul_f32 v[30:31], v[30:31], v[30:31]
	v_pk_mul_f32 v[26:27], v[26:27], v[26:27]
	v_pk_mul_f32 v[34:35], v[16:17], v[16:17]
	v_pk_mul_f32 v[36:37], v[18:19], v[18:19]
	v_cvt_pk_bf16_f32 v16, v28, v29
	v_cvt_pk_bf16_f32 v17, v30, v31
	v_cvt_pk_bf16_f32 v18, v24, v25
	v_cvt_pk_bf16_f32 v19, v26, v27
	v_pk_mul_f32 v[20:21], v[20:21], v[20:21]
	v_pk_mul_f32 v[22:23], v[22:23], v[22:23]
	buffer_store_dwordx4 v[16:19], v52, s[12:15], 0 offen sc1
	s_nop 1
	v_cvt_pk_bf16_f32 v16, v20, v21
	v_cvt_pk_bf16_f32 v17, v22, v23
	v_cvt_pk_bf16_f32 v18, v34, v35
	v_cvt_pk_bf16_f32 v19, v36, v37
	buffer_store_dwordx4 v[16:19], v52, s[12:15], 0 offen offset:256 sc1
	s_nop 0
	s_waitcnt vmcnt(6)
	s_nop 0
	s_nop 0
	v_pk_add_f32 v[16:17], v[240:241], v[242:243]
	v_pk_add_f32 v[18:19], v[244:245], v[246:247]
	v_pk_add_f32 v[20:21], v[248:249], v[250:251]
	v_pk_add_f32 v[22:23], v[252:253], v[254:255]
	v_pk_add_f32 v[16:17], v[16:17], v[18:19]
	v_pk_add_f32 v[20:21], v[20:21], v[22:23]
	v_pk_add_f32 v[16:17], v[16:17], v[20:21]
	v_add_f32_e32 v16, v16, v17
	v_fmamk_f32 v16, v16, 0x3a800000, v148
	v_mul_f32_e32 v17, 0x4b800000, v16
	v_cmp_gt_f32_e32 vcc, s71, v16
	s_nop 1
	v_cndmask_b32_e32 v16, v16, v17, vcc
	v_rsq_f32_e32 v16, v16
	v_lshl_add_u32 v17, v48, 13, v149
	v_mul_f32_e32 v18, 0x45800000, v16
	v_cndmask_b32_e32 v16, v16, v18, vcc
	v_pk_mul_f32 v[14:15], v[14:15], v[16:17] op_sel_hi:[1,0]
	v_pk_mul_f32 v[12:13], v[12:13], v[16:17] op_sel_hi:[1,0]
	v_pk_mul_f32 v[10:11], v[10:11], v[16:17] op_sel_hi:[1,0]
	v_pk_mul_f32 v[8:9], v[8:9], v[16:17] op_sel_hi:[1,0]
	v_pk_mul_f32 v[2:3], v[2:3], v[16:17] op_sel_hi:[1,0]
	v_pk_mul_f32 v[0:1], v[0:1], v[16:17] op_sel_hi:[1,0]
	v_pk_mul_f32 v[6:7], v[6:7], v[16:17] op_sel_hi:[1,0]
	v_pk_mul_f32 v[4:5], v[4:5], v[16:17] op_sel_hi:[1,0]
	v_max_f32_e32 v12, 0, v12
	v_max_f32_e32 v8, 0, v8
	v_max_f32_e32 v13, 0, v13
	v_max_f32_e32 v9, 0, v9
	v_max_f32_e32 v14, 0, v14
	v_max_f32_e32 v10, 0, v10
	v_max_f32_e32 v15, 0, v15
	v_max_f32_e32 v11, 0, v11
	v_max_f32_e32 v0, 0, v0
	v_max_f32_e32 v1, 0, v1
	v_max_f32_e32 v2, 0, v2
	v_max_f32_e32 v3, 0, v3
	v_max_f32_e32 v4, 0, v4
	v_max_f32_e32 v5, 0, v5
	v_max_f32_e32 v6, 0, v6
	v_max_f32_e32 v7, 0, v7
	v_pk_mul_f32 v[12:13], v[12:13], v[12:13]
	v_pk_mul_f32 v[8:9], v[8:9], v[8:9]
	v_pk_mul_f32 v[14:15], v[14:15], v[14:15]
	v_pk_mul_f32 v[10:11], v[10:11], v[10:11]
	v_mul_f32_e32 v16, v0, v0
	v_mul_f32_e32 v18, v1, v1
	v_mul_f32_e32 v19, v2, v2
	v_mul_f32_e32 v20, v3, v3
	v_cvt_pk_bf16_f32 v0, v12, v13
	v_cvt_pk_bf16_f32 v1, v14, v15
	v_cvt_pk_bf16_f32 v2, v8, v9
	v_cvt_pk_bf16_f32 v3, v10, v11
	v_pk_mul_f32 v[4:5], v[4:5], v[4:5]
	v_pk_mul_f32 v[6:7], v[6:7], v[6:7]
	buffer_store_dwordx4 v[0:3], v17, s[12:15], 0 offen sc1
	s_nop 1
	v_cvt_pk_bf16_f32 v0, v4, v5
	v_cvt_pk_bf16_f32 v1, v6, v7
	v_cvt_pk_bf16_f32 v2, v16, v18
	v_cvt_pk_bf16_f32 v3, v19, v20
	buffer_store_dwordx4 v[0:3], v17, s[12:15], 0 offen offset:256 sc1
	s_waitcnt vmcnt(0)
	s_and_saveexec_b64 s[38:39], s[10:11]
	s_cbranch_execz .LBB0_973
	s_mov_b64 s[40:41], exec
	v_mbcnt_lo_u32_b32 v0, s40, 0
	v_mbcnt_hi_u32_b32 v0, s41, v0
	v_cmp_eq_u32_e32 vcc, 0, v0
	s_and_b64 s[6:7], exec, vcc
	s_mov_b64 exec, s[6:7]
	s_cbranch_execz .LBB0_973
	s_lshl_b32 s6, s75, 6
	s_addk_i32 s6, 0x1000
	s_ashr_i32 s7, s6, 31
	s_lshl_b64 s[6:7], s[6:7], 2
	s_add_u32 s6, s73, s6
	s_addc_u32 s7, s74, s7
	s_bcnt1_i32_b64 s8, s[40:41]
	v_mov_b32_e32 v0, s8
	global_atomic_add v131, v0, s[6:7]
	s_branch .LBB0_973

; #define PG8_STAGE(bufoff, gbase, voff) do { _Pragma("unroll") for (int _i = 0; _i < 2; ++_i) \
;         __builtin_amdgcn_global_load_lds((const unsigned*)((const char*)(gbase) + (voff)[_i]), (LAS unsigned*)(lds + (bufoff) + ldsw + _i * 8192), 16, 0, 0); } while (0)
; #define PG8_LDA(dst, b, h) do { _Pragma("unroll") for (int m = 0; m < 4; ++m) _Pragma("unroll") for (int k = 0; k < 2; ++k) dst[m][k] = *(const LAS bf16x8*)(lds + PG8_SA(b, h) + aoff + m * 2048 + k * 1024); } while (0)
; #define PG8_LDB(dst, b, h) do { _Pragma("unroll") for (int n = 0; n < 2; ++n) _Pragma("unroll") for (int k = 0; k < 2; ++k) dst[n][k] = *(const LAS bf16x8*)(lds + PG8_SB(b, h) + boff + n * 2048 + k * 1024); } while (0)
; #define PG8_MMA(ai, bj, At, Bt) do { __builtin_amdgcn_s_setprio(1); _Pragma("unroll") for (int m = 0; m < 4; ++m) _Pragma("unroll") for (int n = 0; n < 2; ++n) _Pragma("unroll") for (int k = 0; k < 2; ++k) \
;         acc[ai][bj][m][n] = __builtin_amdgcn_mfma_f32_16x16x32_bf16(Bt[n][k], At[m][k], acc[ai][bj][m][n], 0, 0, 0); __builtin_amdgcn_s_setprio(0); } while (0)
; #define PG8_WAIT_L(n) asm volatile("s_waitcnt lgkmcnt(" #n ")" ::: "memory")
; #define PG8_BAR __builtin_amdgcn_s_barrier()
; #define PG8_SCHED __builtin_amdgcn_sched_barrier(0)
;     ...
;             PG8_LDB(B0, 0, 0); PG8_SCHED; PG8_LDA(At, 0, 0); PG8_STAGE(PG8_SA(1, 1), a1 + hA, voffA);
;             PG8_WAIT_L(8); PG8_BAR; PG8_WAIT_L(0); PG8_MMA(0, 0, At, B0); PG8_BAR; PG8_SCHED;
;             PG8_LDB(B1, 0, 1); PG8_STAGE(PG8_SB(0, 0), b2, voffB);
;             PG8_BAR; PG8_WAIT_L(0); PG8_MMA(0, 1, At, B1); PG8_BAR;
;             PG8_LDA(At, 0, 1); PG8_STAGE(PG8_SA(0, 0), a2, voffA);
;             PG8_BAR; PG8_WAIT_L(0); PG8_MMA(1, 0, At, B0); PG8_BAR; PG8_SCHED;
.LBB0_1288:
	ds_read_b128 v[146:149], v155
	ds_read_b128 v[160:163], v155 offset:1024
	ds_read_b128 v[170:173], v155 offset:2048
	ds_read_b128 v[174:177], v155 offset:3072
	s_add_u32 s36, s34, 0xfffc0080
	s_addc_u32 s37, s35, -1
	s_cmp_eq_u32 s42, 12
	s_cselect_b32 s39, s7, s37
	s_cselect_b32 s38, s8, s36
	s_cselect_b32 s37, s9, s33
	s_cselect_b32 s36, s23, s25
	v_lshl_add_u64 v[150:151], s[34:35], 0, v[138:139]
	s_add_i32 m0, s31, 0xc000
	ds_read_b128 v[178:181], v156
	ds_read_b128 v[182:185], v156 offset:1024
	ds_read_b128 v[186:189], v156 offset:2048
	ds_read_b128 v[190:193], v156 offset:3072
	ds_read_b128 v[194:197], v156 offset:4096
	ds_read_b128 v[198:201], v156 offset:5120
	ds_read_b128 v[202:205], v156 offset:6144
	ds_read_b128 v[206:209], v156 offset:7168
	global_load_lds_dwordx4 v[150:151], off
	v_lshl_add_u64 v[150:151], s[34:35], 0, v[136:137]
	s_add_i32 m0, s31, 0xe000
	s_nop 0
	global_load_lds_dwordx4 v[150:151], off
	s_waitcnt lgkmcnt(8)
	s_barrier
	s_waitcnt lgkmcnt(0)
	s_setprio 1
	s_waitcnt lgkmcnt(0)
	v_mfma_f32_16x16x32_bf16 v[124:127], v[146:149], v[178:181], v[124:127]
	v_mfma_f32_16x16x32_bf16 v[120:123], v[170:173], v[178:181], v[120:123]
	v_mfma_f32_16x16x32_bf16 v[108:111], v[146:149], v[186:189], v[108:111]
	v_mfma_f32_16x16x32_bf16 v[104:107], v[170:173], v[186:189], v[104:107]
	v_mfma_f32_16x16x32_bf16 v[92:95], v[146:149], v[194:197], v[92:95]
	v_mfma_f32_16x16x32_bf16 v[88:91], v[170:173], v[194:197], v[88:91]
	v_mfma_f32_16x16x32_bf16 v[76:79], v[146:149], v[202:205], v[76:79]
	v_mfma_f32_16x16x32_bf16 v[72:75], v[170:173], v[202:205], v[72:75]
	v_mfma_f32_16x16x32_bf16 v[124:127], v[160:163], v[182:185], v[124:127]
	v_mfma_f32_16x16x32_bf16 v[120:123], v[174:177], v[182:185], v[120:123]
	v_mfma_f32_16x16x32_bf16 v[108:111], v[160:163], v[190:193], v[108:111]
	v_mfma_f32_16x16x32_bf16 v[104:107], v[174:177], v[190:193], v[104:107]
	v_mfma_f32_16x16x32_bf16 v[92:95], v[160:163], v[198:201], v[92:95]
	v_mfma_f32_16x16x32_bf16 v[88:91], v[174:177], v[198:201], v[88:91]
	v_mfma_f32_16x16x32_bf16 v[76:79], v[160:163], v[206:209], v[76:79]
	v_mfma_f32_16x16x32_bf16 v[72:75], v[174:177], v[206:209], v[72:75]
	s_setprio 0
	s_barrier
	s_add_i32 s43, s63, s55
	v_lshl_add_u64 v[150:151], s[36:37], 0, v[130:131]
	s_mov_b32 m0, s43
	ds_read_b128 v[210:213], v157
	ds_read_b128 v[214:217], v157 offset:1024
	ds_read_b128 v[218:221], v157 offset:2048
	ds_read_b128 v[222:225], v157 offset:3072
	global_load_lds_dwordx4 v[150:151], off
	v_lshl_add_u64 v[164:165], s[36:37], 0, v[134:135]
	s_add_i32 m0, s43, 0x2000
	s_nop 0
	global_load_lds_dwordx4 v[164:165], off
	s_barrier
	s_waitcnt lgkmcnt(0)
	s_setprio 1
	s_waitcnt lgkmcnt(0)
	v_mfma_f32_16x16x32_bf16 v[116:119], v[210:213], v[178:181], v[116:119]
	v_mfma_f32_16x16x32_bf16 v[112:115], v[218:221], v[178:181], v[112:115]
	v_mfma_f32_16x16x32_bf16 v[100:103], v[210:213], v[186:189], v[100:103]
	v_mfma_f32_16x16x32_bf16 v[96:99], v[218:221], v[186:189], v[96:99]
	v_mfma_f32_16x16x32_bf16 v[84:87], v[210:213], v[194:197], v[84:87]
	v_mfma_f32_16x16x32_bf16 v[80:83], v[218:221], v[194:197], v[80:83]
	v_mfma_f32_16x16x32_bf16 v[68:71], v[210:213], v[202:205], v[68:71]
	v_mfma_f32_16x16x32_bf16 v[64:67], v[218:221], v[202:205], v[64:67]
	v_mfma_f32_16x16x32_bf16 v[116:119], v[214:217], v[182:185], v[116:119]
	v_mfma_f32_16x16x32_bf16 v[112:115], v[222:225], v[182:185], v[112:115]
	v_mfma_f32_16x16x32_bf16 v[100:103], v[214:217], v[190:193], v[100:103]
	v_mfma_f32_16x16x32_bf16 v[96:99], v[222:225], v[190:193], v[96:99]
	v_mfma_f32_16x16x32_bf16 v[84:87], v[214:217], v[198:201], v[84:87]
	v_mfma_f32_16x16x32_bf16 v[80:83], v[222:225], v[198:201], v[80:83]
	v_mfma_f32_16x16x32_bf16 v[68:71], v[214:217], v[206:209], v[68:71]
	v_mfma_f32_16x16x32_bf16 v[64:67], v[222:225], v[206:209], v[64:67]
	s_setprio 0
	s_mov_b32 m0, s31
	v_lshl_add_u64 v[226:227], s[38:39], 0, v[128:129]
	s_barrier
	ds_read_b128 v[178:181], v156 offset:16384
	ds_read_b128 v[182:185], v156 offset:17408
	ds_read_b128 v[186:189], v156 offset:18432
	ds_read_b128 v[190:193], v156 offset:19456
	ds_read_b128 v[194:197], v156 offset:20480
	ds_read_b128 v[198:201], v156 offset:21504
	ds_read_b128 v[202:205], v156 offset:22528
	ds_read_b128 v[206:209], v156 offset:23552
	global_load_lds_dwordx4 v[226:227], off
	v_lshl_add_u64 v[228:229], s[38:39], 0, v[132:133]
	s_mov_b32 m0, s56
	s_nop 0
	global_load_lds_dwordx4 v[228:229], off
	s_barrier
	s_waitcnt lgkmcnt(0)
	s_setprio 1
	s_waitcnt lgkmcnt(0)
	v_mfma_f32_16x16x32_bf16 v[60:63], v[146:149], v[178:181], v[60:63]
	v_mfma_f32_16x16x32_bf16 v[56:59], v[170:173], v[178:181], v[56:59]
	v_mfma_f32_16x16x32_bf16 v[44:47], v[146:149], v[186:189], v[44:47]
	v_mfma_f32_16x16x32_bf16 v[40:43], v[170:173], v[186:189], v[40:43]
	v_mfma_f32_16x16x32_bf16 v[28:31], v[146:149], v[194:197], v[28:31]
	v_mfma_f32_16x16x32_bf16 v[24:27], v[170:173], v[194:197], v[24:27]
	v_mfma_f32_16x16x32_bf16 v[12:15], v[146:149], v[202:205], v[12:15]
	v_mfma_f32_16x16x32_bf16 v[8:11], v[170:173], v[202:205], v[8:11]
	v_mfma_f32_16x16x32_bf16 v[60:63], v[160:163], v[182:185], v[60:63]
	v_mfma_f32_16x16x32_bf16 v[56:59], v[174:177], v[182:185], v[56:59]
	v_mfma_f32_16x16x32_bf16 v[44:47], v[160:163], v[190:193], v[44:47]
	v_mfma_f32_16x16x32_bf16 v[40:43], v[174:177], v[190:193], v[40:43]
	v_mfma_f32_16x16x32_bf16 v[28:31], v[160:163], v[198:201], v[28:31]
	v_mfma_f32_16x16x32_bf16 v[24:27], v[174:177], v[198:201], v[24:27]
	v_mfma_f32_16x16x32_bf16 v[12:15], v[160:163], v[206:209], v[12:15]
	v_mfma_f32_16x16x32_bf16 v[8:11], v[174:177], v[206:209], v[8:11]
	s_setprio 0
	s_barrier
; #define PG8_STAGE(bufoff, gbase, voff) do { _Pragma("unroll") for (int _i = 0; _i < 2; ++_i) \
;         __builtin_amdgcn_global_load_lds((const unsigned*)((const char*)(gbase) + (voff)[_i]), (LAS unsigned*)(lds + (bufoff) + ldsw + _i * 8192), 16, 0, 0); } while (0)
; #define PG8_LDA(dst, b, h) do { _Pragma("unroll") for (int m = 0; m < 4; ++m) _Pragma("unroll") for (int k = 0; k < 2; ++k) dst[m][k] = *(const LAS bf16x8*)(lds + PG8_SA(b, h) + aoff + m * 2048 + k * 1024); } while (0)
; #define PG8_LDB(dst, b, h) do { _Pragma("unroll") for (int n = 0; n < 2; ++n) _Pragma("unroll") for (int k = 0; k < 2; ++k) dst[n][k] = *(const LAS bf16x8*)(lds + PG8_SB(b, h) + boff + n * 2048 + k * 1024); } while (0)
; #define PG8_MMA(ai, bj, At, Bt) do { __builtin_amdgcn_s_setprio(1); _Pragma("unroll") for (int m = 0; m < 4; ++m) _Pragma("unroll") for (int n = 0; n < 2; ++n) _Pragma("unroll") for (int k = 0; k < 2; ++k) \
;         acc[ai][bj][m][n] = __builtin_amdgcn_mfma_f32_16x16x32_bf16(Bt[n][k], At[m][k], acc[ai][bj][m][n], 0, 0, 0); __builtin_amdgcn_s_setprio(0); } while (0)
; #define PG8_WAIT_V(n) asm volatile("s_waitcnt vmcnt(" #n ")" ::: "memory")
; #define PG8_WAIT_L(n) asm volatile("s_waitcnt lgkmcnt(" #n ")" ::: "memory")
; #define PG8_BAR __builtin_amdgcn_s_barrier()
; #define PG8_SCHED __builtin_amdgcn_sched_barrier(0)
;     ...
;             PG8_BAR; PG8_WAIT_L(0); PG8_MMA(1, 0, At, B0); PG8_BAR; PG8_SCHED;
;             PG8_STAGE(PG8_SB(0, 1), b2 + hB, voffB);
;             PG8_WAIT_V(6); PG8_BAR; PG8_MMA(1, 1, At, B1); PG8_BAR;
;             PG8_LDB(B0, 1, 0); PG8_SCHED; PG8_LDA(At, 1, 0); PG8_STAGE(PG8_SA(0, 1), a2 + hA, voffA);
;             PG8_WAIT_L(8); PG8_BAR; PG8_WAIT_L(0); PG8_MMA(0, 0, At, B0); PG8_BAR; PG8_SCHED;
;             PG8_LDB(B1, 1, 1); PG8_STAGE(PG8_SB(1, 0), b3, voffB);
;             PG8_BAR; PG8_WAIT_L(0); PG8_MMA(0, 1, At, B1); PG8_BAR;
;             PG8_LDA(At, 1, 1); PG8_STAGE(PG8_SA(1, 0), a3, voffA);
	s_add_u32 s44, s36, 0x40000
	s_addc_u32 s45, s37, 0
	s_add_i32 s43, s64, s55
	v_lshl_add_u64 v[146:147], s[44:45], 0, v[130:131]
	s_mov_b32 m0, s43
	s_nop 0
	global_load_lds_dwordx4 v[146:147], off
	v_lshl_add_u64 v[146:147], s[44:45], 0, v[134:135]
	s_add_i32 m0, s43, 0x2000
	s_nop 0
	global_load_lds_dwordx4 v[146:147], off
	s_waitcnt vmcnt(6)
	s_barrier
	s_setprio 1
	v_mfma_f32_16x16x32_bf16 v[52:55], v[210:213], v[178:181], v[52:55]
	v_mfma_f32_16x16x32_bf16 v[48:51], v[218:221], v[178:181], v[48:51]
	v_mfma_f32_16x16x32_bf16 v[36:39], v[210:213], v[186:189], v[36:39]
	v_mfma_f32_16x16x32_bf16 v[32:35], v[218:221], v[186:189], v[32:35]
	v_mfma_f32_16x16x32_bf16 v[20:23], v[210:213], v[194:197], v[20:23]
	v_mfma_f32_16x16x32_bf16 v[16:19], v[218:221], v[194:197], v[16:19]
	v_mfma_f32_16x16x32_bf16 v[4:7], v[210:213], v[202:205], v[4:7]
	v_mfma_f32_16x16x32_bf16 v[0:3], v[218:221], v[202:205], v[0:3]
	v_mfma_f32_16x16x32_bf16 v[52:55], v[214:217], v[182:185], v[52:55]
	v_mfma_f32_16x16x32_bf16 v[48:51], v[222:225], v[182:185], v[48:51]
	v_mfma_f32_16x16x32_bf16 v[36:39], v[214:217], v[190:193], v[36:39]
	v_mfma_f32_16x16x32_bf16 v[32:35], v[222:225], v[190:193], v[32:35]
	v_mfma_f32_16x16x32_bf16 v[20:23], v[214:217], v[198:201], v[20:23]
	v_mfma_f32_16x16x32_bf16 v[16:19], v[222:225], v[198:201], v[16:19]
	v_mfma_f32_16x16x32_bf16 v[4:7], v[214:217], v[206:209], v[4:7]
	v_mfma_f32_16x16x32_bf16 v[0:3], v[222:225], v[206:209], v[0:3]
	s_setprio 0
	s_add_i32 s43, 0, 0x18000
	v_add_u32_e32 v159, s43, v153
	s_barrier
	ds_read_b128 v[146:149], v159
	ds_read_b128 v[160:163], v159 offset:1024
	ds_read_b128 v[170:173], v159 offset:2048
	ds_read_b128 v[174:177], v159 offset:3072
	s_add_u32 s38, s38, 0x40000
	s_addc_u32 s39, s39, 0
	s_mov_b32 m0, s57
	v_lshl_add_u64 v[210:211], s[38:39], 0, v[128:129]
	ds_read_b128 v[178:181], v156 offset:32768
	ds_read_b128 v[182:185], v156 offset:33792
	ds_read_b128 v[186:189], v156 offset:34816
	ds_read_b128 v[190:193], v156 offset:35840
	ds_read_b128 v[194:197], v156 offset:36864
	ds_read_b128 v[198:201], v156 offset:37888
	ds_read_b128 v[202:205], v156 offset:38912
	ds_read_b128 v[206:209], v156 offset:39936
	global_load_lds_dwordx4 v[210:211], off
	v_lshl_add_u64 v[210:211], s[38:39], 0, v[132:133]
	s_mov_b32 m0, s58
	s_nop 0
	global_load_lds_dwordx4 v[210:211], off
	s_waitcnt lgkmcnt(8)
	s_barrier
	s_waitcnt lgkmcnt(0)
	s_setprio 1
	s_waitcnt lgkmcnt(0)
	v_mfma_f32_16x16x32_bf16 v[124:127], v[146:149], v[178:181], v[124:127]
	v_mfma_f32_16x16x32_bf16 v[120:123], v[170:173], v[178:181], v[120:123]
	v_mfma_f32_16x16x32_bf16 v[108:111], v[146:149], v[186:189], v[108:111]
	v_mfma_f32_16x16x32_bf16 v[104:107], v[170:173], v[186:189], v[104:107]
	v_mfma_f32_16x16x32_bf16 v[92:95], v[146:149], v[194:197], v[92:95]
	v_mfma_f32_16x16x32_bf16 v[88:91], v[170:173], v[194:197], v[88:91]
	v_mfma_f32_16x16x32_bf16 v[76:79], v[146:149], v[202:205], v[76:79]
	v_mfma_f32_16x16x32_bf16 v[72:75], v[170:173], v[202:205], v[72:75]
	v_mfma_f32_16x16x32_bf16 v[124:127], v[160:163], v[182:185], v[124:127]
	v_mfma_f32_16x16x32_bf16 v[120:123], v[174:177], v[182:185], v[120:123]
	v_mfma_f32_16x16x32_bf16 v[108:111], v[160:163], v[190:193], v[108:111]
	v_mfma_f32_16x16x32_bf16 v[104:107], v[174:177], v[190:193], v[104:107]
	v_mfma_f32_16x16x32_bf16 v[92:95], v[160:163], v[198:201], v[92:95]
	v_mfma_f32_16x16x32_bf16 v[88:91], v[174:177], v[198:201], v[88:91]
	v_mfma_f32_16x16x32_bf16 v[76:79], v[160:163], v[206:209], v[76:79]
	v_mfma_f32_16x16x32_bf16 v[72:75], v[174:177], v[206:209], v[72:75]
	s_setprio 0
	s_barrier
	s_add_i32 s38, 0, 0x1c000
	s_add_i32 s39, s43, s55
	v_add_u32_e32 v159, s38, v153
	v_lshl_add_u64 v[150:151], v[150:151], 0, s[20:21]
	s_mov_b32 m0, s39
	ds_read_b128 v[210:213], v159
	ds_read_b128 v[214:217], v159 offset:1024
	ds_read_b128 v[218:221], v159 offset:2048
	ds_read_b128 v[222:225], v159 offset:3072
	global_load_lds_dwordx4 v[150:151], off
	v_lshl_add_u64 v[150:151], v[164:165], 0, s[20:21]
	s_add_i32 m0, s39, 0x2000
	s_nop 0
	global_load_lds_dwordx4 v[150:151], off
	s_barrier
	s_waitcnt lgkmcnt(0)
	s_setprio 1
	s_waitcnt lgkmcnt(0)
	v_mfma_f32_16x16x32_bf16 v[116:119], v[210:213], v[178:181], v[116:119]
	v_mfma_f32_16x16x32_bf16 v[112:115], v[218:221], v[178:181], v[112:115]
	v_mfma_f32_16x16x32_bf16 v[100:103], v[210:213], v[186:189], v[100:103]
	v_mfma_f32_16x16x32_bf16 v[96:99], v[218:221], v[186:189], v[96:99]
	v_mfma_f32_16x16x32_bf16 v[84:87], v[210:213], v[194:197], v[84:87]
	v_mfma_f32_16x16x32_bf16 v[80:83], v[218:221], v[194:197], v[80:83]
	v_mfma_f32_16x16x32_bf16 v[68:71], v[210:213], v[202:205], v[68:71]
	v_mfma_f32_16x16x32_bf16 v[64:67], v[218:221], v[202:205], v[64:67]
	v_mfma_f32_16x16x32_bf16 v[116:119], v[214:217], v[182:185], v[116:119]
	v_mfma_f32_16x16x32_bf16 v[112:115], v[222:225], v[182:185], v[112:115]
	v_mfma_f32_16x16x32_bf16 v[100:103], v[214:217], v[190:193], v[100:103]
	v_mfma_f32_16x16x32_bf16 v[96:99], v[222:225], v[190:193], v[96:99]
	v_mfma_f32_16x16x32_bf16 v[84:87], v[214:217], v[198:201], v[84:87]
	v_mfma_f32_16x16x32_bf16 v[80:83], v[222:225], v[198:201], v[80:83]
	v_mfma_f32_16x16x32_bf16 v[68:71], v[214:217], v[206:209], v[68:71]
	v_mfma_f32_16x16x32_bf16 v[64:67], v[222:225], v[206:209], v[64:67]
	s_setprio 0
	s_mov_b32 m0, s60
	v_lshl_add_u64 v[150:151], v[226:227], 0, s[20:21]
	s_barrier
	ds_read_b128 v[178:181], v156 offset:49152
	ds_read_b128 v[182:185], v156 offset:50176
	ds_read_b128 v[186:189], v156 offset:51200
	ds_read_b128 v[190:193], v156 offset:52224
	ds_read_b128 v[194:197], v156 offset:53248
	ds_read_b128 v[198:201], v156 offset:54272
	ds_read_b128 v[202:205], v156 offset:55296
	ds_read_b128 v[206:209], v156 offset:56320
	global_load_lds_dwordx4 v[150:151], off
	v_lshl_add_u64 v[150:151], v[228:229], 0, s[20:21]
	s_mov_b32 m0, s61
	s_nop 0
	global_load_lds_dwordx4 v[150:151], off
	s_barrier
; __device__ __forceinline__ float bflo(unsigned w) { return __uint_as_float(w << 16); }
; __device__ __forceinline__ float bfhi(unsigned w) { return __uint_as_float(w & 0xffff0000u); }
; #define PG8_WAIT_V(n) asm volatile("s_waitcnt vmcnt(" #n ")" ::: "memory")
;     ...
;             PG8_BAR; PG8_WAIT_L(0); PG8_MMA(0, 1, At, B1); PG8_BAR;
;             PG8_LDA(At, 1, 1); PG8_STAGE(PG8_SA(1, 0), a3, voffA);
;             PG8_BAR; PG8_WAIT_L(0); PG8_MMA(1, 0, At, B0); PG8_BAR; PG8_SCHED;
;             PG8_STAGE(PG8_SB(1, 1), b3 + hB, voffB);
;             PG8_WAIT_V(6); PG8_BAR; PG8_MMA(1, 1, At, B1); PG8_BAR;
;         }
;         E(acc, cur, wr, wc, fr, fq);
; __device__ __forceinline__ float row_rstd(const float* ssq, int row) {
;     const f32x4* p = (const f32x4*)(ssq + (size_t)row * 16);
;     const f32x4 a = p[0], b = p[1], c = p[2], d = p[3];
;     const float s = ((a[0] + a[1]) + (a[2] + a[3])) + ((b[0] + b[1]) + (b[2] + b[3])) + ((c[0] + c[1]) + (c[2] + c[3])) + ((d[0] + d[1]) + (d[2] + d[3]));
;     return rsqrtf(s * (1.0f / 1024.0f) + 1e-6f);
; }
; __device__ __forceinline__ u32x4 pack8(const f32x4 v0, const f32x4 v1) { u32x4 w; w.x = pk2(v0[0], v0[1]); w.y = pk2(v0[2], v0[3]); w.z = pk2(v1[0], v1[1]); w.w = pk2(v1[2], v1[3]); return w; }
; __device__ __forceinline__ void unpack8(const u32x4 w, f32x4& v0, f32x4& v1) { v0 = (f32x4){bflo(w.x), bfhi(w.x), bflo(w.y), bfhi(w.y)}; v1 = (f32x4){bflo(w.z), bfhi(w.z), bflo(w.w), bfhi(w.w)}; }
;     __device__ __forceinline__ void operator()(const f32x4 (&acc)[2][2][4][2], const Unit& u, int wr, int wc, int fr, int fq) const {
;         const int row0 = u.pm * 256 + wr * 64 + fr, col0 = u.pn * 256 + wc * 32 + 8 * fq;
; #pragma unroll
;         for (int ai = 0; ai < 2; ++ai)
; #pragma unroll
;             for (int m = 0; m < 4; ++m) {
;                 const int row = row0 + ai * 128 + m * 16; const float rs = row_rstd(ssq, row);
;                 bf16_t* rowp = O + (size_t)row * ldc + col0;
; #pragma unroll
;                 for (int bj = 0; bj < 2; ++bj) { f32x4 v0 = acc[ai][bj][m][0] * rs, v1 = acc[ai][bj][m][1] * rs;
;                     if (ACT == 1) {
; #pragma unroll
;                         for (int j = 0; j < 4; ++j) { const float a = fmaxf(v0[j], 0.f), b = fmaxf(v1[j], 0.f); v0[j] = a * a; v1[j] = b * b; } }
;                     *(u32x4*)(rowp + bj * 128) = pack8(v0, v1); }
	s_waitcnt lgkmcnt(0)
	s_setprio 1
	s_waitcnt lgkmcnt(0)
	v_mfma_f32_16x16x32_bf16 v[60:63], v[146:149], v[178:181], v[60:63]
	v_mfma_f32_16x16x32_bf16 v[56:59], v[170:173], v[178:181], v[56:59]
	v_mfma_f32_16x16x32_bf16 v[44:47], v[146:149], v[186:189], v[44:47]
	v_mfma_f32_16x16x32_bf16 v[40:43], v[170:173], v[186:189], v[40:43]
	v_mfma_f32_16x16x32_bf16 v[28:31], v[146:149], v[194:197], v[28:31]
	v_mfma_f32_16x16x32_bf16 v[24:27], v[170:173], v[194:197], v[24:27]
	v_mfma_f32_16x16x32_bf16 v[12:15], v[146:149], v[202:205], v[12:15]
	v_mfma_f32_16x16x32_bf16 v[8:11], v[170:173], v[202:205], v[8:11]
	v_mfma_f32_16x16x32_bf16 v[60:63], v[160:163], v[182:185], v[60:63]
	v_mfma_f32_16x16x32_bf16 v[56:59], v[174:177], v[182:185], v[56:59]
	v_mfma_f32_16x16x32_bf16 v[44:47], v[160:163], v[190:193], v[44:47]
	v_mfma_f32_16x16x32_bf16 v[40:43], v[174:177], v[190:193], v[40:43]
	v_mfma_f32_16x16x32_bf16 v[28:31], v[160:163], v[198:201], v[28:31]
	v_mfma_f32_16x16x32_bf16 v[24:27], v[174:177], v[198:201], v[24:27]
	v_mfma_f32_16x16x32_bf16 v[12:15], v[160:163], v[206:209], v[12:15]
	v_mfma_f32_16x16x32_bf16 v[8:11], v[174:177], v[206:209], v[8:11]
	s_setprio 0
	s_barrier
	s_add_u32 s36, s36, 0x40080
	s_addc_u32 s37, s37, 0
	s_add_i32 s38, s38, s55
	v_lshl_add_u64 v[146:147], s[36:37], 0, v[130:131]
	s_mov_b32 m0, s38
	s_nop 0
	global_load_lds_dwordx4 v[146:147], off
	v_lshl_add_u64 v[146:147], s[36:37], 0, v[134:135]
	s_add_i32 m0, s38, 0x2000
	s_nop 0
	global_load_lds_dwordx4 v[146:147], off
	s_waitcnt vmcnt(6)
	s_barrier
	s_setprio 1
	v_mfma_f32_16x16x32_bf16 v[52:55], v[210:213], v[178:181], v[52:55]
	v_mfma_f32_16x16x32_bf16 v[48:51], v[218:221], v[178:181], v[48:51]
	v_mfma_f32_16x16x32_bf16 v[36:39], v[210:213], v[186:189], v[36:39]
	v_mfma_f32_16x16x32_bf16 v[32:35], v[218:221], v[186:189], v[32:35]
	v_mfma_f32_16x16x32_bf16 v[20:23], v[210:213], v[194:197], v[20:23]
	v_mfma_f32_16x16x32_bf16 v[16:19], v[218:221], v[194:197], v[16:19]
	v_mfma_f32_16x16x32_bf16 v[4:7], v[210:213], v[202:205], v[4:7]
	v_mfma_f32_16x16x32_bf16 v[0:3], v[218:221], v[202:205], v[0:3]
	v_mfma_f32_16x16x32_bf16 v[52:55], v[214:217], v[182:185], v[52:55]
	v_mfma_f32_16x16x32_bf16 v[48:51], v[222:225], v[182:185], v[48:51]
	v_mfma_f32_16x16x32_bf16 v[36:39], v[214:217], v[190:193], v[36:39]
	v_mfma_f32_16x16x32_bf16 v[32:35], v[222:225], v[190:193], v[32:35]
	v_mfma_f32_16x16x32_bf16 v[20:23], v[214:217], v[198:201], v[20:23]
	v_mfma_f32_16x16x32_bf16 v[16:19], v[222:225], v[198:201], v[16:19]
	v_mfma_f32_16x16x32_bf16 v[4:7], v[214:217], v[206:209], v[4:7]
	v_mfma_f32_16x16x32_bf16 v[0:3], v[222:225], v[206:209], v[0:3]
	s_setprio 0
	s_add_i32 s42, s42, 2
	s_add_u32 s25, s25, 0x100
	s_addc_u32 s33, s33, 0
	s_add_u32 s34, s34, 0x100
	s_addc_u32 s35, s35, 0
	s_cmp_gt_u32 s42, 13
	s_barrier
	s_cbranch_scc0 .LBB0_1288
	v_lshl_add_u32 v150, s30, 8, v152
	v_ashrrev_i32_e32 v151, 31, v150
	v_lshlrev_b64 v[146:147], 6, v[150:151]
	v_lshl_add_u64 v[146:147], s[18:19], 0, v[146:147]
	v_subrev_u32_e32 v186, s18, v146
	v_add_u32_e32 v187, 0x0, v186
	global_load_dwordx4 v[188:191], v187, s[18:19]
	v_add_u32_e32 v187, 0x10, v186
	global_load_dwordx4 v[192:195], v187, s[18:19]
	v_add_u32_e32 v187, 0x20, v186
	global_load_dwordx4 v[196:199], v187, s[18:19]
	v_add_u32_e32 v187, 0x30, v186
	global_load_dwordx4 v[200:203], v187, s[18:19]
	v_add_u32_e32 v187, 0x400, v186
	global_load_dwordx4 v[204:207], v187, s[18:19]
	v_add_u32_e32 v187, 0x410, v186
	global_load_dwordx4 v[208:211], v187, s[18:19]
	v_add_u32_e32 v187, 0x420, v186
	global_load_dwordx4 v[212:215], v187, s[18:19]
	v_add_u32_e32 v187, 0x430, v186
	global_load_dwordx4 v[216:219], v187, s[18:19]
	v_add_u32_e32 v187, 0x800, v186
	global_load_dwordx4 v[220:223], v187, s[18:19]
	v_add_u32_e32 v187, 0x810, v186
	global_load_dwordx4 v[232:235], v187, s[18:19]
	v_add_u32_e32 v187, 0x820, v186
	global_load_dwordx4 v[236:239], v187, s[18:19]
	v_add_u32_e32 v187, 0x830, v186
	global_load_dwordx4 v[240:243], v187, s[18:19]
	v_lshl_or_b32 v148, s6, 8, v154
	v_mov_b64_e32 v[146:147], s[16:17]
	v_ashrrev_i32_e32 v149, 31, v148
	v_mad_i64_i32 v[164:165], s[6:7], v150, s66, v[146:147]
	v_or_b32_e32 v182, 16, v150
	v_lshlrev_b64 v[148:149], 1, v[148:149]
	v_ashrrev_i32_e32 v183, 31, v182
	s_mov_b32 s30, s24
	s_mov_b64 s[34:35], s[28:29]
	s_mov_b64 s[36:37], s[26:27]
	s_waitcnt vmcnt(8)
	v_lshlrev_b64 v[162:163], 6, v[182:183]
	v_lshl_add_u64 v[162:163], s[18:19], 0, v[162:163]
	v_pk_add_f32 v[160:161], v[188:189], v[190:191]
	v_pk_add_f32 v[170:171], v[192:193], v[194:195]
	v_pk_add_f32 v[172:173], v[196:197], v[198:199]
	v_pk_add_f32 v[174:175], v[200:201], v[202:203]
	v_pk_add_f32 v[160:161], v[160:161], v[170:171]
	v_pk_add_f32 v[172:173], v[172:173], v[174:175]
	v_pk_add_f32 v[160:161], v[160:161], v[172:173]
	v_add_f32_e32 v151, v160, v161
	v_fmamk_f32 v151, v151, 0x3a800000, v158
	v_mul_f32_e32 v159, 0x4b800000, v151
	v_cmp_gt_f32_e32 vcc, s65, v151
	v_lshl_add_u64 v[160:161], v[164:165], 0, v[148:149]
	s_nop 0
	v_cndmask_b32_e32 v151, v151, v159, vcc
	v_rsq_f32_e32 v151, v151
	s_nop 0
	v_mul_f32_e32 v159, 0x45800000, v151
	v_cndmask_b32_e32 v164, v151, v159, vcc
	v_pk_mul_f32 v[126:127], v[126:127], v[164:165] op_sel_hi:[1,0]
	v_pk_mul_f32 v[124:125], v[124:125], v[164:165] op_sel_hi:[1,0]
	v_pk_mul_f32 v[122:123], v[122:123], v[164:165] op_sel_hi:[1,0]
	v_pk_mul_f32 v[120:121], v[120:121], v[164:165] op_sel_hi:[1,0]
	v_pk_mul_f32 v[118:119], v[118:119], v[164:165] op_sel_hi:[1,0]
	v_pk_mul_f32 v[116:117], v[116:117], v[164:165] op_sel_hi:[1,0]
	v_pk_mul_f32 v[170:171], v[114:115], v[164:165] op_sel_hi:[1,0]
	v_pk_mul_f32 v[164:165], v[112:113], v[164:165] op_sel_hi:[1,0]
	v_cvt_pk_bf16_f32 v112, v124, v125
	v_cvt_pk_bf16_f32 v113, v126, v127
	v_cvt_pk_bf16_f32 v114, v120, v121
	v_cvt_pk_bf16_f32 v115, v122, v123
	global_store_dwordx4 v[160:161], v[112:115], off sc1
	s_nop 1
	v_cvt_pk_bf16_f32 v112, v116, v117
	v_cvt_pk_bf16_f32 v113, v118, v119
	v_cvt_pk_bf16_f32 v114, v164, v165
	v_cvt_pk_bf16_f32 v115, v170, v171
	global_store_dwordx4 v[160:161], v[112:115], off offset:256 sc1
	s_nop 0
	v_or_b32_e32 v160, 32, v150
	v_mad_i64_i32 v[162:163], s[6:7], v182, s66, v[146:147]
	v_ashrrev_i32_e32 v161, 31, v160
	v_add_u32_e32 v187, 0xc00, v186
	global_load_dwordx4 v[188:191], v187, s[18:19]
	v_add_u32_e32 v187, 0xc10, v186
	global_load_dwordx4 v[192:195], v187, s[18:19]
	v_add_u32_e32 v187, 0xc20, v186
	global_load_dwordx4 v[196:199], v187, s[18:19]
	v_add_u32_e32 v187, 0xc30, v186
	global_load_dwordx4 v[200:203], v187, s[18:19]
	s_waitcnt vmcnt(10)
; __device__ __forceinline__ float bflo(unsigned w) { return __uint_as_float(w << 16); }
; __device__ __forceinline__ float bfhi(unsigned w) { return __uint_as_float(w & 0xffff0000u); }
; __device__ __forceinline__ unsigned pk2(float lo, float hi) { unsigned r; asm volatile("v_cvt_pk_bf16_f32 %0, %1, %2" : "=v"(r) : "v"(lo), "v"(hi)); return r; }
; __device__ __forceinline__ float row_rstd(const float* ssq, int row) {
;     const f32x4* p = (const f32x4*)(ssq + (size_t)row * 16);
;     const f32x4 a = p[0], b = p[1], c = p[2], d = p[3];
;     const float s = ((a[0] + a[1]) + (a[2] + a[3])) + ((b[0] + b[1]) + (b[2] + b[3])) + ((c[0] + c[1]) + (c[2] + c[3])) + ((d[0] + d[1]) + (d[2] + d[3]));
;     return rsqrtf(s * (1.0f / 1024.0f) + 1e-6f);
; }
; __device__ __forceinline__ u32x4 pack8(const f32x4 v0, const f32x4 v1) { u32x4 w; w.x = pk2(v0[0], v0[1]); w.y = pk2(v0[2], v0[3]); w.z = pk2(v1[0], v1[1]); w.w = pk2(v1[2], v1[3]); return w; }
; __device__ __forceinline__ void unpack8(const u32x4 w, f32x4& v0, f32x4& v1) { v0 = (f32x4){bflo(w.x), bfhi(w.x), bflo(w.y), bfhi(w.y)}; v1 = (f32x4){bflo(w.z), bfhi(w.z), bflo(w.w), bfhi(w.w)}; }
;     __device__ __forceinline__ void operator()(const f32x4 (&acc)[2][2][4][2], const Unit& u, int wr, int wc, int fr, int fq) const {
;         const int row0 = u.pm * 256 + wr * 64 + fr, col0 = u.pn * 256 + wc * 32 + 8 * fq;
; #pragma unroll
;         for (int ai = 0; ai < 2; ++ai)
; #pragma unroll
;             for (int m = 0; m < 4; ++m) {
;                 const int row = row0 + ai * 128 + m * 16; const float rs = row_rstd(ssq, row);
;                 bf16_t* rowp = O + (size_t)row * ldc + col0;
; #pragma unroll
;                 for (int bj = 0; bj < 2; ++bj) { f32x4 v0 = acc[ai][bj][m][0] * rs, v1 = acc[ai][bj][m][1] * rs;
;                     if (ACT == 1) {
; #pragma unroll
;                         for (int j = 0; j < 4; ++j) { const float a = fmaxf(v0[j], 0.f), b = fmaxf(v1[j], 0.f); v0[j] = a * a; v1[j] = b * b; } }
;                     *(u32x4*)(rowp + bj * 128) = pack8(v0, v1); }
	v_lshlrev_b64 v[114:115], 6, v[160:161]
	v_lshl_add_u64 v[114:115], s[18:19], 0, v[114:115]
	v_pk_add_f32 v[112:113], v[204:205], v[206:207]
	v_pk_add_f32 v[116:117], v[208:209], v[210:211]
	v_pk_add_f32 v[118:119], v[212:213], v[214:215]
	v_pk_add_f32 v[120:121], v[216:217], v[218:219]
	v_pk_add_f32 v[112:113], v[112:113], v[116:117]
	v_pk_add_f32 v[118:119], v[118:119], v[120:121]
	v_pk_add_f32 v[112:113], v[112:113], v[118:119]
	v_add_f32_e32 v112, v112, v113
	v_fmamk_f32 v112, v112, 0x3a800000, v158
	v_mul_f32_e32 v113, 0x4b800000, v112
	v_cmp_gt_f32_e32 vcc, s65, v112
	s_nop 1
	v_cndmask_b32_e32 v112, v112, v113, vcc
	v_rsq_f32_e32 v116, v112
	v_lshl_add_u64 v[112:113], v[162:163], 0, v[148:149]
	v_mul_f32_e32 v117, 0x45800000, v116
	v_cndmask_b32_e32 v116, v116, v117, vcc
	v_pk_mul_f32 v[110:111], v[110:111], v[116:117] op_sel_hi:[1,0]
	v_pk_mul_f32 v[108:109], v[108:109], v[116:117] op_sel_hi:[1,0]
	v_pk_mul_f32 v[106:107], v[106:107], v[116:117] op_sel_hi:[1,0]
	v_pk_mul_f32 v[104:105], v[104:105], v[116:117] op_sel_hi:[1,0]
	v_pk_mul_f32 v[102:103], v[102:103], v[116:117] op_sel_hi:[1,0]
	v_pk_mul_f32 v[100:101], v[100:101], v[116:117] op_sel_hi:[1,0]
	v_pk_mul_f32 v[118:119], v[98:99], v[116:117] op_sel_hi:[1,0]
	v_pk_mul_f32 v[116:117], v[96:97], v[116:117] op_sel_hi:[1,0]
	v_cvt_pk_bf16_f32 v96, v108, v109
	v_cvt_pk_bf16_f32 v97, v110, v111
	v_cvt_pk_bf16_f32 v98, v104, v105
	v_cvt_pk_bf16_f32 v99, v106, v107
	global_store_dwordx4 v[112:113], v[96:99], off sc1
	s_nop 1
	v_cvt_pk_bf16_f32 v96, v100, v101
	v_cvt_pk_bf16_f32 v97, v102, v103
	v_cvt_pk_bf16_f32 v98, v116, v117
	v_cvt_pk_bf16_f32 v99, v118, v119
	global_store_dwordx4 v[112:113], v[96:99], off offset:256 sc1
	s_nop 0
	v_or_b32_e32 v112, 48, v150
	v_mad_i64_i32 v[114:115], s[6:7], v160, s66, v[146:147]
	v_ashrrev_i32_e32 v113, 31, v112
	v_add_u32_e32 v187, 0x2000, v186
	global_load_dwordx4 v[204:207], v187, s[18:19]
	v_add_u32_e32 v187, 0x2010, v186
	global_load_dwordx4 v[208:211], v187, s[18:19]
	v_add_u32_e32 v187, 0x2020, v186
	global_load_dwordx4 v[212:215], v187, s[18:19]
	v_add_u32_e32 v187, 0x2030, v186
	global_load_dwordx4 v[216:219], v187, s[18:19]
	s_waitcnt vmcnt(12)
	v_lshlrev_b64 v[98:99], 6, v[112:113]
	v_lshl_add_u64 v[98:99], s[18:19], 0, v[98:99]
	v_pk_add_f32 v[96:97], v[220:221], v[222:223]
	v_pk_add_f32 v[100:101], v[232:233], v[234:235]
	v_pk_add_f32 v[102:103], v[236:237], v[238:239]
	v_pk_add_f32 v[104:105], v[240:241], v[242:243]
	v_pk_add_f32 v[96:97], v[96:97], v[100:101]
	v_pk_add_f32 v[102:103], v[102:103], v[104:105]
	v_pk_add_f32 v[96:97], v[96:97], v[102:103]
	v_add_f32_e32 v96, v96, v97
	v_fmamk_f32 v96, v96, 0x3a800000, v158
	v_mul_f32_e32 v97, 0x4b800000, v96
	v_cmp_gt_f32_e32 vcc, s65, v96
	s_nop 1
	v_cndmask_b32_e32 v96, v96, v97, vcc
	v_rsq_f32_e32 v100, v96
	v_lshl_add_u64 v[96:97], v[114:115], 0, v[148:149]
	v_mul_f32_e32 v101, 0x45800000, v100
	v_cndmask_b32_e32 v100, v100, v101, vcc
	v_pk_mul_f32 v[94:95], v[94:95], v[100:101] op_sel_hi:[1,0]
	v_pk_mul_f32 v[92:93], v[92:93], v[100:101] op_sel_hi:[1,0]
	v_pk_mul_f32 v[90:91], v[90:91], v[100:101] op_sel_hi:[1,0]
	v_pk_mul_f32 v[88:89], v[88:89], v[100:101] op_sel_hi:[1,0]
	v_pk_mul_f32 v[86:87], v[86:87], v[100:101] op_sel_hi:[1,0]
	v_pk_mul_f32 v[84:85], v[84:85], v[100:101] op_sel_hi:[1,0]
	v_pk_mul_f32 v[102:103], v[82:83], v[100:101] op_sel_hi:[1,0]
	v_pk_mul_f32 v[100:101], v[80:81], v[100:101] op_sel_hi:[1,0]
	v_cvt_pk_bf16_f32 v80, v92, v93
	v_cvt_pk_bf16_f32 v81, v94, v95
	v_cvt_pk_bf16_f32 v82, v88, v89
	v_cvt_pk_bf16_f32 v83, v90, v91
	global_store_dwordx4 v[96:97], v[80:83], off sc1
	s_nop 1
	v_cvt_pk_bf16_f32 v80, v84, v85
	v_cvt_pk_bf16_f32 v81, v86, v87
	v_cvt_pk_bf16_f32 v82, v100, v101
	v_cvt_pk_bf16_f32 v83, v102, v103
	global_store_dwordx4 v[96:97], v[80:83], off offset:256 sc1
	s_nop 0
	v_add_u32_e32 v96, 0x80, v150
	v_mad_i64_i32 v[98:99], s[6:7], v112, s66, v[146:147]
	v_ashrrev_i32_e32 v97, 31, v96
	v_add_u32_e32 v187, 0x2400, v186
	global_load_dwordx4 v[220:223], v187, s[18:19]
	v_add_u32_e32 v187, 0x2410, v186
	global_load_dwordx4 v[232:235], v187, s[18:19]
	v_add_u32_e32 v187, 0x2420, v186
	global_load_dwordx4 v[236:239], v187, s[18:19]
	v_add_u32_e32 v187, 0x2430, v186
	global_load_dwordx4 v[240:243], v187, s[18:19]
	s_waitcnt vmcnt(12)
	v_lshlrev_b64 v[82:83], 6, v[96:97]
	v_lshl_add_u64 v[82:83], s[18:19], 0, v[82:83]
	v_pk_add_f32 v[80:81], v[188:189], v[190:191]
	v_pk_add_f32 v[84:85], v[192:193], v[194:195]
	v_pk_add_f32 v[86:87], v[196:197], v[198:199]
	v_pk_add_f32 v[88:89], v[200:201], v[202:203]
	v_pk_add_f32 v[80:81], v[80:81], v[84:85]
	v_pk_add_f32 v[86:87], v[86:87], v[88:89]
	v_pk_add_f32 v[80:81], v[80:81], v[86:87]
	v_add_f32_e32 v80, v80, v81
	v_fmamk_f32 v80, v80, 0x3a800000, v158
	v_mul_f32_e32 v81, 0x4b800000, v80
	v_cmp_gt_f32_e32 vcc, s65, v80
	s_nop 1
	v_cndmask_b32_e32 v80, v80, v81, vcc
	v_rsq_f32_e32 v84, v80
	v_lshl_add_u64 v[80:81], v[98:99], 0, v[148:149]
	v_mul_f32_e32 v85, 0x45800000, v84
	v_cndmask_b32_e32 v84, v84, v85, vcc
	v_pk_mul_f32 v[78:79], v[78:79], v[84:85] op_sel_hi:[1,0]
	v_pk_mul_f32 v[76:77], v[76:77], v[84:85] op_sel_hi:[1,0]
	v_pk_mul_f32 v[74:75], v[74:75], v[84:85] op_sel_hi:[1,0]
	v_pk_mul_f32 v[72:73], v[72:73], v[84:85] op_sel_hi:[1,0]
	v_pk_mul_f32 v[70:71], v[70:71], v[84:85] op_sel_hi:[1,0]
	v_pk_mul_f32 v[68:69], v[68:69], v[84:85] op_sel_hi:[1,0]
	v_pk_mul_f32 v[86:87], v[66:67], v[84:85] op_sel_hi:[1,0]
	v_pk_mul_f32 v[84:85], v[64:65], v[84:85] op_sel_hi:[1,0]
	v_cvt_pk_bf16_f32 v64, v76, v77
	v_cvt_pk_bf16_f32 v65, v78, v79
	v_cvt_pk_bf16_f32 v66, v72, v73
	v_cvt_pk_bf16_f32 v67, v74, v75
	global_store_dwordx4 v[80:81], v[64:67], off sc1
	s_nop 1
	v_cvt_pk_bf16_f32 v64, v68, v69
	v_cvt_pk_bf16_f32 v65, v70, v71
	v_cvt_pk_bf16_f32 v66, v84, v85
	v_cvt_pk_bf16_f32 v67, v86, v87
	global_store_dwordx4 v[80:81], v[64:67], off offset:256 sc1
	s_nop 0
	v_add_u32_e32 v80, 0x90, v150
	v_mad_i64_i32 v[82:83], s[6:7], v96, s66, v[146:147]
	v_ashrrev_i32_e32 v81, 31, v80
	v_add_u32_e32 v187, 0x2800, v186
	global_load_dwordx4 v[188:191], v187, s[18:19]
	v_add_u32_e32 v187, 0x2810, v186
	global_load_dwordx4 v[192:195], v187, s[18:19]
	v_add_u32_e32 v187, 0x2820, v186
	global_load_dwordx4 v[196:199], v187, s[18:19]
	v_add_u32_e32 v187, 0x2830, v186
	global_load_dwordx4 v[200:203], v187, s[18:19]
	s_waitcnt vmcnt(12)
; __device__ __forceinline__ float bflo(unsigned w) { return __uint_as_float(w << 16); }
; __device__ __forceinline__ float bfhi(unsigned w) { return __uint_as_float(w & 0xffff0000u); }
; __device__ __forceinline__ unsigned pk2(float lo, float hi) { unsigned r; asm volatile("v_cvt_pk_bf16_f32 %0, %1, %2" : "=v"(r) : "v"(lo), "v"(hi)); return r; }
; __device__ __forceinline__ float row_rstd(const float* ssq, int row) {
;     const f32x4* p = (const f32x4*)(ssq + (size_t)row * 16);
;     const f32x4 a = p[0], b = p[1], c = p[2], d = p[3];
;     const float s = ((a[0] + a[1]) + (a[2] + a[3])) + ((b[0] + b[1]) + (b[2] + b[3])) + ((c[0] + c[1]) + (c[2] + c[3])) + ((d[0] + d[1]) + (d[2] + d[3]));
;     return rsqrtf(s * (1.0f / 1024.0f) + 1e-6f);
; }
; __device__ __forceinline__ u32x4 pack8(const f32x4 v0, const f32x4 v1) { u32x4 w; w.x = pk2(v0[0], v0[1]); w.y = pk2(v0[2], v0[3]); w.z = pk2(v1[0], v1[1]); w.w = pk2(v1[2], v1[3]); return w; }
; __device__ __forceinline__ void unpack8(const u32x4 w, f32x4& v0, f32x4& v1) { v0 = (f32x4){bflo(w.x), bfhi(w.x), bflo(w.y), bfhi(w.y)}; v1 = (f32x4){bflo(w.z), bfhi(w.z), bflo(w.w), bfhi(w.w)}; }
;     __device__ __forceinline__ void operator()(const f32x4 (&acc)[2][2][4][2], const Unit& u, int wr, int wc, int fr, int fq) const {
;         const int row0 = u.pm * 256 + wr * 64 + fr, col0 = u.pn * 256 + wc * 32 + 8 * fq;
; #pragma unroll
;         for (int ai = 0; ai < 2; ++ai)
; #pragma unroll
;             for (int m = 0; m < 4; ++m) {
;                 const int row = row0 + ai * 128 + m * 16; const float rs = row_rstd(ssq, row);
;                 bf16_t* rowp = O + (size_t)row * ldc + col0;
; #pragma unroll
;                 for (int bj = 0; bj < 2; ++bj) { f32x4 v0 = acc[ai][bj][m][0] * rs, v1 = acc[ai][bj][m][1] * rs;
;                     if (ACT == 1) {
; #pragma unroll
;                         for (int j = 0; j < 4; ++j) { const float a = fmaxf(v0[j], 0.f), b = fmaxf(v1[j], 0.f); v0[j] = a * a; v1[j] = b * b; } }
;                     *(u32x4*)(rowp + bj * 128) = pack8(v0, v1); }
	v_lshlrev_b64 v[66:67], 6, v[80:81]
	v_lshl_add_u64 v[66:67], s[18:19], 0, v[66:67]
	v_pk_add_f32 v[64:65], v[204:205], v[206:207]
	v_pk_add_f32 v[68:69], v[208:209], v[210:211]
	v_pk_add_f32 v[70:71], v[212:213], v[214:215]
	v_pk_add_f32 v[72:73], v[216:217], v[218:219]
	v_pk_add_f32 v[64:65], v[64:65], v[68:69]
	v_pk_add_f32 v[70:71], v[70:71], v[72:73]
	v_pk_add_f32 v[64:65], v[64:65], v[70:71]
	v_add_f32_e32 v64, v64, v65
	v_fmamk_f32 v64, v64, 0x3a800000, v158
	v_mul_f32_e32 v65, 0x4b800000, v64
	v_cmp_gt_f32_e32 vcc, s65, v64
	s_nop 1
	v_cndmask_b32_e32 v64, v64, v65, vcc
	v_rsq_f32_e32 v68, v64
	v_lshl_add_u64 v[64:65], v[82:83], 0, v[148:149]
	v_mul_f32_e32 v69, 0x45800000, v68
	v_cndmask_b32_e32 v68, v68, v69, vcc
	v_pk_mul_f32 v[62:63], v[62:63], v[68:69] op_sel_hi:[1,0]
	v_pk_mul_f32 v[60:61], v[60:61], v[68:69] op_sel_hi:[1,0]
	v_pk_mul_f32 v[58:59], v[58:59], v[68:69] op_sel_hi:[1,0]
	v_pk_mul_f32 v[56:57], v[56:57], v[68:69] op_sel_hi:[1,0]
	v_pk_mul_f32 v[54:55], v[54:55], v[68:69] op_sel_hi:[1,0]
	v_pk_mul_f32 v[52:53], v[52:53], v[68:69] op_sel_hi:[1,0]
	v_pk_mul_f32 v[70:71], v[50:51], v[68:69] op_sel_hi:[1,0]
	v_pk_mul_f32 v[68:69], v[48:49], v[68:69] op_sel_hi:[1,0]
	v_cvt_pk_bf16_f32 v48, v60, v61
	v_cvt_pk_bf16_f32 v49, v62, v63
	v_cvt_pk_bf16_f32 v50, v56, v57
	v_cvt_pk_bf16_f32 v51, v58, v59
	global_store_dwordx4 v[64:65], v[48:51], off sc1
	s_nop 1
	v_cvt_pk_bf16_f32 v48, v52, v53
	v_cvt_pk_bf16_f32 v49, v54, v55
	v_cvt_pk_bf16_f32 v50, v68, v69
	v_cvt_pk_bf16_f32 v51, v70, v71
	global_store_dwordx4 v[64:65], v[48:51], off offset:256 sc1
	s_nop 0
	v_add_u32_e32 v64, 0xa0, v150
	v_mad_i64_i32 v[66:67], s[6:7], v80, s66, v[146:147]
	v_ashrrev_i32_e32 v65, 31, v64
	v_add_u32_e32 v187, 0x2c00, v186
	global_load_dwordx4 v[204:207], v187, s[18:19]
	v_add_u32_e32 v187, 0x2c10, v186
	global_load_dwordx4 v[208:211], v187, s[18:19]
	v_add_u32_e32 v187, 0x2c20, v186
	global_load_dwordx4 v[212:215], v187, s[18:19]
	v_add_u32_e32 v187, 0x2c30, v186
	global_load_dwordx4 v[216:219], v187, s[18:19]
	s_waitcnt vmcnt(12)
	v_lshlrev_b64 v[50:51], 6, v[64:65]
	v_lshl_add_u64 v[50:51], s[18:19], 0, v[50:51]
	v_pk_add_f32 v[48:49], v[220:221], v[222:223]
	v_pk_add_f32 v[52:53], v[232:233], v[234:235]
	v_pk_add_f32 v[54:55], v[236:237], v[238:239]
	v_pk_add_f32 v[56:57], v[240:241], v[242:243]
	v_pk_add_f32 v[48:49], v[48:49], v[52:53]
	v_pk_add_f32 v[54:55], v[54:55], v[56:57]
	v_pk_add_f32 v[48:49], v[48:49], v[54:55]
	v_add_f32_e32 v48, v48, v49
	v_fmamk_f32 v48, v48, 0x3a800000, v158
	v_mul_f32_e32 v49, 0x4b800000, v48
	v_cmp_gt_f32_e32 vcc, s65, v48
	s_nop 1
	v_cndmask_b32_e32 v48, v48, v49, vcc
	v_rsq_f32_e32 v52, v48
	v_lshl_add_u64 v[48:49], v[66:67], 0, v[148:149]
	v_mul_f32_e32 v53, 0x45800000, v52
	v_cndmask_b32_e32 v52, v52, v53, vcc
	v_pk_mul_f32 v[46:47], v[46:47], v[52:53] op_sel_hi:[1,0]
	v_pk_mul_f32 v[44:45], v[44:45], v[52:53] op_sel_hi:[1,0]
	v_pk_mul_f32 v[42:43], v[42:43], v[52:53] op_sel_hi:[1,0]
	v_pk_mul_f32 v[40:41], v[40:41], v[52:53] op_sel_hi:[1,0]
	v_pk_mul_f32 v[38:39], v[38:39], v[52:53] op_sel_hi:[1,0]
	v_pk_mul_f32 v[36:37], v[36:37], v[52:53] op_sel_hi:[1,0]
	v_pk_mul_f32 v[54:55], v[34:35], v[52:53] op_sel_hi:[1,0]
	v_pk_mul_f32 v[52:53], v[32:33], v[52:53] op_sel_hi:[1,0]
	v_cvt_pk_bf16_f32 v32, v44, v45
	v_cvt_pk_bf16_f32 v33, v46, v47
	v_cvt_pk_bf16_f32 v34, v40, v41
	v_cvt_pk_bf16_f32 v35, v42, v43
	global_store_dwordx4 v[48:49], v[32:35], off sc1
	s_nop 1
	v_cvt_pk_bf16_f32 v32, v36, v37
	v_cvt_pk_bf16_f32 v33, v38, v39
	v_cvt_pk_bf16_f32 v34, v52, v53
	v_cvt_pk_bf16_f32 v35, v54, v55
	global_store_dwordx4 v[48:49], v[32:35], off offset:256 sc1
	s_nop 0
	v_add_u32_e32 v48, 0xb0, v150
	v_mad_i64_i32 v[50:51], s[6:7], v64, s66, v[146:147]
	v_ashrrev_i32_e32 v49, 31, v48
	s_mov_b32 s6, s22
	s_waitcnt vmcnt(8)
; __device__ __forceinline__ float bflo(unsigned w) { return __uint_as_float(w << 16); }
; __device__ __forceinline__ float bfhi(unsigned w) { return __uint_as_float(w & 0xffff0000u); }
;     ...
;         E(acc, cur, wr, wc, fr, fq);
;         if (!has_next) break;
; #pragma unroll
;         for (int a = 0; a < 2; ++a)
; #pragma unroll
;             for (int b = 0; b < 2; ++b)
; #pragma unroll
;                 for (int m = 0; m < 4; ++m)
; #pragma unroll
;                     for (int n = 0; n < 2; ++n) acc[a][b][m][n] = (f32x4){0.f, 0.f, 0.f, 0.f};
;         cur = nxt; cA = nA; cB = nB; ++ui;
;     }
;     PG8_WAIT_V(0);
;     if (wr == 0) PG8_BAR;
;     PG8_BAR;
; __device__ __forceinline__ float row_rstd(const float* ssq, int row) {
;     const f32x4* p = (const f32x4*)(ssq + (size_t)row * 16);
;     const f32x4 a = p[0], b = p[1], c = p[2], d = p[3];
;     const float s = ((a[0] + a[1]) + (a[2] + a[3])) + ((b[0] + b[1]) + (b[2] + b[3])) + ((c[0] + c[1]) + (c[2] + c[3])) + ((d[0] + d[1]) + (d[2] + d[3]));
;     return rsqrtf(s * (1.0f / 1024.0f) + 1e-6f);
; }
; __device__ __forceinline__ u32x4 pack8(const f32x4 v0, const f32x4 v1) { u32x4 w; w.x = pk2(v0[0], v0[1]); w.y = pk2(v0[2], v0[3]); w.z = pk2(v1[0], v1[1]); w.w = pk2(v1[2], v1[3]); return w; }
; __device__ __forceinline__ void unpack8(const u32x4 w, f32x4& v0, f32x4& v1) { v0 = (f32x4){bflo(w.x), bfhi(w.x), bflo(w.y), bfhi(w.y)}; v1 = (f32x4){bflo(w.z), bfhi(w.z), bflo(w.w), bfhi(w.w)}; }
;     __device__ __forceinline__ void operator()(const f32x4 (&acc)[2][2][4][2], const Unit& u, int wr, int wc, int fr, int fq) const {
;         const int row0 = u.pm * 256 + wr * 64 + fr, col0 = u.pn * 256 + wc * 32 + 8 * fq;
; #pragma unroll
;         for (int ai = 0; ai < 2; ++ai)
; #pragma unroll
;             for (int m = 0; m < 4; ++m) {
;                 const int row = row0 + ai * 128 + m * 16; const float rs = row_rstd(ssq, row);
;                 bf16_t* rowp = O + (size_t)row * ldc + col0;
; #pragma unroll
;                 for (int bj = 0; bj < 2; ++bj) { f32x4 v0 = acc[ai][bj][m][0] * rs, v1 = acc[ai][bj][m][1] * rs;
;                     if (ACT == 1) {
; #pragma unroll
;                         for (int j = 0; j < 4; ++j) { const float a = fmaxf(v0[j], 0.f), b = fmaxf(v1[j], 0.f); v0[j] = a * a; v1[j] = b * b; } }
;                     *(u32x4*)(rowp + bj * 128) = pack8(v0, v1); }
	v_lshlrev_b64 v[34:35], 6, v[48:49]
	v_lshl_add_u64 v[34:35], s[18:19], 0, v[34:35]
	v_pk_add_f32 v[32:33], v[188:189], v[190:191]
	v_pk_add_f32 v[36:37], v[192:193], v[194:195]
	v_pk_add_f32 v[38:39], v[196:197], v[198:199]
	v_pk_add_f32 v[40:41], v[200:201], v[202:203]
	v_pk_add_f32 v[32:33], v[32:33], v[36:37]
	v_pk_add_f32 v[38:39], v[38:39], v[40:41]
	v_pk_add_f32 v[32:33], v[32:33], v[38:39]
	v_add_f32_e32 v32, v32, v33
	v_fmamk_f32 v32, v32, 0x3a800000, v158
	v_mul_f32_e32 v33, 0x4b800000, v32
	v_cmp_gt_f32_e32 vcc, s65, v32
	s_nop 1
	v_cndmask_b32_e32 v32, v32, v33, vcc
	v_rsq_f32_e32 v36, v32
	v_lshl_add_u64 v[32:33], v[50:51], 0, v[148:149]
	v_mul_f32_e32 v37, 0x45800000, v36
	v_cndmask_b32_e32 v36, v36, v37, vcc
	v_pk_mul_f32 v[30:31], v[30:31], v[36:37] op_sel_hi:[1,0]
	v_pk_mul_f32 v[28:29], v[28:29], v[36:37] op_sel_hi:[1,0]
	v_pk_mul_f32 v[26:27], v[26:27], v[36:37] op_sel_hi:[1,0]
	v_pk_mul_f32 v[24:25], v[24:25], v[36:37] op_sel_hi:[1,0]
	v_pk_mul_f32 v[22:23], v[22:23], v[36:37] op_sel_hi:[1,0]
	v_pk_mul_f32 v[20:21], v[20:21], v[36:37] op_sel_hi:[1,0]
	v_pk_mul_f32 v[38:39], v[18:19], v[36:37] op_sel_hi:[1,0]
	v_pk_mul_f32 v[36:37], v[16:17], v[36:37] op_sel_hi:[1,0]
	v_cvt_pk_bf16_f32 v16, v28, v29
	v_cvt_pk_bf16_f32 v17, v30, v31
	v_cvt_pk_bf16_f32 v18, v24, v25
	v_cvt_pk_bf16_f32 v19, v26, v27
	global_store_dwordx4 v[32:33], v[16:19], off sc1
	s_and_b64 vcc, exec, s[10:11]
	s_nop 0
	v_cvt_pk_bf16_f32 v16, v20, v21
	v_cvt_pk_bf16_f32 v17, v22, v23
	v_cvt_pk_bf16_f32 v18, v36, v37
	v_cvt_pk_bf16_f32 v19, v38, v39
	global_store_dwordx4 v[32:33], v[16:19], off offset:256 sc1
	s_nop 0
	s_waitcnt vmcnt(4)
	s_nop 0
	s_nop 0
	v_pk_add_f32 v[16:17], v[204:205], v[206:207]
	v_pk_add_f32 v[18:19], v[208:209], v[210:211]
	v_pk_add_f32 v[20:21], v[212:213], v[214:215]
	v_pk_add_f32 v[22:23], v[216:217], v[218:219]
	v_pk_add_f32 v[16:17], v[16:17], v[18:19]
	v_pk_add_f32 v[20:21], v[20:21], v[22:23]
	v_pk_add_f32 v[16:17], v[16:17], v[20:21]
	v_add_f32_e32 v16, v16, v17
	v_fmamk_f32 v16, v16, 0x3a800000, v158
	v_mul_f32_e32 v17, 0x4b800000, v16
	v_cmp_gt_f32_e64 s[10:11], s65, v16
	s_nop 1
	v_cndmask_b32_e64 v16, v16, v17, s[10:11]
	v_rsq_f32_e32 v18, v16
	v_mad_i64_i32 v[16:17], s[8:9], v48, s66, v[146:147]
	v_lshl_add_u64 v[16:17], v[16:17], 0, v[148:149]
	v_mul_f32_e32 v19, 0x45800000, v18
	v_cndmask_b32_e64 v18, v18, v19, s[10:11]
	v_pk_mul_f32 v[14:15], v[14:15], v[18:19] op_sel_hi:[1,0]
	v_pk_mul_f32 v[12:13], v[12:13], v[18:19] op_sel_hi:[1,0]
	v_pk_mul_f32 v[10:11], v[10:11], v[18:19] op_sel_hi:[1,0]
	v_pk_mul_f32 v[8:9], v[8:9], v[18:19] op_sel_hi:[1,0]
	v_pk_mul_f32 v[6:7], v[6:7], v[18:19] op_sel_hi:[1,0]
	v_pk_mul_f32 v[4:5], v[4:5], v[18:19] op_sel_hi:[1,0]
	v_pk_mul_f32 v[20:21], v[2:3], v[18:19] op_sel_hi:[1,0]
	v_pk_mul_f32 v[18:19], v[0:1], v[18:19] op_sel_hi:[1,0]
	v_cvt_pk_bf16_f32 v0, v12, v13
	v_cvt_pk_bf16_f32 v1, v14, v15
	v_cvt_pk_bf16_f32 v2, v8, v9
	v_cvt_pk_bf16_f32 v3, v10, v11
	global_store_dwordx4 v[16:17], v[0:3], off sc1
	s_nop 1
	v_cvt_pk_bf16_f32 v0, v4, v5
	v_cvt_pk_bf16_f32 v1, v6, v7
	v_cvt_pk_bf16_f32 v2, v18, v19
	v_cvt_pk_bf16_f32 v3, v20, v21
	global_store_dwordx4 v[16:17], v[0:3], off offset:256 sc1
	s_cbranch_vccz .LBB0_1281
	s_waitcnt vmcnt(0)
	s_cmpk_gt_u32 s53, 0xff
	s_cbranch_scc1 .LBB0_1292
	s_barrier

; #define PG8_STAGE(bufoff, gbase, voff) do { _Pragma("unroll") for (int _i = 0; _i < 2; ++_i) \
;         __builtin_amdgcn_global_load_lds((const unsigned*)((const char*)(gbase) + (voff)[_i]), (LAS unsigned*)(lds + (bufoff) + ldsw + _i * 8192), 16, 0, 0); } while (0)
; #define PG8_LDA(dst, b, h) do { _Pragma("unroll") for (int m = 0; m < 4; ++m) _Pragma("unroll") for (int k = 0; k < 2; ++k) dst[m][k] = *(const LAS bf16x8*)(lds + PG8_SA(b, h) + aoff + m * 2048 + k * 1024); } while (0)
; #define PG8_LDB(dst, b, h) do { _Pragma("unroll") for (int n = 0; n < 2; ++n) _Pragma("unroll") for (int k = 0; k < 2; ++k) dst[n][k] = *(const LAS bf16x8*)(lds + PG8_SB(b, h) + boff + n * 2048 + k * 1024); } while (0)
; #define PG8_MMA(ai, bj, At, Bt) do { __builtin_amdgcn_s_setprio(1); _Pragma("unroll") for (int m = 0; m < 4; ++m) _Pragma("unroll") for (int n = 0; n < 2; ++n) _Pragma("unroll") for (int k = 0; k < 2; ++k) \
;         acc[ai][bj][m][n] = __builtin_amdgcn_mfma_f32_16x16x32_bf16(Bt[n][k], At[m][k], acc[ai][bj][m][n], 0, 0, 0); __builtin_amdgcn_s_setprio(0); } while (0)
; #define PG8_WAIT_L(n) asm volatile("s_waitcnt lgkmcnt(" #n ")" ::: "memory")
; #define PG8_BAR __builtin_amdgcn_s_barrier()
; #define PG8_SCHED __builtin_amdgcn_sched_barrier(0)
;     ...
;             PG8_LDB(B0, 0, 0); PG8_SCHED; PG8_LDA(At, 0, 0); PG8_STAGE(PG8_SA(1, 1), a1 + hA, voffA);
;             PG8_WAIT_L(8); PG8_BAR; PG8_WAIT_L(0); PG8_MMA(0, 0, At, B0); PG8_BAR; PG8_SCHED;
;             PG8_LDB(B1, 0, 1); PG8_STAGE(PG8_SB(0, 0), b2, voffB);
;             PG8_BAR; PG8_WAIT_L(0); PG8_MMA(0, 1, At, B1); PG8_BAR;
;             PG8_LDA(At, 0, 1); PG8_STAGE(PG8_SA(0, 0), a2, voffA);
;             PG8_BAR; PG8_WAIT_L(0); PG8_MMA(1, 0, At, B0); PG8_BAR; PG8_SCHED;
.LBB0_2099:
	ds_read_b128 v[156:159], v151
	ds_read_b128 v[160:163], v151 offset:1024
	ds_read_b128 v[170:173], v151 offset:2048
	ds_read_b128 v[174:177], v151 offset:3072
	s_add_u32 s38, s36, 0xfffc0080
	s_addc_u32 s39, s37, -1
	s_cmp_eq_u32 s71, 12
	s_cselect_b32 s41, s25, s39
	s_cselect_b32 s40, s44, s38
	s_cselect_b32 s39, s35, s70
	s_cselect_b32 s38, s45, s69
	v_lshl_add_u64 v[146:147], s[36:37], 0, v[138:139]
	s_add_i32 m0, s53, 0xc000
	ds_read_b128 v[178:181], v152
	ds_read_b128 v[182:185], v152 offset:1024
	ds_read_b128 v[186:189], v152 offset:2048
	ds_read_b128 v[190:193], v152 offset:3072
	ds_read_b128 v[194:197], v152 offset:4096
	ds_read_b128 v[198:201], v152 offset:5120
	ds_read_b128 v[202:205], v152 offset:6144
	ds_read_b128 v[206:209], v152 offset:7168
	global_load_lds_dwordx4 v[146:147], off
	v_lshl_add_u64 v[146:147], s[36:37], 0, v[136:137]
	s_add_i32 m0, s53, 0xe000
	s_nop 0
	global_load_lds_dwordx4 v[146:147], off
	s_waitcnt lgkmcnt(8)
	s_barrier
	s_waitcnt lgkmcnt(0)
	s_setprio 1
	s_waitcnt lgkmcnt(0)
	v_mfma_f32_16x16x32_bf16 v[124:127], v[156:159], v[178:181], v[124:127]
	v_mfma_f32_16x16x32_bf16 v[120:123], v[170:173], v[178:181], v[120:123]
	v_mfma_f32_16x16x32_bf16 v[108:111], v[156:159], v[186:189], v[108:111]
	v_mfma_f32_16x16x32_bf16 v[104:107], v[170:173], v[186:189], v[104:107]
	v_mfma_f32_16x16x32_bf16 v[92:95], v[156:159], v[194:197], v[92:95]
	v_mfma_f32_16x16x32_bf16 v[88:91], v[170:173], v[194:197], v[88:91]
	v_mfma_f32_16x16x32_bf16 v[76:79], v[156:159], v[202:205], v[76:79]
	v_mfma_f32_16x16x32_bf16 v[72:75], v[170:173], v[202:205], v[72:75]
	v_mfma_f32_16x16x32_bf16 v[124:127], v[160:163], v[182:185], v[124:127]
	v_mfma_f32_16x16x32_bf16 v[120:123], v[174:177], v[182:185], v[120:123]
	v_mfma_f32_16x16x32_bf16 v[108:111], v[160:163], v[190:193], v[108:111]
	v_mfma_f32_16x16x32_bf16 v[104:107], v[174:177], v[190:193], v[104:107]
	v_mfma_f32_16x16x32_bf16 v[92:95], v[160:163], v[198:201], v[92:95]
	v_mfma_f32_16x16x32_bf16 v[88:91], v[174:177], v[198:201], v[88:91]
	v_mfma_f32_16x16x32_bf16 v[76:79], v[160:163], v[206:209], v[76:79]
	v_mfma_f32_16x16x32_bf16 v[72:75], v[174:177], v[206:209], v[72:75]
	s_setprio 0
	s_barrier
	s_add_i32 s72, s61, s52
	v_lshl_add_u64 v[146:147], s[38:39], 0, v[130:131]
	s_mov_b32 m0, s72
	ds_read_b128 v[210:213], v153
	ds_read_b128 v[214:217], v153 offset:1024
	ds_read_b128 v[218:221], v153 offset:2048
	ds_read_b128 v[222:225], v153 offset:3072
	global_load_lds_dwordx4 v[146:147], off
	v_lshl_add_u64 v[164:165], s[38:39], 0, v[134:135]
	s_add_i32 m0, s72, 0x2000
	s_nop 0
	global_load_lds_dwordx4 v[164:165], off
	s_barrier
	s_waitcnt lgkmcnt(0)
	s_setprio 1
	s_waitcnt lgkmcnt(0)
	v_mfma_f32_16x16x32_bf16 v[116:119], v[210:213], v[178:181], v[116:119]
	v_mfma_f32_16x16x32_bf16 v[112:115], v[218:221], v[178:181], v[112:115]
	v_mfma_f32_16x16x32_bf16 v[100:103], v[210:213], v[186:189], v[100:103]
	v_mfma_f32_16x16x32_bf16 v[96:99], v[218:221], v[186:189], v[96:99]
	v_mfma_f32_16x16x32_bf16 v[84:87], v[210:213], v[194:197], v[84:87]
	v_mfma_f32_16x16x32_bf16 v[80:83], v[218:221], v[194:197], v[80:83]
	v_mfma_f32_16x16x32_bf16 v[68:71], v[210:213], v[202:205], v[68:71]
	v_mfma_f32_16x16x32_bf16 v[64:67], v[218:221], v[202:205], v[64:67]
	v_mfma_f32_16x16x32_bf16 v[116:119], v[214:217], v[182:185], v[116:119]
	v_mfma_f32_16x16x32_bf16 v[112:115], v[222:225], v[182:185], v[112:115]
	v_mfma_f32_16x16x32_bf16 v[100:103], v[214:217], v[190:193], v[100:103]
	v_mfma_f32_16x16x32_bf16 v[96:99], v[222:225], v[190:193], v[96:99]
	v_mfma_f32_16x16x32_bf16 v[84:87], v[214:217], v[198:201], v[84:87]
	v_mfma_f32_16x16x32_bf16 v[80:83], v[222:225], v[198:201], v[80:83]
	v_mfma_f32_16x16x32_bf16 v[68:71], v[214:217], v[206:209], v[68:71]
	v_mfma_f32_16x16x32_bf16 v[64:67], v[222:225], v[206:209], v[64:67]
	s_setprio 0
	s_mov_b32 m0, s53
	v_lshl_add_u64 v[226:227], s[40:41], 0, v[128:129]
	s_barrier
	ds_read_b128 v[178:181], v152 offset:16384
	ds_read_b128 v[182:185], v152 offset:17408
	ds_read_b128 v[186:189], v152 offset:18432
	ds_read_b128 v[190:193], v152 offset:19456
	ds_read_b128 v[194:197], v152 offset:20480
	ds_read_b128 v[198:201], v152 offset:21504
	ds_read_b128 v[202:205], v152 offset:22528
	ds_read_b128 v[206:209], v152 offset:23552
	global_load_lds_dwordx4 v[226:227], off
	v_lshl_add_u64 v[228:229], s[40:41], 0, v[132:133]
	s_mov_b32 m0, s54
	s_nop 0
	global_load_lds_dwordx4 v[228:229], off
	s_barrier
	s_waitcnt lgkmcnt(0)
	s_setprio 1
	s_waitcnt lgkmcnt(0)
	v_mfma_f32_16x16x32_bf16 v[60:63], v[156:159], v[178:181], v[60:63]
	v_mfma_f32_16x16x32_bf16 v[56:59], v[170:173], v[178:181], v[56:59]
	v_mfma_f32_16x16x32_bf16 v[44:47], v[156:159], v[186:189], v[44:47]
	v_mfma_f32_16x16x32_bf16 v[40:43], v[170:173], v[186:189], v[40:43]
	v_mfma_f32_16x16x32_bf16 v[28:31], v[156:159], v[194:197], v[28:31]
	v_mfma_f32_16x16x32_bf16 v[24:27], v[170:173], v[194:197], v[24:27]
	v_mfma_f32_16x16x32_bf16 v[12:15], v[156:159], v[202:205], v[12:15]
	v_mfma_f32_16x16x32_bf16 v[8:11], v[170:173], v[202:205], v[8:11]
	v_mfma_f32_16x16x32_bf16 v[60:63], v[160:163], v[182:185], v[60:63]
	v_mfma_f32_16x16x32_bf16 v[56:59], v[174:177], v[182:185], v[56:59]
	v_mfma_f32_16x16x32_bf16 v[44:47], v[160:163], v[190:193], v[44:47]
	v_mfma_f32_16x16x32_bf16 v[40:43], v[174:177], v[190:193], v[40:43]
	v_mfma_f32_16x16x32_bf16 v[28:31], v[160:163], v[198:201], v[28:31]
	v_mfma_f32_16x16x32_bf16 v[24:27], v[174:177], v[198:201], v[24:27]
	v_mfma_f32_16x16x32_bf16 v[12:15], v[160:163], v[206:209], v[12:15]
	v_mfma_f32_16x16x32_bf16 v[8:11], v[174:177], v[206:209], v[8:11]
	s_setprio 0
	s_barrier
; #define PG8_STAGE(bufoff, gbase, voff) do { _Pragma("unroll") for (int _i = 0; _i < 2; ++_i) \
;         __builtin_amdgcn_global_load_lds((const unsigned*)((const char*)(gbase) + (voff)[_i]), (LAS unsigned*)(lds + (bufoff) + ldsw + _i * 8192), 16, 0, 0); } while (0)
; #define PG8_LDA(dst, b, h) do { _Pragma("unroll") for (int m = 0; m < 4; ++m) _Pragma("unroll") for (int k = 0; k < 2; ++k) dst[m][k] = *(const LAS bf16x8*)(lds + PG8_SA(b, h) + aoff + m * 2048 + k * 1024); } while (0)
; #define PG8_LDB(dst, b, h) do { _Pragma("unroll") for (int n = 0; n < 2; ++n) _Pragma("unroll") for (int k = 0; k < 2; ++k) dst[n][k] = *(const LAS bf16x8*)(lds + PG8_SB(b, h) + boff + n * 2048 + k * 1024); } while (0)
; #define PG8_MMA(ai, bj, At, Bt) do { __builtin_amdgcn_s_setprio(1); _Pragma("unroll") for (int m = 0; m < 4; ++m) _Pragma("unroll") for (int n = 0; n < 2; ++n) _Pragma("unroll") for (int k = 0; k < 2; ++k) \
;         acc[ai][bj][m][n] = __builtin_amdgcn_mfma_f32_16x16x32_bf16(Bt[n][k], At[m][k], acc[ai][bj][m][n], 0, 0, 0); __builtin_amdgcn_s_setprio(0); } while (0)
; #define PG8_WAIT_V(n) asm volatile("s_waitcnt vmcnt(" #n ")" ::: "memory")
; #define PG8_WAIT_L(n) asm volatile("s_waitcnt lgkmcnt(" #n ")" ::: "memory")
; #define PG8_BAR __builtin_amdgcn_s_barrier()
; #define PG8_SCHED __builtin_amdgcn_sched_barrier(0)
;     ...
;             PG8_STAGE(PG8_SB(0, 1), b2 + hB, voffB);
;             PG8_WAIT_V(6); PG8_BAR; PG8_MMA(1, 1, At, B1); PG8_BAR;
;             PG8_LDB(B0, 1, 0); PG8_SCHED; PG8_LDA(At, 1, 0); PG8_STAGE(PG8_SA(0, 1), a2 + hA, voffA);
;             PG8_WAIT_L(8); PG8_BAR; PG8_WAIT_L(0); PG8_MMA(0, 0, At, B0); PG8_BAR; PG8_SCHED;
;             PG8_LDB(B1, 1, 1); PG8_STAGE(PG8_SB(1, 0), b3, voffB);
;             PG8_BAR; PG8_WAIT_L(0); PG8_MMA(0, 1, At, B1); PG8_BAR;
;             PG8_LDA(At, 1, 1); PG8_STAGE(PG8_SA(1, 0), a3, voffA);
	s_add_u32 s72, s38, 0x40000
	s_addc_u32 s73, s39, 0
	s_add_i32 s74, s62, s52
	v_lshl_add_u64 v[156:157], s[72:73], 0, v[130:131]
	s_mov_b32 m0, s74
	s_nop 0
	global_load_lds_dwordx4 v[156:157], off
	v_lshl_add_u64 v[156:157], s[72:73], 0, v[134:135]
	s_add_i32 m0, s74, 0x2000
	s_nop 0
	global_load_lds_dwordx4 v[156:157], off
	s_waitcnt vmcnt(6)
	s_barrier
	s_setprio 1
	v_mfma_f32_16x16x32_bf16 v[52:55], v[210:213], v[178:181], v[52:55]
	v_mfma_f32_16x16x32_bf16 v[48:51], v[218:221], v[178:181], v[48:51]
	v_mfma_f32_16x16x32_bf16 v[36:39], v[210:213], v[186:189], v[36:39]
	v_mfma_f32_16x16x32_bf16 v[32:35], v[218:221], v[186:189], v[32:35]
	v_mfma_f32_16x16x32_bf16 v[20:23], v[210:213], v[194:197], v[20:23]
	v_mfma_f32_16x16x32_bf16 v[16:19], v[218:221], v[194:197], v[16:19]
	v_mfma_f32_16x16x32_bf16 v[4:7], v[210:213], v[202:205], v[4:7]
	v_mfma_f32_16x16x32_bf16 v[0:3], v[218:221], v[202:205], v[0:3]
	v_mfma_f32_16x16x32_bf16 v[52:55], v[214:217], v[182:185], v[52:55]
	v_mfma_f32_16x16x32_bf16 v[48:51], v[222:225], v[182:185], v[48:51]
	v_mfma_f32_16x16x32_bf16 v[36:39], v[214:217], v[190:193], v[36:39]
	v_mfma_f32_16x16x32_bf16 v[32:35], v[222:225], v[190:193], v[32:35]
	v_mfma_f32_16x16x32_bf16 v[20:23], v[214:217], v[198:201], v[20:23]
	v_mfma_f32_16x16x32_bf16 v[16:19], v[222:225], v[198:201], v[16:19]
	v_mfma_f32_16x16x32_bf16 v[4:7], v[214:217], v[206:209], v[4:7]
	v_mfma_f32_16x16x32_bf16 v[0:3], v[222:225], v[206:209], v[0:3]
	s_setprio 0
	s_add_i32 s72, 0, 0x18000
	v_add_u32_e32 v155, s72, v149
	s_barrier
	ds_read_b128 v[156:159], v155
	ds_read_b128 v[160:163], v155 offset:1024
	ds_read_b128 v[170:173], v155 offset:2048
	ds_read_b128 v[174:177], v155 offset:3072
	s_add_u32 s40, s40, 0x40000
	s_addc_u32 s41, s41, 0
	s_mov_b32 m0, s55
	v_lshl_add_u64 v[210:211], s[40:41], 0, v[128:129]
	ds_read_b128 v[178:181], v152 offset:32768
	ds_read_b128 v[182:185], v152 offset:33792
	ds_read_b128 v[186:189], v152 offset:34816
	ds_read_b128 v[190:193], v152 offset:35840
	ds_read_b128 v[194:197], v152 offset:36864
	ds_read_b128 v[198:201], v152 offset:37888
	ds_read_b128 v[202:205], v152 offset:38912
	ds_read_b128 v[206:209], v152 offset:39936
	global_load_lds_dwordx4 v[210:211], off
	v_lshl_add_u64 v[210:211], s[40:41], 0, v[132:133]
	s_mov_b32 m0, s56
	s_nop 0
	global_load_lds_dwordx4 v[210:211], off
	s_waitcnt lgkmcnt(8)
	s_barrier
	s_waitcnt lgkmcnt(0)
	s_setprio 1
	s_waitcnt lgkmcnt(0)
	v_mfma_f32_16x16x32_bf16 v[124:127], v[156:159], v[178:181], v[124:127]
	v_mfma_f32_16x16x32_bf16 v[120:123], v[170:173], v[178:181], v[120:123]
	v_mfma_f32_16x16x32_bf16 v[108:111], v[156:159], v[186:189], v[108:111]
	v_mfma_f32_16x16x32_bf16 v[104:107], v[170:173], v[186:189], v[104:107]
	v_mfma_f32_16x16x32_bf16 v[92:95], v[156:159], v[194:197], v[92:95]
	v_mfma_f32_16x16x32_bf16 v[88:91], v[170:173], v[194:197], v[88:91]
	v_mfma_f32_16x16x32_bf16 v[76:79], v[156:159], v[202:205], v[76:79]
	v_mfma_f32_16x16x32_bf16 v[72:75], v[170:173], v[202:205], v[72:75]
	v_mfma_f32_16x16x32_bf16 v[124:127], v[160:163], v[182:185], v[124:127]
	v_mfma_f32_16x16x32_bf16 v[120:123], v[174:177], v[182:185], v[120:123]
	v_mfma_f32_16x16x32_bf16 v[108:111], v[160:163], v[190:193], v[108:111]
	v_mfma_f32_16x16x32_bf16 v[104:107], v[174:177], v[190:193], v[104:107]
	v_mfma_f32_16x16x32_bf16 v[92:95], v[160:163], v[198:201], v[92:95]
	v_mfma_f32_16x16x32_bf16 v[88:91], v[174:177], v[198:201], v[88:91]
	v_mfma_f32_16x16x32_bf16 v[76:79], v[160:163], v[206:209], v[76:79]
	v_mfma_f32_16x16x32_bf16 v[72:75], v[174:177], v[206:209], v[72:75]
	s_setprio 0
	s_barrier
	s_add_i32 s40, 0, 0x1c000
	s_add_i32 s41, s72, s52
	v_add_u32_e32 v155, s40, v149
	v_lshl_add_u64 v[146:147], v[146:147], 0, s[26:27]
	s_mov_b32 m0, s41
	ds_read_b128 v[210:213], v155
	ds_read_b128 v[214:217], v155 offset:1024
	ds_read_b128 v[218:221], v155 offset:2048
	ds_read_b128 v[222:225], v155 offset:3072
	global_load_lds_dwordx4 v[146:147], off
	v_lshl_add_u64 v[146:147], v[164:165], 0, s[26:27]
	s_add_i32 m0, s41, 0x2000
	s_nop 0
	global_load_lds_dwordx4 v[146:147], off
	s_barrier
	s_waitcnt lgkmcnt(0)
	s_setprio 1
	s_waitcnt lgkmcnt(0)
	v_mfma_f32_16x16x32_bf16 v[116:119], v[210:213], v[178:181], v[116:119]
	v_mfma_f32_16x16x32_bf16 v[112:115], v[218:221], v[178:181], v[112:115]
	v_mfma_f32_16x16x32_bf16 v[100:103], v[210:213], v[186:189], v[100:103]
	v_mfma_f32_16x16x32_bf16 v[96:99], v[218:221], v[186:189], v[96:99]
	v_mfma_f32_16x16x32_bf16 v[84:87], v[210:213], v[194:197], v[84:87]
	v_mfma_f32_16x16x32_bf16 v[80:83], v[218:221], v[194:197], v[80:83]
	v_mfma_f32_16x16x32_bf16 v[68:71], v[210:213], v[202:205], v[68:71]
	v_mfma_f32_16x16x32_bf16 v[64:67], v[218:221], v[202:205], v[64:67]
	v_mfma_f32_16x16x32_bf16 v[116:119], v[214:217], v[182:185], v[116:119]
	v_mfma_f32_16x16x32_bf16 v[112:115], v[222:225], v[182:185], v[112:115]
	v_mfma_f32_16x16x32_bf16 v[100:103], v[214:217], v[190:193], v[100:103]
	v_mfma_f32_16x16x32_bf16 v[96:99], v[222:225], v[190:193], v[96:99]
	v_mfma_f32_16x16x32_bf16 v[84:87], v[214:217], v[198:201], v[84:87]
	v_mfma_f32_16x16x32_bf16 v[80:83], v[222:225], v[198:201], v[80:83]
	v_mfma_f32_16x16x32_bf16 v[68:71], v[214:217], v[206:209], v[68:71]
	v_mfma_f32_16x16x32_bf16 v[64:67], v[222:225], v[206:209], v[64:67]
	s_setprio 0
	s_mov_b32 m0, s58
	v_lshl_add_u64 v[146:147], v[226:227], 0, s[26:27]
	s_barrier
	ds_read_b128 v[178:181], v152 offset:49152
	ds_read_b128 v[182:185], v152 offset:50176
	ds_read_b128 v[186:189], v152 offset:51200
	ds_read_b128 v[190:193], v152 offset:52224
	ds_read_b128 v[194:197], v152 offset:53248
	ds_read_b128 v[198:201], v152 offset:54272
	ds_read_b128 v[202:205], v152 offset:55296
	ds_read_b128 v[206:209], v152 offset:56320
	global_load_lds_dwordx4 v[146:147], off
	v_lshl_add_u64 v[146:147], v[228:229], 0, s[26:27]
	s_mov_b32 m0, s59
	s_nop 0
	global_load_lds_dwordx4 v[146:147], off
	s_barrier
; #define PG8_STAGE(bufoff, gbase, voff) do { _Pragma("unroll") for (int _i = 0; _i < 2; ++_i) \
;         __builtin_amdgcn_global_load_lds((const unsigned*)((const char*)(gbase) + (voff)[_i]), (LAS unsigned*)(lds + (bufoff) + ldsw + _i * 8192), 16, 0, 0); } while (0)
; #define PG8_MMA(ai, bj, At, Bt) do { __builtin_amdgcn_s_setprio(1); _Pragma("unroll") for (int m = 0; m < 4; ++m) _Pragma("unroll") for (int n = 0; n < 2; ++n) _Pragma("unroll") for (int k = 0; k < 2; ++k) \
;         acc[ai][bj][m][n] = __builtin_amdgcn_mfma_f32_16x16x32_bf16(Bt[n][k], At[m][k], acc[ai][bj][m][n], 0, 0, 0); __builtin_amdgcn_s_setprio(0); } while (0)
; #define PG8_WAIT_V(n) asm volatile("s_waitcnt vmcnt(" #n ")" ::: "memory")
; #define PG8_WAIT_L(n) asm volatile("s_waitcnt lgkmcnt(" #n ")" ::: "memory")
; #define PG8_BAR __builtin_amdgcn_s_barrier()
; #define PG8_SCHED __builtin_amdgcn_sched_barrier(0)
;     ...
;             PG8_BAR; PG8_WAIT_L(0); PG8_MMA(1, 0, At, B0); PG8_BAR; PG8_SCHED;
;             PG8_STAGE(PG8_SB(1, 1), b3 + hB, voffB);
;             PG8_WAIT_V(6); PG8_BAR; PG8_MMA(1, 1, At, B1); PG8_BAR;
;         }
;         E(acc, cur, wr, wc, fr, fq);
;     __device__ __forceinline__ void operator()(const f32x4 (&acc)[2][2][4][2], const Unit& u, int wr, int wc, int fr, int fq) const {
;         const __amdgpu_buffer_rsrc_t rsrc = __builtin_amdgcn_make_buffer_rsrc((void*)O, 0, T_ALL * DFF * 2, 0x00020000);
;         const int row0 = row_off + u.pm * 256 + wr * 64 + fr, col0 = u.pn * 256 + wc * 32 + 8 * fq;
; #pragma unroll
;         for (int ai = 0; ai < 2; ++ai)
; #pragma unroll
;             for (int m = 0; m < 4; ++m) {
;                 const int row = row0 + ai * 128 + m * 16; const float rs = row_rstd(ssq, row);
	s_waitcnt lgkmcnt(0)
	s_setprio 1
	s_waitcnt lgkmcnt(0)
	v_mfma_f32_16x16x32_bf16 v[60:63], v[156:159], v[178:181], v[60:63]
	v_mfma_f32_16x16x32_bf16 v[56:59], v[170:173], v[178:181], v[56:59]
	v_mfma_f32_16x16x32_bf16 v[44:47], v[156:159], v[186:189], v[44:47]
	v_mfma_f32_16x16x32_bf16 v[40:43], v[170:173], v[186:189], v[40:43]
	v_mfma_f32_16x16x32_bf16 v[28:31], v[156:159], v[194:197], v[28:31]
	v_mfma_f32_16x16x32_bf16 v[24:27], v[170:173], v[194:197], v[24:27]
	v_mfma_f32_16x16x32_bf16 v[12:15], v[156:159], v[202:205], v[12:15]
	v_mfma_f32_16x16x32_bf16 v[8:11], v[170:173], v[202:205], v[8:11]
	v_mfma_f32_16x16x32_bf16 v[60:63], v[160:163], v[182:185], v[60:63]
	v_mfma_f32_16x16x32_bf16 v[56:59], v[174:177], v[182:185], v[56:59]
	v_mfma_f32_16x16x32_bf16 v[44:47], v[160:163], v[190:193], v[44:47]
	v_mfma_f32_16x16x32_bf16 v[40:43], v[174:177], v[190:193], v[40:43]
	v_mfma_f32_16x16x32_bf16 v[28:31], v[160:163], v[198:201], v[28:31]
	v_mfma_f32_16x16x32_bf16 v[24:27], v[174:177], v[198:201], v[24:27]
	v_mfma_f32_16x16x32_bf16 v[12:15], v[160:163], v[206:209], v[12:15]
	v_mfma_f32_16x16x32_bf16 v[8:11], v[174:177], v[206:209], v[8:11]
	s_setprio 0
	s_barrier
	s_add_u32 s38, s38, 0x40080
	s_addc_u32 s39, s39, 0
	s_add_i32 s40, s40, s52
	v_lshl_add_u64 v[146:147], s[38:39], 0, v[130:131]
	s_mov_b32 m0, s40
	s_nop 0
	global_load_lds_dwordx4 v[146:147], off
	v_lshl_add_u64 v[146:147], s[38:39], 0, v[134:135]
	s_add_i32 m0, s40, 0x2000
	s_nop 0
	global_load_lds_dwordx4 v[146:147], off
	s_waitcnt vmcnt(6)
	s_barrier
	s_setprio 1
	v_mfma_f32_16x16x32_bf16 v[52:55], v[210:213], v[178:181], v[52:55]
	v_mfma_f32_16x16x32_bf16 v[48:51], v[218:221], v[178:181], v[48:51]
	v_mfma_f32_16x16x32_bf16 v[36:39], v[210:213], v[186:189], v[36:39]
	v_mfma_f32_16x16x32_bf16 v[32:35], v[218:221], v[186:189], v[32:35]
	v_mfma_f32_16x16x32_bf16 v[20:23], v[210:213], v[194:197], v[20:23]
	v_mfma_f32_16x16x32_bf16 v[16:19], v[218:221], v[194:197], v[16:19]
	v_mfma_f32_16x16x32_bf16 v[4:7], v[210:213], v[202:205], v[4:7]
	v_mfma_f32_16x16x32_bf16 v[0:3], v[218:221], v[202:205], v[0:3]
	v_mfma_f32_16x16x32_bf16 v[52:55], v[214:217], v[182:185], v[52:55]
	v_mfma_f32_16x16x32_bf16 v[48:51], v[222:225], v[182:185], v[48:51]
	v_mfma_f32_16x16x32_bf16 v[36:39], v[214:217], v[190:193], v[36:39]
	v_mfma_f32_16x16x32_bf16 v[32:35], v[222:225], v[190:193], v[32:35]
	v_mfma_f32_16x16x32_bf16 v[20:23], v[214:217], v[198:201], v[20:23]
	v_mfma_f32_16x16x32_bf16 v[16:19], v[222:225], v[198:201], v[16:19]
	v_mfma_f32_16x16x32_bf16 v[4:7], v[214:217], v[206:209], v[4:7]
	v_mfma_f32_16x16x32_bf16 v[0:3], v[222:225], v[206:209], v[0:3]
	s_setprio 0
	s_add_i32 s71, s71, 2
	s_add_u32 s69, s69, 0x100
	s_addc_u32 s70, s70, 0
	s_add_u32 s36, s36, 0x100
	s_addc_u32 s37, s37, 0
	s_cmp_gt_u32 s71, 13
	s_barrier
	s_cbranch_scc0 .LBB0_2099
	v_lshl_add_u32 v146, s68, 8, v148
	v_ashrrev_i32_e32 v147, 31, v146
	v_lshlrev_b64 v[156:157], 6, v[146:147]
	v_lshl_add_u64 v[164:165], s[22:23], 0, v[156:157]
	v_subrev_u32_e32 v180, s22, v164
	v_add_u32_e32 v181, 0x0, v180
	global_load_dwordx4 v[182:185], v181, s[22:23]
	v_add_u32_e32 v181, 0x10, v180
	global_load_dwordx4 v[186:189], v181, s[22:23]
	v_add_u32_e32 v181, 0x20, v180
	global_load_dwordx4 v[190:193], v181, s[22:23]
	v_add_u32_e32 v181, 0x30, v180
	global_load_dwordx4 v[194:197], v181, s[22:23]
	v_add_u32_e32 v181, 0x400, v180
	global_load_dwordx4 v[198:201], v181, s[22:23]
	v_add_u32_e32 v181, 0x410, v180
	global_load_dwordx4 v[202:205], v181, s[22:23]
	v_add_u32_e32 v181, 0x420, v180
	global_load_dwordx4 v[206:209], v181, s[22:23]
	v_add_u32_e32 v181, 0x430, v180
	global_load_dwordx4 v[210:213], v181, s[22:23]
	v_add_u32_e32 v181, 0x800, v180
	global_load_dwordx4 v[214:217], v181, s[22:23]
	v_add_u32_e32 v181, 0x810, v180
	global_load_dwordx4 v[218:221], v181, s[22:23]
	v_add_u32_e32 v181, 0x820, v180
	global_load_dwordx4 v[222:225], v181, s[22:23]
	v_add_u32_e32 v181, 0x830, v180
	global_load_dwordx4 v[232:235], v181, s[22:23]
	v_add_u32_e32 v181, 0xc00, v180
	global_load_dwordx4 v[236:239], v181, s[22:23]
	v_add_u32_e32 v181, 0xc10, v180
	global_load_dwordx4 v[240:243], v181, s[22:23]
	v_add_u32_e32 v181, 0xc20, v180
	global_load_dwordx4 v[244:247], v181, s[22:23]
	v_add_u32_e32 v181, 0xc30, v180
	global_load_dwordx4 v[248:251], v181, s[22:23]
	v_or_b32_e32 v164, 16, v146
	v_lshl_or_b32 v147, s33, 9, v150
	v_ashrrev_i32_e32 v165, 31, v164
	v_lshl_add_u32 v155, v146, 13, v147
	s_waitcnt vmcnt(12)
; __device__ __forceinline__ u32x4 pack8(const f32x4 v0, const f32x4 v1) { u32x4 w; w.x = pk2(v0[0], v0[1]); w.y = pk2(v0[2], v0[3]); w.z = pk2(v1[0], v1[1]); w.w = pk2(v1[2], v1[3]); return w; }
; __device__ __forceinline__ float row_rstd(const float* ssq, int row) {
;     const f32x4* p = (const f32x4*)(ssq + (size_t)row * 16);
;     const f32x4 a = p[0], b = p[1], c = p[2], d = p[3];
;     const float s = ((a[0] + a[1]) + (a[2] + a[3])) + ((b[0] + b[1]) + (b[2] + b[3])) + ((c[0] + c[1]) + (c[2] + c[3])) + ((d[0] + d[1]) + (d[2] + d[3]));
;     return rsqrtf(s * (1.0f / 1024.0f) + 1e-6f);
;     __device__ __forceinline__ void operator()(const f32x4 (&acc)[2][2][4][2], const Unit& u, int wr, int wc, int fr, int fq) const {
;         const __amdgpu_buffer_rsrc_t rsrc = __builtin_amdgcn_make_buffer_rsrc((void*)O, 0, T_ALL * DFF * 2, 0x00020000);
;         const int row0 = row_off + u.pm * 256 + wr * 64 + fr, col0 = u.pn * 256 + wc * 32 + 8 * fq;
; #pragma unroll
;         for (int ai = 0; ai < 2; ++ai)
; #pragma unroll
;             for (int m = 0; m < 4; ++m) {
;                 const int row = row0 + ai * 128 + m * 16; const float rs = row_rstd(ssq, row);
; #pragma unroll
;                 for (int bj = 0; bj < 2; ++bj) { f32x4 v0 = acc[ai][bj][m][0] * rs, v1 = acc[ai][bj][m][1] * rs;
; #pragma unroll
;                     for (int j = 0; j < 4; ++j) { const float a = fmaxf(v0[j], 0.f), b = fmaxf(v1[j], 0.f); v0[j] = a * a; v1[j] = b * b; }
;                     __builtin_amdgcn_raw_buffer_store_b128(pack8(v0, v1), rsrc, (unsigned)(((size_t)row * DFF + col0 + bj * 128) * 2), 0, 16  ); }
;             }
	s_nop 0
	s_nop 0
	v_pk_add_f32 v[156:157], v[182:183], v[184:185]
	v_pk_add_f32 v[158:159], v[186:187], v[188:189]
	v_pk_add_f32 v[160:161], v[190:191], v[192:193]
	v_pk_add_f32 v[162:163], v[194:195], v[196:197]
	v_pk_add_f32 v[156:157], v[156:157], v[158:159]
	v_pk_add_f32 v[160:161], v[160:161], v[162:163]
	v_pk_add_f32 v[156:157], v[156:157], v[160:161]
	v_add_f32_e32 v156, v156, v157
	v_fmamk_f32 v156, v156, 0x3a800000, v154
	v_mul_f32_e32 v157, 0x4b800000, v156
	v_cmp_gt_f32_e32 vcc, s63, v156
	s_nop 1
	v_cndmask_b32_e32 v156, v156, v157, vcc
	v_rsq_f32_e32 v158, v156
	v_lshlrev_b64 v[156:157], 6, v[164:165]
	v_lshl_add_u64 v[156:157], s[22:23], 0, v[156:157]
	v_mul_f32_e32 v159, 0x45800000, v158
	v_cndmask_b32_e32 v158, v158, v159, vcc
	v_pk_mul_f32 v[126:127], v[126:127], v[158:159] op_sel_hi:[1,0]
	v_pk_mul_f32 v[124:125], v[124:125], v[158:159] op_sel_hi:[1,0]
	v_pk_mul_f32 v[122:123], v[122:123], v[158:159] op_sel_hi:[1,0]
	v_pk_mul_f32 v[120:121], v[120:121], v[158:159] op_sel_hi:[1,0]
	v_pk_mul_f32 v[114:115], v[114:115], v[158:159] op_sel_hi:[1,0]
	v_pk_mul_f32 v[112:113], v[112:113], v[158:159] op_sel_hi:[1,0]
	v_pk_mul_f32 v[118:119], v[118:119], v[158:159] op_sel_hi:[1,0]
	v_pk_mul_f32 v[116:117], v[116:117], v[158:159] op_sel_hi:[1,0]
	v_max_f32_e32 v124, 0, v124
	v_max_f32_e32 v120, 0, v120
	v_max_f32_e32 v125, 0, v125
	v_max_f32_e32 v121, 0, v121
	v_max_f32_e32 v126, 0, v126
	v_max_f32_e32 v122, 0, v122
	v_max_f32_e32 v127, 0, v127
	v_max_f32_e32 v123, 0, v123
	v_max_f32_e32 v112, 0, v112
	v_max_f32_e32 v113, 0, v113
	v_max_f32_e32 v114, 0, v114
	v_max_f32_e32 v115, 0, v115
	v_max_f32_e32 v116, 0, v116
	v_max_f32_e32 v117, 0, v117
	v_max_f32_e32 v118, 0, v118
	v_max_f32_e32 v119, 0, v119
	v_pk_mul_f32 v[124:125], v[124:125], v[124:125]
	v_pk_mul_f32 v[120:121], v[120:121], v[120:121]
	v_pk_mul_f32 v[126:127], v[126:127], v[126:127]
	v_pk_mul_f32 v[122:123], v[122:123], v[122:123]
	v_pk_mul_f32 v[158:159], v[112:113], v[112:113]
	v_pk_mul_f32 v[160:161], v[114:115], v[114:115]
	v_cvt_pk_bf16_f32 v112, v124, v125
	v_cvt_pk_bf16_f32 v113, v126, v127
	v_cvt_pk_bf16_f32 v114, v120, v121
	v_cvt_pk_bf16_f32 v115, v122, v123
	v_pk_mul_f32 v[116:117], v[116:117], v[116:117]
	v_pk_mul_f32 v[118:119], v[118:119], v[118:119]
	buffer_store_dwordx4 v[112:115], v155, s[12:15], 0 offen sc1
	s_nop 1
	v_cvt_pk_bf16_f32 v112, v116, v117
	v_cvt_pk_bf16_f32 v113, v118, v119
	v_cvt_pk_bf16_f32 v114, v158, v159
	v_cvt_pk_bf16_f32 v115, v160, v161
	buffer_store_dwordx4 v[112:115], v155, s[12:15], 0 offen offset:256 sc1
	s_nop 0
	v_or_b32_e32 v156, 32, v146
	v_ashrrev_i32_e32 v157, 31, v156
	v_lshl_add_u32 v155, v164, 13, v147
	v_add_u32_e32 v181, 0x2000, v180
	global_load_dwordx4 v[182:185], v181, s[22:23]
	v_add_u32_e32 v181, 0x2010, v180
	global_load_dwordx4 v[186:189], v181, s[22:23]
	v_add_u32_e32 v181, 0x2020, v180
	global_load_dwordx4 v[190:193], v181, s[22:23]
	v_add_u32_e32 v181, 0x2030, v180
	global_load_dwordx4 v[194:197], v181, s[22:23]
	s_waitcnt vmcnt(14)
	s_nop 0
	s_nop 0
	v_pk_add_f32 v[112:113], v[198:199], v[200:201]
	v_pk_add_f32 v[114:115], v[202:203], v[204:205]
	v_pk_add_f32 v[116:117], v[206:207], v[208:209]
	v_pk_add_f32 v[118:119], v[210:211], v[212:213]
	v_pk_add_f32 v[112:113], v[112:113], v[114:115]
	v_pk_add_f32 v[116:117], v[116:117], v[118:119]
	v_pk_add_f32 v[112:113], v[112:113], v[116:117]
	v_add_f32_e32 v112, v112, v113
	v_fmamk_f32 v112, v112, 0x3a800000, v154
	v_mul_f32_e32 v113, 0x4b800000, v112
	v_cmp_gt_f32_e32 vcc, s63, v112
	s_nop 1
	v_cndmask_b32_e32 v112, v112, v113, vcc
	v_rsq_f32_e32 v114, v112
	v_lshlrev_b64 v[112:113], 6, v[156:157]
	v_lshl_add_u64 v[112:113], s[22:23], 0, v[112:113]
	v_mul_f32_e32 v115, 0x45800000, v114
	v_cndmask_b32_e32 v114, v114, v115, vcc
	v_pk_mul_f32 v[110:111], v[110:111], v[114:115] op_sel_hi:[1,0]
	v_pk_mul_f32 v[108:109], v[108:109], v[114:115] op_sel_hi:[1,0]
	v_pk_mul_f32 v[106:107], v[106:107], v[114:115] op_sel_hi:[1,0]
	v_pk_mul_f32 v[104:105], v[104:105], v[114:115] op_sel_hi:[1,0]
	v_pk_mul_f32 v[98:99], v[98:99], v[114:115] op_sel_hi:[1,0]
	v_pk_mul_f32 v[96:97], v[96:97], v[114:115] op_sel_hi:[1,0]
	v_pk_mul_f32 v[102:103], v[102:103], v[114:115] op_sel_hi:[1,0]
	v_pk_mul_f32 v[100:101], v[100:101], v[114:115] op_sel_hi:[1,0]
	v_max_f32_e32 v108, 0, v108
	v_max_f32_e32 v104, 0, v104
	v_max_f32_e32 v109, 0, v109
	v_max_f32_e32 v105, 0, v105
	v_max_f32_e32 v110, 0, v110
	v_max_f32_e32 v106, 0, v106
	v_max_f32_e32 v111, 0, v111
	v_max_f32_e32 v107, 0, v107
	v_max_f32_e32 v96, 0, v96
	v_max_f32_e32 v97, 0, v97
	v_max_f32_e32 v98, 0, v98
	v_max_f32_e32 v99, 0, v99
	v_max_f32_e32 v100, 0, v100
	v_max_f32_e32 v101, 0, v101
	v_max_f32_e32 v102, 0, v102
	v_max_f32_e32 v103, 0, v103
	v_pk_mul_f32 v[108:109], v[108:109], v[108:109]
	v_pk_mul_f32 v[104:105], v[104:105], v[104:105]
	v_pk_mul_f32 v[110:111], v[110:111], v[110:111]
	v_pk_mul_f32 v[106:107], v[106:107], v[106:107]
	v_pk_mul_f32 v[114:115], v[96:97], v[96:97]
	v_pk_mul_f32 v[116:117], v[98:99], v[98:99]
	v_cvt_pk_bf16_f32 v96, v108, v109
	v_cvt_pk_bf16_f32 v97, v110, v111
	v_cvt_pk_bf16_f32 v98, v104, v105
	v_cvt_pk_bf16_f32 v99, v106, v107
	v_pk_mul_f32 v[100:101], v[100:101], v[100:101]
	v_pk_mul_f32 v[102:103], v[102:103], v[102:103]
	buffer_store_dwordx4 v[96:99], v155, s[12:15], 0 offen sc1
	s_nop 1
	v_cvt_pk_bf16_f32 v96, v100, v101
	v_cvt_pk_bf16_f32 v97, v102, v103
	v_cvt_pk_bf16_f32 v98, v114, v115
	v_cvt_pk_bf16_f32 v99, v116, v117
	buffer_store_dwordx4 v[96:99], v155, s[12:15], 0 offen offset:256 sc1
	s_nop 0
	v_or_b32_e32 v112, 48, v146
	v_ashrrev_i32_e32 v113, 31, v112
	v_lshl_add_u32 v116, v156, 13, v147
	v_add_u32_e32 v181, 0x2400, v180
	global_load_dwordx4 v[198:201], v181, s[22:23]
	v_add_u32_e32 v181, 0x2410, v180
	global_load_dwordx4 v[202:205], v181, s[22:23]
	v_add_u32_e32 v181, 0x2420, v180
	global_load_dwordx4 v[206:209], v181, s[22:23]
	v_add_u32_e32 v181, 0x2430, v180
	global_load_dwordx4 v[210:213], v181, s[22:23]
	s_waitcnt vmcnt(16)
; __device__ __forceinline__ u32x4 pack8(const f32x4 v0, const f32x4 v1) { u32x4 w; w.x = pk2(v0[0], v0[1]); w.y = pk2(v0[2], v0[3]); w.z = pk2(v1[0], v1[1]); w.w = pk2(v1[2], v1[3]); return w; }
; __device__ __forceinline__ float row_rstd(const float* ssq, int row) {
;     const f32x4* p = (const f32x4*)(ssq + (size_t)row * 16);
;     const f32x4 a = p[0], b = p[1], c = p[2], d = p[3];
;     const float s = ((a[0] + a[1]) + (a[2] + a[3])) + ((b[0] + b[1]) + (b[2] + b[3])) + ((c[0] + c[1]) + (c[2] + c[3])) + ((d[0] + d[1]) + (d[2] + d[3]));
;     return rsqrtf(s * (1.0f / 1024.0f) + 1e-6f);
;     __device__ __forceinline__ void operator()(const f32x4 (&acc)[2][2][4][2], const Unit& u, int wr, int wc, int fr, int fq) const {
;         const __amdgpu_buffer_rsrc_t rsrc = __builtin_amdgcn_make_buffer_rsrc((void*)O, 0, T_ALL * DFF * 2, 0x00020000);
;         const int row0 = row_off + u.pm * 256 + wr * 64 + fr, col0 = u.pn * 256 + wc * 32 + 8 * fq;
; #pragma unroll
;         for (int ai = 0; ai < 2; ++ai)
; #pragma unroll
;             for (int m = 0; m < 4; ++m) {
;                 const int row = row0 + ai * 128 + m * 16; const float rs = row_rstd(ssq, row);
; #pragma unroll
;                 for (int bj = 0; bj < 2; ++bj) { f32x4 v0 = acc[ai][bj][m][0] * rs, v1 = acc[ai][bj][m][1] * rs;
; #pragma unroll
;                     for (int j = 0; j < 4; ++j) { const float a = fmaxf(v0[j], 0.f), b = fmaxf(v1[j], 0.f); v0[j] = a * a; v1[j] = b * b; }
;                     __builtin_amdgcn_raw_buffer_store_b128(pack8(v0, v1), rsrc, (unsigned)(((size_t)row * DFF + col0 + bj * 128) * 2), 0, 16  ); }
;             }
	s_nop 0
	s_nop 0
	v_pk_add_f32 v[96:97], v[214:215], v[216:217]
	v_pk_add_f32 v[98:99], v[218:219], v[220:221]
	v_pk_add_f32 v[100:101], v[222:223], v[224:225]
	v_pk_add_f32 v[102:103], v[232:233], v[234:235]
	v_pk_add_f32 v[96:97], v[96:97], v[98:99]
	v_pk_add_f32 v[100:101], v[100:101], v[102:103]
	v_pk_add_f32 v[96:97], v[96:97], v[100:101]
	v_add_f32_e32 v96, v96, v97
	v_fmamk_f32 v96, v96, 0x3a800000, v154
	v_mul_f32_e32 v97, 0x4b800000, v96
	v_cmp_gt_f32_e32 vcc, s63, v96
	s_nop 1
	v_cndmask_b32_e32 v96, v96, v97, vcc
	v_rsq_f32_e32 v98, v96
	v_lshlrev_b64 v[96:97], 6, v[112:113]
	v_lshl_add_u64 v[96:97], s[22:23], 0, v[96:97]
	v_mul_f32_e32 v99, 0x45800000, v98
	v_cndmask_b32_e32 v98, v98, v99, vcc
	v_pk_mul_f32 v[94:95], v[94:95], v[98:99] op_sel_hi:[1,0]
	v_pk_mul_f32 v[92:93], v[92:93], v[98:99] op_sel_hi:[1,0]
	v_pk_mul_f32 v[90:91], v[90:91], v[98:99] op_sel_hi:[1,0]
	v_pk_mul_f32 v[88:89], v[88:89], v[98:99] op_sel_hi:[1,0]
	v_pk_mul_f32 v[82:83], v[82:83], v[98:99] op_sel_hi:[1,0]
	v_pk_mul_f32 v[80:81], v[80:81], v[98:99] op_sel_hi:[1,0]
	v_pk_mul_f32 v[86:87], v[86:87], v[98:99] op_sel_hi:[1,0]
	v_pk_mul_f32 v[84:85], v[84:85], v[98:99] op_sel_hi:[1,0]
	v_max_f32_e32 v92, 0, v92
	v_max_f32_e32 v88, 0, v88
	v_max_f32_e32 v93, 0, v93
	v_max_f32_e32 v89, 0, v89
	v_max_f32_e32 v94, 0, v94
	v_max_f32_e32 v90, 0, v90
	v_max_f32_e32 v95, 0, v95
	v_max_f32_e32 v91, 0, v91
	v_max_f32_e32 v80, 0, v80
	v_max_f32_e32 v81, 0, v81
	v_max_f32_e32 v82, 0, v82
	v_max_f32_e32 v83, 0, v83
	v_max_f32_e32 v84, 0, v84
	v_max_f32_e32 v85, 0, v85
	v_max_f32_e32 v86, 0, v86
	v_max_f32_e32 v87, 0, v87
	v_pk_mul_f32 v[92:93], v[92:93], v[92:93]
	v_pk_mul_f32 v[88:89], v[88:89], v[88:89]
	v_pk_mul_f32 v[94:95], v[94:95], v[94:95]
	v_pk_mul_f32 v[90:91], v[90:91], v[90:91]
	v_pk_mul_f32 v[98:99], v[80:81], v[80:81]
	v_pk_mul_f32 v[100:101], v[82:83], v[82:83]
	v_cvt_pk_bf16_f32 v80, v92, v93
	v_cvt_pk_bf16_f32 v81, v94, v95
	v_cvt_pk_bf16_f32 v82, v88, v89
	v_cvt_pk_bf16_f32 v83, v90, v91
	v_pk_mul_f32 v[84:85], v[84:85], v[84:85]
	v_pk_mul_f32 v[86:87], v[86:87], v[86:87]
	buffer_store_dwordx4 v[80:83], v116, s[12:15], 0 offen sc1
	s_nop 1
	v_cvt_pk_bf16_f32 v80, v84, v85
	v_cvt_pk_bf16_f32 v81, v86, v87
	v_cvt_pk_bf16_f32 v82, v98, v99
	v_cvt_pk_bf16_f32 v83, v100, v101
	buffer_store_dwordx4 v[80:83], v116, s[12:15], 0 offen offset:256 sc1
	s_nop 0
	v_add_u32_e32 v96, 0x80, v146
	v_ashrrev_i32_e32 v97, 31, v96
	v_lshl_add_u32 v100, v112, 13, v147
	v_add_u32_e32 v181, 0x2800, v180
	global_load_dwordx4 v[214:217], v181, s[22:23]
	v_add_u32_e32 v181, 0x2810, v180
	global_load_dwordx4 v[218:221], v181, s[22:23]
	v_add_u32_e32 v181, 0x2820, v180
	global_load_dwordx4 v[222:225], v181, s[22:23]
	v_add_u32_e32 v181, 0x2830, v180
	global_load_dwordx4 v[232:235], v181, s[22:23]
	s_waitcnt vmcnt(18)
	s_nop 0
	s_nop 0
	v_pk_add_f32 v[80:81], v[236:237], v[238:239]
	v_pk_add_f32 v[82:83], v[240:241], v[242:243]
	v_pk_add_f32 v[84:85], v[244:245], v[246:247]
	v_pk_add_f32 v[86:87], v[248:249], v[250:251]
	v_pk_add_f32 v[80:81], v[80:81], v[82:83]
	v_pk_add_f32 v[84:85], v[84:85], v[86:87]
	v_pk_add_f32 v[80:81], v[80:81], v[84:85]
	v_add_f32_e32 v80, v80, v81
	v_fmamk_f32 v80, v80, 0x3a800000, v154
	v_mul_f32_e32 v81, 0x4b800000, v80
	v_cmp_gt_f32_e32 vcc, s63, v80
	s_nop 1
	v_cndmask_b32_e32 v80, v80, v81, vcc
	v_rsq_f32_e32 v82, v80
	v_lshlrev_b64 v[80:81], 6, v[96:97]
	v_lshl_add_u64 v[80:81], s[22:23], 0, v[80:81]
	v_mul_f32_e32 v83, 0x45800000, v82
	v_cndmask_b32_e32 v82, v82, v83, vcc
	v_pk_mul_f32 v[78:79], v[78:79], v[82:83] op_sel_hi:[1,0]
	v_pk_mul_f32 v[76:77], v[76:77], v[82:83] op_sel_hi:[1,0]
	v_pk_mul_f32 v[74:75], v[74:75], v[82:83] op_sel_hi:[1,0]
	v_pk_mul_f32 v[72:73], v[72:73], v[82:83] op_sel_hi:[1,0]
	v_pk_mul_f32 v[66:67], v[66:67], v[82:83] op_sel_hi:[1,0]
	v_pk_mul_f32 v[64:65], v[64:65], v[82:83] op_sel_hi:[1,0]
	v_pk_mul_f32 v[70:71], v[70:71], v[82:83] op_sel_hi:[1,0]
	v_pk_mul_f32 v[68:69], v[68:69], v[82:83] op_sel_hi:[1,0]
	v_max_f32_e32 v76, 0, v76
	v_max_f32_e32 v72, 0, v72
	v_max_f32_e32 v77, 0, v77
	v_max_f32_e32 v73, 0, v73
	v_max_f32_e32 v78, 0, v78
	v_max_f32_e32 v74, 0, v74
	v_max_f32_e32 v79, 0, v79
	v_max_f32_e32 v75, 0, v75
	v_max_f32_e32 v64, 0, v64
	v_max_f32_e32 v65, 0, v65
	v_max_f32_e32 v66, 0, v66
	v_max_f32_e32 v67, 0, v67
	v_max_f32_e32 v68, 0, v68
	v_max_f32_e32 v69, 0, v69
	v_max_f32_e32 v70, 0, v70
	v_max_f32_e32 v71, 0, v71
	v_pk_mul_f32 v[76:77], v[76:77], v[76:77]
	v_pk_mul_f32 v[72:73], v[72:73], v[72:73]
	v_pk_mul_f32 v[78:79], v[78:79], v[78:79]
	v_pk_mul_f32 v[74:75], v[74:75], v[74:75]
	v_pk_mul_f32 v[82:83], v[64:65], v[64:65]
	v_pk_mul_f32 v[84:85], v[66:67], v[66:67]
	v_cvt_pk_bf16_f32 v64, v76, v77
	v_cvt_pk_bf16_f32 v65, v78, v79
	v_cvt_pk_bf16_f32 v66, v72, v73
	v_cvt_pk_bf16_f32 v67, v74, v75
	v_pk_mul_f32 v[68:69], v[68:69], v[68:69]
	v_pk_mul_f32 v[70:71], v[70:71], v[70:71]
	buffer_store_dwordx4 v[64:67], v100, s[12:15], 0 offen sc1
	s_nop 1
	v_cvt_pk_bf16_f32 v64, v68, v69
	v_cvt_pk_bf16_f32 v65, v70, v71
	v_cvt_pk_bf16_f32 v66, v82, v83
	v_cvt_pk_bf16_f32 v67, v84, v85
	buffer_store_dwordx4 v[64:67], v100, s[12:15], 0 offen offset:256 sc1
	s_nop 0
	v_add_u32_e32 v80, 0x90, v146
	v_ashrrev_i32_e32 v81, 31, v80
	v_lshl_add_u32 v84, v96, 13, v147
	v_add_u32_e32 v181, 0x2c00, v180
	global_load_dwordx4 v[236:239], v181, s[22:23]
	v_add_u32_e32 v181, 0x2c10, v180
	global_load_dwordx4 v[240:243], v181, s[22:23]
	v_add_u32_e32 v181, 0x2c20, v180
	global_load_dwordx4 v[244:247], v181, s[22:23]
	v_add_u32_e32 v181, 0x2c30, v180
	global_load_dwordx4 v[248:251], v181, s[22:23]
	s_waitcnt vmcnt(18)
; __device__ __forceinline__ u32x4 pack8(const f32x4 v0, const f32x4 v1) { u32x4 w; w.x = pk2(v0[0], v0[1]); w.y = pk2(v0[2], v0[3]); w.z = pk2(v1[0], v1[1]); w.w = pk2(v1[2], v1[3]); return w; }
; __device__ __forceinline__ float row_rstd(const float* ssq, int row) {
;     const f32x4* p = (const f32x4*)(ssq + (size_t)row * 16);
;     const f32x4 a = p[0], b = p[1], c = p[2], d = p[3];
;     const float s = ((a[0] + a[1]) + (a[2] + a[3])) + ((b[0] + b[1]) + (b[2] + b[3])) + ((c[0] + c[1]) + (c[2] + c[3])) + ((d[0] + d[1]) + (d[2] + d[3]));
;     return rsqrtf(s * (1.0f / 1024.0f) + 1e-6f);
;     __device__ __forceinline__ void operator()(const f32x4 (&acc)[2][2][4][2], const Unit& u, int wr, int wc, int fr, int fq) const {
;         const __amdgpu_buffer_rsrc_t rsrc = __builtin_amdgcn_make_buffer_rsrc((void*)O, 0, T_ALL * DFF * 2, 0x00020000);
;         const int row0 = row_off + u.pm * 256 + wr * 64 + fr, col0 = u.pn * 256 + wc * 32 + 8 * fq;
; #pragma unroll
;         for (int ai = 0; ai < 2; ++ai)
; #pragma unroll
;             for (int m = 0; m < 4; ++m) {
;                 const int row = row0 + ai * 128 + m * 16; const float rs = row_rstd(ssq, row);
; #pragma unroll
;                 for (int bj = 0; bj < 2; ++bj) { f32x4 v0 = acc[ai][bj][m][0] * rs, v1 = acc[ai][bj][m][1] * rs;
; #pragma unroll
;                     for (int j = 0; j < 4; ++j) { const float a = fmaxf(v0[j], 0.f), b = fmaxf(v1[j], 0.f); v0[j] = a * a; v1[j] = b * b; }
;                     __builtin_amdgcn_raw_buffer_store_b128(pack8(v0, v1), rsrc, (unsigned)(((size_t)row * DFF + col0 + bj * 128) * 2), 0, 16  ); }
;             }
	s_nop 0
	s_nop 0
	v_pk_add_f32 v[64:65], v[182:183], v[184:185]
	v_pk_add_f32 v[66:67], v[186:187], v[188:189]
	v_pk_add_f32 v[68:69], v[190:191], v[192:193]
	v_pk_add_f32 v[70:71], v[194:195], v[196:197]
	v_pk_add_f32 v[64:65], v[64:65], v[66:67]
	v_pk_add_f32 v[68:69], v[68:69], v[70:71]
	v_pk_add_f32 v[64:65], v[64:65], v[68:69]
	v_add_f32_e32 v64, v64, v65
	v_fmamk_f32 v64, v64, 0x3a800000, v154
	v_mul_f32_e32 v65, 0x4b800000, v64
	v_cmp_gt_f32_e32 vcc, s63, v64
	s_nop 1
	v_cndmask_b32_e32 v64, v64, v65, vcc
	v_rsq_f32_e32 v66, v64
	v_lshlrev_b64 v[64:65], 6, v[80:81]
	v_lshl_add_u64 v[64:65], s[22:23], 0, v[64:65]
	v_mul_f32_e32 v67, 0x45800000, v66
	v_cndmask_b32_e32 v66, v66, v67, vcc
	v_pk_mul_f32 v[62:63], v[62:63], v[66:67] op_sel_hi:[1,0]
	v_pk_mul_f32 v[60:61], v[60:61], v[66:67] op_sel_hi:[1,0]
	v_pk_mul_f32 v[58:59], v[58:59], v[66:67] op_sel_hi:[1,0]
	v_pk_mul_f32 v[56:57], v[56:57], v[66:67] op_sel_hi:[1,0]
	v_pk_mul_f32 v[50:51], v[50:51], v[66:67] op_sel_hi:[1,0]
	v_pk_mul_f32 v[48:49], v[48:49], v[66:67] op_sel_hi:[1,0]
	v_pk_mul_f32 v[54:55], v[54:55], v[66:67] op_sel_hi:[1,0]
	v_pk_mul_f32 v[52:53], v[52:53], v[66:67] op_sel_hi:[1,0]
	v_max_f32_e32 v60, 0, v60
	v_max_f32_e32 v56, 0, v56
	v_max_f32_e32 v61, 0, v61
	v_max_f32_e32 v57, 0, v57
	v_max_f32_e32 v62, 0, v62
	v_max_f32_e32 v58, 0, v58
	v_max_f32_e32 v63, 0, v63
	v_max_f32_e32 v59, 0, v59
	v_max_f32_e32 v48, 0, v48
	v_max_f32_e32 v49, 0, v49
	v_max_f32_e32 v50, 0, v50
	v_max_f32_e32 v51, 0, v51
	v_max_f32_e32 v52, 0, v52
	v_max_f32_e32 v53, 0, v53
	v_max_f32_e32 v54, 0, v54
	v_max_f32_e32 v55, 0, v55
	v_pk_mul_f32 v[60:61], v[60:61], v[60:61]
	v_pk_mul_f32 v[56:57], v[56:57], v[56:57]
	v_pk_mul_f32 v[62:63], v[62:63], v[62:63]
	v_pk_mul_f32 v[58:59], v[58:59], v[58:59]
	v_pk_mul_f32 v[66:67], v[48:49], v[48:49]
	v_pk_mul_f32 v[68:69], v[50:51], v[50:51]
	v_cvt_pk_bf16_f32 v48, v60, v61
	v_cvt_pk_bf16_f32 v49, v62, v63
	v_cvt_pk_bf16_f32 v50, v56, v57
	v_cvt_pk_bf16_f32 v51, v58, v59
	v_pk_mul_f32 v[52:53], v[52:53], v[52:53]
	v_pk_mul_f32 v[54:55], v[54:55], v[54:55]
	buffer_store_dwordx4 v[48:51], v84, s[12:15], 0 offen sc1
	s_nop 1
	v_cvt_pk_bf16_f32 v48, v52, v53
	v_cvt_pk_bf16_f32 v49, v54, v55
	v_cvt_pk_bf16_f32 v50, v66, v67
	v_cvt_pk_bf16_f32 v51, v68, v69
	buffer_store_dwordx4 v[48:51], v84, s[12:15], 0 offen offset:256 sc1
	s_nop 0
	v_add_u32_e32 v64, 0xa0, v146
	v_ashrrev_i32_e32 v65, 31, v64
	v_lshl_add_u32 v68, v80, 13, v147
	s_waitcnt vmcnt(14)
	s_nop 0
	s_nop 0
	v_pk_add_f32 v[48:49], v[198:199], v[200:201]
	v_pk_add_f32 v[50:51], v[202:203], v[204:205]
	v_pk_add_f32 v[52:53], v[206:207], v[208:209]
	v_pk_add_f32 v[54:55], v[210:211], v[212:213]
	v_pk_add_f32 v[48:49], v[48:49], v[50:51]
	v_pk_add_f32 v[52:53], v[52:53], v[54:55]
	v_pk_add_f32 v[48:49], v[48:49], v[52:53]
	v_add_f32_e32 v48, v48, v49
	v_fmamk_f32 v48, v48, 0x3a800000, v154
	v_mul_f32_e32 v49, 0x4b800000, v48
	v_cmp_gt_f32_e32 vcc, s63, v48
	s_nop 1
	v_cndmask_b32_e32 v48, v48, v49, vcc
	v_rsq_f32_e32 v50, v48
	v_lshlrev_b64 v[48:49], 6, v[64:65]
	v_lshl_add_u64 v[48:49], s[22:23], 0, v[48:49]
	v_mul_f32_e32 v51, 0x45800000, v50
	v_cndmask_b32_e32 v50, v50, v51, vcc
	v_pk_mul_f32 v[46:47], v[46:47], v[50:51] op_sel_hi:[1,0]
	v_pk_mul_f32 v[44:45], v[44:45], v[50:51] op_sel_hi:[1,0]
	v_pk_mul_f32 v[42:43], v[42:43], v[50:51] op_sel_hi:[1,0]
	v_pk_mul_f32 v[40:41], v[40:41], v[50:51] op_sel_hi:[1,0]
	v_pk_mul_f32 v[34:35], v[34:35], v[50:51] op_sel_hi:[1,0]
	v_pk_mul_f32 v[32:33], v[32:33], v[50:51] op_sel_hi:[1,0]
	v_pk_mul_f32 v[38:39], v[38:39], v[50:51] op_sel_hi:[1,0]
	v_pk_mul_f32 v[36:37], v[36:37], v[50:51] op_sel_hi:[1,0]
	v_max_f32_e32 v44, 0, v44
	v_max_f32_e32 v40, 0, v40
	v_max_f32_e32 v45, 0, v45
	v_max_f32_e32 v41, 0, v41
	v_max_f32_e32 v46, 0, v46
	v_max_f32_e32 v42, 0, v42
	v_max_f32_e32 v47, 0, v47
	v_max_f32_e32 v43, 0, v43
	v_max_f32_e32 v32, 0, v32
	v_max_f32_e32 v33, 0, v33
	v_max_f32_e32 v34, 0, v34
	v_max_f32_e32 v35, 0, v35
	v_max_f32_e32 v36, 0, v36
	v_max_f32_e32 v37, 0, v37
	v_max_f32_e32 v38, 0, v38
	v_max_f32_e32 v39, 0, v39
	v_pk_mul_f32 v[44:45], v[44:45], v[44:45]
	v_pk_mul_f32 v[40:41], v[40:41], v[40:41]
	v_pk_mul_f32 v[46:47], v[46:47], v[46:47]
	v_pk_mul_f32 v[42:43], v[42:43], v[42:43]
	v_pk_mul_f32 v[50:51], v[32:33], v[32:33]
	v_pk_mul_f32 v[52:53], v[34:35], v[34:35]
	v_cvt_pk_bf16_f32 v32, v44, v45
	v_cvt_pk_bf16_f32 v33, v46, v47
	v_cvt_pk_bf16_f32 v34, v40, v41
	v_cvt_pk_bf16_f32 v35, v42, v43
	v_pk_mul_f32 v[36:37], v[36:37], v[36:37]
	v_pk_mul_f32 v[38:39], v[38:39], v[38:39]
	buffer_store_dwordx4 v[32:35], v68, s[12:15], 0 offen sc1
	s_nop 1
	v_cvt_pk_bf16_f32 v32, v36, v37
	v_cvt_pk_bf16_f32 v33, v38, v39
	v_cvt_pk_bf16_f32 v34, v50, v51
	v_cvt_pk_bf16_f32 v35, v52, v53
	buffer_store_dwordx4 v[32:35], v68, s[12:15], 0 offen offset:256 sc1
	s_nop 0
	v_add_u32_e32 v48, 0xb0, v146
	v_ashrrev_i32_e32 v49, 31, v48
	v_lshl_add_u32 v52, v64, 13, v147
	s_waitcnt vmcnt(10)
; __device__ __forceinline__ u32x4 pack8(const f32x4 v0, const f32x4 v1) { u32x4 w; w.x = pk2(v0[0], v0[1]); w.y = pk2(v0[2], v0[3]); w.z = pk2(v1[0], v1[1]); w.w = pk2(v1[2], v1[3]); return w; }
; __device__ __forceinline__ float row_rstd(const float* ssq, int row) {
;     const f32x4* p = (const f32x4*)(ssq + (size_t)row * 16);
;     const f32x4 a = p[0], b = p[1], c = p[2], d = p[3];
;     const float s = ((a[0] + a[1]) + (a[2] + a[3])) + ((b[0] + b[1]) + (b[2] + b[3])) + ((c[0] + c[1]) + (c[2] + c[3])) + ((d[0] + d[1]) + (d[2] + d[3]));
;     return rsqrtf(s * (1.0f / 1024.0f) + 1e-6f);
;     __device__ __forceinline__ void operator()(const f32x4 (&acc)[2][2][4][2], const Unit& u, int wr, int wc, int fr, int fq) const {
;         const __amdgpu_buffer_rsrc_t rsrc = __builtin_amdgcn_make_buffer_rsrc((void*)O, 0, T_ALL * DFF * 2, 0x00020000);
;         const int row0 = row_off + u.pm * 256 + wr * 64 + fr, col0 = u.pn * 256 + wc * 32 + 8 * fq;
; #pragma unroll
;         for (int ai = 0; ai < 2; ++ai)
; #pragma unroll
;             for (int m = 0; m < 4; ++m) {
;                 const int row = row0 + ai * 128 + m * 16; const float rs = row_rstd(ssq, row);
; #pragma unroll
;                 for (int bj = 0; bj < 2; ++bj) { f32x4 v0 = acc[ai][bj][m][0] * rs, v1 = acc[ai][bj][m][1] * rs;
; #pragma unroll
;                     for (int j = 0; j < 4; ++j) { const float a = fmaxf(v0[j], 0.f), b = fmaxf(v1[j], 0.f); v0[j] = a * a; v1[j] = b * b; }
;                     __builtin_amdgcn_raw_buffer_store_b128(pack8(v0, v1), rsrc, (unsigned)(((size_t)row * DFF + col0 + bj * 128) * 2), 0, 16  ); }
;             }
;         asm volatile("s_waitcnt vmcnt(0)" ::: "memory");
;         if (fr == 0 && fq == 0) (void)__hip_atomic_fetch_add(ready + 64 * (pm_off + u.pm), 1u, __ATOMIC_RELAXED, __HIP_MEMORY_SCOPE_AGENT);
	s_nop 0
	s_nop 0
	v_pk_add_f32 v[32:33], v[214:215], v[216:217]
	v_pk_add_f32 v[34:35], v[218:219], v[220:221]
	v_pk_add_f32 v[36:37], v[222:223], v[224:225]
	v_pk_add_f32 v[38:39], v[232:233], v[234:235]
	v_pk_add_f32 v[32:33], v[32:33], v[34:35]
	v_pk_add_f32 v[36:37], v[36:37], v[38:39]
	v_pk_add_f32 v[32:33], v[32:33], v[36:37]
	v_add_f32_e32 v32, v32, v33
	v_fmamk_f32 v32, v32, 0x3a800000, v154
	v_mul_f32_e32 v33, 0x4b800000, v32
	v_cmp_gt_f32_e32 vcc, s63, v32
	s_nop 1
	v_cndmask_b32_e32 v32, v32, v33, vcc
	v_rsq_f32_e32 v34, v32
	v_lshlrev_b64 v[32:33], 6, v[48:49]
	v_lshl_add_u64 v[32:33], s[22:23], 0, v[32:33]
	v_mul_f32_e32 v35, 0x45800000, v34
	v_cndmask_b32_e32 v34, v34, v35, vcc
	v_pk_mul_f32 v[30:31], v[30:31], v[34:35] op_sel_hi:[1,0]
	v_pk_mul_f32 v[28:29], v[28:29], v[34:35] op_sel_hi:[1,0]
	v_pk_mul_f32 v[26:27], v[26:27], v[34:35] op_sel_hi:[1,0]
	v_pk_mul_f32 v[24:25], v[24:25], v[34:35] op_sel_hi:[1,0]
	v_pk_mul_f32 v[18:19], v[18:19], v[34:35] op_sel_hi:[1,0]
	v_pk_mul_f32 v[16:17], v[16:17], v[34:35] op_sel_hi:[1,0]
	v_pk_mul_f32 v[22:23], v[22:23], v[34:35] op_sel_hi:[1,0]
	v_pk_mul_f32 v[20:21], v[20:21], v[34:35] op_sel_hi:[1,0]
	v_max_f32_e32 v28, 0, v28
	v_max_f32_e32 v24, 0, v24
	v_max_f32_e32 v29, 0, v29
	v_max_f32_e32 v25, 0, v25
	v_max_f32_e32 v30, 0, v30
	v_max_f32_e32 v26, 0, v26
	v_max_f32_e32 v31, 0, v31
	v_max_f32_e32 v27, 0, v27
	v_max_f32_e32 v16, 0, v16
	v_max_f32_e32 v17, 0, v17
	v_max_f32_e32 v18, 0, v18
	v_max_f32_e32 v19, 0, v19
	v_max_f32_e32 v20, 0, v20
	v_max_f32_e32 v21, 0, v21
	v_max_f32_e32 v22, 0, v22
	v_max_f32_e32 v23, 0, v23
	v_pk_mul_f32 v[28:29], v[28:29], v[28:29]
	v_pk_mul_f32 v[24:25], v[24:25], v[24:25]
	v_pk_mul_f32 v[30:31], v[30:31], v[30:31]
	v_pk_mul_f32 v[26:27], v[26:27], v[26:27]
	v_pk_mul_f32 v[34:35], v[16:17], v[16:17]
	v_pk_mul_f32 v[36:37], v[18:19], v[18:19]
	v_cvt_pk_bf16_f32 v16, v28, v29
	v_cvt_pk_bf16_f32 v17, v30, v31
	v_cvt_pk_bf16_f32 v18, v24, v25
	v_cvt_pk_bf16_f32 v19, v26, v27
	v_pk_mul_f32 v[20:21], v[20:21], v[20:21]
	v_pk_mul_f32 v[22:23], v[22:23], v[22:23]
	buffer_store_dwordx4 v[16:19], v52, s[12:15], 0 offen sc1
	s_nop 1
	v_cvt_pk_bf16_f32 v16, v20, v21
	v_cvt_pk_bf16_f32 v17, v22, v23
	v_cvt_pk_bf16_f32 v18, v34, v35
	v_cvt_pk_bf16_f32 v19, v36, v37
	buffer_store_dwordx4 v[16:19], v52, s[12:15], 0 offen offset:256 sc1
	s_nop 0
	s_waitcnt vmcnt(6)
	s_nop 0
	s_nop 0
	v_pk_add_f32 v[16:17], v[236:237], v[238:239]
	v_pk_add_f32 v[18:19], v[240:241], v[242:243]
	v_pk_add_f32 v[20:21], v[244:245], v[246:247]
	v_pk_add_f32 v[22:23], v[248:249], v[250:251]
	v_pk_add_f32 v[16:17], v[16:17], v[18:19]
	v_pk_add_f32 v[20:21], v[20:21], v[22:23]
	v_pk_add_f32 v[16:17], v[16:17], v[20:21]
	v_add_f32_e32 v16, v16, v17
	v_fmamk_f32 v16, v16, 0x3a800000, v154
	v_mul_f32_e32 v17, 0x4b800000, v16
	v_cmp_gt_f32_e32 vcc, s63, v16
	s_nop 1
	v_cndmask_b32_e32 v16, v16, v17, vcc
	v_rsq_f32_e32 v16, v16
	v_lshl_add_u32 v17, v48, 13, v147
	v_mul_f32_e32 v18, 0x45800000, v16
	v_cndmask_b32_e32 v16, v16, v18, vcc
	v_pk_mul_f32 v[14:15], v[14:15], v[16:17] op_sel_hi:[1,0]
	v_pk_mul_f32 v[12:13], v[12:13], v[16:17] op_sel_hi:[1,0]
	v_pk_mul_f32 v[10:11], v[10:11], v[16:17] op_sel_hi:[1,0]
	v_pk_mul_f32 v[8:9], v[8:9], v[16:17] op_sel_hi:[1,0]
	v_pk_mul_f32 v[2:3], v[2:3], v[16:17] op_sel_hi:[1,0]
	v_pk_mul_f32 v[0:1], v[0:1], v[16:17] op_sel_hi:[1,0]
	v_pk_mul_f32 v[6:7], v[6:7], v[16:17] op_sel_hi:[1,0]
	v_pk_mul_f32 v[4:5], v[4:5], v[16:17] op_sel_hi:[1,0]
	v_max_f32_e32 v12, 0, v12
	v_max_f32_e32 v8, 0, v8
	v_max_f32_e32 v13, 0, v13
	v_max_f32_e32 v9, 0, v9
	v_max_f32_e32 v14, 0, v14
	v_max_f32_e32 v10, 0, v10
	v_max_f32_e32 v15, 0, v15
	v_max_f32_e32 v11, 0, v11
	v_max_f32_e32 v0, 0, v0
	v_max_f32_e32 v1, 0, v1
	v_max_f32_e32 v2, 0, v2
	v_max_f32_e32 v3, 0, v3
	v_max_f32_e32 v4, 0, v4
	v_max_f32_e32 v5, 0, v5
	v_max_f32_e32 v6, 0, v6
	v_max_f32_e32 v7, 0, v7
	v_pk_mul_f32 v[12:13], v[12:13], v[12:13]
	v_pk_mul_f32 v[8:9], v[8:9], v[8:9]
	v_pk_mul_f32 v[14:15], v[14:15], v[14:15]
	v_pk_mul_f32 v[10:11], v[10:11], v[10:11]
	v_mul_f32_e32 v16, v0, v0
	v_mul_f32_e32 v18, v1, v1
	v_mul_f32_e32 v19, v2, v2
	v_mul_f32_e32 v20, v3, v3
	v_cvt_pk_bf16_f32 v0, v12, v13
	v_cvt_pk_bf16_f32 v1, v14, v15
	v_cvt_pk_bf16_f32 v2, v8, v9
	v_cvt_pk_bf16_f32 v3, v10, v11
	v_pk_mul_f32 v[4:5], v[4:5], v[4:5]
	v_pk_mul_f32 v[6:7], v[6:7], v[6:7]
	buffer_store_dwordx4 v[0:3], v17, s[12:15], 0 offen sc1
	s_nop 1
	v_cvt_pk_bf16_f32 v0, v4, v5
	v_cvt_pk_bf16_f32 v1, v6, v7
	v_cvt_pk_bf16_f32 v2, v16, v18
	v_cvt_pk_bf16_f32 v3, v19, v20
	buffer_store_dwordx4 v[0:3], v17, s[12:15], 0 offen offset:256 sc1
	s_waitcnt vmcnt(0)
	s_and_saveexec_b64 s[36:37], s[6:7]
	s_cbranch_execz .LBB0_2091
	s_mov_b64 s[38:39], exec
	v_mbcnt_lo_u32_b32 v0, s38, 0
	v_mbcnt_hi_u32_b32 v0, s39, v0
	v_cmp_eq_u32_e32 vcc, 0, v0
	s_and_b64 s[40:41], exec, vcc
	s_mov_b64 exec, s[40:41]
	s_cbranch_execz .LBB0_2091
	s_lshl_b32 s40, s68, 6
	s_ashr_i32 s41, s40, 31
	s_lshl_b64 s[40:41], s[40:41], 2
	s_add_u32 s40, s66, s40
	s_addc_u32 s41, s67, s41
	s_bcnt1_i32_b64 s25, s[38:39]
	v_mov_b32_e32 v0, s25
	global_atomic_add v131, v0, s[40:41]
	s_branch .LBB0_2091

; #define PG8_STAGE(bufoff, gbase, voff) do { _Pragma("unroll") for (int _i = 0; _i < 2; ++_i) \
;         __builtin_amdgcn_global_load_lds((const unsigned*)((const char*)(gbase) + (voff)[_i]), (LAS unsigned*)(lds + (bufoff) + ldsw + _i * 8192), 16, 0, 0); } while (0)
; #define PG8_LDA(dst, b, h) do { _Pragma("unroll") for (int m = 0; m < 4; ++m) _Pragma("unroll") for (int k = 0; k < 2; ++k) dst[m][k] = *(const LAS bf16x8*)(lds + PG8_SA(b, h) + aoff + m * 2048 + k * 1024); } while (0)
; #define PG8_LDB(dst, b, h) do { _Pragma("unroll") for (int n = 0; n < 2; ++n) _Pragma("unroll") for (int k = 0; k < 2; ++k) dst[n][k] = *(const LAS bf16x8*)(lds + PG8_SB(b, h) + boff + n * 2048 + k * 1024); } while (0)
; #define PG8_MMA(ai, bj, At, Bt) do { __builtin_amdgcn_s_setprio(1); _Pragma("unroll") for (int m = 0; m < 4; ++m) _Pragma("unroll") for (int n = 0; n < 2; ++n) _Pragma("unroll") for (int k = 0; k < 2; ++k) \
;         acc[ai][bj][m][n] = __builtin_amdgcn_mfma_f32_16x16x32_bf16(Bt[n][k], At[m][k], acc[ai][bj][m][n], 0, 0, 0); __builtin_amdgcn_s_setprio(0); } while (0)
; #define PG8_WAIT_L(n) asm volatile("s_waitcnt lgkmcnt(" #n ")" ::: "memory")
; #define PG8_BAR __builtin_amdgcn_s_barrier()
; #define PG8_SCHED __builtin_amdgcn_sched_barrier(0)
;     ...
;             PG8_LDB(B0, 0, 0); PG8_SCHED; PG8_LDA(At, 0, 0); PG8_STAGE(PG8_SA(1, 1), a1 + hA, voffA);
;             PG8_WAIT_L(8); PG8_BAR; PG8_WAIT_L(0); PG8_MMA(0, 0, At, B0); PG8_BAR; PG8_SCHED;
;             PG8_LDB(B1, 0, 1); PG8_STAGE(PG8_SB(0, 0), b2, voffB);
;             PG8_BAR; PG8_WAIT_L(0); PG8_MMA(0, 1, At, B1); PG8_BAR;
;             PG8_LDA(At, 0, 1); PG8_STAGE(PG8_SA(0, 0), a2, voffA);
;             PG8_BAR; PG8_WAIT_L(0); PG8_MMA(1, 0, At, B0); PG8_BAR; PG8_SCHED;
.LBB0_2122:
	ds_read_b128 v[150:153], v143
	ds_read_b128 v[154:157], v143 offset:1024
	ds_read_b128 v[158:161], v143 offset:2048
	ds_read_b128 v[162:165], v143 offset:3072
	s_add_u32 s36, s34, 0xfffc0080
	s_addc_u32 s37, s35, -1
	s_cmp_eq_u32 s71, 12
	s_cselect_b32 s39, s21, s37
	s_cselect_b32 s38, s44, s36
	s_cselect_b32 s37, s29, s70
	s_cselect_b32 s36, s45, s69
	v_lshl_add_u64 v[202:203], s[34:35], 0, v[138:139]
	s_add_i32 m0, s53, 0xc000
	ds_read_b128 v[170:173], v146
	ds_read_b128 v[174:177], v146 offset:1024
	ds_read_b128 v[178:181], v146 offset:2048
	ds_read_b128 v[182:185], v146 offset:3072
	ds_read_b128 v[186:189], v146 offset:4096
	ds_read_b128 v[190:193], v146 offset:5120
	ds_read_b128 v[194:197], v146 offset:6144
	ds_read_b128 v[198:201], v146 offset:7168
	global_load_lds_dwordx4 v[202:203], off
	v_lshl_add_u64 v[202:203], s[34:35], 0, v[136:137]
	s_add_i32 m0, s53, 0xe000
	s_nop 0
	global_load_lds_dwordx4 v[202:203], off
	s_waitcnt lgkmcnt(8)
	s_barrier
	s_waitcnt lgkmcnt(0)
	s_setprio 1
	s_waitcnt lgkmcnt(0)
	v_mfma_f32_16x16x32_bf16 v[124:127], v[150:153], v[170:173], v[124:127]
	v_mfma_f32_16x16x32_bf16 v[120:123], v[158:161], v[170:173], v[120:123]
	v_mfma_f32_16x16x32_bf16 v[108:111], v[150:153], v[178:181], v[108:111]
	v_mfma_f32_16x16x32_bf16 v[104:107], v[158:161], v[178:181], v[104:107]
	v_mfma_f32_16x16x32_bf16 v[92:95], v[150:153], v[186:189], v[92:95]
	v_mfma_f32_16x16x32_bf16 v[88:91], v[158:161], v[186:189], v[88:91]
	v_mfma_f32_16x16x32_bf16 v[76:79], v[150:153], v[194:197], v[76:79]
	v_mfma_f32_16x16x32_bf16 v[72:75], v[158:161], v[194:197], v[72:75]
	v_mfma_f32_16x16x32_bf16 v[124:127], v[154:157], v[174:177], v[124:127]
	v_mfma_f32_16x16x32_bf16 v[120:123], v[162:165], v[174:177], v[120:123]
	v_mfma_f32_16x16x32_bf16 v[108:111], v[154:157], v[182:185], v[108:111]
	v_mfma_f32_16x16x32_bf16 v[104:107], v[162:165], v[182:185], v[104:107]
	v_mfma_f32_16x16x32_bf16 v[92:95], v[154:157], v[190:193], v[92:95]
	v_mfma_f32_16x16x32_bf16 v[88:91], v[162:165], v[190:193], v[88:91]
	v_mfma_f32_16x16x32_bf16 v[76:79], v[154:157], v[198:201], v[76:79]
	v_mfma_f32_16x16x32_bf16 v[72:75], v[162:165], v[198:201], v[72:75]
	s_setprio 0
	s_barrier
	s_add_i32 s72, s61, s52
	v_lshl_add_u64 v[218:219], s[36:37], 0, v[130:131]
	s_mov_b32 m0, s72
	ds_read_b128 v[202:205], v147
	ds_read_b128 v[206:209], v147 offset:1024
	ds_read_b128 v[210:213], v147 offset:2048
	ds_read_b128 v[214:217], v147 offset:3072
	global_load_lds_dwordx4 v[218:219], off
	v_lshl_add_u64 v[220:221], s[36:37], 0, v[134:135]
	s_add_i32 m0, s72, 0x2000
	s_nop 0
	global_load_lds_dwordx4 v[220:221], off
	s_barrier
	s_waitcnt lgkmcnt(0)
	s_setprio 1
	s_waitcnt lgkmcnt(0)
	v_mfma_f32_16x16x32_bf16 v[116:119], v[202:205], v[170:173], v[116:119]
	v_mfma_f32_16x16x32_bf16 v[112:115], v[210:213], v[170:173], v[112:115]
	v_mfma_f32_16x16x32_bf16 v[100:103], v[202:205], v[178:181], v[100:103]
	v_mfma_f32_16x16x32_bf16 v[96:99], v[210:213], v[178:181], v[96:99]
	v_mfma_f32_16x16x32_bf16 v[84:87], v[202:205], v[186:189], v[84:87]
	v_mfma_f32_16x16x32_bf16 v[80:83], v[210:213], v[186:189], v[80:83]
	v_mfma_f32_16x16x32_bf16 v[68:71], v[202:205], v[194:197], v[68:71]
	v_mfma_f32_16x16x32_bf16 v[64:67], v[210:213], v[194:197], v[64:67]
	v_mfma_f32_16x16x32_bf16 v[116:119], v[206:209], v[174:177], v[116:119]
	v_mfma_f32_16x16x32_bf16 v[112:115], v[214:217], v[174:177], v[112:115]
	v_mfma_f32_16x16x32_bf16 v[100:103], v[206:209], v[182:185], v[100:103]
	v_mfma_f32_16x16x32_bf16 v[96:99], v[214:217], v[182:185], v[96:99]
	v_mfma_f32_16x16x32_bf16 v[84:87], v[206:209], v[190:193], v[84:87]
	v_mfma_f32_16x16x32_bf16 v[80:83], v[214:217], v[190:193], v[80:83]
	v_mfma_f32_16x16x32_bf16 v[68:71], v[206:209], v[198:201], v[68:71]
	v_mfma_f32_16x16x32_bf16 v[64:67], v[214:217], v[198:201], v[64:67]
	s_setprio 0
	s_mov_b32 m0, s53
	v_lshl_add_u64 v[222:223], s[38:39], 0, v[128:129]
	s_barrier
	ds_read_b128 v[170:173], v146 offset:16384
	ds_read_b128 v[174:177], v146 offset:17408
	ds_read_b128 v[178:181], v146 offset:18432
	ds_read_b128 v[182:185], v146 offset:19456
	ds_read_b128 v[186:189], v146 offset:20480
	ds_read_b128 v[190:193], v146 offset:21504
	ds_read_b128 v[194:197], v146 offset:22528
	ds_read_b128 v[198:201], v146 offset:23552
	global_load_lds_dwordx4 v[222:223], off
	v_lshl_add_u64 v[224:225], s[38:39], 0, v[132:133]
	s_mov_b32 m0, s54
	s_nop 0
	global_load_lds_dwordx4 v[224:225], off
	s_barrier
	s_waitcnt lgkmcnt(0)
	s_setprio 1
	s_waitcnt lgkmcnt(0)
	v_mfma_f32_16x16x32_bf16 v[60:63], v[150:153], v[170:173], v[60:63]
	v_mfma_f32_16x16x32_bf16 v[56:59], v[158:161], v[170:173], v[56:59]
	v_mfma_f32_16x16x32_bf16 v[44:47], v[150:153], v[178:181], v[44:47]
	v_mfma_f32_16x16x32_bf16 v[40:43], v[158:161], v[178:181], v[40:43]
	v_mfma_f32_16x16x32_bf16 v[28:31], v[150:153], v[186:189], v[28:31]
	v_mfma_f32_16x16x32_bf16 v[24:27], v[158:161], v[186:189], v[24:27]
	v_mfma_f32_16x16x32_bf16 v[12:15], v[150:153], v[194:197], v[12:15]
	v_mfma_f32_16x16x32_bf16 v[8:11], v[158:161], v[194:197], v[8:11]
	v_mfma_f32_16x16x32_bf16 v[60:63], v[154:157], v[174:177], v[60:63]
	v_mfma_f32_16x16x32_bf16 v[56:59], v[162:165], v[174:177], v[56:59]
	v_mfma_f32_16x16x32_bf16 v[44:47], v[154:157], v[182:185], v[44:47]
	v_mfma_f32_16x16x32_bf16 v[40:43], v[162:165], v[182:185], v[40:43]
	v_mfma_f32_16x16x32_bf16 v[28:31], v[154:157], v[190:193], v[28:31]
	v_mfma_f32_16x16x32_bf16 v[24:27], v[162:165], v[190:193], v[24:27]
	v_mfma_f32_16x16x32_bf16 v[12:15], v[154:157], v[198:201], v[12:15]
	v_mfma_f32_16x16x32_bf16 v[8:11], v[162:165], v[198:201], v[8:11]
	s_setprio 0
	s_barrier
; #define PG8_STAGE(bufoff, gbase, voff) do { _Pragma("unroll") for (int _i = 0; _i < 2; ++_i) \
;         __builtin_amdgcn_global_load_lds((const unsigned*)((const char*)(gbase) + (voff)[_i]), (LAS unsigned*)(lds + (bufoff) + ldsw + _i * 8192), 16, 0, 0); } while (0)
; #define PG8_LDA(dst, b, h) do { _Pragma("unroll") for (int m = 0; m < 4; ++m) _Pragma("unroll") for (int k = 0; k < 2; ++k) dst[m][k] = *(const LAS bf16x8*)(lds + PG8_SA(b, h) + aoff + m * 2048 + k * 1024); } while (0)
; #define PG8_LDB(dst, b, h) do { _Pragma("unroll") for (int n = 0; n < 2; ++n) _Pragma("unroll") for (int k = 0; k < 2; ++k) dst[n][k] = *(const LAS bf16x8*)(lds + PG8_SB(b, h) + boff + n * 2048 + k * 1024); } while (0)
; #define PG8_MMA(ai, bj, At, Bt) do { __builtin_amdgcn_s_setprio(1); _Pragma("unroll") for (int m = 0; m < 4; ++m) _Pragma("unroll") for (int n = 0; n < 2; ++n) _Pragma("unroll") for (int k = 0; k < 2; ++k) \
;         acc[ai][bj][m][n] = __builtin_amdgcn_mfma_f32_16x16x32_bf16(Bt[n][k], At[m][k], acc[ai][bj][m][n], 0, 0, 0); __builtin_amdgcn_s_setprio(0); } while (0)
; #define PG8_WAIT_V(n) asm volatile("s_waitcnt vmcnt(" #n ")" ::: "memory")
; #define PG8_WAIT_L(n) asm volatile("s_waitcnt lgkmcnt(" #n ")" ::: "memory")
; #define PG8_BAR __builtin_amdgcn_s_barrier()
; #define PG8_SCHED __builtin_amdgcn_sched_barrier(0)
;     ...
;             PG8_STAGE(PG8_SB(0, 1), b2 + hB, voffB);
;             PG8_WAIT_V(6); PG8_BAR; PG8_MMA(1, 1, At, B1); PG8_BAR;
;             PG8_LDB(B0, 1, 0); PG8_SCHED; PG8_LDA(At, 1, 0); PG8_STAGE(PG8_SA(0, 1), a2 + hA, voffA);
;             PG8_WAIT_L(8); PG8_BAR; PG8_WAIT_L(0); PG8_MMA(0, 0, At, B0); PG8_BAR; PG8_SCHED;
;             PG8_LDB(B1, 1, 1); PG8_STAGE(PG8_SB(1, 0), b3, voffB);
;             PG8_BAR; PG8_WAIT_L(0); PG8_MMA(0, 1, At, B1); PG8_BAR;
;             PG8_LDA(At, 1, 1); PG8_STAGE(PG8_SA(1, 0), a3, voffA);
	s_add_u32 s72, s36, 0x40000
	s_addc_u32 s73, s37, 0
	s_add_i32 s74, s62, s52
	v_lshl_add_u64 v[150:151], s[72:73], 0, v[130:131]
	s_mov_b32 m0, s74
	s_nop 0
	global_load_lds_dwordx4 v[150:151], off
	v_lshl_add_u64 v[150:151], s[72:73], 0, v[134:135]
	s_add_i32 m0, s74, 0x2000
	s_nop 0
	global_load_lds_dwordx4 v[150:151], off
	s_waitcnt vmcnt(6)
	s_barrier
	s_setprio 1
	v_mfma_f32_16x16x32_bf16 v[52:55], v[202:205], v[170:173], v[52:55]
	v_mfma_f32_16x16x32_bf16 v[48:51], v[210:213], v[170:173], v[48:51]
	v_mfma_f32_16x16x32_bf16 v[36:39], v[202:205], v[178:181], v[36:39]
	v_mfma_f32_16x16x32_bf16 v[32:35], v[210:213], v[178:181], v[32:35]
	v_mfma_f32_16x16x32_bf16 v[20:23], v[202:205], v[186:189], v[20:23]
	v_mfma_f32_16x16x32_bf16 v[16:19], v[210:213], v[186:189], v[16:19]
	v_mfma_f32_16x16x32_bf16 v[4:7], v[202:205], v[194:197], v[4:7]
	v_mfma_f32_16x16x32_bf16 v[0:3], v[210:213], v[194:197], v[0:3]
	v_mfma_f32_16x16x32_bf16 v[52:55], v[206:209], v[174:177], v[52:55]
	v_mfma_f32_16x16x32_bf16 v[48:51], v[214:217], v[174:177], v[48:51]
	v_mfma_f32_16x16x32_bf16 v[36:39], v[206:209], v[182:185], v[36:39]
	v_mfma_f32_16x16x32_bf16 v[32:35], v[214:217], v[182:185], v[32:35]
	v_mfma_f32_16x16x32_bf16 v[20:23], v[206:209], v[190:193], v[20:23]
	v_mfma_f32_16x16x32_bf16 v[16:19], v[214:217], v[190:193], v[16:19]
	v_mfma_f32_16x16x32_bf16 v[4:7], v[206:209], v[198:201], v[4:7]
	v_mfma_f32_16x16x32_bf16 v[0:3], v[214:217], v[198:201], v[0:3]
	s_setprio 0
	s_add_i32 s72, 0, 0x18000
	v_add_u32_e32 v149, s72, v141
	s_barrier
	ds_read_b128 v[150:153], v149
	ds_read_b128 v[154:157], v149 offset:1024
	ds_read_b128 v[158:161], v149 offset:2048
	ds_read_b128 v[162:165], v149 offset:3072
	s_add_u32 s38, s38, 0x40000
	s_addc_u32 s39, s39, 0
	s_mov_b32 m0, s55
	v_lshl_add_u64 v[202:203], s[38:39], 0, v[128:129]
	ds_read_b128 v[170:173], v146 offset:32768
	ds_read_b128 v[174:177], v146 offset:33792
	ds_read_b128 v[178:181], v146 offset:34816
	ds_read_b128 v[182:185], v146 offset:35840
	ds_read_b128 v[186:189], v146 offset:36864
	ds_read_b128 v[190:193], v146 offset:37888
	ds_read_b128 v[194:197], v146 offset:38912
	ds_read_b128 v[198:201], v146 offset:39936
	global_load_lds_dwordx4 v[202:203], off
	v_lshl_add_u64 v[202:203], s[38:39], 0, v[132:133]
	s_mov_b32 m0, s56
	s_nop 0
	global_load_lds_dwordx4 v[202:203], off
	s_waitcnt lgkmcnt(8)
	s_barrier
	s_waitcnt lgkmcnt(0)
	s_setprio 1
	s_waitcnt lgkmcnt(0)
	v_mfma_f32_16x16x32_bf16 v[124:127], v[150:153], v[170:173], v[124:127]
	v_mfma_f32_16x16x32_bf16 v[120:123], v[158:161], v[170:173], v[120:123]
	v_mfma_f32_16x16x32_bf16 v[108:111], v[150:153], v[178:181], v[108:111]
	v_mfma_f32_16x16x32_bf16 v[104:107], v[158:161], v[178:181], v[104:107]
	v_mfma_f32_16x16x32_bf16 v[92:95], v[150:153], v[186:189], v[92:95]
	v_mfma_f32_16x16x32_bf16 v[88:91], v[158:161], v[186:189], v[88:91]
	v_mfma_f32_16x16x32_bf16 v[76:79], v[150:153], v[194:197], v[76:79]
	v_mfma_f32_16x16x32_bf16 v[72:75], v[158:161], v[194:197], v[72:75]
	v_mfma_f32_16x16x32_bf16 v[124:127], v[154:157], v[174:177], v[124:127]
	v_mfma_f32_16x16x32_bf16 v[120:123], v[162:165], v[174:177], v[120:123]
	v_mfma_f32_16x16x32_bf16 v[108:111], v[154:157], v[182:185], v[108:111]
	v_mfma_f32_16x16x32_bf16 v[104:107], v[162:165], v[182:185], v[104:107]
	v_mfma_f32_16x16x32_bf16 v[92:95], v[154:157], v[190:193], v[92:95]
	v_mfma_f32_16x16x32_bf16 v[88:91], v[162:165], v[190:193], v[88:91]
	v_mfma_f32_16x16x32_bf16 v[76:79], v[154:157], v[198:201], v[76:79]
	v_mfma_f32_16x16x32_bf16 v[72:75], v[162:165], v[198:201], v[72:75]
	s_setprio 0
	s_barrier
	s_add_i32 s38, 0, 0x1c000
	s_add_i32 s39, s72, s52
	v_add_u32_e32 v149, s38, v141
	v_lshl_add_u64 v[218:219], v[218:219], 0, s[22:23]
	s_mov_b32 m0, s39
	ds_read_b128 v[202:205], v149
	ds_read_b128 v[206:209], v149 offset:1024
	ds_read_b128 v[210:213], v149 offset:2048
	ds_read_b128 v[214:217], v149 offset:3072
	global_load_lds_dwordx4 v[218:219], off
	v_lshl_add_u64 v[218:219], v[220:221], 0, s[22:23]
	s_add_i32 m0, s39, 0x2000
	s_nop 0
	global_load_lds_dwordx4 v[218:219], off
	s_barrier
	s_waitcnt lgkmcnt(0)
	s_setprio 1
	s_waitcnt lgkmcnt(0)
	v_mfma_f32_16x16x32_bf16 v[116:119], v[202:205], v[170:173], v[116:119]
	v_mfma_f32_16x16x32_bf16 v[112:115], v[210:213], v[170:173], v[112:115]
	v_mfma_f32_16x16x32_bf16 v[100:103], v[202:205], v[178:181], v[100:103]
	v_mfma_f32_16x16x32_bf16 v[96:99], v[210:213], v[178:181], v[96:99]
	v_mfma_f32_16x16x32_bf16 v[84:87], v[202:205], v[186:189], v[84:87]
	v_mfma_f32_16x16x32_bf16 v[80:83], v[210:213], v[186:189], v[80:83]
	v_mfma_f32_16x16x32_bf16 v[68:71], v[202:205], v[194:197], v[68:71]
	v_mfma_f32_16x16x32_bf16 v[64:67], v[210:213], v[194:197], v[64:67]
	v_mfma_f32_16x16x32_bf16 v[116:119], v[206:209], v[174:177], v[116:119]
	v_mfma_f32_16x16x32_bf16 v[112:115], v[214:217], v[174:177], v[112:115]
	v_mfma_f32_16x16x32_bf16 v[100:103], v[206:209], v[182:185], v[100:103]
	v_mfma_f32_16x16x32_bf16 v[96:99], v[214:217], v[182:185], v[96:99]
	v_mfma_f32_16x16x32_bf16 v[84:87], v[206:209], v[190:193], v[84:87]
	v_mfma_f32_16x16x32_bf16 v[80:83], v[214:217], v[190:193], v[80:83]
	v_mfma_f32_16x16x32_bf16 v[68:71], v[206:209], v[198:201], v[68:71]
	v_mfma_f32_16x16x32_bf16 v[64:67], v[214:217], v[198:201], v[64:67]
	s_setprio 0
	s_mov_b32 m0, s58
	v_lshl_add_u64 v[218:219], v[222:223], 0, s[22:23]
	s_barrier
	ds_read_b128 v[170:173], v146 offset:49152
	ds_read_b128 v[174:177], v146 offset:50176
	ds_read_b128 v[178:181], v146 offset:51200
	ds_read_b128 v[182:185], v146 offset:52224
	ds_read_b128 v[186:189], v146 offset:53248
	ds_read_b128 v[190:193], v146 offset:54272
	ds_read_b128 v[194:197], v146 offset:55296
	ds_read_b128 v[198:201], v146 offset:56320
	global_load_lds_dwordx4 v[218:219], off
	v_lshl_add_u64 v[218:219], v[224:225], 0, s[22:23]
	s_mov_b32 m0, s59
	s_nop 0
	global_load_lds_dwordx4 v[218:219], off
	s_barrier
; #define PG8_STAGE(bufoff, gbase, voff) do { _Pragma("unroll") for (int _i = 0; _i < 2; ++_i) \
;         __builtin_amdgcn_global_load_lds((const unsigned*)((const char*)(gbase) + (voff)[_i]), (LAS unsigned*)(lds + (bufoff) + ldsw + _i * 8192), 16, 0, 0); } while (0)
; #define PG8_MMA(ai, bj, At, Bt) do { __builtin_amdgcn_s_setprio(1); _Pragma("unroll") for (int m = 0; m < 4; ++m) _Pragma("unroll") for (int n = 0; n < 2; ++n) _Pragma("unroll") for (int k = 0; k < 2; ++k) \
;         acc[ai][bj][m][n] = __builtin_amdgcn_mfma_f32_16x16x32_bf16(Bt[n][k], At[m][k], acc[ai][bj][m][n], 0, 0, 0); __builtin_amdgcn_s_setprio(0); } while (0)
; #define PG8_WAIT_V(n) asm volatile("s_waitcnt vmcnt(" #n ")" ::: "memory")
; #define PG8_WAIT_L(n) asm volatile("s_waitcnt lgkmcnt(" #n ")" ::: "memory")
; #define PG8_BAR __builtin_amdgcn_s_barrier()
; #define PG8_SCHED __builtin_amdgcn_sched_barrier(0)
;     ...
;             PG8_BAR; PG8_WAIT_L(0); PG8_MMA(1, 0, At, B0); PG8_BAR; PG8_SCHED;
;             PG8_STAGE(PG8_SB(1, 1), b3 + hB, voffB);
;             PG8_WAIT_V(6); PG8_BAR; PG8_MMA(1, 1, At, B1); PG8_BAR;
;         }
;         E(acc, cur, wr, wc, fr, fq);
;     __device__ __forceinline__ void operator()(const f32x4 (&acc)[2][2][4][2], const Unit& u, int wr, int wc, int fr, int fq) const {
;         const __amdgpu_buffer_rsrc_t rsrc = __builtin_amdgcn_make_buffer_rsrc((void*)O, 0, T_ALL * DFF * 2, 0x00020000);
;         const int row0 = row_off + u.pm * 256 + wr * 64 + fr, col0 = u.pn * 256 + wc * 32 + 8 * fq;
; #pragma unroll
;         for (int ai = 0; ai < 2; ++ai)
; #pragma unroll
;             for (int m = 0; m < 4; ++m) {
;                 const int row = row0 + ai * 128 + m * 16; const float rs = row_rstd(ssq, row);
	s_waitcnt lgkmcnt(0)
	s_setprio 1
	s_waitcnt lgkmcnt(0)
	v_mfma_f32_16x16x32_bf16 v[60:63], v[150:153], v[170:173], v[60:63]
	v_mfma_f32_16x16x32_bf16 v[56:59], v[158:161], v[170:173], v[56:59]
	v_mfma_f32_16x16x32_bf16 v[44:47], v[150:153], v[178:181], v[44:47]
	v_mfma_f32_16x16x32_bf16 v[40:43], v[158:161], v[178:181], v[40:43]
	v_mfma_f32_16x16x32_bf16 v[28:31], v[150:153], v[186:189], v[28:31]
	v_mfma_f32_16x16x32_bf16 v[24:27], v[158:161], v[186:189], v[24:27]
	v_mfma_f32_16x16x32_bf16 v[12:15], v[150:153], v[194:197], v[12:15]
	v_mfma_f32_16x16x32_bf16 v[8:11], v[158:161], v[194:197], v[8:11]
	v_mfma_f32_16x16x32_bf16 v[60:63], v[154:157], v[174:177], v[60:63]
	v_mfma_f32_16x16x32_bf16 v[56:59], v[162:165], v[174:177], v[56:59]
	v_mfma_f32_16x16x32_bf16 v[44:47], v[154:157], v[182:185], v[44:47]
	v_mfma_f32_16x16x32_bf16 v[40:43], v[162:165], v[182:185], v[40:43]
	v_mfma_f32_16x16x32_bf16 v[28:31], v[154:157], v[190:193], v[28:31]
	v_mfma_f32_16x16x32_bf16 v[24:27], v[162:165], v[190:193], v[24:27]
	v_mfma_f32_16x16x32_bf16 v[12:15], v[154:157], v[198:201], v[12:15]
	v_mfma_f32_16x16x32_bf16 v[8:11], v[162:165], v[198:201], v[8:11]
	s_setprio 0
	s_barrier
	s_add_u32 s36, s36, 0x40080
	s_addc_u32 s37, s37, 0
	s_add_i32 s38, s38, s52
	v_lshl_add_u64 v[150:151], s[36:37], 0, v[130:131]
	s_mov_b32 m0, s38
	s_nop 0
	global_load_lds_dwordx4 v[150:151], off
	v_lshl_add_u64 v[150:151], s[36:37], 0, v[134:135]
	s_add_i32 m0, s38, 0x2000
	s_nop 0
	global_load_lds_dwordx4 v[150:151], off
	s_waitcnt vmcnt(6)
	s_barrier
	s_setprio 1
	v_mfma_f32_16x16x32_bf16 v[52:55], v[202:205], v[170:173], v[52:55]
	v_mfma_f32_16x16x32_bf16 v[48:51], v[210:213], v[170:173], v[48:51]
	v_mfma_f32_16x16x32_bf16 v[36:39], v[202:205], v[178:181], v[36:39]
	v_mfma_f32_16x16x32_bf16 v[32:35], v[210:213], v[178:181], v[32:35]
	v_mfma_f32_16x16x32_bf16 v[20:23], v[202:205], v[186:189], v[20:23]
	v_mfma_f32_16x16x32_bf16 v[16:19], v[210:213], v[186:189], v[16:19]
	v_mfma_f32_16x16x32_bf16 v[4:7], v[202:205], v[194:197], v[4:7]
	v_mfma_f32_16x16x32_bf16 v[0:3], v[210:213], v[194:197], v[0:3]
	v_mfma_f32_16x16x32_bf16 v[52:55], v[206:209], v[174:177], v[52:55]
	v_mfma_f32_16x16x32_bf16 v[48:51], v[214:217], v[174:177], v[48:51]
	v_mfma_f32_16x16x32_bf16 v[36:39], v[206:209], v[182:185], v[36:39]
	v_mfma_f32_16x16x32_bf16 v[32:35], v[214:217], v[182:185], v[32:35]
	v_mfma_f32_16x16x32_bf16 v[20:23], v[206:209], v[190:193], v[20:23]
	v_mfma_f32_16x16x32_bf16 v[16:19], v[214:217], v[190:193], v[16:19]
	v_mfma_f32_16x16x32_bf16 v[4:7], v[206:209], v[198:201], v[4:7]
	v_mfma_f32_16x16x32_bf16 v[0:3], v[214:217], v[198:201], v[0:3]
	s_setprio 0
	s_add_i32 s71, s71, 2
	s_add_u32 s69, s69, 0x100
	s_addc_u32 s70, s70, 0
	s_add_u32 s34, s34, 0x100
	s_addc_u32 s35, s35, 0
	s_cmp_gt_u32 s71, 13
	s_barrier
	s_cbranch_scc0 .LBB0_2122
	v_lshl_add_u32 v150, s68, 8, v140
	v_add_u32_e32 v164, 0x4000, v150
	v_ashrrev_i32_e32 v165, 31, v164
	v_lshlrev_b64 v[152:153], 6, v[164:165]
	v_lshl_add_u64 v[170:171], s[14:15], 0, v[152:153]
	v_subrev_u32_e32 v176, s14, v170
	v_add_u32_e32 v177, 0x0, v176
	global_load_dwordx4 v[178:181], v177, s[14:15]
	v_add_u32_e32 v177, 0x10, v176
	global_load_dwordx4 v[182:185], v177, s[14:15]
	v_add_u32_e32 v177, 0x20, v176
	global_load_dwordx4 v[186:189], v177, s[14:15]
	v_add_u32_e32 v177, 0x30, v176
	global_load_dwordx4 v[190:193], v177, s[14:15]
	v_add_u32_e32 v177, 0x400, v176
	global_load_dwordx4 v[194:197], v177, s[14:15]
	v_add_u32_e32 v177, 0x410, v176
	global_load_dwordx4 v[198:201], v177, s[14:15]
	v_add_u32_e32 v177, 0x420, v176
	global_load_dwordx4 v[202:205], v177, s[14:15]
	v_add_u32_e32 v177, 0x430, v176
	global_load_dwordx4 v[206:209], v177, s[14:15]
	v_add_u32_e32 v177, 0x800, v176
	global_load_dwordx4 v[210:213], v177, s[14:15]
	v_add_u32_e32 v177, 0x810, v176
	global_load_dwordx4 v[214:217], v177, s[14:15]
	v_add_u32_e32 v177, 0x820, v176
	global_load_dwordx4 v[232:235], v177, s[14:15]
	v_add_u32_e32 v177, 0x830, v176
	global_load_dwordx4 v[236:239], v177, s[14:15]
	v_add_u32_e32 v177, 0xc00, v176
	global_load_dwordx4 v[240:243], v177, s[14:15]
	v_add_u32_e32 v177, 0xc10, v176
	global_load_dwordx4 v[244:247], v177, s[14:15]
	v_add_u32_e32 v177, 0xc20, v176
	global_load_dwordx4 v[248:251], v177, s[14:15]
	v_add_u32_e32 v177, 0xc30, v176
	global_load_dwordx4 v[252:255], v177, s[14:15]
	s_nop 0
	v_lshl_or_b32 v149, s33, 9, v142
	v_lshl_add_u32 v151, v164, 13, v149
	v_add_u32_e32 v174, 0x4010, v150
	v_ashrrev_i32_e32 v175, 31, v174
	s_waitcnt vmcnt(12)
; __device__ __forceinline__ u32x4 pack8(const f32x4 v0, const f32x4 v1) { u32x4 w; w.x = pk2(v0[0], v0[1]); w.y = pk2(v0[2], v0[3]); w.z = pk2(v1[0], v1[1]); w.w = pk2(v1[2], v1[3]); return w; }
; __device__ __forceinline__ float row_rstd(const float* ssq, int row) {
;     const f32x4* p = (const f32x4*)(ssq + (size_t)row * 16);
;     const f32x4 a = p[0], b = p[1], c = p[2], d = p[3];
;     const float s = ((a[0] + a[1]) + (a[2] + a[3])) + ((b[0] + b[1]) + (b[2] + b[3])) + ((c[0] + c[1]) + (c[2] + c[3])) + ((d[0] + d[1]) + (d[2] + d[3]));
;     return rsqrtf(s * (1.0f / 1024.0f) + 1e-6f);
;     __device__ __forceinline__ void operator()(const f32x4 (&acc)[2][2][4][2], const Unit& u, int wr, int wc, int fr, int fq) const {
;         const __amdgpu_buffer_rsrc_t rsrc = __builtin_amdgcn_make_buffer_rsrc((void*)O, 0, T_ALL * DFF * 2, 0x00020000);
;         const int row0 = row_off + u.pm * 256 + wr * 64 + fr, col0 = u.pn * 256 + wc * 32 + 8 * fq;
; #pragma unroll
;         for (int ai = 0; ai < 2; ++ai)
; #pragma unroll
;             for (int m = 0; m < 4; ++m) {
;                 const int row = row0 + ai * 128 + m * 16; const float rs = row_rstd(ssq, row);
; #pragma unroll
;                 for (int bj = 0; bj < 2; ++bj) { f32x4 v0 = acc[ai][bj][m][0] * rs, v1 = acc[ai][bj][m][1] * rs;
; #pragma unroll
;                     for (int j = 0; j < 4; ++j) { const float a = fmaxf(v0[j], 0.f), b = fmaxf(v1[j], 0.f); v0[j] = a * a; v1[j] = b * b; }
;                     __builtin_amdgcn_raw_buffer_store_b128(pack8(v0, v1), rsrc, (unsigned)(((size_t)row * DFF + col0 + bj * 128) * 2), 0, 16  ); }
;             }
	s_nop 0
	s_nop 0
	v_pk_add_f32 v[152:153], v[178:179], v[180:181]
	v_pk_add_f32 v[154:155], v[182:183], v[184:185]
	v_pk_add_f32 v[156:157], v[186:187], v[188:189]
	v_pk_add_f32 v[158:159], v[190:191], v[192:193]
	v_pk_add_f32 v[152:153], v[152:153], v[154:155]
	v_pk_add_f32 v[156:157], v[156:157], v[158:159]
	v_pk_add_f32 v[152:153], v[152:153], v[156:157]
	v_add_f32_e32 v152, v152, v153
	v_fmamk_f32 v152, v152, 0x3a800000, v148
	v_mul_f32_e32 v153, 0x4b800000, v152
	v_cmp_gt_f32_e32 vcc, s63, v152
	s_nop 1
	v_cndmask_b32_e32 v152, v152, v153, vcc
	v_rsq_f32_e32 v154, v152
	v_lshlrev_b64 v[152:153], 6, v[174:175]
	v_lshl_add_u64 v[152:153], s[14:15], 0, v[152:153]
	v_mul_f32_e32 v155, 0x45800000, v154
	v_cndmask_b32_e32 v154, v154, v155, vcc
	v_pk_mul_f32 v[126:127], v[126:127], v[154:155] op_sel_hi:[1,0]
	v_pk_mul_f32 v[124:125], v[124:125], v[154:155] op_sel_hi:[1,0]
	v_pk_mul_f32 v[122:123], v[122:123], v[154:155] op_sel_hi:[1,0]
	v_pk_mul_f32 v[120:121], v[120:121], v[154:155] op_sel_hi:[1,0]
	v_pk_mul_f32 v[114:115], v[114:115], v[154:155] op_sel_hi:[1,0]
	v_pk_mul_f32 v[112:113], v[112:113], v[154:155] op_sel_hi:[1,0]
	v_pk_mul_f32 v[118:119], v[118:119], v[154:155] op_sel_hi:[1,0]
	v_pk_mul_f32 v[116:117], v[116:117], v[154:155] op_sel_hi:[1,0]
	v_max_f32_e32 v124, 0, v124
	v_max_f32_e32 v120, 0, v120
	v_max_f32_e32 v125, 0, v125
	v_max_f32_e32 v121, 0, v121
	v_max_f32_e32 v126, 0, v126
	v_max_f32_e32 v122, 0, v122
	v_max_f32_e32 v127, 0, v127
	v_max_f32_e32 v123, 0, v123
	v_max_f32_e32 v112, 0, v112
	v_max_f32_e32 v113, 0, v113
	v_max_f32_e32 v114, 0, v114
	v_max_f32_e32 v115, 0, v115
	v_max_f32_e32 v116, 0, v116
	v_max_f32_e32 v117, 0, v117
	v_max_f32_e32 v118, 0, v118
	v_max_f32_e32 v119, 0, v119
	v_pk_mul_f32 v[124:125], v[124:125], v[124:125]
	v_pk_mul_f32 v[120:121], v[120:121], v[120:121]
	v_pk_mul_f32 v[126:127], v[126:127], v[126:127]
	v_pk_mul_f32 v[122:123], v[122:123], v[122:123]
	v_pk_mul_f32 v[154:155], v[112:113], v[112:113]
	v_pk_mul_f32 v[156:157], v[114:115], v[114:115]
	v_cvt_pk_bf16_f32 v112, v124, v125
	v_cvt_pk_bf16_f32 v113, v126, v127
	v_cvt_pk_bf16_f32 v114, v120, v121
	v_cvt_pk_bf16_f32 v115, v122, v123
	v_pk_mul_f32 v[116:117], v[116:117], v[116:117]
	v_pk_mul_f32 v[118:119], v[118:119], v[118:119]
	buffer_store_dwordx4 v[112:115], v151, s[8:11], 0 offen sc1
	s_nop 1
	v_cvt_pk_bf16_f32 v112, v116, v117
	v_cvt_pk_bf16_f32 v113, v118, v119
	v_cvt_pk_bf16_f32 v114, v154, v155
	v_cvt_pk_bf16_f32 v115, v156, v157
	buffer_store_dwordx4 v[112:115], v151, s[8:11], 0 offen offset:256 sc1
	s_nop 0
	v_add_u32_e32 v152, 0x4020, v150
	v_ashrrev_i32_e32 v153, 31, v152
	v_lshl_add_u32 v151, v174, 13, v149
	v_add_u32_e32 v177, 0x2000, v176
	global_load_dwordx4 v[178:181], v177, s[14:15]
	v_add_u32_e32 v177, 0x2010, v176
	global_load_dwordx4 v[182:185], v177, s[14:15]
	v_add_u32_e32 v177, 0x2020, v176
	global_load_dwordx4 v[186:189], v177, s[14:15]
	v_add_u32_e32 v177, 0x2030, v176
	global_load_dwordx4 v[190:193], v177, s[14:15]
	s_waitcnt vmcnt(14)
	s_nop 0
	s_nop 0
	v_pk_add_f32 v[112:113], v[194:195], v[196:197]
	v_pk_add_f32 v[114:115], v[198:199], v[200:201]
	v_pk_add_f32 v[116:117], v[202:203], v[204:205]
	v_pk_add_f32 v[118:119], v[206:207], v[208:209]
	v_pk_add_f32 v[112:113], v[112:113], v[114:115]
	v_pk_add_f32 v[116:117], v[116:117], v[118:119]
	v_pk_add_f32 v[112:113], v[112:113], v[116:117]
	v_add_f32_e32 v112, v112, v113
	v_fmamk_f32 v112, v112, 0x3a800000, v148
	v_mul_f32_e32 v113, 0x4b800000, v112
	v_cmp_gt_f32_e32 vcc, s63, v112
	s_nop 1
	v_cndmask_b32_e32 v112, v112, v113, vcc
	v_rsq_f32_e32 v114, v112
	v_lshlrev_b64 v[112:113], 6, v[152:153]
	v_lshl_add_u64 v[112:113], s[14:15], 0, v[112:113]
	v_mul_f32_e32 v115, 0x45800000, v114
	v_cndmask_b32_e32 v114, v114, v115, vcc
	v_pk_mul_f32 v[110:111], v[110:111], v[114:115] op_sel_hi:[1,0]
	v_pk_mul_f32 v[108:109], v[108:109], v[114:115] op_sel_hi:[1,0]
	v_pk_mul_f32 v[106:107], v[106:107], v[114:115] op_sel_hi:[1,0]
	v_pk_mul_f32 v[104:105], v[104:105], v[114:115] op_sel_hi:[1,0]
	v_pk_mul_f32 v[98:99], v[98:99], v[114:115] op_sel_hi:[1,0]
	v_pk_mul_f32 v[96:97], v[96:97], v[114:115] op_sel_hi:[1,0]
	v_pk_mul_f32 v[102:103], v[102:103], v[114:115] op_sel_hi:[1,0]
	v_pk_mul_f32 v[100:101], v[100:101], v[114:115] op_sel_hi:[1,0]
	v_max_f32_e32 v108, 0, v108
	v_max_f32_e32 v104, 0, v104
	v_max_f32_e32 v109, 0, v109
	v_max_f32_e32 v105, 0, v105
	v_max_f32_e32 v110, 0, v110
	v_max_f32_e32 v106, 0, v106
	v_max_f32_e32 v111, 0, v111
	v_max_f32_e32 v107, 0, v107
	v_max_f32_e32 v96, 0, v96
	v_max_f32_e32 v97, 0, v97
	v_max_f32_e32 v98, 0, v98
	v_max_f32_e32 v99, 0, v99
	v_max_f32_e32 v100, 0, v100
	v_max_f32_e32 v101, 0, v101
	v_max_f32_e32 v102, 0, v102
	v_max_f32_e32 v103, 0, v103
	v_pk_mul_f32 v[108:109], v[108:109], v[108:109]
	v_pk_mul_f32 v[104:105], v[104:105], v[104:105]
	v_pk_mul_f32 v[110:111], v[110:111], v[110:111]
	v_pk_mul_f32 v[106:107], v[106:107], v[106:107]
	v_pk_mul_f32 v[114:115], v[96:97], v[96:97]
	v_pk_mul_f32 v[116:117], v[98:99], v[98:99]
	v_cvt_pk_bf16_f32 v96, v108, v109
	v_cvt_pk_bf16_f32 v97, v110, v111
	v_cvt_pk_bf16_f32 v98, v104, v105
	v_cvt_pk_bf16_f32 v99, v106, v107
	v_pk_mul_f32 v[100:101], v[100:101], v[100:101]
	v_pk_mul_f32 v[102:103], v[102:103], v[102:103]
	buffer_store_dwordx4 v[96:99], v151, s[8:11], 0 offen sc1
	s_nop 1
	v_cvt_pk_bf16_f32 v96, v100, v101
	v_cvt_pk_bf16_f32 v97, v102, v103
	v_cvt_pk_bf16_f32 v98, v114, v115
	v_cvt_pk_bf16_f32 v99, v116, v117
	buffer_store_dwordx4 v[96:99], v151, s[8:11], 0 offen offset:256 sc1
	s_nop 0
	v_add_u32_e32 v112, 0x4030, v150
	v_ashrrev_i32_e32 v113, 31, v112
	v_lshl_add_u32 v116, v152, 13, v149
	v_add_u32_e32 v177, 0x2400, v176
	global_load_dwordx4 v[194:197], v177, s[14:15]
	v_add_u32_e32 v177, 0x2410, v176
	global_load_dwordx4 v[198:201], v177, s[14:15]
	v_add_u32_e32 v177, 0x2420, v176
	global_load_dwordx4 v[202:205], v177, s[14:15]
	v_add_u32_e32 v177, 0x2430, v176
	global_load_dwordx4 v[206:209], v177, s[14:15]
	s_waitcnt vmcnt(16)
; __device__ __forceinline__ u32x4 pack8(const f32x4 v0, const f32x4 v1) { u32x4 w; w.x = pk2(v0[0], v0[1]); w.y = pk2(v0[2], v0[3]); w.z = pk2(v1[0], v1[1]); w.w = pk2(v1[2], v1[3]); return w; }
; __device__ __forceinline__ float row_rstd(const float* ssq, int row) {
;     const f32x4* p = (const f32x4*)(ssq + (size_t)row * 16);
;     const f32x4 a = p[0], b = p[1], c = p[2], d = p[3];
;     const float s = ((a[0] + a[1]) + (a[2] + a[3])) + ((b[0] + b[1]) + (b[2] + b[3])) + ((c[0] + c[1]) + (c[2] + c[3])) + ((d[0] + d[1]) + (d[2] + d[3]));
;     return rsqrtf(s * (1.0f / 1024.0f) + 1e-6f);
;     __device__ __forceinline__ void operator()(const f32x4 (&acc)[2][2][4][2], const Unit& u, int wr, int wc, int fr, int fq) const {
;         const __amdgpu_buffer_rsrc_t rsrc = __builtin_amdgcn_make_buffer_rsrc((void*)O, 0, T_ALL * DFF * 2, 0x00020000);
;         const int row0 = row_off + u.pm * 256 + wr * 64 + fr, col0 = u.pn * 256 + wc * 32 + 8 * fq;
; #pragma unroll
;         for (int ai = 0; ai < 2; ++ai)
; #pragma unroll
;             for (int m = 0; m < 4; ++m) {
;                 const int row = row0 + ai * 128 + m * 16; const float rs = row_rstd(ssq, row);
; #pragma unroll
;                 for (int bj = 0; bj < 2; ++bj) { f32x4 v0 = acc[ai][bj][m][0] * rs, v1 = acc[ai][bj][m][1] * rs;
; #pragma unroll
;                     for (int j = 0; j < 4; ++j) { const float a = fmaxf(v0[j], 0.f), b = fmaxf(v1[j], 0.f); v0[j] = a * a; v1[j] = b * b; }
;                     __builtin_amdgcn_raw_buffer_store_b128(pack8(v0, v1), rsrc, (unsigned)(((size_t)row * DFF + col0 + bj * 128) * 2), 0, 16  ); }
;             }
	s_nop 0
	s_nop 0
	v_pk_add_f32 v[96:97], v[210:211], v[212:213]
	v_pk_add_f32 v[98:99], v[214:215], v[216:217]
	v_pk_add_f32 v[100:101], v[232:233], v[234:235]
	v_pk_add_f32 v[102:103], v[236:237], v[238:239]
	v_pk_add_f32 v[96:97], v[96:97], v[98:99]
	v_pk_add_f32 v[100:101], v[100:101], v[102:103]
	v_pk_add_f32 v[96:97], v[96:97], v[100:101]
	v_add_f32_e32 v96, v96, v97
	v_fmamk_f32 v96, v96, 0x3a800000, v148
	v_mul_f32_e32 v97, 0x4b800000, v96
	v_cmp_gt_f32_e32 vcc, s63, v96
	s_nop 1
	v_cndmask_b32_e32 v96, v96, v97, vcc
	v_rsq_f32_e32 v98, v96
	v_lshlrev_b64 v[96:97], 6, v[112:113]
	v_lshl_add_u64 v[96:97], s[14:15], 0, v[96:97]
	v_mul_f32_e32 v99, 0x45800000, v98
	v_cndmask_b32_e32 v98, v98, v99, vcc
	v_pk_mul_f32 v[94:95], v[94:95], v[98:99] op_sel_hi:[1,0]
	v_pk_mul_f32 v[92:93], v[92:93], v[98:99] op_sel_hi:[1,0]
	v_pk_mul_f32 v[90:91], v[90:91], v[98:99] op_sel_hi:[1,0]
	v_pk_mul_f32 v[88:89], v[88:89], v[98:99] op_sel_hi:[1,0]
	v_pk_mul_f32 v[82:83], v[82:83], v[98:99] op_sel_hi:[1,0]
	v_pk_mul_f32 v[80:81], v[80:81], v[98:99] op_sel_hi:[1,0]
	v_pk_mul_f32 v[86:87], v[86:87], v[98:99] op_sel_hi:[1,0]
	v_pk_mul_f32 v[84:85], v[84:85], v[98:99] op_sel_hi:[1,0]
	v_max_f32_e32 v92, 0, v92
	v_max_f32_e32 v88, 0, v88
	v_max_f32_e32 v93, 0, v93
	v_max_f32_e32 v89, 0, v89
	v_max_f32_e32 v94, 0, v94
	v_max_f32_e32 v90, 0, v90
	v_max_f32_e32 v95, 0, v95
	v_max_f32_e32 v91, 0, v91
	v_max_f32_e32 v80, 0, v80
	v_max_f32_e32 v81, 0, v81
	v_max_f32_e32 v82, 0, v82
	v_max_f32_e32 v83, 0, v83
	v_max_f32_e32 v84, 0, v84
	v_max_f32_e32 v85, 0, v85
	v_max_f32_e32 v86, 0, v86
	v_max_f32_e32 v87, 0, v87
	v_pk_mul_f32 v[92:93], v[92:93], v[92:93]
	v_pk_mul_f32 v[88:89], v[88:89], v[88:89]
	v_pk_mul_f32 v[94:95], v[94:95], v[94:95]
	v_pk_mul_f32 v[90:91], v[90:91], v[90:91]
	v_pk_mul_f32 v[98:99], v[80:81], v[80:81]
	v_pk_mul_f32 v[100:101], v[82:83], v[82:83]
	v_cvt_pk_bf16_f32 v80, v92, v93
	v_cvt_pk_bf16_f32 v81, v94, v95
	v_cvt_pk_bf16_f32 v82, v88, v89
	v_cvt_pk_bf16_f32 v83, v90, v91
	v_pk_mul_f32 v[84:85], v[84:85], v[84:85]
	v_pk_mul_f32 v[86:87], v[86:87], v[86:87]
	buffer_store_dwordx4 v[80:83], v116, s[8:11], 0 offen sc1
	s_nop 1
	v_cvt_pk_bf16_f32 v80, v84, v85
	v_cvt_pk_bf16_f32 v81, v86, v87
	v_cvt_pk_bf16_f32 v82, v98, v99
	v_cvt_pk_bf16_f32 v83, v100, v101
	buffer_store_dwordx4 v[80:83], v116, s[8:11], 0 offen offset:256 sc1
	s_nop 0
	v_add_u32_e32 v96, 0x4080, v150
	v_ashrrev_i32_e32 v97, 31, v96
	v_lshl_add_u32 v100, v112, 13, v149
	v_add_u32_e32 v177, 0x2800, v176
	global_load_dwordx4 v[210:213], v177, s[14:15]
	v_add_u32_e32 v177, 0x2810, v176
	global_load_dwordx4 v[214:217], v177, s[14:15]
	v_add_u32_e32 v177, 0x2820, v176
	global_load_dwordx4 v[232:235], v177, s[14:15]
	v_add_u32_e32 v177, 0x2830, v176
	global_load_dwordx4 v[236:239], v177, s[14:15]
	s_waitcnt vmcnt(18)
	s_nop 0
	s_nop 0
	v_pk_add_f32 v[80:81], v[240:241], v[242:243]
	v_pk_add_f32 v[82:83], v[244:245], v[246:247]
	v_pk_add_f32 v[84:85], v[248:249], v[250:251]
	v_pk_add_f32 v[86:87], v[252:253], v[254:255]
	v_pk_add_f32 v[80:81], v[80:81], v[82:83]
	v_pk_add_f32 v[84:85], v[84:85], v[86:87]
	v_pk_add_f32 v[80:81], v[80:81], v[84:85]
	v_add_f32_e32 v80, v80, v81
	v_fmamk_f32 v80, v80, 0x3a800000, v148
	v_mul_f32_e32 v81, 0x4b800000, v80
	v_cmp_gt_f32_e32 vcc, s63, v80
	s_nop 1
	v_cndmask_b32_e32 v80, v80, v81, vcc
	v_rsq_f32_e32 v82, v80
	v_lshlrev_b64 v[80:81], 6, v[96:97]
	v_lshl_add_u64 v[80:81], s[14:15], 0, v[80:81]
	v_mul_f32_e32 v83, 0x45800000, v82
	v_cndmask_b32_e32 v82, v82, v83, vcc
	v_pk_mul_f32 v[78:79], v[78:79], v[82:83] op_sel_hi:[1,0]
	v_pk_mul_f32 v[76:77], v[76:77], v[82:83] op_sel_hi:[1,0]
	v_pk_mul_f32 v[74:75], v[74:75], v[82:83] op_sel_hi:[1,0]
	v_pk_mul_f32 v[72:73], v[72:73], v[82:83] op_sel_hi:[1,0]
	v_pk_mul_f32 v[66:67], v[66:67], v[82:83] op_sel_hi:[1,0]
	v_pk_mul_f32 v[64:65], v[64:65], v[82:83] op_sel_hi:[1,0]
	v_pk_mul_f32 v[70:71], v[70:71], v[82:83] op_sel_hi:[1,0]
	v_pk_mul_f32 v[68:69], v[68:69], v[82:83] op_sel_hi:[1,0]
	v_max_f32_e32 v76, 0, v76
	v_max_f32_e32 v72, 0, v72
	v_max_f32_e32 v77, 0, v77
	v_max_f32_e32 v73, 0, v73
	v_max_f32_e32 v78, 0, v78
	v_max_f32_e32 v74, 0, v74
	v_max_f32_e32 v79, 0, v79
	v_max_f32_e32 v75, 0, v75
	v_max_f32_e32 v64, 0, v64
	v_max_f32_e32 v65, 0, v65
	v_max_f32_e32 v66, 0, v66
	v_max_f32_e32 v67, 0, v67
	v_max_f32_e32 v68, 0, v68
	v_max_f32_e32 v69, 0, v69
	v_max_f32_e32 v70, 0, v70
	v_max_f32_e32 v71, 0, v71
	v_pk_mul_f32 v[76:77], v[76:77], v[76:77]
	v_pk_mul_f32 v[72:73], v[72:73], v[72:73]
	v_pk_mul_f32 v[78:79], v[78:79], v[78:79]
	v_pk_mul_f32 v[74:75], v[74:75], v[74:75]
	v_pk_mul_f32 v[82:83], v[64:65], v[64:65]
	v_pk_mul_f32 v[84:85], v[66:67], v[66:67]
	v_cvt_pk_bf16_f32 v64, v76, v77
	v_cvt_pk_bf16_f32 v65, v78, v79
	v_cvt_pk_bf16_f32 v66, v72, v73
	v_cvt_pk_bf16_f32 v67, v74, v75
	v_pk_mul_f32 v[68:69], v[68:69], v[68:69]
	v_pk_mul_f32 v[70:71], v[70:71], v[70:71]
	buffer_store_dwordx4 v[64:67], v100, s[8:11], 0 offen sc1
	s_nop 1
	v_cvt_pk_bf16_f32 v64, v68, v69
	v_cvt_pk_bf16_f32 v65, v70, v71
	v_cvt_pk_bf16_f32 v66, v82, v83
	v_cvt_pk_bf16_f32 v67, v84, v85
	buffer_store_dwordx4 v[64:67], v100, s[8:11], 0 offen offset:256 sc1
	s_nop 0
	v_add_u32_e32 v80, 0x4090, v150
	v_ashrrev_i32_e32 v81, 31, v80
	v_lshl_add_u32 v84, v96, 13, v149
	v_add_u32_e32 v177, 0x2c00, v176
	global_load_dwordx4 v[240:243], v177, s[14:15]
	v_add_u32_e32 v177, 0x2c10, v176
	global_load_dwordx4 v[244:247], v177, s[14:15]
	v_add_u32_e32 v177, 0x2c20, v176
	global_load_dwordx4 v[248:251], v177, s[14:15]
	v_add_u32_e32 v177, 0x2c30, v176
	global_load_dwordx4 v[252:255], v177, s[14:15]
	s_waitcnt vmcnt(18)
; __device__ __forceinline__ u32x4 pack8(const f32x4 v0, const f32x4 v1) { u32x4 w; w.x = pk2(v0[0], v0[1]); w.y = pk2(v0[2], v0[3]); w.z = pk2(v1[0], v1[1]); w.w = pk2(v1[2], v1[3]); return w; }
; __device__ __forceinline__ float row_rstd(const float* ssq, int row) {
;     const f32x4* p = (const f32x4*)(ssq + (size_t)row * 16);
;     const f32x4 a = p[0], b = p[1], c = p[2], d = p[3];
;     const float s = ((a[0] + a[1]) + (a[2] + a[3])) + ((b[0] + b[1]) + (b[2] + b[3])) + ((c[0] + c[1]) + (c[2] + c[3])) + ((d[0] + d[1]) + (d[2] + d[3]));
;     return rsqrtf(s * (1.0f / 1024.0f) + 1e-6f);
;     __device__ __forceinline__ void operator()(const f32x4 (&acc)[2][2][4][2], const Unit& u, int wr, int wc, int fr, int fq) const {
;         const __amdgpu_buffer_rsrc_t rsrc = __builtin_amdgcn_make_buffer_rsrc((void*)O, 0, T_ALL * DFF * 2, 0x00020000);
;         const int row0 = row_off + u.pm * 256 + wr * 64 + fr, col0 = u.pn * 256 + wc * 32 + 8 * fq;
; #pragma unroll
;         for (int ai = 0; ai < 2; ++ai)
; #pragma unroll
;             for (int m = 0; m < 4; ++m) {
;                 const int row = row0 + ai * 128 + m * 16; const float rs = row_rstd(ssq, row);
; #pragma unroll
;                 for (int bj = 0; bj < 2; ++bj) { f32x4 v0 = acc[ai][bj][m][0] * rs, v1 = acc[ai][bj][m][1] * rs;
; #pragma unroll
;                     for (int j = 0; j < 4; ++j) { const float a = fmaxf(v0[j], 0.f), b = fmaxf(v1[j], 0.f); v0[j] = a * a; v1[j] = b * b; }
;                     __builtin_amdgcn_raw_buffer_store_b128(pack8(v0, v1), rsrc, (unsigned)(((size_t)row * DFF + col0 + bj * 128) * 2), 0, 16  ); }
;             }
	s_nop 0
	s_nop 0
	v_pk_add_f32 v[64:65], v[178:179], v[180:181]
	v_pk_add_f32 v[66:67], v[182:183], v[184:185]
	v_pk_add_f32 v[68:69], v[186:187], v[188:189]
	v_pk_add_f32 v[70:71], v[190:191], v[192:193]
	v_pk_add_f32 v[64:65], v[64:65], v[66:67]
	v_pk_add_f32 v[68:69], v[68:69], v[70:71]
	v_pk_add_f32 v[64:65], v[64:65], v[68:69]
	v_add_f32_e32 v64, v64, v65
	v_fmamk_f32 v64, v64, 0x3a800000, v148
	v_mul_f32_e32 v65, 0x4b800000, v64
	v_cmp_gt_f32_e32 vcc, s63, v64
	s_nop 1
	v_cndmask_b32_e32 v64, v64, v65, vcc
	v_rsq_f32_e32 v66, v64
	v_lshlrev_b64 v[64:65], 6, v[80:81]
	v_lshl_add_u64 v[64:65], s[14:15], 0, v[64:65]
	v_mul_f32_e32 v67, 0x45800000, v66
	v_cndmask_b32_e32 v66, v66, v67, vcc
	v_pk_mul_f32 v[62:63], v[62:63], v[66:67] op_sel_hi:[1,0]
	v_pk_mul_f32 v[60:61], v[60:61], v[66:67] op_sel_hi:[1,0]
	v_pk_mul_f32 v[58:59], v[58:59], v[66:67] op_sel_hi:[1,0]
	v_pk_mul_f32 v[56:57], v[56:57], v[66:67] op_sel_hi:[1,0]
	v_pk_mul_f32 v[50:51], v[50:51], v[66:67] op_sel_hi:[1,0]
	v_pk_mul_f32 v[48:49], v[48:49], v[66:67] op_sel_hi:[1,0]
	v_pk_mul_f32 v[54:55], v[54:55], v[66:67] op_sel_hi:[1,0]
	v_pk_mul_f32 v[52:53], v[52:53], v[66:67] op_sel_hi:[1,0]
	v_max_f32_e32 v60, 0, v60
	v_max_f32_e32 v56, 0, v56
	v_max_f32_e32 v61, 0, v61
	v_max_f32_e32 v57, 0, v57
	v_max_f32_e32 v62, 0, v62
	v_max_f32_e32 v58, 0, v58
	v_max_f32_e32 v63, 0, v63
	v_max_f32_e32 v59, 0, v59
	v_max_f32_e32 v48, 0, v48
	v_max_f32_e32 v49, 0, v49
	v_max_f32_e32 v50, 0, v50
	v_max_f32_e32 v51, 0, v51
	v_max_f32_e32 v52, 0, v52
	v_max_f32_e32 v53, 0, v53
	v_max_f32_e32 v54, 0, v54
	v_max_f32_e32 v55, 0, v55
	v_pk_mul_f32 v[60:61], v[60:61], v[60:61]
	v_pk_mul_f32 v[56:57], v[56:57], v[56:57]
	v_pk_mul_f32 v[62:63], v[62:63], v[62:63]
	v_pk_mul_f32 v[58:59], v[58:59], v[58:59]
	v_pk_mul_f32 v[66:67], v[48:49], v[48:49]
	v_pk_mul_f32 v[68:69], v[50:51], v[50:51]
	v_cvt_pk_bf16_f32 v48, v60, v61
	v_cvt_pk_bf16_f32 v49, v62, v63
	v_cvt_pk_bf16_f32 v50, v56, v57
	v_cvt_pk_bf16_f32 v51, v58, v59
	v_pk_mul_f32 v[52:53], v[52:53], v[52:53]
	v_pk_mul_f32 v[54:55], v[54:55], v[54:55]
	buffer_store_dwordx4 v[48:51], v84, s[8:11], 0 offen sc1
	s_nop 1
	v_cvt_pk_bf16_f32 v48, v52, v53
	v_cvt_pk_bf16_f32 v49, v54, v55
	v_cvt_pk_bf16_f32 v50, v66, v67
	v_cvt_pk_bf16_f32 v51, v68, v69
	buffer_store_dwordx4 v[48:51], v84, s[8:11], 0 offen offset:256 sc1
	s_nop 0
	v_add_u32_e32 v64, 0x40a0, v150
	v_ashrrev_i32_e32 v65, 31, v64
	v_lshl_add_u32 v68, v80, 13, v149
	s_waitcnt vmcnt(14)
	s_nop 0
	s_nop 0
	v_pk_add_f32 v[48:49], v[194:195], v[196:197]
	v_pk_add_f32 v[50:51], v[198:199], v[200:201]
	v_pk_add_f32 v[52:53], v[202:203], v[204:205]
	v_pk_add_f32 v[54:55], v[206:207], v[208:209]
	v_pk_add_f32 v[48:49], v[48:49], v[50:51]
	v_pk_add_f32 v[52:53], v[52:53], v[54:55]
	v_pk_add_f32 v[48:49], v[48:49], v[52:53]
	v_add_f32_e32 v48, v48, v49
	v_fmamk_f32 v48, v48, 0x3a800000, v148
	v_mul_f32_e32 v49, 0x4b800000, v48
	v_cmp_gt_f32_e32 vcc, s63, v48
	s_nop 1
	v_cndmask_b32_e32 v48, v48, v49, vcc
	v_rsq_f32_e32 v50, v48
	v_lshlrev_b64 v[48:49], 6, v[64:65]
	v_lshl_add_u64 v[48:49], s[14:15], 0, v[48:49]
	v_mul_f32_e32 v51, 0x45800000, v50
	v_cndmask_b32_e32 v50, v50, v51, vcc
	v_pk_mul_f32 v[46:47], v[46:47], v[50:51] op_sel_hi:[1,0]
	v_pk_mul_f32 v[44:45], v[44:45], v[50:51] op_sel_hi:[1,0]
	v_pk_mul_f32 v[42:43], v[42:43], v[50:51] op_sel_hi:[1,0]
	v_pk_mul_f32 v[40:41], v[40:41], v[50:51] op_sel_hi:[1,0]
	v_pk_mul_f32 v[34:35], v[34:35], v[50:51] op_sel_hi:[1,0]
	v_pk_mul_f32 v[32:33], v[32:33], v[50:51] op_sel_hi:[1,0]
	v_pk_mul_f32 v[38:39], v[38:39], v[50:51] op_sel_hi:[1,0]
	v_pk_mul_f32 v[36:37], v[36:37], v[50:51] op_sel_hi:[1,0]
	v_max_f32_e32 v44, 0, v44
	v_max_f32_e32 v40, 0, v40
	v_max_f32_e32 v45, 0, v45
	v_max_f32_e32 v41, 0, v41
	v_max_f32_e32 v46, 0, v46
	v_max_f32_e32 v42, 0, v42
	v_max_f32_e32 v47, 0, v47
	v_max_f32_e32 v43, 0, v43
	v_max_f32_e32 v32, 0, v32
	v_max_f32_e32 v33, 0, v33
	v_max_f32_e32 v34, 0, v34
	v_max_f32_e32 v35, 0, v35
	v_max_f32_e32 v36, 0, v36
	v_max_f32_e32 v37, 0, v37
	v_max_f32_e32 v38, 0, v38
	v_max_f32_e32 v39, 0, v39
	v_pk_mul_f32 v[44:45], v[44:45], v[44:45]
	v_pk_mul_f32 v[40:41], v[40:41], v[40:41]
	v_pk_mul_f32 v[46:47], v[46:47], v[46:47]
	v_pk_mul_f32 v[42:43], v[42:43], v[42:43]
	v_pk_mul_f32 v[50:51], v[32:33], v[32:33]
	v_pk_mul_f32 v[52:53], v[34:35], v[34:35]
	v_cvt_pk_bf16_f32 v32, v44, v45
	v_cvt_pk_bf16_f32 v33, v46, v47
	v_cvt_pk_bf16_f32 v34, v40, v41
	v_cvt_pk_bf16_f32 v35, v42, v43
	v_pk_mul_f32 v[36:37], v[36:37], v[36:37]
	v_pk_mul_f32 v[38:39], v[38:39], v[38:39]
	buffer_store_dwordx4 v[32:35], v68, s[8:11], 0 offen sc1
	s_nop 1
	v_cvt_pk_bf16_f32 v32, v36, v37
	v_cvt_pk_bf16_f32 v33, v38, v39
	v_cvt_pk_bf16_f32 v34, v50, v51
	v_cvt_pk_bf16_f32 v35, v52, v53
	buffer_store_dwordx4 v[32:35], v68, s[8:11], 0 offen offset:256 sc1
	s_nop 0
	v_add_u32_e32 v48, 0x40b0, v150
	v_ashrrev_i32_e32 v49, 31, v48
	v_lshl_add_u32 v52, v64, 13, v149
	s_waitcnt vmcnt(10)
; __device__ __forceinline__ u32x4 pack8(const f32x4 v0, const f32x4 v1) { u32x4 w; w.x = pk2(v0[0], v0[1]); w.y = pk2(v0[2], v0[3]); w.z = pk2(v1[0], v1[1]); w.w = pk2(v1[2], v1[3]); return w; }
; __device__ __forceinline__ float row_rstd(const float* ssq, int row) {
;     const f32x4* p = (const f32x4*)(ssq + (size_t)row * 16);
;     const f32x4 a = p[0], b = p[1], c = p[2], d = p[3];
;     const float s = ((a[0] + a[1]) + (a[2] + a[3])) + ((b[0] + b[1]) + (b[2] + b[3])) + ((c[0] + c[1]) + (c[2] + c[3])) + ((d[0] + d[1]) + (d[2] + d[3]));
;     return rsqrtf(s * (1.0f / 1024.0f) + 1e-6f);
;     __device__ __forceinline__ void operator()(const f32x4 (&acc)[2][2][4][2], const Unit& u, int wr, int wc, int fr, int fq) const {
;         const __amdgpu_buffer_rsrc_t rsrc = __builtin_amdgcn_make_buffer_rsrc((void*)O, 0, T_ALL * DFF * 2, 0x00020000);
;         const int row0 = row_off + u.pm * 256 + wr * 64 + fr, col0 = u.pn * 256 + wc * 32 + 8 * fq;
; #pragma unroll
;         for (int ai = 0; ai < 2; ++ai)
; #pragma unroll
;             for (int m = 0; m < 4; ++m) {
;                 const int row = row0 + ai * 128 + m * 16; const float rs = row_rstd(ssq, row);
; #pragma unroll
;                 for (int bj = 0; bj < 2; ++bj) { f32x4 v0 = acc[ai][bj][m][0] * rs, v1 = acc[ai][bj][m][1] * rs;
; #pragma unroll
;                     for (int j = 0; j < 4; ++j) { const float a = fmaxf(v0[j], 0.f), b = fmaxf(v1[j], 0.f); v0[j] = a * a; v1[j] = b * b; }
;                     __builtin_amdgcn_raw_buffer_store_b128(pack8(v0, v1), rsrc, (unsigned)(((size_t)row * DFF + col0 + bj * 128) * 2), 0, 16  ); }
;             }
;         asm volatile("s_waitcnt vmcnt(0)" ::: "memory");
;         if (fr == 0 && fq == 0) (void)__hip_atomic_fetch_add(ready + 64 * (pm_off + u.pm), 1u, __ATOMIC_RELAXED, __HIP_MEMORY_SCOPE_AGENT);
	s_nop 0
	s_nop 0
	v_pk_add_f32 v[32:33], v[210:211], v[212:213]
	v_pk_add_f32 v[34:35], v[214:215], v[216:217]
	v_pk_add_f32 v[36:37], v[232:233], v[234:235]
	v_pk_add_f32 v[38:39], v[236:237], v[238:239]
	v_pk_add_f32 v[32:33], v[32:33], v[34:35]
	v_pk_add_f32 v[36:37], v[36:37], v[38:39]
	v_pk_add_f32 v[32:33], v[32:33], v[36:37]
	v_add_f32_e32 v32, v32, v33
	v_fmamk_f32 v32, v32, 0x3a800000, v148
	v_mul_f32_e32 v33, 0x4b800000, v32
	v_cmp_gt_f32_e32 vcc, s63, v32
	s_nop 1
	v_cndmask_b32_e32 v32, v32, v33, vcc
	v_rsq_f32_e32 v34, v32
	v_lshlrev_b64 v[32:33], 6, v[48:49]
	v_lshl_add_u64 v[32:33], s[14:15], 0, v[32:33]
	v_mul_f32_e32 v35, 0x45800000, v34
	v_cndmask_b32_e32 v34, v34, v35, vcc
	v_pk_mul_f32 v[30:31], v[30:31], v[34:35] op_sel_hi:[1,0]
	v_pk_mul_f32 v[28:29], v[28:29], v[34:35] op_sel_hi:[1,0]
	v_pk_mul_f32 v[26:27], v[26:27], v[34:35] op_sel_hi:[1,0]
	v_pk_mul_f32 v[24:25], v[24:25], v[34:35] op_sel_hi:[1,0]
	v_pk_mul_f32 v[18:19], v[18:19], v[34:35] op_sel_hi:[1,0]
	v_pk_mul_f32 v[16:17], v[16:17], v[34:35] op_sel_hi:[1,0]
	v_pk_mul_f32 v[22:23], v[22:23], v[34:35] op_sel_hi:[1,0]
	v_pk_mul_f32 v[20:21], v[20:21], v[34:35] op_sel_hi:[1,0]
	v_max_f32_e32 v28, 0, v28
	v_max_f32_e32 v24, 0, v24
	v_max_f32_e32 v29, 0, v29
	v_max_f32_e32 v25, 0, v25
	v_max_f32_e32 v30, 0, v30
	v_max_f32_e32 v26, 0, v26
	v_max_f32_e32 v31, 0, v31
	v_max_f32_e32 v27, 0, v27
	v_max_f32_e32 v16, 0, v16
	v_max_f32_e32 v17, 0, v17
	v_max_f32_e32 v18, 0, v18
	v_max_f32_e32 v19, 0, v19
	v_max_f32_e32 v20, 0, v20
	v_max_f32_e32 v21, 0, v21
	v_max_f32_e32 v22, 0, v22
	v_max_f32_e32 v23, 0, v23
	v_pk_mul_f32 v[28:29], v[28:29], v[28:29]
	v_pk_mul_f32 v[24:25], v[24:25], v[24:25]
	v_pk_mul_f32 v[30:31], v[30:31], v[30:31]
	v_pk_mul_f32 v[26:27], v[26:27], v[26:27]
	v_pk_mul_f32 v[34:35], v[16:17], v[16:17]
	v_pk_mul_f32 v[36:37], v[18:19], v[18:19]
	v_cvt_pk_bf16_f32 v16, v28, v29
	v_cvt_pk_bf16_f32 v17, v30, v31
	v_cvt_pk_bf16_f32 v18, v24, v25
	v_cvt_pk_bf16_f32 v19, v26, v27
	v_pk_mul_f32 v[20:21], v[20:21], v[20:21]
	v_pk_mul_f32 v[22:23], v[22:23], v[22:23]
	buffer_store_dwordx4 v[16:19], v52, s[8:11], 0 offen sc1
	s_nop 1
	v_cvt_pk_bf16_f32 v16, v20, v21
	v_cvt_pk_bf16_f32 v17, v22, v23
	v_cvt_pk_bf16_f32 v18, v34, v35
	v_cvt_pk_bf16_f32 v19, v36, v37
	buffer_store_dwordx4 v[16:19], v52, s[8:11], 0 offen offset:256 sc1
	s_nop 0
	s_waitcnt vmcnt(6)
	s_nop 0
	s_nop 0
	v_pk_add_f32 v[16:17], v[240:241], v[242:243]
	v_pk_add_f32 v[18:19], v[244:245], v[246:247]
	v_pk_add_f32 v[20:21], v[248:249], v[250:251]
	v_pk_add_f32 v[22:23], v[252:253], v[254:255]
	v_pk_add_f32 v[16:17], v[16:17], v[18:19]
	v_pk_add_f32 v[20:21], v[20:21], v[22:23]
	v_pk_add_f32 v[16:17], v[16:17], v[20:21]
	v_add_f32_e32 v16, v16, v17
	v_fmamk_f32 v16, v16, 0x3a800000, v148
	v_mul_f32_e32 v17, 0x4b800000, v16
	v_cmp_gt_f32_e32 vcc, s63, v16
	s_nop 1
	v_cndmask_b32_e32 v16, v16, v17, vcc
	v_rsq_f32_e32 v16, v16
	v_lshl_add_u32 v17, v48, 13, v149
	v_mul_f32_e32 v18, 0x45800000, v16
	v_cndmask_b32_e32 v16, v16, v18, vcc
	v_pk_mul_f32 v[14:15], v[14:15], v[16:17] op_sel_hi:[1,0]
	v_pk_mul_f32 v[12:13], v[12:13], v[16:17] op_sel_hi:[1,0]
	v_pk_mul_f32 v[10:11], v[10:11], v[16:17] op_sel_hi:[1,0]
	v_pk_mul_f32 v[8:9], v[8:9], v[16:17] op_sel_hi:[1,0]
	v_pk_mul_f32 v[2:3], v[2:3], v[16:17] op_sel_hi:[1,0]
	v_pk_mul_f32 v[0:1], v[0:1], v[16:17] op_sel_hi:[1,0]
	v_pk_mul_f32 v[6:7], v[6:7], v[16:17] op_sel_hi:[1,0]
	v_pk_mul_f32 v[4:5], v[4:5], v[16:17] op_sel_hi:[1,0]
	v_max_f32_e32 v12, 0, v12
	v_max_f32_e32 v8, 0, v8
	v_max_f32_e32 v13, 0, v13
	v_max_f32_e32 v9, 0, v9
	v_max_f32_e32 v14, 0, v14
	v_max_f32_e32 v10, 0, v10
	v_max_f32_e32 v15, 0, v15
	v_max_f32_e32 v11, 0, v11
	v_max_f32_e32 v0, 0, v0
	v_max_f32_e32 v1, 0, v1
	v_max_f32_e32 v2, 0, v2
	v_max_f32_e32 v3, 0, v3
	v_max_f32_e32 v4, 0, v4
	v_max_f32_e32 v5, 0, v5
	v_max_f32_e32 v6, 0, v6
	v_max_f32_e32 v7, 0, v7
	v_pk_mul_f32 v[12:13], v[12:13], v[12:13]
	v_pk_mul_f32 v[8:9], v[8:9], v[8:9]
	v_pk_mul_f32 v[14:15], v[14:15], v[14:15]
	v_pk_mul_f32 v[10:11], v[10:11], v[10:11]
	v_mul_f32_e32 v16, v0, v0
	v_mul_f32_e32 v18, v1, v1
	v_mul_f32_e32 v19, v2, v2
	v_mul_f32_e32 v20, v3, v3
	v_cvt_pk_bf16_f32 v0, v12, v13
	v_cvt_pk_bf16_f32 v1, v14, v15
	v_cvt_pk_bf16_f32 v2, v8, v9
	v_cvt_pk_bf16_f32 v3, v10, v11
	v_pk_mul_f32 v[4:5], v[4:5], v[4:5]
	v_pk_mul_f32 v[6:7], v[6:7], v[6:7]
	buffer_store_dwordx4 v[0:3], v17, s[8:11], 0 offen sc1
	s_nop 1
	v_cvt_pk_bf16_f32 v0, v4, v5
	v_cvt_pk_bf16_f32 v1, v6, v7
	v_cvt_pk_bf16_f32 v2, v16, v18
	v_cvt_pk_bf16_f32 v3, v19, v20
	buffer_store_dwordx4 v[0:3], v17, s[8:11], 0 offen offset:256 sc1
	s_waitcnt vmcnt(0)
	s_and_saveexec_b64 s[34:35], s[6:7]
	s_cbranch_execz .LBB0_2114
	s_mov_b64 s[36:37], exec
	v_mbcnt_lo_u32_b32 v0, s36, 0
	v_mbcnt_hi_u32_b32 v0, s37, v0
	v_cmp_eq_u32_e32 vcc, 0, v0
	s_and_b64 s[38:39], exec, vcc
	s_mov_b64 exec, s[38:39]
	s_cbranch_execz .LBB0_2114
	s_lshl_b32 s21, s68, 6
	s_add_i32 s38, s21, 0x1000
	s_ashr_i32 s39, s38, 31
	s_lshl_b64 s[38:39], s[38:39], 2
	s_add_u32 s38, s66, s38
	s_addc_u32 s39, s67, s39
	s_bcnt1_i32_b64 s21, s[36:37]
	v_mov_b32_e32 v0, s21
	global_atomic_add v131, v0, s[38:39]
	s_branch .LBB0_2114
